# UV sweep lists without padding rows: each token's 128 selections cut into 32 full batches, batches ordered by (chunk of first row, token)
# baseline (speedup 1.0000x reference)
; __device__ __forceinline__ unsigned f2key(float f) { const unsigned u = __float_as_uint(f); return (u & 0x80000000u) ? ~u : (u | 0x80000000u); }
; __device__ __forceinline__ void peer_tile(const Args& A, LAS unsigned char* lds, int tile) {
;     ...
;         const int tg = w & 3, hg = w >> 2, tl = 16 * tg + l15;
;         const size_t m = (size_t)tile * 64 + tl;
;         unsigned LA[4][2][16];
; #pragma unroll
;         for (int hh = 0; hh < 4; ++hh) {
;             const int h = 4 * hg + hh;
; #pragma unroll
;             for (int p = 0; p < 2; ++p) {
;                 const int hp = 2 * h + p;
;                 unsigned k0[16], k1[16];
;                 { const bf16_t* sp = QRY + m * 2048 + hp * 128 + 32 * g;
;                   const u32x4 s0 = *(const u32x4*)sp, s1 = *(const u32x4*)(sp + 8), s2 = *(const u32x4*)(sp + 16), s3 = *(const u32x4*)(sp + 24);
;                   const unsigned sw[16] = {s0.x, s0.y, s0.z, s0.w, s1.x, s1.y, s1.z, s1.w, s2.x, s2.y, s2.z, s2.w, s3.x, s3.y, s3.z, s3.w};
; #pragma unroll
;                   for (int i = 0; i < 16; ++i) {
;                       const float lo = (float)__builtin_bit_cast(_Float16, (unsigned short)(sw[i] & 0xffffu)), hi = (float)__builtin_bit_cast(_Float16, (unsigned short)(sw[i] >> 16));
;                       const unsigned klo = (f2key(lo) & ~127u) | (unsigned)(127 - (32 * g + 2 * i)), khi = (f2key(hi) & ~127u) | (unsigned)(127 - (32 * g + 2 * i + 1));
;                       if (i < 8) { k0[2 * i] = klo; k0[2 * i + 1] = khi; } else { k1[2 * (i - 8)] = klo; k1[2 * (i - 8) + 1] = khi; } } }
.LBB0_699:
	v_mov_b32_e32 v19, v214
	s_ashr_i32 s3, s2, 31
	v_ashrrev_i32_e32 v7, 6, v19
	v_and_b32_e32 v0, 15, v19
	v_lshlrev_b32_e32 v1, 4, v7
	v_and_or_b32 v13, v1, 48, v0
	s_lshl_b64 s[28:29], s[2:3], 6
	v_or_b32_e32 v0, s28, v13
	v_mov_b32_e32 v1, s29
	v_bfe_u32 v221, v19, 4, 2
	v_ashrrev_i32_e32 v11, 8, v19
	v_lshlrev_b64 v[0:1], 12, v[0:1]
	v_lshlrev_b32_e32 v2, 10, v11
	v_lshl_add_u64 v[0:1], s[54:55], 0, v[0:1]
	v_lshlrev_b32_e32 v112, 6, v221
	v_lshl_add_u64 v[0:1], v[0:1], 0, v[112:113]
	v_ashrrev_i32_e32 v3, 31, v2
	v_lshl_add_u64 v[4:5], v[2:3], 1, v[0:1]
	global_load_dwordx4 v[20:23], v[4:5], off
	global_load_dwordx4 v[24:27], v[4:5], off offset:16
	global_load_dwordx4 v[0:3], v[4:5], off offset:48
	global_load_dwordx4 v[28:31], v[4:5], off offset:32
	v_lshlrev_b32_e32 v15, 5, v221
	v_or_b32_e32 v8, 8, v15
	v_or_b32_e32 v14, 2, v15
	v_or_b32_e32 v12, 4, v15
	v_or_b32_e32 v10, 6, v15
	v_and_b32_e32 v9, 63, v19
	v_cmp_gt_u32_e64 s[0:1], 16, v9
	v_cmp_gt_u32_e64 s[4:5], 32, v9
	v_mul_lo_u32 v6, v19, s17
	s_mov_b32 s3, 8
	s_waitcnt vmcnt(3)
	v_cvt_f32_f16_sdwa v17, v20 dst_sel:DWORD dst_unused:UNUSED_PAD src0_sel:WORD_1
	v_cvt_f32_f16_e32 v16, v20
	v_cvt_f32_f16_sdwa v20, v21 dst_sel:DWORD dst_unused:UNUSED_PAD src0_sel:WORD_1
	v_cvt_f32_f16_e32 v18, v21
	v_cvt_f32_f16_e32 v21, v22
	v_cvt_f32_f16_sdwa v22, v22 dst_sel:DWORD dst_unused:UNUSED_PAD src0_sel:WORD_1
	v_not_b32_e32 v34, v17
	v_or_b32_e32 v35, 0x80000000, v17
	v_cmp_gt_i32_e32 vcc, 0, v17
	v_not_b32_e32 v36, v16
	v_or_b32_e32 v37, 0x80000000, v16
	v_cndmask_b32_e32 v17, v35, v34, vcc
	v_cmp_gt_i32_e32 vcc, 0, v16
	v_cvt_f32_f16_e32 v32, v23
	v_cvt_f32_f16_sdwa v23, v23 dst_sel:DWORD dst_unused:UNUSED_PAD src0_sel:WORD_1
	v_not_b32_e32 v38, v20
	v_or_b32_e32 v39, 0x80000000, v20
	v_cndmask_b32_e32 v16, v37, v36, vcc
	v_cmp_gt_i32_e32 vcc, 0, v20
	v_not_b32_e32 v40, v18
	v_or_b32_e32 v41, 0x80000000, v18
	v_cndmask_b32_e32 v20, v39, v38, vcc
	v_cmp_gt_i32_e32 vcc, 0, v18
	s_waitcnt vmcnt(2)
	v_cvt_f32_f16_e32 v33, v24
	v_cvt_f32_f16_sdwa v24, v24 dst_sel:DWORD dst_unused:UNUSED_PAD src0_sel:WORD_1
	v_not_b32_e32 v42, v22
	v_or_b32_e32 v43, 0x80000000, v22
	v_cndmask_b32_e32 v18, v41, v40, vcc
	v_cmp_gt_i32_e32 vcc, 0, v22
	v_not_b32_e32 v44, v21
	v_or_b32_e32 v45, 0x80000000, v21
	v_cndmask_b32_e32 v22, v43, v42, vcc
	v_cmp_gt_i32_e32 vcc, 0, v21
	v_not_b32_e32 v46, v23
	v_or_b32_e32 v47, 0x80000000, v23
	v_cndmask_b32_e32 v21, v45, v44, vcc
	v_cmp_gt_i32_e32 vcc, 0, v23
	v_not_b32_e32 v48, v32
	v_or_b32_e32 v49, 0x80000000, v32
	v_cndmask_b32_e32 v23, v47, v46, vcc
	v_cmp_gt_i32_e32 vcc, 0, v32
	v_and_b32_e32 v16, 0xffffff80, v16
	v_not_b32_e32 v50, v24
	v_or_b32_e32 v51, 0x80000000, v24
	v_cndmask_b32_e32 v32, v49, v48, vcc
	v_sub_u32_e32 v16, v16, v15
	v_cmp_gt_i32_e32 vcc, 0, v24
	v_add_u32_e32 v35, 0x7f, v16
	v_and_b32_e32 v17, 0xffffff80, v17
	v_cndmask_b32_e32 v16, v51, v50, vcc
	v_and_b32_e32 v16, 0xffffff80, v16
	v_sub_u32_e32 v17, v17, v15
	v_sub_u32_e32 v16, v16, v8
	v_add_u32_e32 v34, 0x7e, v17
	v_add_u32_e32 v41, 0x7e, v16
	v_not_b32_e32 v16, v33
	v_or_b32_e32 v17, 0x80000000, v33
	v_cmp_gt_i32_e32 vcc, 0, v33
	v_and_b32_e32 v20, 0xffffff80, v20
	v_and_b32_e32 v18, 0xffffff80, v18
	v_cndmask_b32_e32 v16, v17, v16, vcc
	v_cvt_f32_f16_sdwa v17, v25 dst_sel:DWORD dst_unused:UNUSED_PAD src0_sel:WORD_1
	v_and_b32_e32 v21, 0xffffff80, v21
	v_sub_u32_e32 v20, v20, v14
	v_sub_u32_e32 v18, v18, v14
	v_sub_u32_e32 v21, v21, v12
	v_add_u32_e32 v36, 0x7e, v20
	v_add_u32_e32 v37, 0x7f, v18
	v_add_u32_e32 v39, 0x7f, v21
	v_and_b32_e32 v16, 0xffffff80, v16
	v_cvt_f32_f16_e32 v18, v25
	v_not_b32_e32 v20, v17
	v_or_b32_e32 v21, 0x80000000, v17
	v_cmp_gt_i32_e32 vcc, 0, v17
	v_sub_u32_e32 v16, v16, v8
	v_add_u32_e32 v33, 0x7f, v16
	v_cndmask_b32_e32 v17, v21, v20, vcc
	v_or_b32_e32 v16, 10, v15
	v_and_b32_e32 v17, 0xffffff80, v17
	v_sub_u32_e32 v17, v17, v16
	v_add_u32_e32 v42, 0x7e, v17
	v_not_b32_e32 v17, v18
	v_or_b32_e32 v20, 0x80000000, v18
	v_cmp_gt_i32_e32 vcc, 0, v18
	v_cvt_f32_f16_sdwa v18, v26 dst_sel:DWORD dst_unused:UNUSED_PAD src0_sel:WORD_1
	v_and_b32_e32 v22, 0xffffff80, v22
	v_sub_u32_e32 v22, v22, v12
	v_cndmask_b32_e32 v17, v20, v17, vcc
	v_add_u32_e32 v38, 0x7e, v22
	v_and_b32_e32 v17, 0xffffff80, v17
	v_cvt_f32_f16_e32 v20, v26
	v_not_b32_e32 v21, v18
	v_or_b32_e32 v22, 0x80000000, v18
	v_cmp_gt_i32_e32 vcc, 0, v18
	v_sub_u32_e32 v17, v17, v16
	v_add_u32_e32 v43, 0x7f, v17
	v_cndmask_b32_e32 v18, v22, v21, vcc
	v_or_b32_e32 v17, 12, v15
	v_and_b32_e32 v18, 0xffffff80, v18
	v_sub_u32_e32 v18, v18, v17
	v_add_u32_e32 v44, 0x7e, v18
	v_not_b32_e32 v18, v20
	v_or_b32_e32 v21, 0x80000000, v20
	v_cmp_gt_i32_e32 vcc, 0, v20
	v_cvt_f32_f16_sdwa v20, v27 dst_sel:DWORD dst_unused:UNUSED_PAD src0_sel:WORD_1
	v_and_b32_e32 v23, 0xffffff80, v23
	v_sub_u32_e32 v23, v23, v10
	v_cndmask_b32_e32 v18, v21, v18, vcc
	v_add_u32_e32 v40, 0x7e, v23
	v_and_b32_e32 v18, 0xffffff80, v18
	v_cvt_f32_f16_e32 v21, v27
	v_not_b32_e32 v22, v20
	v_or_b32_e32 v23, 0x80000000, v20
	v_cmp_gt_i32_e32 vcc, 0, v20
	v_sub_u32_e32 v18, v18, v17
	v_add_u32_e32 v45, 0x7f, v18
	v_cndmask_b32_e32 v20, v23, v22, vcc
	v_or_b32_e32 v18, 14, v15
	v_and_b32_e32 v20, 0xffffff80, v20
	v_sub_u32_e32 v20, v20, v18
	v_add_u32_e32 v27, 0x7e, v20
	v_not_b32_e32 v20, v21
	v_or_b32_e32 v22, 0x80000000, v21
	v_cmp_gt_i32_e32 vcc, 0, v21
	s_waitcnt vmcnt(0)
; __device__ __forceinline__ unsigned f2key(float f) { const unsigned u = __float_as_uint(f); return (u & 0x80000000u) ? ~u : (u | 0x80000000u); }
; __device__ __forceinline__ void peer_tile(const Args& A, LAS unsigned char* lds, int tile) {
;     ...
;                 { const bf16_t* sp = QRY + m * 2048 + hp * 128 + 32 * g;
;                   const u32x4 s0 = *(const u32x4*)sp, s1 = *(const u32x4*)(sp + 8), s2 = *(const u32x4*)(sp + 16), s3 = *(const u32x4*)(sp + 24);
;                   const unsigned sw[16] = {s0.x, s0.y, s0.z, s0.w, s1.x, s1.y, s1.z, s1.w, s2.x, s2.y, s2.z, s2.w, s3.x, s3.y, s3.z, s3.w};
; #pragma unroll
;                   for (int i = 0; i < 16; ++i) {
;                       const float lo = (float)__builtin_bit_cast(_Float16, (unsigned short)(sw[i] & 0xffffu)), hi = (float)__builtin_bit_cast(_Float16, (unsigned short)(sw[i] >> 16));
;                       const unsigned klo = (f2key(lo) & ~127u) | (unsigned)(127 - (32 * g + 2 * i)), khi = (f2key(hi) & ~127u) | (unsigned)(127 - (32 * g + 2 * i + 1));
;                       if (i < 8) { k0[2 * i] = klo; k0[2 * i + 1] = khi; } else { k1[2 * (i - 8)] = klo; k1[2 * (i - 8) + 1] = khi; } } }
;                 sort16_desc(k0); sort16_desc(k1); merge16(k0, k1);
	v_cvt_f32_f16_sdwa v21, v28 dst_sel:DWORD dst_unused:UNUSED_PAD src0_sel:WORD_1
	v_and_b32_e32 v32, 0xffffff80, v32
	v_cndmask_b32_e32 v20, v22, v20, vcc
	v_and_b32_e32 v20, 0xffffff80, v20
	v_cvt_f32_f16_e32 v22, v28
	v_not_b32_e32 v23, v21
	v_or_b32_e32 v24, 0x80000000, v21
	v_cmp_gt_i32_e32 vcc, 0, v21
	v_sub_u32_e32 v20, v20, v18
	v_add_u32_e32 v46, 0x7f, v20
	v_cndmask_b32_e32 v21, v24, v23, vcc
	v_or_b32_e32 v20, 16, v15
	v_and_b32_e32 v21, 0xffffff80, v21
	v_sub_u32_e32 v21, v21, v20
	v_add_u32_e32 v47, 0x7e, v21
	v_not_b32_e32 v21, v22
	v_or_b32_e32 v23, 0x80000000, v22
	v_cmp_gt_i32_e32 vcc, 0, v22
	v_cvt_f32_f16_sdwa v22, v29 dst_sel:DWORD dst_unused:UNUSED_PAD src0_sel:WORD_1
	v_sub_u32_e32 v32, v32, v10
	v_cndmask_b32_e32 v21, v23, v21, vcc
	v_and_b32_e32 v21, 0xffffff80, v21
	v_cvt_f32_f16_e32 v23, v29
	v_not_b32_e32 v24, v22
	v_or_b32_e32 v25, 0x80000000, v22
	v_cmp_gt_i32_e32 vcc, 0, v22
	v_sub_u32_e32 v21, v21, v20
	v_add_u32_e32 v48, 0x7f, v21
	v_cndmask_b32_e32 v22, v25, v24, vcc
	v_or_b32_e32 v21, 18, v15
	v_and_b32_e32 v22, 0xffffff80, v22
	v_sub_u32_e32 v22, v22, v21
	v_add_u32_e32 v29, 0x7e, v22
	v_not_b32_e32 v22, v23
	v_or_b32_e32 v24, 0x80000000, v23
	v_cmp_gt_i32_e32 vcc, 0, v23
	v_cvt_f32_f16_sdwa v23, v30 dst_sel:DWORD dst_unused:UNUSED_PAD src0_sel:WORD_1
	v_add_u32_e32 v32, 0x7f, v32
	v_cndmask_b32_e32 v22, v24, v22, vcc
	v_and_b32_e32 v22, 0xffffff80, v22
	v_cvt_f32_f16_e32 v24, v30
	v_not_b32_e32 v25, v23
	v_or_b32_e32 v26, 0x80000000, v23
	v_cmp_gt_i32_e32 vcc, 0, v23
	v_sub_u32_e32 v22, v22, v21
	v_add_u32_e32 v49, 0x7f, v22
	v_cndmask_b32_e32 v23, v26, v25, vcc
	v_or_b32_e32 v22, 20, v15
	v_and_b32_e32 v23, 0xffffff80, v23
	v_sub_u32_e32 v23, v23, v22
	v_add_u32_e32 v30, 0x7e, v23
	v_not_b32_e32 v23, v24
	v_or_b32_e32 v25, 0x80000000, v24
	v_cmp_gt_i32_e32 vcc, 0, v24
	v_cvt_f32_f16_sdwa v24, v31 dst_sel:DWORD dst_unused:UNUSED_PAD src0_sel:WORD_1
	v_max_u32_e32 v64, v48, v47
	v_cndmask_b32_e32 v23, v25, v23, vcc
	v_and_b32_e32 v23, 0xffffff80, v23
	v_cvt_f32_f16_e32 v25, v31
	v_not_b32_e32 v26, v24
	v_or_b32_e32 v28, 0x80000000, v24
	v_cmp_gt_i32_e32 vcc, 0, v24
	v_sub_u32_e32 v23, v23, v22
	v_add_u32_e32 v50, 0x7f, v23
	v_cndmask_b32_e32 v24, v28, v26, vcc
	v_or_b32_e32 v23, 22, v15
	v_and_b32_e32 v24, 0xffffff80, v24
	v_sub_u32_e32 v24, v24, v23
	v_add_u32_e32 v31, 0x7e, v24
	v_not_b32_e32 v24, v25
	v_or_b32_e32 v26, 0x80000000, v25
	v_cmp_gt_i32_e32 vcc, 0, v25
	v_cvt_f32_f16_sdwa v25, v0 dst_sel:DWORD dst_unused:UNUSED_PAD src0_sel:WORD_1
	v_cvt_f32_f16_e32 v0, v0
	v_cndmask_b32_e32 v24, v26, v24, vcc
	v_and_b32_e32 v24, 0xffffff80, v24
	v_not_b32_e32 v26, v25
	v_or_b32_e32 v28, 0x80000000, v25
	v_cmp_gt_i32_e32 vcc, 0, v25
	v_sub_u32_e32 v24, v24, v23
	v_add_u32_e32 v51, 0x7f, v24
	v_cndmask_b32_e32 v25, v28, v26, vcc
	v_or_b32_e32 v24, 24, v15
	v_and_b32_e32 v25, 0xffffff80, v25
	v_sub_u32_e32 v25, v25, v24
	v_add_u32_e32 v52, 0x7e, v25
	v_not_b32_e32 v25, v0
	v_or_b32_e32 v26, 0x80000000, v0
	v_cmp_gt_i32_e32 vcc, 0, v0
	v_min_u32_e32 v47, v48, v47
	v_max_u32_e32 v48, v29, v49
	v_cndmask_b32_e32 v0, v26, v25, vcc
	v_cvt_f32_f16_sdwa v26, v1 dst_sel:DWORD dst_unused:UNUSED_PAD src0_sel:WORD_1
	v_cvt_f32_f16_e32 v1, v1
	v_or_b32_e32 v25, 26, v15
	v_and_b32_e32 v0, 0xffffff80, v0
	v_not_b32_e32 v28, v26
	v_or_b32_e32 v53, 0x80000000, v26
	v_cmp_gt_i32_e32 vcc, 0, v26
	v_sub_u32_e32 v0, v0, v24
	v_add_u32_e32 v0, 0x7f, v0
	v_cndmask_b32_e32 v26, v53, v28, vcc
	v_and_b32_e32 v26, 0xffffff80, v26
	v_sub_u32_e32 v26, v26, v25
	v_add_u32_e32 v53, 0x7e, v26
	v_not_b32_e32 v26, v1
	v_or_b32_e32 v28, 0x80000000, v1
	v_cmp_gt_i32_e32 vcc, 0, v1
	v_min_u32_e32 v29, v29, v49
	v_max_u32_e32 v49, v50, v30
	v_cndmask_b32_e32 v1, v28, v26, vcc
	v_cvt_f32_f16_sdwa v28, v2 dst_sel:DWORD dst_unused:UNUSED_PAD src0_sel:WORD_1
	v_cvt_f32_f16_e32 v2, v2
	v_or_b32_e32 v26, 28, v15
	v_and_b32_e32 v1, 0xffffff80, v1
	v_not_b32_e32 v54, v28
	v_or_b32_e32 v55, 0x80000000, v28
	v_cmp_gt_i32_e32 vcc, 0, v28
	v_sub_u32_e32 v1, v1, v25
	v_add_u32_e32 v1, 0x7f, v1
	v_cndmask_b32_e32 v28, v55, v54, vcc
	v_and_b32_e32 v28, 0xffffff80, v28
	v_sub_u32_e32 v28, v28, v26
	v_add_u32_e32 v54, 0x7e, v28
	v_not_b32_e32 v28, v2
	v_or_b32_e32 v55, 0x80000000, v2
	v_cmp_gt_i32_e32 vcc, 0, v2
	v_min_u32_e32 v30, v50, v30
	v_max_u32_e32 v50, v31, v51
	v_cndmask_b32_e32 v2, v55, v28, vcc
	v_cvt_f32_f16_e32 v55, v3
	v_cvt_f32_f16_sdwa v3, v3 dst_sel:DWORD dst_unused:UNUSED_PAD src0_sel:WORD_1
	v_and_b32_e32 v2, 0xffffff80, v2
	v_or_b32_e32 v28, 30, v15
	v_not_b32_e32 v56, v55
	v_or_b32_e32 v57, 0x80000000, v55
	v_cmp_gt_i32_e32 vcc, 0, v55
	v_sub_u32_e32 v2, v2, v26
	v_add_u32_e32 v2, 0x7f, v2
	v_cndmask_b32_e32 v55, v57, v56, vcc
	v_not_b32_e32 v56, v3
	v_or_b32_e32 v57, 0x80000000, v3
	v_cmp_gt_i32_e32 vcc, 0, v3
	v_and_b32_e32 v55, 0xffffff80, v55
	v_sub_u32_e32 v55, v55, v28
	v_cndmask_b32_e32 v3, v57, v56, vcc
	v_and_b32_e32 v3, 0xffffff80, v3
	v_sub_u32_e32 v3, v3, v28
	v_add_u32_e32 v55, 0x7f, v55
	v_add_u32_e32 v3, 0x7e, v3
	v_max_u32_e32 v56, v35, v34
	v_min_u32_e32 v34, v35, v34
	v_max_u32_e32 v35, v36, v37
	v_min_u32_e32 v36, v36, v37
	v_max_u32_e32 v37, v39, v38
	v_min_u32_e32 v38, v39, v38
	v_max_u32_e32 v39, v40, v32
	v_min_u32_e32 v32, v40, v32
	v_max_u32_e32 v40, v33, v41
	v_min_u32_e32 v33, v33, v41
	v_max_u32_e32 v41, v42, v43
	v_min_u32_e32 v42, v42, v43
	v_max_u32_e32 v43, v45, v44
	v_min_u32_e32 v44, v45, v44
	v_max_u32_e32 v45, v27, v46
	v_min_u32_e32 v27, v27, v46
	v_min_u32_e32 v31, v31, v51
	v_max_u32_e32 v51, v0, v52
	v_min_u32_e32 v0, v0, v52
	v_max_u32_e32 v52, v53, v1
	v_min_u32_e32 v1, v53, v1
	v_max_u32_e32 v53, v2, v54
; #define CE_DESC(a, b) do { const unsigned _mx = (a) > (b) ? (a) : (b), _mn = (a) > (b) ? (b) : (a); (a) = _mx; (b) = _mn; } while (0)
; __device__ __forceinline__ void sort16_desc(unsigned (&k)[16]) {
; #pragma unroll
;     for (int size = 2; size <= 16; size <<= 1)
; #pragma unroll
;         for (int stride = size >> 1; stride > 0; stride >>= 1)
; #pragma unroll
;             for (int i = 0; i < 16; ++i) { const int j = i ^ stride;
;                 if (j > i) { if ((i & size) == 0) CE_DESC(k[i], k[j]); else CE_DESC(k[j], k[i]); } }
; }
	v_min_u32_e32 v2, v2, v54
	v_max_u32_e32 v54, v3, v55
	v_min_u32_e32 v3, v3, v55
	v_max_u32_e32 v46, v56, v36
	v_min_u32_e32 v36, v56, v36
	v_max_u32_e32 v56, v34, v35
	v_min_u32_e32 v34, v34, v35
	v_max_u32_e32 v35, v32, v37
	v_min_u32_e32 v32, v32, v37
	v_max_u32_e32 v37, v39, v38
	v_min_u32_e32 v38, v39, v38
	v_max_u32_e32 v39, v40, v42
	v_min_u32_e32 v40, v40, v42
	v_max_u32_e32 v42, v33, v41
	v_min_u32_e32 v33, v33, v41
	v_max_u32_e32 v41, v27, v43
	v_min_u32_e32 v27, v27, v43
	v_max_u32_e32 v43, v45, v44
	v_min_u32_e32 v44, v45, v44
	v_max_u32_e32 v55, v64, v29
	v_min_u32_e32 v29, v64, v29
	v_max_u32_e32 v64, v47, v48
	v_min_u32_e32 v47, v47, v48
	v_max_u32_e32 v48, v31, v49
	v_min_u32_e32 v31, v31, v49
	v_max_u32_e32 v49, v50, v30
	v_min_u32_e32 v30, v50, v30
	v_max_u32_e32 v50, v51, v1
	v_min_u32_e32 v1, v51, v1
	v_max_u32_e32 v51, v0, v52
	v_min_u32_e32 v0, v0, v52
	v_max_u32_e32 v52, v3, v53
	v_min_u32_e32 v3, v3, v53
	v_max_u32_e32 v53, v54, v2
	v_min_u32_e32 v2, v54, v2
	v_max_u32_e32 v45, v46, v56
	v_min_u32_e32 v46, v46, v56
	v_max_u32_e32 v56, v36, v34
	v_min_u32_e32 v34, v36, v34
	v_max_u32_e32 v36, v38, v32
	v_min_u32_e32 v32, v38, v32
	v_max_u32_e32 v38, v37, v35
	v_min_u32_e32 v35, v37, v35
	v_max_u32_e32 v37, v39, v42
	v_min_u32_e32 v39, v39, v42
	v_max_u32_e32 v42, v40, v33
	v_min_u32_e32 v33, v40, v33
	v_max_u32_e32 v40, v44, v27
	v_min_u32_e32 v27, v44, v27
	v_max_u32_e32 v44, v43, v41
	v_min_u32_e32 v41, v43, v41
	v_max_u32_e32 v54, v55, v64
	v_min_u32_e32 v55, v55, v64
	v_max_u32_e32 v64, v29, v47
	v_min_u32_e32 v29, v29, v47
	v_max_u32_e32 v47, v30, v31
	v_min_u32_e32 v30, v30, v31
	v_max_u32_e32 v31, v49, v48
	v_min_u32_e32 v48, v49, v48
	v_max_u32_e32 v49, v50, v51
	v_min_u32_e32 v50, v50, v51
	v_max_u32_e32 v51, v1, v0
	v_min_u32_e32 v0, v1, v0
	v_max_u32_e32 v1, v2, v3
	v_min_u32_e32 v2, v2, v3
	v_max_u32_e32 v3, v53, v52
	v_min_u32_e32 v52, v53, v52
	v_max_u32_e32 v43, v45, v32
	v_min_u32_e32 v32, v45, v32
	v_max_u32_e32 v45, v46, v36
	v_min_u32_e32 v36, v46, v36
	v_max_u32_e32 v46, v56, v35
	v_min_u32_e32 v35, v56, v35
	v_max_u32_e32 v56, v34, v38
	v_min_u32_e32 v34, v34, v38
	v_max_u32_e32 v38, v27, v37
	v_min_u32_e32 v27, v27, v37
	v_max_u32_e32 v37, v40, v39
	v_min_u32_e32 v39, v40, v39
	v_max_u32_e32 v40, v41, v42
	v_min_u32_e32 v41, v41, v42
	v_max_u32_e32 v42, v44, v33
	v_min_u32_e32 v33, v44, v33
	v_max_u32_e32 v53, v54, v30
	v_min_u32_e32 v30, v54, v30
	v_max_u32_e32 v54, v55, v47
	v_min_u32_e32 v47, v55, v47
	v_max_u32_e32 v55, v64, v48
	v_min_u32_e32 v48, v64, v48
	v_max_u32_e32 v64, v29, v31
	v_min_u32_e32 v29, v29, v31
	v_max_u32_e32 v31, v2, v49
	v_min_u32_e32 v2, v2, v49
	v_max_u32_e32 v49, v1, v50
	v_min_u32_e32 v1, v1, v50
	v_max_u32_e32 v50, v52, v51
	v_min_u32_e32 v51, v52, v51
	v_max_u32_e32 v52, v3, v0
	v_min_u32_e32 v0, v3, v0
	v_max_u32_e32 v44, v43, v46
	v_min_u32_e32 v43, v43, v46
	v_max_u32_e32 v46, v45, v56
	v_min_u32_e32 v45, v45, v56
	v_max_u32_e32 v56, v32, v35
	v_min_u32_e32 v32, v32, v35
	v_max_u32_e32 v35, v36, v34
	v_min_u32_e32 v34, v36, v34
	v_max_u32_e32 v36, v41, v27
	v_min_u32_e32 v27, v41, v27
	v_max_u32_e32 v41, v33, v39
	v_min_u32_e32 v33, v33, v39
	v_max_u32_e32 v39, v40, v38
	v_min_u32_e32 v38, v40, v38
	v_max_u32_e32 v40, v42, v37
	v_min_u32_e32 v37, v42, v37
	v_max_u32_e32 v3, v53, v55
	v_min_u32_e32 v53, v53, v55
	v_max_u32_e32 v55, v54, v64
	v_min_u32_e32 v54, v54, v64
	v_max_u32_e32 v64, v30, v48
	v_min_u32_e32 v30, v30, v48
	v_max_u32_e32 v48, v47, v29
	v_min_u32_e32 v29, v47, v29
	v_max_u32_e32 v47, v51, v2
	v_min_u32_e32 v2, v51, v2
	v_max_u32_e32 v51, v0, v1
	v_min_u32_e32 v0, v0, v1
	v_max_u32_e32 v1, v50, v31
	v_min_u32_e32 v31, v50, v31
	v_max_u32_e32 v50, v52, v49
	v_min_u32_e32 v49, v52, v49
	v_max_u32_e32 v42, v44, v46
	v_min_u32_e32 v44, v44, v46
	v_max_u32_e32 v46, v43, v45
	v_min_u32_e32 v43, v43, v45
	v_max_u32_e32 v45, v56, v35
	v_min_u32_e32 v35, v56, v35
	v_max_u32_e32 v56, v32, v34
	v_min_u32_e32 v32, v32, v34
	v_max_u32_e32 v34, v33, v27
	v_min_u32_e32 v27, v33, v27
	v_max_u32_e32 v33, v41, v36
	v_min_u32_e32 v36, v41, v36
	v_max_u32_e32 v41, v37, v38
	v_min_u32_e32 v37, v37, v38
	v_max_u32_e32 v38, v40, v39
	v_min_u32_e32 v39, v40, v39
	v_max_u32_e32 v52, v3, v55
	v_min_u32_e32 v3, v3, v55
	v_max_u32_e32 v55, v53, v54
	v_min_u32_e32 v53, v53, v54
	v_max_u32_e32 v54, v64, v48
	v_min_u32_e32 v48, v64, v48
	v_max_u32_e32 v64, v30, v29
	v_min_u32_e32 v29, v30, v29
	v_max_u32_e32 v30, v0, v2
	v_min_u32_e32 v0, v0, v2
	v_max_u32_e32 v2, v51, v47
	v_min_u32_e32 v47, v51, v47
	v_max_u32_e32 v51, v49, v31
	v_min_u32_e32 v31, v49, v31
	v_max_u32_e32 v49, v50, v1
	v_min_u32_e32 v1, v50, v1
	v_max_u32_e32 v40, v42, v27
	v_min_u32_e32 v27, v42, v27
	v_max_u32_e32 v42, v44, v34
	v_min_u32_e32 v34, v44, v34
	v_max_u32_e32 v44, v46, v36
	v_min_u32_e32 v36, v46, v36
	v_max_u32_e32 v46, v43, v33
	v_min_u32_e32 v33, v43, v33
	v_max_u32_e32 v43, v45, v37
	v_min_u32_e32 v37, v45, v37
	v_max_u32_e32 v45, v35, v41
	v_min_u32_e32 v35, v35, v41
	v_max_u32_e32 v41, v56, v39
	v_min_u32_e32 v39, v56, v39
	v_max_u32_e32 v56, v32, v38
	v_min_u32_e32 v32, v32, v38
	v_max_u32_e32 v50, v52, v0
	v_min_u32_e32 v0, v52, v0
	v_max_u32_e32 v52, v3, v30
	v_min_u32_e32 v3, v3, v30
	v_max_u32_e32 v30, v55, v47
	v_min_u32_e32 v47, v55, v47
	v_max_u32_e32 v55, v53, v2
	v_min_u32_e32 v2, v53, v2
	v_max_u32_e32 v53, v54, v31
	v_min_u32_e32 v31, v54, v31
	v_max_u32_e32 v54, v48, v51
	v_min_u32_e32 v48, v48, v51
	v_max_u32_e32 v51, v64, v1
	v_min_u32_e32 v1, v64, v1
	v_max_u32_e32 v64, v29, v49
	v_min_u32_e32 v29, v29, v49
	v_max_u32_e32 v38, v40, v43
	v_min_u32_e32 v40, v40, v43
; #define CE_DESC(a, b) do { const unsigned _mx = (a) > (b) ? (a) : (b), _mn = (a) > (b) ? (b) : (a); (a) = _mx; (b) = _mn; } while (0)
; __device__ __forceinline__ void merge16(unsigned (&a)[16], const unsigned (&b)[16]) {
; #pragma unroll
;     for (int i = 0; i < 16; ++i) a[i] = a[i] > b[15 - i] ? a[i] : b[15 - i];
; #pragma unroll
;     for (int stride = 8; stride > 0; stride >>= 1)
; #pragma unroll
;         for (int i = 0; i < 16; ++i) { const int j = i ^ stride; if (j > i) CE_DESC(a[i], a[j]); }
; }
; __device__ __forceinline__ void peer_tile(const Args& A, LAS unsigned char* lds, int tile) {
;     ...
;                 for (int msk = 16; msk <= 32; msk <<= 1) {
; #pragma unroll
;                     for (int i = 0; i < 16; ++i) k1[i] = (unsigned)__shfl_xor((int)k0[i], msk);
;                     merge16(k0, k1); }
	v_max_u32_e32 v43, v42, v45
	v_min_u32_e32 v42, v42, v45
	v_max_u32_e32 v45, v44, v41
	v_min_u32_e32 v41, v44, v41
	v_max_u32_e32 v44, v46, v56
	v_min_u32_e32 v46, v46, v56
	v_max_u32_e32 v56, v27, v37
	v_min_u32_e32 v27, v27, v37
	v_max_u32_e32 v37, v34, v35
	v_min_u32_e32 v34, v34, v35
	v_max_u32_e32 v35, v36, v39
	v_min_u32_e32 v36, v36, v39
	v_max_u32_e32 v39, v33, v32
	v_min_u32_e32 v32, v33, v32
	v_max_u32_e32 v49, v50, v53
	v_min_u32_e32 v50, v50, v53
	v_max_u32_e32 v53, v52, v54
	v_min_u32_e32 v52, v52, v54
	v_max_u32_e32 v54, v30, v51
	v_min_u32_e32 v30, v30, v51
	v_max_u32_e32 v51, v55, v64
	v_min_u32_e32 v55, v55, v64
	v_max_u32_e32 v64, v0, v31
	v_min_u32_e32 v0, v0, v31
	v_max_u32_e32 v31, v3, v48
	v_min_u32_e32 v3, v3, v48
	v_max_u32_e32 v48, v47, v1
	v_min_u32_e32 v1, v47, v1
	v_max_u32_e32 v47, v2, v29
	v_min_u32_e32 v2, v2, v29
	v_max_u32_e32 v33, v38, v45
	v_min_u32_e32 v38, v38, v45
	v_max_u32_e32 v45, v43, v44
	v_min_u32_e32 v43, v43, v44
	v_max_u32_e32 v44, v40, v41
	v_min_u32_e32 v40, v40, v41
	v_max_u32_e32 v41, v42, v46
	v_min_u32_e32 v42, v42, v46
	v_max_u32_e32 v46, v56, v35
	v_min_u32_e32 v35, v56, v35
	v_max_u32_e32 v56, v37, v39
	v_min_u32_e32 v37, v37, v39
	v_max_u32_e32 v39, v27, v36
	v_min_u32_e32 v27, v27, v36
	v_max_u32_e32 v36, v34, v32
	v_min_u32_e32 v32, v34, v32
	v_max_u32_e32 v29, v49, v54
	v_min_u32_e32 v49, v49, v54
	v_max_u32_e32 v54, v53, v51
	v_min_u32_e32 v51, v53, v51
	v_max_u32_e32 v53, v50, v30
	v_min_u32_e32 v30, v50, v30
	v_max_u32_e32 v50, v52, v55
	v_min_u32_e32 v52, v52, v55
	v_max_u32_e32 v55, v64, v48
	v_min_u32_e32 v48, v64, v48
	v_max_u32_e32 v64, v31, v47
	v_min_u32_e32 v31, v31, v47
	v_max_u32_e32 v47, v0, v1
	v_min_u32_e32 v0, v0, v1
	v_max_u32_e32 v1, v3, v2
	v_min_u32_e32 v2, v3, v2
	v_min_u32_e32 v34, v33, v45
	v_min_u32_e32 v57, v38, v43
	v_min_u32_e32 v58, v44, v41
	v_min_u32_e32 v59, v40, v42
	v_min_u32_e32 v60, v46, v56
	v_min_u32_e32 v61, v35, v37
	v_min_u32_e32 v62, v39, v36
	v_min_u32_e32 v63, v27, v32
	v_min_u32_e32 v3, v29, v54
	v_min_u32_e32 v65, v49, v51
	v_min_u32_e32 v66, v53, v50
	v_min_u32_e32 v67, v30, v52
	v_min_u32_e32 v68, v55, v64
	v_min_u32_e32 v69, v48, v31
	v_min_u32_e32 v70, v47, v1
	v_min_u32_e32 v71, v0, v2
	v_max3_u32 v33, v33, v45, v71
	v_max3_u32 v0, v34, v0, v2
	v_max3_u32 v2, v38, v43, v70
	v_max3_u32 v1, v57, v47, v1
	v_max3_u32 v34, v44, v41, v69
	v_max3_u32 v31, v58, v48, v31
	v_max3_u32 v38, v40, v42, v68
	v_max3_u32 v40, v59, v55, v64
	v_max3_u32 v41, v46, v56, v67
	v_max3_u32 v30, v60, v30, v52
	v_max3_u32 v35, v35, v37, v66
	v_max3_u32 v37, v61, v53, v50
	v_max3_u32 v36, v39, v36, v65
	v_max3_u32 v39, v62, v49, v51
	v_max3_u32 v3, v27, v32, v3
	v_max3_u32 v27, v63, v29, v54
	v_max_u32_e32 v29, v33, v41
	v_min_u32_e32 v32, v33, v41
	v_max_u32_e32 v33, v0, v30
	v_min_u32_e32 v0, v0, v30
	v_max_u32_e32 v30, v2, v35
	v_min_u32_e32 v2, v2, v35
	v_max_u32_e32 v35, v1, v37
	v_min_u32_e32 v1, v1, v37
	v_max_u32_e32 v37, v34, v36
	v_min_u32_e32 v34, v34, v36
	v_max_u32_e32 v36, v31, v39
	v_min_u32_e32 v31, v31, v39
	v_max_u32_e32 v39, v38, v3
	v_min_u32_e32 v3, v38, v3
	v_max_u32_e32 v38, v40, v27
	v_min_u32_e32 v27, v40, v27
	v_max_u32_e32 v40, v29, v37
	v_min_u32_e32 v29, v29, v37
	v_max_u32_e32 v37, v33, v36
	v_min_u32_e32 v33, v33, v36
	v_max_u32_e32 v36, v30, v39
	v_min_u32_e32 v30, v30, v39
	v_max_u32_e32 v39, v35, v38
	v_min_u32_e32 v35, v35, v38
	v_max_u32_e32 v38, v32, v34
	v_min_u32_e32 v32, v32, v34
	v_max_u32_e32 v34, v0, v31
	v_min_u32_e32 v0, v0, v31
	v_max_u32_e32 v31, v2, v3
	v_min_u32_e32 v2, v2, v3
	v_max_u32_e32 v3, v1, v27
	v_min_u32_e32 v1, v1, v27
	v_max_u32_e32 v27, v40, v36
	v_min_u32_e32 v36, v40, v36
	v_max_u32_e32 v40, v37, v39
	v_min_u32_e32 v37, v37, v39
	v_max_u32_e32 v39, v29, v30
	v_min_u32_e32 v29, v29, v30
	v_max_u32_e32 v30, v33, v35
	v_min_u32_e32 v33, v33, v35
	v_max_u32_e32 v35, v38, v31
	v_min_u32_e32 v31, v38, v31
	v_max_u32_e32 v38, v34, v3
	v_min_u32_e32 v3, v34, v3
	v_max_u32_e32 v34, v32, v2
	v_min_u32_e32 v2, v32, v2
	v_max_u32_e32 v32, v0, v1
	v_min_u32_e32 v0, v0, v1
	v_cmp_lt_i32_e32 vcc, v217, v216
	v_max_u32_e32 v41, v36, v37
	v_min_u32_e32 v36, v36, v37
	v_max_u32_e32 v37, v39, v30
	v_min_u32_e32 v30, v39, v30
	v_max_u32_e32 v39, v29, v33
	v_min_u32_e32 v29, v29, v33
	v_max_u32_e32 v33, v35, v38
	v_min_u32_e32 v35, v35, v38
	v_max_u32_e32 v38, v31, v3
	v_min_u32_e32 v3, v31, v3
	v_max_u32_e32 v31, v34, v32
	v_min_u32_e32 v32, v34, v32
	v_max_u32_e32 v34, v2, v0
	v_min_u32_e32 v0, v2, v0
	v_cndmask_b32_e32 v2, v215, v217, vcc
	v_max_u32_e32 v1, v27, v40
	v_min_u32_e32 v40, v27, v40
	v_lshlrev_b32_e32 v27, 2, v2
	ds_bpermute_b32 v2, v27, v1
	ds_bpermute_b32 v42, v27, v40
	ds_bpermute_b32 v43, v27, v41
	ds_bpermute_b32 v44, v27, v36
	ds_bpermute_b32 v45, v27, v37
	ds_bpermute_b32 v46, v27, v30
	ds_bpermute_b32 v47, v27, v39
	ds_bpermute_b32 v48, v27, v29
	ds_bpermute_b32 v49, v27, v33
	ds_bpermute_b32 v50, v27, v35
	ds_bpermute_b32 v51, v27, v38
	ds_bpermute_b32 v52, v27, v0
	ds_bpermute_b32 v53, v27, v34
	ds_bpermute_b32 v54, v27, v32
	ds_bpermute_b32 v55, v27, v31
	ds_bpermute_b32 v56, v27, v3
	s_waitcnt lgkmcnt(4)
	v_max_u32_e32 v1, v1, v52
	s_waitcnt lgkmcnt(3)
	v_max_u32_e32 v40, v40, v53
	s_waitcnt lgkmcnt(2)
	v_max_u32_e32 v41, v41, v54
	s_waitcnt lgkmcnt(1)
	v_max_u32_e32 v36, v36, v55
	s_waitcnt lgkmcnt(0)
; #define CE_DESC(a, b) do { const unsigned _mx = (a) > (b) ? (a) : (b), _mn = (a) > (b) ? (b) : (a); (a) = _mx; (b) = _mn; } while (0)
; __device__ __forceinline__ void merge16(unsigned (&a)[16], const unsigned (&b)[16]) {
; #pragma unroll
;     for (int i = 0; i < 16; ++i) a[i] = a[i] > b[15 - i] ? a[i] : b[15 - i];
; #pragma unroll
;     for (int stride = 8; stride > 0; stride >>= 1)
; #pragma unroll
;         for (int i = 0; i < 16; ++i) { const int j = i ^ stride; if (j > i) CE_DESC(a[i], a[j]); }
; }
; __device__ __forceinline__ void peer_tile(const Args& A, LAS unsigned char* lds, int tile) {
;     ...
;                 { const bf16_t* sp = QRY + m * 2048 + hp * 128 + 32 * g;
;                   const u32x4 s0 = *(const u32x4*)sp, s1 = *(const u32x4*)(sp + 8), s2 = *(const u32x4*)(sp + 16), s3 = *(const u32x4*)(sp + 24);
;     ...
;                 for (int msk = 16; msk <= 32; msk <<= 1) {
; #pragma unroll
;                     for (int i = 0; i < 16; ++i) k1[i] = (unsigned)__shfl_xor((int)k0[i], msk);
;                     merge16(k0, k1); }
	v_max_u32_e32 v37, v37, v56
	v_max_u32_e32 v30, v30, v51
	v_max_u32_e32 v39, v39, v50
	v_max_u32_e32 v29, v29, v49
	v_max_u32_e32 v33, v33, v48
	v_max_u32_e32 v35, v35, v47
	v_max_u32_e32 v38, v38, v46
	v_max_u32_e32 v3, v3, v45
	v_max_u32_e32 v31, v31, v44
	v_max_u32_e32 v32, v32, v43
	v_max_u32_e32 v34, v34, v42
	v_max_u32_e32 v0, v0, v2
	v_max_u32_e32 v2, v1, v33
	v_min_u32_e32 v1, v1, v33
	v_max_u32_e32 v33, v40, v35
	v_min_u32_e32 v35, v40, v35
	v_max_u32_e32 v40, v41, v38
	v_min_u32_e32 v38, v41, v38
	v_max_u32_e32 v41, v36, v3
	v_min_u32_e32 v3, v36, v3
	v_max_u32_e32 v36, v37, v31
	v_min_u32_e32 v31, v37, v31
	v_max_u32_e32 v37, v30, v32
	v_min_u32_e32 v30, v30, v32
	v_max_u32_e32 v32, v39, v34
	v_min_u32_e32 v34, v39, v34
	v_max_u32_e32 v39, v29, v0
	v_min_u32_e32 v0, v29, v0
	v_max_u32_e32 v29, v2, v36
	v_min_u32_e32 v2, v2, v36
	v_max_u32_e32 v36, v33, v37
	v_min_u32_e32 v33, v33, v37
	v_max_u32_e32 v37, v40, v32
	v_min_u32_e32 v32, v40, v32
	v_max_u32_e32 v40, v41, v39
	v_min_u32_e32 v39, v41, v39
	v_max_u32_e32 v41, v1, v31
	v_min_u32_e32 v1, v1, v31
	v_max_u32_e32 v31, v35, v30
	v_min_u32_e32 v30, v35, v30
	v_max_u32_e32 v35, v38, v34
	v_min_u32_e32 v34, v38, v34
	v_max_u32_e32 v38, v3, v0
	v_min_u32_e32 v0, v3, v0
	v_max_u32_e32 v3, v29, v37
	v_min_u32_e32 v29, v29, v37
	v_max_u32_e32 v37, v36, v40
	v_min_u32_e32 v36, v36, v40
	v_max_u32_e32 v40, v2, v32
	v_min_u32_e32 v2, v2, v32
	v_max_u32_e32 v32, v33, v39
	v_min_u32_e32 v33, v33, v39
	v_max_u32_e32 v39, v41, v35
	v_min_u32_e32 v35, v41, v35
	v_max_u32_e32 v41, v31, v38
	v_min_u32_e32 v31, v31, v38
	v_max_u32_e32 v38, v1, v34
	v_min_u32_e32 v1, v1, v34
	v_max_u32_e32 v34, v30, v0
	v_min_u32_e32 v0, v30, v0
	v_cmp_lt_i32_e32 vcc, v218, v216
	v_max_u32_e32 v42, v40, v32
	v_min_u32_e32 v32, v40, v32
	v_max_u32_e32 v40, v2, v33
	v_min_u32_e32 v2, v2, v33
	v_max_u32_e32 v33, v39, v41
	v_min_u32_e32 v39, v39, v41
	v_max_u32_e32 v41, v35, v31
	v_min_u32_e32 v31, v35, v31
	v_max_u32_e32 v35, v38, v34
	v_min_u32_e32 v34, v38, v34
	v_max_u32_e32 v38, v1, v0
	v_min_u32_e32 v0, v1, v0
	v_cndmask_b32_e32 v1, v215, v218, vcc
	v_max_u32_e32 v30, v3, v37
	v_min_u32_e32 v3, v3, v37
	v_max_u32_e32 v37, v29, v36
	v_min_u32_e32 v36, v29, v36
	v_lshlrev_b32_e32 v29, 2, v1
	ds_bpermute_b32 v46, v29, v0
	ds_bpermute_b32 v1, v29, v30
	ds_bpermute_b32 v43, v29, v3
	ds_bpermute_b32 v44, v29, v37
	ds_bpermute_b32 v45, v29, v36
	s_waitcnt lgkmcnt(4)
	v_max_u32_e32 v30, v30, v46
	global_load_dwordx4 v[46:49], v[4:5], off offset:272
	global_load_dwordx4 v[50:53], v[4:5], off offset:256
	ds_bpermute_b32 v54, v29, v42
	ds_bpermute_b32 v55, v29, v32
	ds_bpermute_b32 v56, v29, v40
	ds_bpermute_b32 v57, v29, v2
	ds_bpermute_b32 v58, v29, v33
	ds_bpermute_b32 v59, v29, v39
	ds_bpermute_b32 v60, v29, v41
	ds_bpermute_b32 v61, v29, v31
	ds_bpermute_b32 v62, v29, v35
	ds_bpermute_b32 v63, v29, v38
	ds_bpermute_b32 v64, v29, v34
	s_waitcnt lgkmcnt(4)
	v_max_u32_e32 v32, v32, v60
	s_waitcnt lgkmcnt(3)
	v_max_u32_e32 v42, v42, v61
	s_waitcnt lgkmcnt(2)
	v_max_u32_e32 v36, v36, v62
	s_waitcnt lgkmcnt(1)
	v_max_u32_e32 v3, v3, v63
	s_waitcnt lgkmcnt(0)
	v_max_u32_e32 v37, v37, v64
	v_max_u32_e32 v40, v40, v59
	v_max_u32_e32 v2, v2, v58
	v_max_u32_e32 v33, v33, v57
	v_max_u32_e32 v39, v39, v56
	v_max_u32_e32 v41, v41, v55
	v_max_u32_e32 v31, v31, v54
	v_max_u32_e32 v35, v35, v45
	v_max_u32_e32 v34, v34, v44
	v_max_u32_e32 v38, v38, v43
	v_max_u32_e32 v0, v0, v1
	v_max_u32_e32 v1, v30, v33
	v_min_u32_e32 v30, v30, v33
	v_max_u32_e32 v33, v3, v39
	v_min_u32_e32 v3, v3, v39
	v_max_u32_e32 v39, v37, v41
	v_min_u32_e32 v37, v37, v41
	v_max_u32_e32 v41, v36, v31
	v_min_u32_e32 v31, v36, v31
	v_max_u32_e32 v36, v42, v35
	v_min_u32_e32 v35, v42, v35
	v_max_u32_e32 v42, v32, v34
	v_min_u32_e32 v32, v32, v34
	v_max_u32_e32 v34, v40, v38
	v_min_u32_e32 v38, v40, v38
	v_max_u32_e32 v40, v2, v0
	v_min_u32_e32 v0, v2, v0
	v_max_u32_e32 v2, v1, v36
	v_min_u32_e32 v1, v1, v36
	v_max_u32_e32 v36, v33, v42
	v_min_u32_e32 v33, v33, v42
	v_max_u32_e32 v42, v39, v34
	v_min_u32_e32 v34, v39, v34
	v_max_u32_e32 v39, v41, v40
	v_min_u32_e32 v40, v41, v40
	v_max_u32_e32 v41, v30, v35
	v_min_u32_e32 v30, v30, v35
	v_max_u32_e32 v35, v3, v32
	v_min_u32_e32 v3, v3, v32
	v_max_u32_e32 v32, v37, v38
	v_min_u32_e32 v37, v37, v38
	v_max_u32_e32 v38, v31, v0
	v_min_u32_e32 v0, v31, v0
	v_max_u32_e32 v31, v2, v42
	v_min_u32_e32 v2, v2, v42
	v_max_u32_e32 v42, v36, v39
	v_min_u32_e32 v36, v36, v39
	v_max_u32_e32 v39, v1, v34
	v_min_u32_e32 v1, v1, v34
	v_max_u32_e32 v34, v33, v40
	v_min_u32_e32 v33, v33, v40
	v_max_u32_e32 v54, v41, v32
	v_min_u32_e32 v32, v41, v32
	v_max_u32_e32 v55, v35, v38
	v_min_u32_e32 v56, v35, v38
	v_max_u32_e32 v57, v30, v37
	v_min_u32_e32 v30, v30, v37
	v_max_u32_e32 v58, v3, v0
	v_min_u32_e32 v0, v3, v0
	v_max_u32_e32 v45, v31, v42
	v_min_u32_e32 v44, v31, v42
	v_max_u32_e32 v43, v2, v36
	v_min_u32_e32 v42, v2, v36
	v_max_u32_e32 v41, v39, v34
	v_min_u32_e32 v40, v39, v34
	v_max_u32_e32 v39, v1, v33
	v_min_u32_e32 v38, v1, v33
	v_max_u32_e32 v37, v54, v55
	v_min_u32_e32 v36, v54, v55
	v_max_u32_e32 v35, v32, v56
	v_min_u32_e32 v34, v32, v56
	v_max_u32_e32 v33, v57, v58
	v_min_u32_e32 v32, v57, v58
	v_max_u32_e32 v31, v30, v0
	v_min_u32_e32 v30, v30, v0
	global_load_dwordx4 v[0:3], v[4:5], off offset:304
	global_load_dwordx4 v[54:57], v[4:5], off offset:288
	s_waitcnt vmcnt(2)
; __device__ __forceinline__ unsigned f2key(float f) { const unsigned u = __float_as_uint(f); return (u & 0x80000000u) ? ~u : (u | 0x80000000u); }
; __device__ __forceinline__ void peer_tile(const Args& A, LAS unsigned char* lds, int tile) {
;     ...
;                 { const bf16_t* sp = QRY + m * 2048 + hp * 128 + 32 * g;
;                   const u32x4 s0 = *(const u32x4*)sp, s1 = *(const u32x4*)(sp + 8), s2 = *(const u32x4*)(sp + 16), s3 = *(const u32x4*)(sp + 24);
;                   const unsigned sw[16] = {s0.x, s0.y, s0.z, s0.w, s1.x, s1.y, s1.z, s1.w, s2.x, s2.y, s2.z, s2.w, s3.x, s3.y, s3.z, s3.w};
; #pragma unroll
;                   for (int i = 0; i < 16; ++i) {
;                       const float lo = (float)__builtin_bit_cast(_Float16, (unsigned short)(sw[i] & 0xffffu)), hi = (float)__builtin_bit_cast(_Float16, (unsigned short)(sw[i] >> 16));
;                       const unsigned klo = (f2key(lo) & ~127u) | (unsigned)(127 - (32 * g + 2 * i)), khi = (f2key(hi) & ~127u) | (unsigned)(127 - (32 * g + 2 * i + 1));
;                       if (i < 8) { k0[2 * i] = klo; k0[2 * i + 1] = khi; } else { k1[2 * (i - 8)] = klo; k1[2 * (i - 8) + 1] = khi; } } }
	v_cvt_f32_f16_sdwa v58, v50 dst_sel:DWORD dst_unused:UNUSED_PAD src0_sel:WORD_1
	v_cvt_f32_f16_e32 v50, v50
	v_not_b32_e32 v59, v58
	v_or_b32_e32 v60, 0x80000000, v58
	v_cmp_gt_i32_e32 vcc, 0, v58
	s_nop 1
	v_cndmask_b32_e32 v58, v60, v59, vcc
	v_not_b32_e32 v59, v50
	v_or_b32_e32 v60, 0x80000000, v50
	v_cmp_gt_i32_e32 vcc, 0, v50
	v_and_b32_e32 v58, 0xffffff80, v58
	v_sub_u32_e32 v58, v58, v15
	v_cndmask_b32_e32 v50, v60, v59, vcc
	v_cvt_f32_f16_sdwa v59, v51 dst_sel:DWORD dst_unused:UNUSED_PAD src0_sel:WORD_1
	v_cvt_f32_f16_e32 v51, v51
	v_and_b32_e32 v50, 0xffffff80, v50
	v_sub_u32_e32 v50, v50, v15
	v_not_b32_e32 v60, v59
	v_or_b32_e32 v61, 0x80000000, v59
	v_cmp_gt_i32_e32 vcc, 0, v59
	v_add_u32_e32 v58, 0x7e, v58
	v_add_u32_e32 v50, 0x7f, v50
	v_cndmask_b32_e32 v59, v61, v60, vcc
	v_not_b32_e32 v60, v51
	v_or_b32_e32 v61, 0x80000000, v51
	v_cmp_gt_i32_e32 vcc, 0, v51
	v_and_b32_e32 v59, 0xffffff80, v59
	v_sub_u32_e32 v59, v59, v14
	v_cndmask_b32_e32 v51, v61, v60, vcc
	v_cvt_f32_f16_sdwa v60, v52 dst_sel:DWORD dst_unused:UNUSED_PAD src0_sel:WORD_1
	v_cvt_f32_f16_e32 v52, v52
	v_and_b32_e32 v51, 0xffffff80, v51
	v_sub_u32_e32 v51, v51, v14
	v_not_b32_e32 v61, v60
	v_or_b32_e32 v62, 0x80000000, v60
	v_cmp_gt_i32_e32 vcc, 0, v60
	v_add_u32_e32 v59, 0x7e, v59
	v_add_u32_e32 v51, 0x7f, v51
	v_cndmask_b32_e32 v60, v62, v61, vcc
	v_not_b32_e32 v61, v52
	v_or_b32_e32 v62, 0x80000000, v52
	v_cmp_gt_i32_e32 vcc, 0, v52
	v_and_b32_e32 v60, 0xffffff80, v60
	v_sub_u32_e32 v60, v60, v12
	v_cndmask_b32_e32 v52, v62, v61, vcc
	v_cvt_f32_f16_sdwa v61, v53 dst_sel:DWORD dst_unused:UNUSED_PAD src0_sel:WORD_1
	v_cvt_f32_f16_e32 v53, v53
	v_and_b32_e32 v52, 0xffffff80, v52
	v_sub_u32_e32 v52, v52, v12
	v_not_b32_e32 v62, v61
	v_or_b32_e32 v63, 0x80000000, v61
	v_cmp_gt_i32_e32 vcc, 0, v61
	v_add_u32_e32 v60, 0x7e, v60
	v_add_u32_e32 v52, 0x7f, v52
	v_cndmask_b32_e32 v61, v63, v62, vcc
	v_not_b32_e32 v62, v53
	v_or_b32_e32 v63, 0x80000000, v53
	v_cmp_gt_i32_e32 vcc, 0, v53
	v_and_b32_e32 v61, 0xffffff80, v61
	v_sub_u32_e32 v61, v61, v10
	v_cndmask_b32_e32 v53, v63, v62, vcc
	v_cvt_f32_f16_sdwa v62, v46 dst_sel:DWORD dst_unused:UNUSED_PAD src0_sel:WORD_1
	v_cvt_f32_f16_e32 v46, v46
	v_and_b32_e32 v53, 0xffffff80, v53
	v_sub_u32_e32 v53, v53, v10
	v_not_b32_e32 v63, v62
	v_or_b32_e32 v64, 0x80000000, v62
	v_cmp_gt_i32_e32 vcc, 0, v62
	v_add_u32_e32 v61, 0x7e, v61
	v_add_u32_e32 v53, 0x7f, v53
	v_cndmask_b32_e32 v62, v64, v63, vcc
	v_not_b32_e32 v63, v46
	v_or_b32_e32 v64, 0x80000000, v46
	v_cmp_gt_i32_e32 vcc, 0, v46
	v_and_b32_e32 v62, 0xffffff80, v62
	v_sub_u32_e32 v62, v62, v8
	v_cndmask_b32_e32 v46, v64, v63, vcc
	v_cvt_f32_f16_sdwa v63, v47 dst_sel:DWORD dst_unused:UNUSED_PAD src0_sel:WORD_1
	v_cvt_f32_f16_e32 v47, v47
	v_and_b32_e32 v46, 0xffffff80, v46
	v_sub_u32_e32 v46, v46, v8
	v_not_b32_e32 v64, v63
	v_or_b32_e32 v65, 0x80000000, v63
	v_cmp_gt_i32_e32 vcc, 0, v63
	v_add_u32_e32 v62, 0x7e, v62
	v_add_u32_e32 v46, 0x7f, v46
	v_cndmask_b32_e32 v63, v65, v64, vcc
	v_not_b32_e32 v64, v47
	v_or_b32_e32 v65, 0x80000000, v47
	v_cmp_gt_i32_e32 vcc, 0, v47
	v_and_b32_e32 v63, 0xffffff80, v63
	v_sub_u32_e32 v63, v63, v16
	v_cndmask_b32_e32 v47, v65, v64, vcc
	v_cvt_f32_f16_sdwa v64, v48 dst_sel:DWORD dst_unused:UNUSED_PAD src0_sel:WORD_1
	v_cvt_f32_f16_e32 v48, v48
	v_and_b32_e32 v47, 0xffffff80, v47
	v_sub_u32_e32 v47, v47, v16
	v_not_b32_e32 v65, v64
	v_or_b32_e32 v66, 0x80000000, v64
	v_cmp_gt_i32_e32 vcc, 0, v64
	v_add_u32_e32 v63, 0x7e, v63
	v_add_u32_e32 v47, 0x7f, v47
	v_cndmask_b32_e32 v64, v66, v65, vcc
	v_not_b32_e32 v65, v48
	v_or_b32_e32 v66, 0x80000000, v48
	v_cmp_gt_i32_e32 vcc, 0, v48
	v_and_b32_e32 v64, 0xffffff80, v64
	v_sub_u32_e32 v64, v64, v17
	v_cndmask_b32_e32 v48, v66, v65, vcc
	v_cvt_f32_f16_sdwa v65, v49 dst_sel:DWORD dst_unused:UNUSED_PAD src0_sel:WORD_1
	v_cvt_f32_f16_e32 v49, v49
	v_and_b32_e32 v48, 0xffffff80, v48
	v_sub_u32_e32 v48, v48, v17
	v_not_b32_e32 v66, v65
	v_or_b32_e32 v67, 0x80000000, v65
	v_cmp_gt_i32_e32 vcc, 0, v65
	v_add_u32_e32 v64, 0x7e, v64
	v_add_u32_e32 v48, 0x7f, v48
	v_cndmask_b32_e32 v65, v67, v66, vcc
	v_not_b32_e32 v66, v49
	v_or_b32_e32 v67, 0x80000000, v49
	v_cmp_gt_i32_e32 vcc, 0, v49
	v_and_b32_e32 v65, 0xffffff80, v65
	v_sub_u32_e32 v65, v65, v18
	v_cndmask_b32_e32 v49, v67, v66, vcc
	s_waitcnt vmcnt(0)
; __device__ __forceinline__ unsigned f2key(float f) { const unsigned u = __float_as_uint(f); return (u & 0x80000000u) ? ~u : (u | 0x80000000u); }
; #define CE_DESC(a, b) do { const unsigned _mx = (a) > (b) ? (a) : (b), _mn = (a) > (b) ? (b) : (a); (a) = _mx; (b) = _mn; } while (0)
; __device__ __forceinline__ void sort16_desc(unsigned (&k)[16]) {
; #pragma unroll
;     for (int size = 2; size <= 16; size <<= 1)
; #pragma unroll
;         for (int stride = size >> 1; stride > 0; stride >>= 1)
; #pragma unroll
;             for (int i = 0; i < 16; ++i) { const int j = i ^ stride;
;                 if (j > i) { if ((i & size) == 0) CE_DESC(k[i], k[j]); else CE_DESC(k[j], k[i]); } }
; }
; __device__ __forceinline__ void peer_tile(const Args& A, LAS unsigned char* lds, int tile) {
;     ...
;                 { const bf16_t* sp = QRY + m * 2048 + hp * 128 + 32 * g;
;                   const u32x4 s0 = *(const u32x4*)sp, s1 = *(const u32x4*)(sp + 8), s2 = *(const u32x4*)(sp + 16), s3 = *(const u32x4*)(sp + 24);
;                   const unsigned sw[16] = {s0.x, s0.y, s0.z, s0.w, s1.x, s1.y, s1.z, s1.w, s2.x, s2.y, s2.z, s2.w, s3.x, s3.y, s3.z, s3.w};
; #pragma unroll
;                   for (int i = 0; i < 16; ++i) {
;                       const float lo = (float)__builtin_bit_cast(_Float16, (unsigned short)(sw[i] & 0xffffu)), hi = (float)__builtin_bit_cast(_Float16, (unsigned short)(sw[i] >> 16));
;                       const unsigned klo = (f2key(lo) & ~127u) | (unsigned)(127 - (32 * g + 2 * i)), khi = (f2key(hi) & ~127u) | (unsigned)(127 - (32 * g + 2 * i + 1));
;                       if (i < 8) { k0[2 * i] = klo; k0[2 * i + 1] = khi; } else { k1[2 * (i - 8)] = klo; k1[2 * (i - 8) + 1] = khi; } } }
;                 sort16_desc(k0); sort16_desc(k1); merge16(k0, k1);
	v_cvt_f32_f16_sdwa v66, v54 dst_sel:DWORD dst_unused:UNUSED_PAD src0_sel:WORD_1
	v_cvt_f32_f16_e32 v54, v54
	v_and_b32_e32 v49, 0xffffff80, v49
	v_sub_u32_e32 v49, v49, v18
	v_not_b32_e32 v67, v66
	v_or_b32_e32 v68, 0x80000000, v66
	v_cmp_gt_i32_e32 vcc, 0, v66
	v_add_u32_e32 v65, 0x7e, v65
	v_add_u32_e32 v49, 0x7f, v49
	v_cndmask_b32_e32 v66, v68, v67, vcc
	v_not_b32_e32 v67, v54
	v_or_b32_e32 v68, 0x80000000, v54
	v_cmp_gt_i32_e32 vcc, 0, v54
	v_and_b32_e32 v66, 0xffffff80, v66
	v_sub_u32_e32 v66, v66, v20
	v_cndmask_b32_e32 v54, v68, v67, vcc
	v_cvt_f32_f16_sdwa v67, v55 dst_sel:DWORD dst_unused:UNUSED_PAD src0_sel:WORD_1
	v_cvt_f32_f16_e32 v55, v55
	v_and_b32_e32 v54, 0xffffff80, v54
	v_sub_u32_e32 v54, v54, v20
	v_not_b32_e32 v68, v67
	v_or_b32_e32 v69, 0x80000000, v67
	v_cmp_gt_i32_e32 vcc, 0, v67
	v_add_u32_e32 v66, 0x7e, v66
	v_add_u32_e32 v54, 0x7f, v54
	v_cndmask_b32_e32 v67, v69, v68, vcc
	v_not_b32_e32 v68, v55
	v_or_b32_e32 v69, 0x80000000, v55
	v_cmp_gt_i32_e32 vcc, 0, v55
	v_and_b32_e32 v67, 0xffffff80, v67
	v_sub_u32_e32 v67, v67, v21
	v_cndmask_b32_e32 v55, v69, v68, vcc
	v_cvt_f32_f16_sdwa v68, v56 dst_sel:DWORD dst_unused:UNUSED_PAD src0_sel:WORD_1
	v_cvt_f32_f16_e32 v56, v56
	v_and_b32_e32 v55, 0xffffff80, v55
	v_sub_u32_e32 v55, v55, v21
	v_not_b32_e32 v69, v68
	v_or_b32_e32 v70, 0x80000000, v68
	v_cmp_gt_i32_e32 vcc, 0, v68
	v_add_u32_e32 v67, 0x7e, v67
	v_add_u32_e32 v55, 0x7f, v55
	v_cndmask_b32_e32 v68, v70, v69, vcc
	v_not_b32_e32 v69, v56
	v_or_b32_e32 v70, 0x80000000, v56
	v_cmp_gt_i32_e32 vcc, 0, v56
	v_and_b32_e32 v68, 0xffffff80, v68
	v_sub_u32_e32 v68, v68, v22
	v_cndmask_b32_e32 v56, v70, v69, vcc
	v_cvt_f32_f16_sdwa v69, v57 dst_sel:DWORD dst_unused:UNUSED_PAD src0_sel:WORD_1
	v_cvt_f32_f16_e32 v57, v57
	v_and_b32_e32 v56, 0xffffff80, v56
	v_sub_u32_e32 v56, v56, v22
	v_not_b32_e32 v70, v69
	v_or_b32_e32 v71, 0x80000000, v69
	v_cmp_gt_i32_e32 vcc, 0, v69
	v_add_u32_e32 v68, 0x7e, v68
	v_add_u32_e32 v56, 0x7f, v56
	v_cndmask_b32_e32 v69, v71, v70, vcc
	v_not_b32_e32 v70, v57
	v_or_b32_e32 v71, 0x80000000, v57
	v_cmp_gt_i32_e32 vcc, 0, v57
	v_and_b32_e32 v69, 0xffffff80, v69
	v_sub_u32_e32 v69, v69, v23
	v_cndmask_b32_e32 v57, v71, v70, vcc
	v_cvt_f32_f16_sdwa v70, v0 dst_sel:DWORD dst_unused:UNUSED_PAD src0_sel:WORD_1
	v_cvt_f32_f16_e32 v0, v0
	v_and_b32_e32 v57, 0xffffff80, v57
	v_sub_u32_e32 v57, v57, v23
	v_not_b32_e32 v71, v70
	v_or_b32_e32 v72, 0x80000000, v70
	v_cmp_gt_i32_e32 vcc, 0, v70
	v_add_u32_e32 v69, 0x7e, v69
	v_add_u32_e32 v57, 0x7f, v57
	v_cndmask_b32_e32 v70, v72, v71, vcc
	v_not_b32_e32 v71, v0
	v_or_b32_e32 v72, 0x80000000, v0
	v_cmp_gt_i32_e32 vcc, 0, v0
	v_and_b32_e32 v70, 0xffffff80, v70
	v_sub_u32_e32 v70, v70, v24
	v_cndmask_b32_e32 v0, v72, v71, vcc
	v_cvt_f32_f16_sdwa v71, v1 dst_sel:DWORD dst_unused:UNUSED_PAD src0_sel:WORD_1
	v_cvt_f32_f16_e32 v1, v1
	v_and_b32_e32 v0, 0xffffff80, v0
	v_sub_u32_e32 v0, v0, v24
	v_not_b32_e32 v72, v71
	v_or_b32_e32 v73, 0x80000000, v71
	v_cmp_gt_i32_e32 vcc, 0, v71
	v_add_u32_e32 v70, 0x7e, v70
	v_add_u32_e32 v0, 0x7f, v0
	v_cndmask_b32_e32 v71, v73, v72, vcc
	v_not_b32_e32 v72, v1
	v_or_b32_e32 v73, 0x80000000, v1
	v_cmp_gt_i32_e32 vcc, 0, v1
	v_and_b32_e32 v71, 0xffffff80, v71
	v_sub_u32_e32 v71, v71, v25
	v_cndmask_b32_e32 v1, v73, v72, vcc
	v_cvt_f32_f16_sdwa v72, v2 dst_sel:DWORD dst_unused:UNUSED_PAD src0_sel:WORD_1
	v_cvt_f32_f16_e32 v2, v2
	v_and_b32_e32 v1, 0xffffff80, v1
	v_sub_u32_e32 v1, v1, v25
	v_not_b32_e32 v73, v72
	v_or_b32_e32 v74, 0x80000000, v72
	v_cmp_gt_i32_e32 vcc, 0, v72
	v_add_u32_e32 v71, 0x7e, v71
	v_add_u32_e32 v1, 0x7f, v1
	v_cndmask_b32_e32 v72, v74, v73, vcc
	v_not_b32_e32 v73, v2
	v_or_b32_e32 v74, 0x80000000, v2
	v_cmp_gt_i32_e32 vcc, 0, v2
	v_and_b32_e32 v72, 0xffffff80, v72
	v_sub_u32_e32 v72, v72, v26
	v_cndmask_b32_e32 v2, v74, v73, vcc
	v_cvt_f32_f16_sdwa v73, v3 dst_sel:DWORD dst_unused:UNUSED_PAD src0_sel:WORD_1
	v_cvt_f32_f16_e32 v3, v3
	v_and_b32_e32 v2, 0xffffff80, v2
	v_sub_u32_e32 v2, v2, v26
	v_not_b32_e32 v74, v73
	v_or_b32_e32 v75, 0x80000000, v73
	v_cmp_gt_i32_e32 vcc, 0, v73
	v_add_u32_e32 v72, 0x7e, v72
	v_add_u32_e32 v2, 0x7f, v2
	v_cndmask_b32_e32 v73, v75, v74, vcc
	v_not_b32_e32 v74, v3
	v_or_b32_e32 v75, 0x80000000, v3
	v_cmp_gt_i32_e32 vcc, 0, v3
	v_and_b32_e32 v73, 0xffffff80, v73
	v_sub_u32_e32 v73, v73, v28
	v_cndmask_b32_e32 v3, v75, v74, vcc
	v_and_b32_e32 v3, 0xffffff80, v3
	v_sub_u32_e32 v3, v3, v28
	v_add_u32_e32 v73, 0x7e, v73
	v_add_u32_e32 v3, 0x7f, v3
	v_max_u32_e32 v74, v50, v58
	v_min_u32_e32 v50, v50, v58
	v_max_u32_e32 v58, v59, v51
	v_min_u32_e32 v51, v59, v51
	v_max_u32_e32 v59, v52, v60
	v_min_u32_e32 v52, v52, v60
	v_max_u32_e32 v60, v61, v53
	v_min_u32_e32 v53, v61, v53
	v_max_u32_e32 v61, v46, v62
	v_min_u32_e32 v46, v46, v62
	v_max_u32_e32 v62, v63, v47
	v_min_u32_e32 v47, v63, v47
	v_max_u32_e32 v63, v48, v64
	v_min_u32_e32 v48, v48, v64
	v_max_u32_e32 v64, v65, v49
	v_min_u32_e32 v49, v65, v49
	v_max_u32_e32 v82, v54, v66
	v_min_u32_e32 v54, v54, v66
	v_max_u32_e32 v66, v67, v55
	v_min_u32_e32 v55, v67, v55
	v_max_u32_e32 v67, v56, v68
	v_min_u32_e32 v56, v56, v68
	v_max_u32_e32 v68, v69, v57
	v_min_u32_e32 v57, v69, v57
	v_max_u32_e32 v69, v0, v70
	v_min_u32_e32 v0, v0, v70
	v_max_u32_e32 v70, v71, v1
	v_min_u32_e32 v1, v71, v1
	v_max_u32_e32 v71, v2, v72
	v_min_u32_e32 v2, v2, v72
	v_max_u32_e32 v72, v73, v3
	v_min_u32_e32 v3, v73, v3
	v_max_u32_e32 v65, v74, v51
	v_min_u32_e32 v51, v74, v51
	v_max_u32_e32 v74, v50, v58
	v_min_u32_e32 v50, v50, v58
	v_max_u32_e32 v58, v53, v59
	v_min_u32_e32 v53, v53, v59
	v_max_u32_e32 v59, v60, v52
	v_min_u32_e32 v52, v60, v52
; #define CE_DESC(a, b) do { const unsigned _mx = (a) > (b) ? (a) : (b), _mn = (a) > (b) ? (b) : (a); (a) = _mx; (b) = _mn; } while (0)
; __device__ __forceinline__ void sort16_desc(unsigned (&k)[16]) {
; #pragma unroll
;     for (int size = 2; size <= 16; size <<= 1)
; #pragma unroll
;         for (int stride = size >> 1; stride > 0; stride >>= 1)
; #pragma unroll
;             for (int i = 0; i < 16; ++i) { const int j = i ^ stride;
;                 if (j > i) { if ((i & size) == 0) CE_DESC(k[i], k[j]); else CE_DESC(k[j], k[i]); } }
; }
	v_max_u32_e32 v60, v61, v47
	v_min_u32_e32 v47, v61, v47
	v_max_u32_e32 v61, v46, v62
	v_min_u32_e32 v46, v46, v62
	v_max_u32_e32 v62, v49, v63
	v_min_u32_e32 v49, v49, v63
	v_max_u32_e32 v63, v64, v48
	v_min_u32_e32 v48, v64, v48
	v_max_u32_e32 v73, v82, v55
	v_min_u32_e32 v55, v82, v55
	v_max_u32_e32 v82, v54, v66
	v_min_u32_e32 v54, v54, v66
	v_max_u32_e32 v66, v57, v67
	v_min_u32_e32 v57, v57, v67
	v_max_u32_e32 v67, v68, v56
	v_min_u32_e32 v56, v68, v56
	v_max_u32_e32 v68, v69, v1
	v_min_u32_e32 v1, v69, v1
	v_max_u32_e32 v69, v0, v70
	v_min_u32_e32 v0, v0, v70
	v_max_u32_e32 v70, v3, v71
	v_min_u32_e32 v3, v3, v71
	v_max_u32_e32 v71, v72, v2
	v_min_u32_e32 v2, v72, v2
	v_max_u32_e32 v64, v65, v74
	v_min_u32_e32 v65, v65, v74
	v_max_u32_e32 v74, v51, v50
	v_min_u32_e32 v50, v51, v50
	v_max_u32_e32 v51, v52, v53
	v_min_u32_e32 v52, v52, v53
	v_max_u32_e32 v53, v59, v58
	v_min_u32_e32 v58, v59, v58
	v_max_u32_e32 v59, v60, v61
	v_min_u32_e32 v60, v60, v61
	v_max_u32_e32 v61, v47, v46
	v_min_u32_e32 v46, v47, v46
	v_max_u32_e32 v47, v48, v49
	v_min_u32_e32 v48, v48, v49
	v_max_u32_e32 v49, v63, v62
	v_min_u32_e32 v62, v63, v62
	v_max_u32_e32 v72, v73, v82
	v_min_u32_e32 v73, v73, v82
	v_max_u32_e32 v82, v55, v54
	v_min_u32_e32 v54, v55, v54
	v_max_u32_e32 v55, v56, v57
	v_min_u32_e32 v56, v56, v57
	v_max_u32_e32 v57, v67, v66
	v_min_u32_e32 v66, v67, v66
	v_max_u32_e32 v67, v68, v69
	v_min_u32_e32 v68, v68, v69
	v_max_u32_e32 v69, v1, v0
	v_min_u32_e32 v0, v1, v0
	v_max_u32_e32 v1, v2, v3
	v_min_u32_e32 v2, v2, v3
	v_max_u32_e32 v3, v71, v70
	v_min_u32_e32 v70, v71, v70
	v_max_u32_e32 v63, v64, v52
	v_min_u32_e32 v52, v64, v52
	v_max_u32_e32 v64, v65, v51
	v_min_u32_e32 v51, v65, v51
	v_max_u32_e32 v65, v74, v58
	v_min_u32_e32 v58, v74, v58
	v_max_u32_e32 v74, v50, v53
	v_min_u32_e32 v50, v50, v53
	v_max_u32_e32 v53, v48, v59
	v_min_u32_e32 v48, v48, v59
	v_max_u32_e32 v59, v47, v60
	v_min_u32_e32 v47, v47, v60
	v_max_u32_e32 v60, v62, v61
	v_min_u32_e32 v61, v62, v61
	v_max_u32_e32 v62, v49, v46
	v_min_u32_e32 v46, v49, v46
	v_max_u32_e32 v71, v72, v56
	v_min_u32_e32 v56, v72, v56
	v_max_u32_e32 v72, v73, v55
	v_min_u32_e32 v55, v73, v55
	v_max_u32_e32 v73, v82, v66
	v_min_u32_e32 v66, v82, v66
	v_max_u32_e32 v82, v54, v57
	v_min_u32_e32 v54, v54, v57
	v_max_u32_e32 v57, v2, v67
	v_min_u32_e32 v2, v2, v67
	v_max_u32_e32 v67, v1, v68
	v_min_u32_e32 v1, v1, v68
	v_max_u32_e32 v68, v70, v69
	v_min_u32_e32 v69, v70, v69
	v_max_u32_e32 v70, v3, v0
	v_min_u32_e32 v0, v3, v0
	v_max_u32_e32 v49, v63, v65
	v_min_u32_e32 v63, v63, v65
	v_max_u32_e32 v65, v64, v74
	v_min_u32_e32 v64, v64, v74
	v_max_u32_e32 v74, v52, v58
	v_min_u32_e32 v52, v52, v58
	v_max_u32_e32 v58, v51, v50
	v_min_u32_e32 v50, v51, v50
	v_max_u32_e32 v51, v61, v48
	v_min_u32_e32 v48, v61, v48
	v_max_u32_e32 v61, v46, v47
	v_min_u32_e32 v46, v46, v47
	v_max_u32_e32 v47, v60, v53
	v_min_u32_e32 v53, v60, v53
	v_max_u32_e32 v60, v62, v59
	v_min_u32_e32 v59, v62, v59
	v_max_u32_e32 v3, v71, v73
	v_min_u32_e32 v71, v71, v73
	v_max_u32_e32 v73, v72, v82
	v_min_u32_e32 v72, v72, v82
	v_max_u32_e32 v82, v56, v66
	v_min_u32_e32 v56, v56, v66
	v_max_u32_e32 v66, v55, v54
	v_min_u32_e32 v54, v55, v54
	v_max_u32_e32 v55, v69, v2
	v_min_u32_e32 v2, v69, v2
	v_max_u32_e32 v69, v0, v1
	v_min_u32_e32 v0, v0, v1
	v_max_u32_e32 v1, v68, v57
	v_min_u32_e32 v57, v68, v57
	v_max_u32_e32 v68, v70, v67
	v_min_u32_e32 v67, v70, v67
	v_max_u32_e32 v62, v49, v65
	v_min_u32_e32 v49, v49, v65
	v_max_u32_e32 v65, v63, v64
	v_min_u32_e32 v63, v63, v64
	v_max_u32_e32 v64, v74, v58
	v_min_u32_e32 v58, v74, v58
	v_max_u32_e32 v74, v52, v50
	v_min_u32_e32 v50, v52, v50
	v_max_u32_e32 v52, v46, v48
	v_min_u32_e32 v46, v46, v48
	v_max_u32_e32 v48, v61, v51
	v_min_u32_e32 v51, v61, v51
	v_max_u32_e32 v61, v59, v53
	v_min_u32_e32 v53, v59, v53
	v_max_u32_e32 v59, v60, v47
	v_min_u32_e32 v47, v60, v47
	v_max_u32_e32 v70, v3, v73
	v_min_u32_e32 v3, v3, v73
	v_max_u32_e32 v73, v71, v72
	v_min_u32_e32 v71, v71, v72
	v_max_u32_e32 v72, v82, v66
	v_min_u32_e32 v66, v82, v66
	v_max_u32_e32 v82, v56, v54
	v_min_u32_e32 v54, v56, v54
	v_max_u32_e32 v56, v0, v2
	v_min_u32_e32 v0, v0, v2
	v_max_u32_e32 v2, v69, v55
	v_min_u32_e32 v55, v69, v55
	v_max_u32_e32 v69, v67, v57
	v_min_u32_e32 v57, v67, v57
	v_max_u32_e32 v67, v68, v1
	v_min_u32_e32 v1, v68, v1
	v_max_u32_e32 v60, v62, v46
	v_min_u32_e32 v46, v62, v46
	v_max_u32_e32 v62, v49, v52
	v_min_u32_e32 v49, v49, v52
	v_max_u32_e32 v52, v65, v51
	v_min_u32_e32 v51, v65, v51
	v_max_u32_e32 v65, v63, v48
	v_min_u32_e32 v48, v63, v48
	v_max_u32_e32 v63, v64, v53
	v_min_u32_e32 v53, v64, v53
	v_max_u32_e32 v64, v58, v61
	v_min_u32_e32 v58, v58, v61
	v_max_u32_e32 v61, v74, v47
	v_min_u32_e32 v47, v74, v47
	v_max_u32_e32 v74, v50, v59
	v_min_u32_e32 v50, v50, v59
	v_max_u32_e32 v68, v70, v0
	v_min_u32_e32 v0, v70, v0
	v_max_u32_e32 v70, v3, v56
	v_min_u32_e32 v3, v3, v56
	v_max_u32_e32 v56, v73, v55
	v_min_u32_e32 v55, v73, v55
	v_max_u32_e32 v73, v71, v2
	v_min_u32_e32 v2, v71, v2
	v_max_u32_e32 v71, v72, v57
	v_min_u32_e32 v57, v72, v57
	v_max_u32_e32 v72, v66, v69
	v_min_u32_e32 v66, v66, v69
	v_max_u32_e32 v69, v82, v1
	v_min_u32_e32 v1, v82, v1
	v_max_u32_e32 v82, v54, v67
	v_min_u32_e32 v54, v54, v67
	v_max_u32_e32 v59, v60, v63
	v_min_u32_e32 v60, v60, v63
	v_max_u32_e32 v63, v62, v64
	v_min_u32_e32 v62, v62, v64
	v_max_u32_e32 v64, v52, v61
	v_min_u32_e32 v52, v52, v61
	v_max_u32_e32 v61, v65, v74
	v_min_u32_e32 v65, v65, v74
	v_max_u32_e32 v74, v46, v53
	v_min_u32_e32 v46, v46, v53
	v_max_u32_e32 v53, v49, v58
	v_min_u32_e32 v49, v49, v58
	v_max_u32_e32 v58, v51, v47
; #define CE_DESC(a, b) do { const unsigned _mx = (a) > (b) ? (a) : (b), _mn = (a) > (b) ? (b) : (a); (a) = _mx; (b) = _mn; } while (0)
; __device__ __forceinline__ void sort16_desc(unsigned (&k)[16]) {
; #pragma unroll
;     for (int size = 2; size <= 16; size <<= 1)
; #pragma unroll
;         for (int stride = size >> 1; stride > 0; stride >>= 1)
; #pragma unroll
;             for (int i = 0; i < 16; ++i) { const int j = i ^ stride;
;                 if (j > i) { if ((i & size) == 0) CE_DESC(k[i], k[j]); else CE_DESC(k[j], k[i]); } }
; }
; __device__ __forceinline__ void merge16(unsigned (&a)[16], const unsigned (&b)[16]) {
; #pragma unroll
;     for (int i = 0; i < 16; ++i) a[i] = a[i] > b[15 - i] ? a[i] : b[15 - i];
; #pragma unroll
;     for (int stride = 8; stride > 0; stride >>= 1)
; #pragma unroll
;         for (int i = 0; i < 16; ++i) { const int j = i ^ stride; if (j > i) CE_DESC(a[i], a[j]); }
; }
; __device__ __forceinline__ void peer_tile(const Args& A, LAS unsigned char* lds, int tile) {
;     ...
;                 for (int msk = 16; msk <= 32; msk <<= 1) {
; #pragma unroll
;                     for (int i = 0; i < 16; ++i) k1[i] = (unsigned)__shfl_xor((int)k0[i], msk);
;                     merge16(k0, k1); }
	v_min_u32_e32 v47, v51, v47
	v_max_u32_e32 v51, v48, v50
	v_min_u32_e32 v48, v48, v50
	v_max_u32_e32 v67, v68, v71
	v_min_u32_e32 v68, v68, v71
	v_max_u32_e32 v71, v70, v72
	v_min_u32_e32 v70, v70, v72
	v_max_u32_e32 v72, v56, v69
	v_min_u32_e32 v56, v56, v69
	v_max_u32_e32 v69, v73, v82
	v_min_u32_e32 v73, v73, v82
	v_max_u32_e32 v82, v0, v57
	v_min_u32_e32 v0, v0, v57
	v_max_u32_e32 v57, v3, v66
	v_min_u32_e32 v3, v3, v66
	v_max_u32_e32 v66, v55, v1
	v_min_u32_e32 v1, v55, v1
	v_max_u32_e32 v55, v2, v54
	v_min_u32_e32 v2, v2, v54
	v_max_u32_e32 v50, v59, v64
	v_min_u32_e32 v59, v59, v64
	v_max_u32_e32 v64, v63, v61
	v_min_u32_e32 v61, v63, v61
	v_max_u32_e32 v63, v60, v52
	v_min_u32_e32 v52, v60, v52
	v_max_u32_e32 v60, v62, v65
	v_min_u32_e32 v62, v62, v65
	v_max_u32_e32 v65, v74, v58
	v_min_u32_e32 v58, v74, v58
	v_max_u32_e32 v74, v53, v51
	v_min_u32_e32 v51, v53, v51
	v_max_u32_e32 v53, v46, v47
	v_min_u32_e32 v46, v46, v47
	v_max_u32_e32 v47, v49, v48
	v_min_u32_e32 v48, v49, v48
	v_max_u32_e32 v54, v67, v72
	v_min_u32_e32 v67, v67, v72
	v_max_u32_e32 v72, v71, v69
	v_min_u32_e32 v69, v71, v69
	v_max_u32_e32 v71, v68, v56
	v_min_u32_e32 v56, v68, v56
	v_max_u32_e32 v68, v70, v73
	v_min_u32_e32 v70, v70, v73
	v_max_u32_e32 v73, v82, v66
	v_min_u32_e32 v66, v82, v66
	v_max_u32_e32 v82, v57, v55
	v_min_u32_e32 v55, v57, v55
	v_max_u32_e32 v57, v0, v1
	v_min_u32_e32 v0, v0, v1
	v_max_u32_e32 v1, v3, v2
	v_min_u32_e32 v2, v3, v2
	v_min_u32_e32 v49, v50, v64
	v_min_u32_e32 v75, v59, v61
	v_min_u32_e32 v76, v63, v60
	v_min_u32_e32 v77, v52, v62
	v_min_u32_e32 v78, v65, v74
	v_min_u32_e32 v79, v58, v51
	v_min_u32_e32 v80, v53, v47
	v_min_u32_e32 v81, v46, v48
	v_min_u32_e32 v3, v54, v72
	v_min_u32_e32 v83, v67, v69
	v_min_u32_e32 v84, v71, v68
	v_min_u32_e32 v85, v56, v70
	v_min_u32_e32 v86, v73, v82
	v_min_u32_e32 v87, v66, v55
	v_min_u32_e32 v88, v57, v1
	v_min_u32_e32 v89, v0, v2
	v_max3_u32 v50, v50, v64, v89
	v_max3_u32 v0, v49, v0, v2
	v_max3_u32 v2, v59, v61, v88
	v_max3_u32 v1, v75, v57, v1
	v_max3_u32 v49, v63, v60, v87
	v_max3_u32 v55, v76, v66, v55
	v_max3_u32 v52, v52, v62, v86
	v_max3_u32 v57, v77, v73, v82
	v_max3_u32 v59, v65, v74, v85
	v_max3_u32 v56, v78, v56, v70
	v_max3_u32 v51, v58, v51, v84
	v_max3_u32 v58, v79, v71, v68
	v_max3_u32 v47, v53, v47, v83
	v_max3_u32 v53, v80, v67, v69
	v_max3_u32 v3, v46, v48, v3
	v_max3_u32 v46, v81, v54, v72
	v_max_u32_e32 v48, v50, v59
	v_min_u32_e32 v50, v50, v59
	v_max_u32_e32 v54, v0, v56
	v_min_u32_e32 v0, v0, v56
	v_max_u32_e32 v56, v2, v51
	v_min_u32_e32 v2, v2, v51
	v_max_u32_e32 v51, v1, v58
	v_min_u32_e32 v1, v1, v58
	v_max_u32_e32 v58, v49, v47
	v_min_u32_e32 v47, v49, v47
	v_max_u32_e32 v49, v55, v53
	v_min_u32_e32 v53, v55, v53
	v_max_u32_e32 v55, v52, v3
	v_min_u32_e32 v3, v52, v3
	v_max_u32_e32 v52, v57, v46
	v_min_u32_e32 v46, v57, v46
	v_max_u32_e32 v57, v48, v58
	v_min_u32_e32 v48, v48, v58
	v_max_u32_e32 v58, v54, v49
	v_min_u32_e32 v49, v54, v49
	v_max_u32_e32 v54, v56, v55
	v_min_u32_e32 v55, v56, v55
	v_max_u32_e32 v56, v51, v52
	v_min_u32_e32 v51, v51, v52
	v_max_u32_e32 v52, v50, v47
	v_min_u32_e32 v47, v50, v47
	v_max_u32_e32 v50, v0, v53
	v_min_u32_e32 v0, v0, v53
	v_max_u32_e32 v53, v2, v3
	v_min_u32_e32 v2, v2, v3
	v_max_u32_e32 v3, v1, v46
	v_min_u32_e32 v1, v1, v46
	v_max_u32_e32 v46, v57, v54
	v_min_u32_e32 v54, v57, v54
	v_max_u32_e32 v57, v58, v56
	v_min_u32_e32 v56, v58, v56
	v_max_u32_e32 v58, v48, v55
	v_min_u32_e32 v48, v48, v55
	v_max_u32_e32 v55, v49, v51
	v_min_u32_e32 v49, v49, v51
	v_max_u32_e32 v51, v52, v53
	v_min_u32_e32 v52, v52, v53
	v_max_u32_e32 v53, v50, v3
	v_min_u32_e32 v3, v50, v3
	v_max_u32_e32 v50, v47, v2
	v_min_u32_e32 v2, v47, v2
	v_max_u32_e32 v47, v0, v1
	v_min_u32_e32 v0, v0, v1
	v_max_u32_e32 v1, v46, v57
	v_min_u32_e32 v46, v46, v57
	v_max_u32_e32 v57, v54, v56
	v_min_u32_e32 v54, v54, v56
	v_max_u32_e32 v56, v58, v55
	v_min_u32_e32 v55, v58, v55
	v_max_u32_e32 v58, v48, v49
	v_min_u32_e32 v48, v48, v49
	v_max_u32_e32 v49, v51, v53
	v_min_u32_e32 v51, v51, v53
	v_max_u32_e32 v53, v52, v3
	v_min_u32_e32 v3, v52, v3
	v_max_u32_e32 v52, v50, v47
	v_min_u32_e32 v47, v50, v47
	v_max_u32_e32 v50, v2, v0
	v_min_u32_e32 v0, v2, v0
	ds_bpermute_b32 v2, v27, v1
	ds_bpermute_b32 v59, v27, v46
	ds_bpermute_b32 v60, v27, v57
	ds_bpermute_b32 v61, v27, v54
	ds_bpermute_b32 v62, v27, v56
	ds_bpermute_b32 v63, v27, v55
	ds_bpermute_b32 v64, v27, v58
	ds_bpermute_b32 v65, v27, v48
	ds_bpermute_b32 v66, v27, v49
	ds_bpermute_b32 v67, v27, v51
	ds_bpermute_b32 v68, v27, v53
	ds_bpermute_b32 v69, v27, v0
	ds_bpermute_b32 v70, v27, v50
	ds_bpermute_b32 v71, v27, v47
	ds_bpermute_b32 v72, v27, v52
	ds_bpermute_b32 v73, v27, v3
	s_waitcnt lgkmcnt(4)
	v_max_u32_e32 v1, v1, v69
	s_waitcnt lgkmcnt(3)
	v_max_u32_e32 v46, v46, v70
	s_waitcnt lgkmcnt(2)
	v_max_u32_e32 v57, v57, v71
	s_waitcnt lgkmcnt(1)
	v_max_u32_e32 v54, v54, v72
	s_waitcnt lgkmcnt(0)
; #define CE_DESC(a, b) do { const unsigned _mx = (a) > (b) ? (a) : (b), _mn = (a) > (b) ? (b) : (a); (a) = _mx; (b) = _mn; } while (0)
; __device__ __forceinline__ void merge16(unsigned (&a)[16], const unsigned (&b)[16]) {
; #pragma unroll
;     for (int i = 0; i < 16; ++i) a[i] = a[i] > b[15 - i] ? a[i] : b[15 - i];
; #pragma unroll
;     for (int stride = 8; stride > 0; stride >>= 1)
; #pragma unroll
;         for (int i = 0; i < 16; ++i) { const int j = i ^ stride; if (j > i) CE_DESC(a[i], a[j]); }
; }
; __device__ __forceinline__ void peer_tile(const Args& A, LAS unsigned char* lds, int tile) {
;     ...
;                 { const bf16_t* sp = QRY + m * 2048 + hp * 128 + 32 * g;
;                   const u32x4 s0 = *(const u32x4*)sp, s1 = *(const u32x4*)(sp + 8), s2 = *(const u32x4*)(sp + 16), s3 = *(const u32x4*)(sp + 24);
;     ...
;                 for (int msk = 16; msk <= 32; msk <<= 1) {
; #pragma unroll
;                     for (int i = 0; i < 16; ++i) k1[i] = (unsigned)__shfl_xor((int)k0[i], msk);
;                     merge16(k0, k1); }
	v_max_u32_e32 v56, v56, v73
	v_max_u32_e32 v55, v55, v68
	v_max_u32_e32 v58, v58, v67
	v_max_u32_e32 v48, v48, v66
	v_max_u32_e32 v49, v49, v65
	v_max_u32_e32 v51, v51, v64
	v_max_u32_e32 v53, v53, v63
	v_max_u32_e32 v3, v3, v62
	v_max_u32_e32 v52, v52, v61
	v_max_u32_e32 v47, v47, v60
	v_max_u32_e32 v50, v50, v59
	v_max_u32_e32 v0, v0, v2
	v_max_u32_e32 v2, v1, v49
	v_min_u32_e32 v1, v1, v49
	v_max_u32_e32 v49, v46, v51
	v_min_u32_e32 v46, v46, v51
	v_max_u32_e32 v51, v57, v53
	v_min_u32_e32 v53, v57, v53
	v_max_u32_e32 v57, v54, v3
	v_min_u32_e32 v3, v54, v3
	v_max_u32_e32 v54, v56, v52
	v_min_u32_e32 v52, v56, v52
	v_max_u32_e32 v56, v55, v47
	v_min_u32_e32 v47, v55, v47
	v_max_u32_e32 v55, v58, v50
	v_min_u32_e32 v50, v58, v50
	v_max_u32_e32 v58, v48, v0
	v_min_u32_e32 v0, v48, v0
	v_max_u32_e32 v48, v2, v54
	v_min_u32_e32 v2, v2, v54
	v_max_u32_e32 v54, v49, v56
	v_min_u32_e32 v49, v49, v56
	v_max_u32_e32 v56, v51, v55
	v_min_u32_e32 v51, v51, v55
	v_max_u32_e32 v55, v57, v58
	v_min_u32_e32 v57, v57, v58
	v_max_u32_e32 v58, v1, v52
	v_min_u32_e32 v1, v1, v52
	v_max_u32_e32 v52, v46, v47
	v_min_u32_e32 v46, v46, v47
	v_max_u32_e32 v47, v53, v50
	v_min_u32_e32 v50, v53, v50
	v_max_u32_e32 v53, v3, v0
	v_min_u32_e32 v0, v3, v0
	v_max_u32_e32 v3, v48, v56
	v_min_u32_e32 v48, v48, v56
	v_max_u32_e32 v56, v54, v55
	v_min_u32_e32 v54, v54, v55
	v_max_u32_e32 v55, v2, v51
	v_min_u32_e32 v2, v2, v51
	v_max_u32_e32 v51, v49, v57
	v_min_u32_e32 v49, v49, v57
	v_max_u32_e32 v57, v58, v47
	v_min_u32_e32 v47, v58, v47
	v_max_u32_e32 v58, v52, v53
	v_min_u32_e32 v52, v52, v53
	v_max_u32_e32 v53, v1, v50
	v_min_u32_e32 v1, v1, v50
	v_max_u32_e32 v50, v46, v0
	v_min_u32_e32 v0, v46, v0
	v_max_u32_e32 v46, v3, v56
	v_min_u32_e32 v3, v3, v56
	v_max_u32_e32 v56, v48, v54
	v_min_u32_e32 v48, v48, v54
	v_max_u32_e32 v54, v55, v51
	v_min_u32_e32 v51, v55, v51
	v_max_u32_e32 v55, v2, v49
	v_min_u32_e32 v2, v2, v49
	v_max_u32_e32 v49, v57, v58
	v_min_u32_e32 v57, v57, v58
	v_max_u32_e32 v58, v47, v52
	v_min_u32_e32 v47, v47, v52
	v_max_u32_e32 v52, v53, v50
	v_min_u32_e32 v50, v53, v50
	v_max_u32_e32 v53, v1, v0
	v_min_u32_e32 v0, v1, v0
	ds_bpermute_b32 v62, v29, v0
	ds_bpermute_b32 v1, v29, v46
	ds_bpermute_b32 v59, v29, v3
	ds_bpermute_b32 v60, v29, v56
	ds_bpermute_b32 v61, v29, v48
	s_waitcnt lgkmcnt(4)
	v_max_u32_e32 v46, v46, v62
	global_load_dwordx4 v[62:65], v[4:5], off offset:528
	global_load_dwordx4 v[66:69], v[4:5], off offset:512
	ds_bpermute_b32 v70, v29, v54
	ds_bpermute_b32 v71, v29, v51
	ds_bpermute_b32 v72, v29, v55
	ds_bpermute_b32 v73, v29, v2
	ds_bpermute_b32 v74, v29, v49
	ds_bpermute_b32 v75, v29, v57
	ds_bpermute_b32 v76, v29, v58
	ds_bpermute_b32 v77, v29, v47
	ds_bpermute_b32 v78, v29, v52
	ds_bpermute_b32 v79, v29, v53
	ds_bpermute_b32 v80, v29, v50
	s_waitcnt lgkmcnt(4)
	v_max_u32_e32 v51, v51, v76
	s_waitcnt lgkmcnt(3)
	v_max_u32_e32 v54, v54, v77
	s_waitcnt lgkmcnt(2)
	v_max_u32_e32 v48, v48, v78
	s_waitcnt lgkmcnt(1)
	v_max_u32_e32 v3, v3, v79
	s_waitcnt lgkmcnt(0)
	v_max_u32_e32 v56, v56, v80
	v_max_u32_e32 v55, v55, v75
	v_max_u32_e32 v2, v2, v74
	v_max_u32_e32 v49, v49, v73
	v_max_u32_e32 v57, v57, v72
	v_max_u32_e32 v58, v58, v71
	v_max_u32_e32 v47, v47, v70
	v_max_u32_e32 v52, v52, v61
	v_max_u32_e32 v50, v50, v60
	v_max_u32_e32 v53, v53, v59
	v_max_u32_e32 v0, v0, v1
	v_max_u32_e32 v1, v46, v49
	v_min_u32_e32 v46, v46, v49
	v_max_u32_e32 v49, v3, v57
	v_min_u32_e32 v3, v3, v57
	v_max_u32_e32 v57, v56, v58
	v_min_u32_e32 v56, v56, v58
	v_max_u32_e32 v58, v48, v47
	v_min_u32_e32 v47, v48, v47
	v_max_u32_e32 v48, v54, v52
	v_min_u32_e32 v52, v54, v52
	v_max_u32_e32 v54, v51, v50
	v_min_u32_e32 v50, v51, v50
	v_max_u32_e32 v51, v55, v53
	v_min_u32_e32 v53, v55, v53
	v_max_u32_e32 v55, v2, v0
	v_min_u32_e32 v0, v2, v0
	v_max_u32_e32 v2, v1, v48
	v_min_u32_e32 v1, v1, v48
	v_max_u32_e32 v48, v49, v54
	v_min_u32_e32 v49, v49, v54
	v_max_u32_e32 v54, v57, v51
	v_min_u32_e32 v51, v57, v51
	v_max_u32_e32 v57, v58, v55
	v_min_u32_e32 v55, v58, v55
	v_max_u32_e32 v58, v46, v52
	v_min_u32_e32 v46, v46, v52
	v_max_u32_e32 v52, v3, v50
	v_min_u32_e32 v3, v3, v50
	v_max_u32_e32 v50, v56, v53
	v_min_u32_e32 v53, v56, v53
	v_max_u32_e32 v56, v47, v0
	v_min_u32_e32 v0, v47, v0
	v_max_u32_e32 v47, v2, v54
	v_min_u32_e32 v2, v2, v54
	v_max_u32_e32 v54, v48, v57
	v_min_u32_e32 v48, v48, v57
	v_max_u32_e32 v70, v1, v51
	v_min_u32_e32 v1, v1, v51
	v_max_u32_e32 v51, v49, v55
	v_min_u32_e32 v49, v49, v55
	v_max_u32_e32 v71, v58, v50
	v_min_u32_e32 v50, v58, v50
	v_max_u32_e32 v72, v52, v56
	v_min_u32_e32 v73, v52, v56
	v_max_u32_e32 v74, v46, v53
	v_min_u32_e32 v46, v46, v53
	v_max_u32_e32 v75, v3, v0
	v_min_u32_e32 v0, v3, v0
	v_max_u32_e32 v61, v47, v54
	v_min_u32_e32 v60, v47, v54
	v_max_u32_e32 v59, v2, v48
	v_min_u32_e32 v58, v2, v48
	v_max_u32_e32 v57, v70, v51
	v_min_u32_e32 v56, v70, v51
	v_max_u32_e32 v55, v1, v49
	v_min_u32_e32 v54, v1, v49
	v_max_u32_e32 v53, v71, v72
	v_min_u32_e32 v52, v71, v72
	v_max_u32_e32 v51, v50, v73
	v_min_u32_e32 v50, v50, v73
	v_max_u32_e32 v47, v46, v0
	v_min_u32_e32 v46, v46, v0
	global_load_dwordx4 v[0:3], v[4:5], off offset:560
	global_load_dwordx4 v[70:73], v[4:5], off offset:544
	v_max_u32_e32 v49, v74, v75
	v_min_u32_e32 v48, v74, v75
	s_waitcnt vmcnt(2)
; __device__ __forceinline__ unsigned f2key(float f) { const unsigned u = __float_as_uint(f); return (u & 0x80000000u) ? ~u : (u | 0x80000000u); }
; __device__ __forceinline__ void peer_tile(const Args& A, LAS unsigned char* lds, int tile) {
;     ...
;                 { const bf16_t* sp = QRY + m * 2048 + hp * 128 + 32 * g;
;                   const u32x4 s0 = *(const u32x4*)sp, s1 = *(const u32x4*)(sp + 8), s2 = *(const u32x4*)(sp + 16), s3 = *(const u32x4*)(sp + 24);
;                   const unsigned sw[16] = {s0.x, s0.y, s0.z, s0.w, s1.x, s1.y, s1.z, s1.w, s2.x, s2.y, s2.z, s2.w, s3.x, s3.y, s3.z, s3.w};
; #pragma unroll
;                   for (int i = 0; i < 16; ++i) {
;                       const float lo = (float)__builtin_bit_cast(_Float16, (unsigned short)(sw[i] & 0xffffu)), hi = (float)__builtin_bit_cast(_Float16, (unsigned short)(sw[i] >> 16));
;                       const unsigned klo = (f2key(lo) & ~127u) | (unsigned)(127 - (32 * g + 2 * i)), khi = (f2key(hi) & ~127u) | (unsigned)(127 - (32 * g + 2 * i + 1));
;                       if (i < 8) { k0[2 * i] = klo; k0[2 * i + 1] = khi; } else { k1[2 * (i - 8)] = klo; k1[2 * (i - 8) + 1] = khi; } } }
	v_cvt_f32_f16_sdwa v74, v66 dst_sel:DWORD dst_unused:UNUSED_PAD src0_sel:WORD_1
	v_cvt_f32_f16_e32 v66, v66
	v_not_b32_e32 v75, v74
	v_or_b32_e32 v76, 0x80000000, v74
	v_cmp_gt_i32_e32 vcc, 0, v74
	s_nop 1
	v_cndmask_b32_e32 v74, v76, v75, vcc
	v_not_b32_e32 v75, v66
	v_or_b32_e32 v76, 0x80000000, v66
	v_cmp_gt_i32_e32 vcc, 0, v66
	v_and_b32_e32 v74, 0xffffff80, v74
	v_sub_u32_e32 v74, v74, v15
	v_cndmask_b32_e32 v66, v76, v75, vcc
	v_cvt_f32_f16_sdwa v75, v67 dst_sel:DWORD dst_unused:UNUSED_PAD src0_sel:WORD_1
	v_cvt_f32_f16_e32 v67, v67
	v_and_b32_e32 v66, 0xffffff80, v66
	v_sub_u32_e32 v66, v66, v15
	v_not_b32_e32 v76, v75
	v_or_b32_e32 v77, 0x80000000, v75
	v_cmp_gt_i32_e32 vcc, 0, v75
	v_add_u32_e32 v74, 0x7e, v74
	v_add_u32_e32 v66, 0x7f, v66
	v_cndmask_b32_e32 v75, v77, v76, vcc
	v_not_b32_e32 v76, v67
	v_or_b32_e32 v77, 0x80000000, v67
	v_cmp_gt_i32_e32 vcc, 0, v67
	v_and_b32_e32 v75, 0xffffff80, v75
	v_sub_u32_e32 v75, v75, v14
	v_cndmask_b32_e32 v67, v77, v76, vcc
	v_cvt_f32_f16_sdwa v76, v68 dst_sel:DWORD dst_unused:UNUSED_PAD src0_sel:WORD_1
	v_cvt_f32_f16_e32 v68, v68
	v_and_b32_e32 v67, 0xffffff80, v67
	v_sub_u32_e32 v67, v67, v14
	v_not_b32_e32 v77, v76
	v_or_b32_e32 v78, 0x80000000, v76
	v_cmp_gt_i32_e32 vcc, 0, v76
	v_add_u32_e32 v75, 0x7e, v75
	v_add_u32_e32 v67, 0x7f, v67
	v_cndmask_b32_e32 v76, v78, v77, vcc
	v_not_b32_e32 v77, v68
	v_or_b32_e32 v78, 0x80000000, v68
	v_cmp_gt_i32_e32 vcc, 0, v68
	v_and_b32_e32 v76, 0xffffff80, v76
	v_sub_u32_e32 v76, v76, v12
	v_cndmask_b32_e32 v68, v78, v77, vcc
	v_cvt_f32_f16_sdwa v77, v69 dst_sel:DWORD dst_unused:UNUSED_PAD src0_sel:WORD_1
	v_cvt_f32_f16_e32 v69, v69
	v_and_b32_e32 v68, 0xffffff80, v68
	v_sub_u32_e32 v68, v68, v12
	v_not_b32_e32 v78, v77
	v_or_b32_e32 v79, 0x80000000, v77
	v_cmp_gt_i32_e32 vcc, 0, v77
	v_add_u32_e32 v76, 0x7e, v76
	v_add_u32_e32 v68, 0x7f, v68
	v_cndmask_b32_e32 v77, v79, v78, vcc
	v_not_b32_e32 v78, v69
	v_or_b32_e32 v79, 0x80000000, v69
	v_cmp_gt_i32_e32 vcc, 0, v69
	v_and_b32_e32 v77, 0xffffff80, v77
	v_sub_u32_e32 v77, v77, v10
	v_cndmask_b32_e32 v69, v79, v78, vcc
	v_cvt_f32_f16_sdwa v78, v62 dst_sel:DWORD dst_unused:UNUSED_PAD src0_sel:WORD_1
	v_cvt_f32_f16_e32 v62, v62
	v_and_b32_e32 v69, 0xffffff80, v69
	v_sub_u32_e32 v69, v69, v10
	v_not_b32_e32 v79, v78
	v_or_b32_e32 v80, 0x80000000, v78
	v_cmp_gt_i32_e32 vcc, 0, v78
	v_add_u32_e32 v77, 0x7e, v77
	v_add_u32_e32 v69, 0x7f, v69
	v_cndmask_b32_e32 v78, v80, v79, vcc
	v_not_b32_e32 v79, v62
	v_or_b32_e32 v80, 0x80000000, v62
	v_cmp_gt_i32_e32 vcc, 0, v62
	v_and_b32_e32 v78, 0xffffff80, v78
	v_sub_u32_e32 v78, v78, v8
	v_cndmask_b32_e32 v62, v80, v79, vcc
	v_cvt_f32_f16_sdwa v79, v63 dst_sel:DWORD dst_unused:UNUSED_PAD src0_sel:WORD_1
	v_cvt_f32_f16_e32 v63, v63
	v_and_b32_e32 v62, 0xffffff80, v62
	v_sub_u32_e32 v62, v62, v8
	v_not_b32_e32 v80, v79
	v_or_b32_e32 v81, 0x80000000, v79
	v_cmp_gt_i32_e32 vcc, 0, v79
	v_add_u32_e32 v78, 0x7e, v78
	v_add_u32_e32 v62, 0x7f, v62
	v_cndmask_b32_e32 v79, v81, v80, vcc
	v_not_b32_e32 v80, v63
	v_or_b32_e32 v81, 0x80000000, v63
	v_cmp_gt_i32_e32 vcc, 0, v63
	v_and_b32_e32 v79, 0xffffff80, v79
	v_sub_u32_e32 v79, v79, v16
	v_cndmask_b32_e32 v63, v81, v80, vcc
	v_cvt_f32_f16_sdwa v80, v64 dst_sel:DWORD dst_unused:UNUSED_PAD src0_sel:WORD_1
	v_cvt_f32_f16_e32 v64, v64
	v_and_b32_e32 v63, 0xffffff80, v63
	v_sub_u32_e32 v63, v63, v16
	v_not_b32_e32 v81, v80
	v_or_b32_e32 v82, 0x80000000, v80
	v_cmp_gt_i32_e32 vcc, 0, v80
	v_add_u32_e32 v79, 0x7e, v79
	v_add_u32_e32 v63, 0x7f, v63
	v_cndmask_b32_e32 v80, v82, v81, vcc
	v_not_b32_e32 v81, v64
	v_or_b32_e32 v82, 0x80000000, v64
	v_cmp_gt_i32_e32 vcc, 0, v64
	v_and_b32_e32 v80, 0xffffff80, v80
	v_sub_u32_e32 v80, v80, v17
	v_cndmask_b32_e32 v64, v82, v81, vcc
	v_cvt_f32_f16_sdwa v81, v65 dst_sel:DWORD dst_unused:UNUSED_PAD src0_sel:WORD_1
	v_cvt_f32_f16_e32 v65, v65
	v_and_b32_e32 v64, 0xffffff80, v64
	v_sub_u32_e32 v64, v64, v17
	v_not_b32_e32 v82, v81
	v_or_b32_e32 v83, 0x80000000, v81
	v_cmp_gt_i32_e32 vcc, 0, v81
	v_add_u32_e32 v80, 0x7e, v80
	v_add_u32_e32 v64, 0x7f, v64
	v_cndmask_b32_e32 v81, v83, v82, vcc
	v_not_b32_e32 v82, v65
	v_or_b32_e32 v83, 0x80000000, v65
	v_cmp_gt_i32_e32 vcc, 0, v65
	v_and_b32_e32 v81, 0xffffff80, v81
	v_sub_u32_e32 v81, v81, v18
	v_cndmask_b32_e32 v65, v83, v82, vcc
	s_waitcnt vmcnt(0)
; __device__ __forceinline__ unsigned f2key(float f) { const unsigned u = __float_as_uint(f); return (u & 0x80000000u) ? ~u : (u | 0x80000000u); }
; #define CE_DESC(a, b) do { const unsigned _mx = (a) > (b) ? (a) : (b), _mn = (a) > (b) ? (b) : (a); (a) = _mx; (b) = _mn; } while (0)
; __device__ __forceinline__ void sort16_desc(unsigned (&k)[16]) {
; #pragma unroll
;     for (int size = 2; size <= 16; size <<= 1)
; #pragma unroll
;         for (int stride = size >> 1; stride > 0; stride >>= 1)
; #pragma unroll
;             for (int i = 0; i < 16; ++i) { const int j = i ^ stride;
;                 if (j > i) { if ((i & size) == 0) CE_DESC(k[i], k[j]); else CE_DESC(k[j], k[i]); } }
; }
; __device__ __forceinline__ void peer_tile(const Args& A, LAS unsigned char* lds, int tile) {
;     ...
;                 { const bf16_t* sp = QRY + m * 2048 + hp * 128 + 32 * g;
;                   const u32x4 s0 = *(const u32x4*)sp, s1 = *(const u32x4*)(sp + 8), s2 = *(const u32x4*)(sp + 16), s3 = *(const u32x4*)(sp + 24);
;                   const unsigned sw[16] = {s0.x, s0.y, s0.z, s0.w, s1.x, s1.y, s1.z, s1.w, s2.x, s2.y, s2.z, s2.w, s3.x, s3.y, s3.z, s3.w};
; #pragma unroll
;                   for (int i = 0; i < 16; ++i) {
;                       const float lo = (float)__builtin_bit_cast(_Float16, (unsigned short)(sw[i] & 0xffffu)), hi = (float)__builtin_bit_cast(_Float16, (unsigned short)(sw[i] >> 16));
;                       const unsigned klo = (f2key(lo) & ~127u) | (unsigned)(127 - (32 * g + 2 * i)), khi = (f2key(hi) & ~127u) | (unsigned)(127 - (32 * g + 2 * i + 1));
;                       if (i < 8) { k0[2 * i] = klo; k0[2 * i + 1] = khi; } else { k1[2 * (i - 8)] = klo; k1[2 * (i - 8) + 1] = khi; } } }
;                 sort16_desc(k0); sort16_desc(k1); merge16(k0, k1);
	v_cvt_f32_f16_sdwa v82, v70 dst_sel:DWORD dst_unused:UNUSED_PAD src0_sel:WORD_1
	v_cvt_f32_f16_e32 v70, v70
	v_and_b32_e32 v65, 0xffffff80, v65
	v_sub_u32_e32 v65, v65, v18
	v_not_b32_e32 v83, v82
	v_or_b32_e32 v84, 0x80000000, v82
	v_cmp_gt_i32_e32 vcc, 0, v82
	v_add_u32_e32 v81, 0x7e, v81
	v_add_u32_e32 v65, 0x7f, v65
	v_cndmask_b32_e32 v82, v84, v83, vcc
	v_not_b32_e32 v83, v70
	v_or_b32_e32 v84, 0x80000000, v70
	v_cmp_gt_i32_e32 vcc, 0, v70
	v_and_b32_e32 v82, 0xffffff80, v82
	v_sub_u32_e32 v82, v82, v20
	v_cndmask_b32_e32 v70, v84, v83, vcc
	v_cvt_f32_f16_sdwa v83, v71 dst_sel:DWORD dst_unused:UNUSED_PAD src0_sel:WORD_1
	v_cvt_f32_f16_e32 v71, v71
	v_and_b32_e32 v70, 0xffffff80, v70
	v_sub_u32_e32 v70, v70, v20
	v_not_b32_e32 v84, v83
	v_or_b32_e32 v85, 0x80000000, v83
	v_cmp_gt_i32_e32 vcc, 0, v83
	v_add_u32_e32 v82, 0x7e, v82
	v_add_u32_e32 v70, 0x7f, v70
	v_cndmask_b32_e32 v83, v85, v84, vcc
	v_not_b32_e32 v84, v71
	v_or_b32_e32 v85, 0x80000000, v71
	v_cmp_gt_i32_e32 vcc, 0, v71
	v_and_b32_e32 v83, 0xffffff80, v83
	v_sub_u32_e32 v83, v83, v21
	v_cndmask_b32_e32 v71, v85, v84, vcc
	v_cvt_f32_f16_sdwa v84, v72 dst_sel:DWORD dst_unused:UNUSED_PAD src0_sel:WORD_1
	v_cvt_f32_f16_e32 v72, v72
	v_and_b32_e32 v71, 0xffffff80, v71
	v_sub_u32_e32 v71, v71, v21
	v_not_b32_e32 v85, v84
	v_or_b32_e32 v86, 0x80000000, v84
	v_cmp_gt_i32_e32 vcc, 0, v84
	v_add_u32_e32 v83, 0x7e, v83
	v_add_u32_e32 v71, 0x7f, v71
	v_cndmask_b32_e32 v84, v86, v85, vcc
	v_not_b32_e32 v85, v72
	v_or_b32_e32 v86, 0x80000000, v72
	v_cmp_gt_i32_e32 vcc, 0, v72
	v_and_b32_e32 v84, 0xffffff80, v84
	v_sub_u32_e32 v84, v84, v22
	v_cndmask_b32_e32 v72, v86, v85, vcc
	v_cvt_f32_f16_sdwa v85, v73 dst_sel:DWORD dst_unused:UNUSED_PAD src0_sel:WORD_1
	v_cvt_f32_f16_e32 v73, v73
	v_and_b32_e32 v72, 0xffffff80, v72
	v_sub_u32_e32 v72, v72, v22
	v_not_b32_e32 v86, v85
	v_or_b32_e32 v87, 0x80000000, v85
	v_cmp_gt_i32_e32 vcc, 0, v85
	v_add_u32_e32 v84, 0x7e, v84
	v_add_u32_e32 v72, 0x7f, v72
	v_cndmask_b32_e32 v85, v87, v86, vcc
	v_not_b32_e32 v86, v73
	v_or_b32_e32 v87, 0x80000000, v73
	v_cmp_gt_i32_e32 vcc, 0, v73
	v_and_b32_e32 v85, 0xffffff80, v85
	v_sub_u32_e32 v85, v85, v23
	v_cndmask_b32_e32 v73, v87, v86, vcc
	v_cvt_f32_f16_sdwa v86, v0 dst_sel:DWORD dst_unused:UNUSED_PAD src0_sel:WORD_1
	v_cvt_f32_f16_e32 v0, v0
	v_and_b32_e32 v73, 0xffffff80, v73
	v_sub_u32_e32 v73, v73, v23
	v_not_b32_e32 v87, v86
	v_or_b32_e32 v88, 0x80000000, v86
	v_cmp_gt_i32_e32 vcc, 0, v86
	v_add_u32_e32 v85, 0x7e, v85
	v_add_u32_e32 v73, 0x7f, v73
	v_cndmask_b32_e32 v86, v88, v87, vcc
	v_not_b32_e32 v87, v0
	v_or_b32_e32 v88, 0x80000000, v0
	v_cmp_gt_i32_e32 vcc, 0, v0
	v_and_b32_e32 v86, 0xffffff80, v86
	v_sub_u32_e32 v86, v86, v24
	v_cndmask_b32_e32 v0, v88, v87, vcc
	v_cvt_f32_f16_sdwa v87, v1 dst_sel:DWORD dst_unused:UNUSED_PAD src0_sel:WORD_1
	v_cvt_f32_f16_e32 v1, v1
	v_and_b32_e32 v0, 0xffffff80, v0
	v_sub_u32_e32 v0, v0, v24
	v_not_b32_e32 v88, v87
	v_or_b32_e32 v89, 0x80000000, v87
	v_cmp_gt_i32_e32 vcc, 0, v87
	v_add_u32_e32 v86, 0x7e, v86
	v_add_u32_e32 v0, 0x7f, v0
	v_cndmask_b32_e32 v87, v89, v88, vcc
	v_not_b32_e32 v88, v1
	v_or_b32_e32 v89, 0x80000000, v1
	v_cmp_gt_i32_e32 vcc, 0, v1
	v_and_b32_e32 v87, 0xffffff80, v87
	v_sub_u32_e32 v87, v87, v25
	v_cndmask_b32_e32 v1, v89, v88, vcc
	v_cvt_f32_f16_sdwa v88, v2 dst_sel:DWORD dst_unused:UNUSED_PAD src0_sel:WORD_1
	v_cvt_f32_f16_e32 v2, v2
	v_and_b32_e32 v1, 0xffffff80, v1
	v_sub_u32_e32 v1, v1, v25
	v_not_b32_e32 v89, v88
	v_or_b32_e32 v90, 0x80000000, v88
	v_cmp_gt_i32_e32 vcc, 0, v88
	v_add_u32_e32 v87, 0x7e, v87
	v_add_u32_e32 v1, 0x7f, v1
	v_cndmask_b32_e32 v88, v90, v89, vcc
	v_not_b32_e32 v89, v2
	v_or_b32_e32 v90, 0x80000000, v2
	v_cmp_gt_i32_e32 vcc, 0, v2
	v_and_b32_e32 v88, 0xffffff80, v88
	v_sub_u32_e32 v88, v88, v26
	v_cndmask_b32_e32 v2, v90, v89, vcc
	v_cvt_f32_f16_sdwa v89, v3 dst_sel:DWORD dst_unused:UNUSED_PAD src0_sel:WORD_1
	v_cvt_f32_f16_e32 v3, v3
	v_and_b32_e32 v2, 0xffffff80, v2
	v_sub_u32_e32 v2, v2, v26
	v_not_b32_e32 v90, v89
	v_or_b32_e32 v91, 0x80000000, v89
	v_cmp_gt_i32_e32 vcc, 0, v89
	v_add_u32_e32 v88, 0x7e, v88
	v_add_u32_e32 v2, 0x7f, v2
	v_cndmask_b32_e32 v89, v91, v90, vcc
	v_not_b32_e32 v90, v3
	v_or_b32_e32 v91, 0x80000000, v3
	v_cmp_gt_i32_e32 vcc, 0, v3
	v_and_b32_e32 v89, 0xffffff80, v89
	v_sub_u32_e32 v89, v89, v28
	v_cndmask_b32_e32 v3, v91, v90, vcc
	v_and_b32_e32 v3, 0xffffff80, v3
	v_sub_u32_e32 v3, v3, v28
	v_add_u32_e32 v89, 0x7e, v89
	v_add_u32_e32 v3, 0x7f, v3
	v_max_u32_e32 v90, v66, v74
	v_min_u32_e32 v66, v66, v74
	v_max_u32_e32 v74, v75, v67
	v_min_u32_e32 v67, v75, v67
	v_max_u32_e32 v75, v68, v76
	v_min_u32_e32 v68, v68, v76
	v_max_u32_e32 v76, v77, v69
	v_min_u32_e32 v69, v77, v69
	v_max_u32_e32 v77, v62, v78
	v_min_u32_e32 v62, v62, v78
	v_max_u32_e32 v78, v79, v63
	v_min_u32_e32 v63, v79, v63
	v_max_u32_e32 v79, v64, v80
	v_min_u32_e32 v64, v64, v80
	v_max_u32_e32 v80, v81, v65
	v_min_u32_e32 v65, v81, v65
	v_max_u32_e32 v98, v70, v82
	v_min_u32_e32 v70, v70, v82
	v_max_u32_e32 v82, v83, v71
	v_min_u32_e32 v71, v83, v71
	v_max_u32_e32 v83, v72, v84
	v_min_u32_e32 v72, v72, v84
	v_max_u32_e32 v84, v85, v73
	v_min_u32_e32 v73, v85, v73
	v_max_u32_e32 v85, v0, v86
	v_min_u32_e32 v0, v0, v86
	v_max_u32_e32 v86, v87, v1
	v_min_u32_e32 v1, v87, v1
	v_max_u32_e32 v87, v2, v88
	v_min_u32_e32 v2, v2, v88
	v_max_u32_e32 v88, v89, v3
	v_min_u32_e32 v3, v89, v3
	v_max_u32_e32 v81, v90, v67
	v_min_u32_e32 v67, v90, v67
	v_max_u32_e32 v90, v66, v74
	v_min_u32_e32 v66, v66, v74
	v_max_u32_e32 v74, v69, v75
	v_min_u32_e32 v69, v69, v75
	v_max_u32_e32 v75, v76, v68
	v_min_u32_e32 v68, v76, v68
; #define CE_DESC(a, b) do { const unsigned _mx = (a) > (b) ? (a) : (b), _mn = (a) > (b) ? (b) : (a); (a) = _mx; (b) = _mn; } while (0)
; __device__ __forceinline__ void sort16_desc(unsigned (&k)[16]) {
; #pragma unroll
;     for (int size = 2; size <= 16; size <<= 1)
; #pragma unroll
;         for (int stride = size >> 1; stride > 0; stride >>= 1)
; #pragma unroll
;             for (int i = 0; i < 16; ++i) { const int j = i ^ stride;
;                 if (j > i) { if ((i & size) == 0) CE_DESC(k[i], k[j]); else CE_DESC(k[j], k[i]); } }
; }
	v_max_u32_e32 v76, v77, v63
	v_min_u32_e32 v63, v77, v63
	v_max_u32_e32 v77, v62, v78
	v_min_u32_e32 v62, v62, v78
	v_max_u32_e32 v78, v65, v79
	v_min_u32_e32 v65, v65, v79
	v_max_u32_e32 v79, v80, v64
	v_min_u32_e32 v64, v80, v64
	v_max_u32_e32 v89, v98, v71
	v_min_u32_e32 v71, v98, v71
	v_max_u32_e32 v98, v70, v82
	v_min_u32_e32 v70, v70, v82
	v_max_u32_e32 v82, v73, v83
	v_min_u32_e32 v73, v73, v83
	v_max_u32_e32 v83, v84, v72
	v_min_u32_e32 v72, v84, v72
	v_max_u32_e32 v84, v85, v1
	v_min_u32_e32 v1, v85, v1
	v_max_u32_e32 v85, v0, v86
	v_min_u32_e32 v0, v0, v86
	v_max_u32_e32 v86, v3, v87
	v_min_u32_e32 v3, v3, v87
	v_max_u32_e32 v87, v88, v2
	v_min_u32_e32 v2, v88, v2
	v_max_u32_e32 v80, v81, v90
	v_min_u32_e32 v81, v81, v90
	v_max_u32_e32 v90, v67, v66
	v_min_u32_e32 v66, v67, v66
	v_max_u32_e32 v67, v68, v69
	v_min_u32_e32 v68, v68, v69
	v_max_u32_e32 v69, v75, v74
	v_min_u32_e32 v74, v75, v74
	v_max_u32_e32 v75, v76, v77
	v_min_u32_e32 v76, v76, v77
	v_max_u32_e32 v77, v63, v62
	v_min_u32_e32 v62, v63, v62
	v_max_u32_e32 v63, v64, v65
	v_min_u32_e32 v64, v64, v65
	v_max_u32_e32 v65, v79, v78
	v_min_u32_e32 v78, v79, v78
	v_max_u32_e32 v88, v89, v98
	v_min_u32_e32 v89, v89, v98
	v_max_u32_e32 v98, v71, v70
	v_min_u32_e32 v70, v71, v70
	v_max_u32_e32 v71, v72, v73
	v_min_u32_e32 v72, v72, v73
	v_max_u32_e32 v73, v83, v82
	v_min_u32_e32 v82, v83, v82
	v_max_u32_e32 v83, v84, v85
	v_min_u32_e32 v84, v84, v85
	v_max_u32_e32 v85, v1, v0
	v_min_u32_e32 v0, v1, v0
	v_max_u32_e32 v1, v2, v3
	v_min_u32_e32 v2, v2, v3
	v_max_u32_e32 v3, v87, v86
	v_min_u32_e32 v86, v87, v86
	v_max_u32_e32 v79, v80, v68
	v_min_u32_e32 v68, v80, v68
	v_max_u32_e32 v80, v81, v67
	v_min_u32_e32 v67, v81, v67
	v_max_u32_e32 v81, v90, v74
	v_min_u32_e32 v74, v90, v74
	v_max_u32_e32 v90, v66, v69
	v_min_u32_e32 v66, v66, v69
	v_max_u32_e32 v69, v64, v75
	v_min_u32_e32 v64, v64, v75
	v_max_u32_e32 v75, v63, v76
	v_min_u32_e32 v63, v63, v76
	v_max_u32_e32 v76, v78, v77
	v_min_u32_e32 v77, v78, v77
	v_max_u32_e32 v78, v65, v62
	v_min_u32_e32 v62, v65, v62
	v_max_u32_e32 v87, v88, v72
	v_min_u32_e32 v72, v88, v72
	v_max_u32_e32 v88, v89, v71
	v_min_u32_e32 v71, v89, v71
	v_max_u32_e32 v89, v98, v82
	v_min_u32_e32 v82, v98, v82
	v_max_u32_e32 v98, v70, v73
	v_min_u32_e32 v70, v70, v73
	v_max_u32_e32 v73, v2, v83
	v_min_u32_e32 v2, v2, v83
	v_max_u32_e32 v83, v1, v84
	v_min_u32_e32 v1, v1, v84
	v_max_u32_e32 v84, v86, v85
	v_min_u32_e32 v85, v86, v85
	v_max_u32_e32 v86, v3, v0
	v_min_u32_e32 v0, v3, v0
	v_max_u32_e32 v65, v79, v81
	v_min_u32_e32 v79, v79, v81
	v_max_u32_e32 v81, v80, v90
	v_min_u32_e32 v80, v80, v90
	v_max_u32_e32 v90, v68, v74
	v_min_u32_e32 v68, v68, v74
	v_max_u32_e32 v74, v67, v66
	v_min_u32_e32 v66, v67, v66
	v_max_u32_e32 v67, v77, v64
	v_min_u32_e32 v64, v77, v64
	v_max_u32_e32 v77, v62, v63
	v_min_u32_e32 v62, v62, v63
	v_max_u32_e32 v63, v76, v69
	v_min_u32_e32 v69, v76, v69
	v_max_u32_e32 v76, v78, v75
	v_min_u32_e32 v75, v78, v75
	v_max_u32_e32 v3, v87, v89
	v_min_u32_e32 v87, v87, v89
	v_max_u32_e32 v89, v88, v98
	v_min_u32_e32 v88, v88, v98
	v_max_u32_e32 v98, v72, v82
	v_min_u32_e32 v72, v72, v82
	v_max_u32_e32 v82, v71, v70
	v_min_u32_e32 v70, v71, v70
	v_max_u32_e32 v71, v85, v2
	v_min_u32_e32 v2, v85, v2
	v_max_u32_e32 v85, v0, v1
	v_min_u32_e32 v0, v0, v1
	v_max_u32_e32 v1, v84, v73
	v_min_u32_e32 v73, v84, v73
	v_max_u32_e32 v84, v86, v83
	v_min_u32_e32 v83, v86, v83
	v_max_u32_e32 v78, v65, v81
	v_min_u32_e32 v65, v65, v81
	v_max_u32_e32 v81, v79, v80
	v_min_u32_e32 v79, v79, v80
	v_max_u32_e32 v80, v90, v74
	v_min_u32_e32 v74, v90, v74
	v_max_u32_e32 v90, v68, v66
	v_min_u32_e32 v66, v68, v66
	v_max_u32_e32 v68, v62, v64
	v_min_u32_e32 v62, v62, v64
	v_max_u32_e32 v64, v77, v67
	v_min_u32_e32 v67, v77, v67
	v_max_u32_e32 v77, v75, v69
	v_min_u32_e32 v69, v75, v69
	v_max_u32_e32 v75, v76, v63
	v_min_u32_e32 v63, v76, v63
	v_max_u32_e32 v86, v3, v89
	v_min_u32_e32 v3, v3, v89
	v_max_u32_e32 v89, v87, v88
	v_min_u32_e32 v87, v87, v88
	v_max_u32_e32 v88, v98, v82
	v_min_u32_e32 v82, v98, v82
	v_max_u32_e32 v98, v72, v70
	v_min_u32_e32 v70, v72, v70
	v_max_u32_e32 v72, v0, v2
	v_min_u32_e32 v0, v0, v2
	v_max_u32_e32 v2, v85, v71
	v_min_u32_e32 v71, v85, v71
	v_max_u32_e32 v85, v83, v73
	v_min_u32_e32 v73, v83, v73
	v_max_u32_e32 v83, v84, v1
	v_min_u32_e32 v1, v84, v1
	v_max_u32_e32 v76, v78, v62
	v_min_u32_e32 v62, v78, v62
	v_max_u32_e32 v78, v65, v68
	v_min_u32_e32 v65, v65, v68
	v_max_u32_e32 v68, v81, v67
	v_min_u32_e32 v67, v81, v67
	v_max_u32_e32 v81, v79, v64
	v_min_u32_e32 v64, v79, v64
	v_max_u32_e32 v79, v80, v69
	v_min_u32_e32 v69, v80, v69
	v_max_u32_e32 v80, v74, v77
	v_min_u32_e32 v74, v74, v77
	v_max_u32_e32 v77, v90, v63
	v_min_u32_e32 v63, v90, v63
	v_max_u32_e32 v90, v66, v75
	v_min_u32_e32 v66, v66, v75
	v_max_u32_e32 v84, v86, v0
	v_min_u32_e32 v0, v86, v0
	v_max_u32_e32 v86, v3, v72
	v_min_u32_e32 v3, v3, v72
	v_max_u32_e32 v72, v89, v71
	v_min_u32_e32 v71, v89, v71
	v_max_u32_e32 v89, v87, v2
	v_min_u32_e32 v2, v87, v2
	v_max_u32_e32 v87, v88, v73
	v_min_u32_e32 v73, v88, v73
	v_max_u32_e32 v88, v82, v85
	v_min_u32_e32 v82, v82, v85
	v_max_u32_e32 v85, v98, v1
	v_min_u32_e32 v1, v98, v1
	v_max_u32_e32 v98, v70, v83
	v_min_u32_e32 v70, v70, v83
	v_max_u32_e32 v75, v76, v79
	v_min_u32_e32 v76, v76, v79
	v_max_u32_e32 v79, v78, v80
	v_min_u32_e32 v78, v78, v80
	v_max_u32_e32 v80, v68, v77
	v_min_u32_e32 v68, v68, v77
	v_max_u32_e32 v77, v81, v90
	v_min_u32_e32 v81, v81, v90
	v_max_u32_e32 v90, v62, v69
	v_min_u32_e32 v62, v62, v69
	v_max_u32_e32 v69, v65, v74
	v_min_u32_e32 v65, v65, v74
	v_max_u32_e32 v74, v67, v63
; #define CE_DESC(a, b) do { const unsigned _mx = (a) > (b) ? (a) : (b), _mn = (a) > (b) ? (b) : (a); (a) = _mx; (b) = _mn; } while (0)
; __device__ __forceinline__ void sort16_desc(unsigned (&k)[16]) {
; #pragma unroll
;     for (int size = 2; size <= 16; size <<= 1)
; #pragma unroll
;         for (int stride = size >> 1; stride > 0; stride >>= 1)
; #pragma unroll
;             for (int i = 0; i < 16; ++i) { const int j = i ^ stride;
;                 if (j > i) { if ((i & size) == 0) CE_DESC(k[i], k[j]); else CE_DESC(k[j], k[i]); } }
; }
; __device__ __forceinline__ void merge16(unsigned (&a)[16], const unsigned (&b)[16]) {
; #pragma unroll
;     for (int i = 0; i < 16; ++i) a[i] = a[i] > b[15 - i] ? a[i] : b[15 - i];
; #pragma unroll
;     for (int stride = 8; stride > 0; stride >>= 1)
; #pragma unroll
;         for (int i = 0; i < 16; ++i) { const int j = i ^ stride; if (j > i) CE_DESC(a[i], a[j]); }
; }
; __device__ __forceinline__ void peer_tile(const Args& A, LAS unsigned char* lds, int tile) {
;     ...
;                 for (int msk = 16; msk <= 32; msk <<= 1) {
; #pragma unroll
;                     for (int i = 0; i < 16; ++i) k1[i] = (unsigned)__shfl_xor((int)k0[i], msk);
;                     merge16(k0, k1); }
	v_min_u32_e32 v63, v67, v63
	v_max_u32_e32 v67, v64, v66
	v_min_u32_e32 v64, v64, v66
	v_max_u32_e32 v83, v84, v87
	v_min_u32_e32 v84, v84, v87
	v_max_u32_e32 v87, v86, v88
	v_min_u32_e32 v86, v86, v88
	v_max_u32_e32 v88, v72, v85
	v_min_u32_e32 v72, v72, v85
	v_max_u32_e32 v85, v89, v98
	v_min_u32_e32 v89, v89, v98
	v_max_u32_e32 v98, v0, v73
	v_min_u32_e32 v0, v0, v73
	v_max_u32_e32 v73, v3, v82
	v_min_u32_e32 v3, v3, v82
	v_max_u32_e32 v82, v71, v1
	v_min_u32_e32 v1, v71, v1
	v_max_u32_e32 v71, v2, v70
	v_min_u32_e32 v2, v2, v70
	v_max_u32_e32 v66, v75, v80
	v_min_u32_e32 v75, v75, v80
	v_max_u32_e32 v80, v79, v77
	v_min_u32_e32 v77, v79, v77
	v_max_u32_e32 v79, v76, v68
	v_min_u32_e32 v68, v76, v68
	v_max_u32_e32 v76, v78, v81
	v_min_u32_e32 v78, v78, v81
	v_max_u32_e32 v81, v90, v74
	v_min_u32_e32 v74, v90, v74
	v_max_u32_e32 v90, v69, v67
	v_min_u32_e32 v67, v69, v67
	v_max_u32_e32 v69, v62, v63
	v_min_u32_e32 v62, v62, v63
	v_max_u32_e32 v63, v65, v64
	v_min_u32_e32 v64, v65, v64
	v_max_u32_e32 v70, v83, v88
	v_min_u32_e32 v83, v83, v88
	v_max_u32_e32 v88, v87, v85
	v_min_u32_e32 v85, v87, v85
	v_max_u32_e32 v87, v84, v72
	v_min_u32_e32 v72, v84, v72
	v_max_u32_e32 v84, v86, v89
	v_min_u32_e32 v86, v86, v89
	v_max_u32_e32 v89, v98, v82
	v_min_u32_e32 v82, v98, v82
	v_max_u32_e32 v98, v73, v71
	v_min_u32_e32 v71, v73, v71
	v_max_u32_e32 v73, v0, v1
	v_min_u32_e32 v0, v0, v1
	v_max_u32_e32 v1, v3, v2
	v_min_u32_e32 v2, v3, v2
	v_min_u32_e32 v65, v66, v80
	v_min_u32_e32 v91, v75, v77
	v_min_u32_e32 v92, v79, v76
	v_min_u32_e32 v93, v68, v78
	v_min_u32_e32 v94, v81, v90
	v_min_u32_e32 v95, v74, v67
	v_min_u32_e32 v96, v69, v63
	v_min_u32_e32 v97, v62, v64
	v_min_u32_e32 v3, v70, v88
	v_min_u32_e32 v99, v83, v85
	v_min_u32_e32 v100, v87, v84
	v_min_u32_e32 v101, v72, v86
	v_min_u32_e32 v102, v89, v98
	v_min_u32_e32 v103, v82, v71
	v_min_u32_e32 v104, v73, v1
	v_min_u32_e32 v105, v0, v2
	v_max3_u32 v66, v66, v80, v105
	v_max3_u32 v0, v65, v0, v2
	v_max3_u32 v2, v75, v77, v104
	v_max3_u32 v1, v91, v73, v1
	v_max3_u32 v65, v79, v76, v103
	v_max3_u32 v71, v92, v82, v71
	v_max3_u32 v68, v68, v78, v102
	v_max3_u32 v73, v93, v89, v98
	v_max3_u32 v75, v81, v90, v101
	v_max3_u32 v72, v94, v72, v86
	v_max3_u32 v67, v74, v67, v100
	v_max3_u32 v74, v95, v87, v84
	v_max3_u32 v63, v69, v63, v99
	v_max3_u32 v69, v96, v83, v85
	v_max3_u32 v3, v62, v64, v3
	v_max3_u32 v62, v97, v70, v88
	v_max_u32_e32 v64, v66, v75
	v_min_u32_e32 v66, v66, v75
	v_max_u32_e32 v70, v0, v72
	v_min_u32_e32 v0, v0, v72
	v_max_u32_e32 v72, v2, v67
	v_min_u32_e32 v2, v2, v67
	v_max_u32_e32 v67, v1, v74
	v_min_u32_e32 v1, v1, v74
	v_max_u32_e32 v74, v65, v63
	v_min_u32_e32 v63, v65, v63
	v_max_u32_e32 v65, v71, v69
	v_min_u32_e32 v69, v71, v69
	v_max_u32_e32 v71, v68, v3
	v_min_u32_e32 v3, v68, v3
	v_max_u32_e32 v68, v73, v62
	v_min_u32_e32 v62, v73, v62
	v_max_u32_e32 v73, v64, v74
	v_min_u32_e32 v64, v64, v74
	v_max_u32_e32 v74, v70, v65
	v_min_u32_e32 v65, v70, v65
	v_max_u32_e32 v70, v72, v71
	v_min_u32_e32 v71, v72, v71
	v_max_u32_e32 v72, v67, v68
	v_min_u32_e32 v67, v67, v68
	v_max_u32_e32 v68, v66, v63
	v_min_u32_e32 v63, v66, v63
	v_max_u32_e32 v66, v0, v69
	v_min_u32_e32 v0, v0, v69
	v_max_u32_e32 v69, v2, v3
	v_min_u32_e32 v2, v2, v3
	v_max_u32_e32 v3, v1, v62
	v_min_u32_e32 v1, v1, v62
	v_max_u32_e32 v62, v73, v70
	v_min_u32_e32 v70, v73, v70
	v_max_u32_e32 v73, v74, v72
	v_min_u32_e32 v72, v74, v72
	v_max_u32_e32 v74, v64, v71
	v_min_u32_e32 v64, v64, v71
	v_max_u32_e32 v71, v65, v67
	v_min_u32_e32 v65, v65, v67
	v_max_u32_e32 v67, v68, v69
	v_min_u32_e32 v68, v68, v69
	v_max_u32_e32 v69, v66, v3
	v_min_u32_e32 v3, v66, v3
	v_max_u32_e32 v66, v63, v2
	v_min_u32_e32 v2, v63, v2
	v_max_u32_e32 v63, v0, v1
	v_min_u32_e32 v0, v0, v1
	v_max_u32_e32 v1, v62, v73
	v_min_u32_e32 v62, v62, v73
	v_max_u32_e32 v73, v70, v72
	v_min_u32_e32 v70, v70, v72
	v_max_u32_e32 v72, v74, v71
	v_min_u32_e32 v71, v74, v71
	v_max_u32_e32 v74, v64, v65
	v_min_u32_e32 v64, v64, v65
	v_max_u32_e32 v65, v67, v69
	v_min_u32_e32 v67, v67, v69
	v_max_u32_e32 v69, v68, v3
	v_min_u32_e32 v3, v68, v3
	v_max_u32_e32 v68, v66, v63
	v_min_u32_e32 v63, v66, v63
	v_max_u32_e32 v66, v2, v0
	v_min_u32_e32 v0, v2, v0
	ds_bpermute_b32 v2, v27, v1
	ds_bpermute_b32 v75, v27, v62
	ds_bpermute_b32 v76, v27, v73
	ds_bpermute_b32 v77, v27, v70
	ds_bpermute_b32 v78, v27, v72
	ds_bpermute_b32 v79, v27, v71
	ds_bpermute_b32 v80, v27, v74
	ds_bpermute_b32 v81, v27, v64
	ds_bpermute_b32 v82, v27, v65
	ds_bpermute_b32 v83, v27, v67
	ds_bpermute_b32 v84, v27, v69
	ds_bpermute_b32 v85, v27, v0
	ds_bpermute_b32 v86, v27, v66
	ds_bpermute_b32 v87, v27, v63
	ds_bpermute_b32 v88, v27, v68
	ds_bpermute_b32 v89, v27, v3
	s_waitcnt lgkmcnt(4)
	v_max_u32_e32 v1, v1, v85
	s_waitcnt lgkmcnt(3)
	v_max_u32_e32 v62, v62, v86
	s_waitcnt lgkmcnt(2)
	v_max_u32_e32 v73, v73, v87
	s_waitcnt lgkmcnt(1)
	v_max_u32_e32 v70, v70, v88
	s_waitcnt lgkmcnt(0)
; #define CE_DESC(a, b) do { const unsigned _mx = (a) > (b) ? (a) : (b), _mn = (a) > (b) ? (b) : (a); (a) = _mx; (b) = _mn; } while (0)
; __device__ __forceinline__ void merge16(unsigned (&a)[16], const unsigned (&b)[16]) {
; #pragma unroll
;     for (int i = 0; i < 16; ++i) a[i] = a[i] > b[15 - i] ? a[i] : b[15 - i];
; #pragma unroll
;     for (int stride = 8; stride > 0; stride >>= 1)
; #pragma unroll
;         for (int i = 0; i < 16; ++i) { const int j = i ^ stride; if (j > i) CE_DESC(a[i], a[j]); }
; }
; __device__ __forceinline__ void peer_tile(const Args& A, LAS unsigned char* lds, int tile) {
;     ...
;                 { const bf16_t* sp = QRY + m * 2048 + hp * 128 + 32 * g;
;                   const u32x4 s0 = *(const u32x4*)sp, s1 = *(const u32x4*)(sp + 8), s2 = *(const u32x4*)(sp + 16), s3 = *(const u32x4*)(sp + 24);
;     ...
;                 for (int msk = 16; msk <= 32; msk <<= 1) {
; #pragma unroll
;                     for (int i = 0; i < 16; ++i) k1[i] = (unsigned)__shfl_xor((int)k0[i], msk);
;                     merge16(k0, k1); }
	v_max_u32_e32 v72, v72, v89
	v_max_u32_e32 v71, v71, v84
	v_max_u32_e32 v74, v74, v83
	v_max_u32_e32 v64, v64, v82
	v_max_u32_e32 v65, v65, v81
	v_max_u32_e32 v67, v67, v80
	v_max_u32_e32 v69, v69, v79
	v_max_u32_e32 v3, v3, v78
	v_max_u32_e32 v68, v68, v77
	v_max_u32_e32 v63, v63, v76
	v_max_u32_e32 v66, v66, v75
	v_max_u32_e32 v0, v0, v2
	v_max_u32_e32 v2, v1, v65
	v_min_u32_e32 v1, v1, v65
	v_max_u32_e32 v65, v62, v67
	v_min_u32_e32 v62, v62, v67
	v_max_u32_e32 v67, v73, v69
	v_min_u32_e32 v69, v73, v69
	v_max_u32_e32 v73, v70, v3
	v_min_u32_e32 v3, v70, v3
	v_max_u32_e32 v70, v72, v68
	v_min_u32_e32 v68, v72, v68
	v_max_u32_e32 v72, v71, v63
	v_min_u32_e32 v63, v71, v63
	v_max_u32_e32 v71, v74, v66
	v_min_u32_e32 v66, v74, v66
	v_max_u32_e32 v74, v64, v0
	v_min_u32_e32 v0, v64, v0
	v_max_u32_e32 v64, v2, v70
	v_min_u32_e32 v2, v2, v70
	v_max_u32_e32 v70, v65, v72
	v_min_u32_e32 v65, v65, v72
	v_max_u32_e32 v72, v67, v71
	v_min_u32_e32 v67, v67, v71
	v_max_u32_e32 v71, v73, v74
	v_min_u32_e32 v73, v73, v74
	v_max_u32_e32 v74, v1, v68
	v_min_u32_e32 v1, v1, v68
	v_max_u32_e32 v68, v62, v63
	v_min_u32_e32 v62, v62, v63
	v_max_u32_e32 v63, v69, v66
	v_min_u32_e32 v66, v69, v66
	v_max_u32_e32 v69, v3, v0
	v_min_u32_e32 v0, v3, v0
	v_max_u32_e32 v3, v64, v72
	v_min_u32_e32 v64, v64, v72
	v_max_u32_e32 v72, v70, v71
	v_min_u32_e32 v70, v70, v71
	v_max_u32_e32 v71, v2, v67
	v_min_u32_e32 v2, v2, v67
	v_max_u32_e32 v67, v65, v73
	v_min_u32_e32 v65, v65, v73
	v_max_u32_e32 v73, v74, v63
	v_min_u32_e32 v63, v74, v63
	v_max_u32_e32 v74, v68, v69
	v_min_u32_e32 v68, v68, v69
	v_max_u32_e32 v69, v1, v66
	v_min_u32_e32 v1, v1, v66
	v_max_u32_e32 v66, v62, v0
	v_min_u32_e32 v0, v62, v0
	v_max_u32_e32 v62, v3, v72
	v_min_u32_e32 v3, v3, v72
	v_max_u32_e32 v72, v64, v70
	v_min_u32_e32 v64, v64, v70
	v_max_u32_e32 v70, v71, v67
	v_min_u32_e32 v67, v71, v67
	v_max_u32_e32 v71, v2, v65
	v_min_u32_e32 v2, v2, v65
	v_max_u32_e32 v65, v73, v74
	v_min_u32_e32 v73, v73, v74
	v_max_u32_e32 v74, v63, v68
	v_min_u32_e32 v63, v63, v68
	v_max_u32_e32 v68, v69, v66
	v_min_u32_e32 v66, v69, v66
	v_max_u32_e32 v69, v1, v0
	v_min_u32_e32 v0, v1, v0
	ds_bpermute_b32 v78, v29, v0
	ds_bpermute_b32 v1, v29, v62
	ds_bpermute_b32 v75, v29, v3
	ds_bpermute_b32 v76, v29, v72
	ds_bpermute_b32 v77, v29, v64
	s_waitcnt lgkmcnt(4)
	v_max_u32_e32 v62, v62, v78
	global_load_dwordx4 v[78:81], v[4:5], off offset:784
	global_load_dwordx4 v[82:85], v[4:5], off offset:768
	ds_bpermute_b32 v86, v29, v70
	ds_bpermute_b32 v87, v29, v67
	ds_bpermute_b32 v88, v29, v71
	ds_bpermute_b32 v89, v29, v2
	ds_bpermute_b32 v90, v29, v65
	ds_bpermute_b32 v91, v29, v73
	ds_bpermute_b32 v92, v29, v74
	ds_bpermute_b32 v93, v29, v63
	ds_bpermute_b32 v94, v29, v68
	ds_bpermute_b32 v95, v29, v69
	ds_bpermute_b32 v96, v29, v66
	s_waitcnt lgkmcnt(4)
	v_max_u32_e32 v67, v67, v92
	s_waitcnt lgkmcnt(3)
	v_max_u32_e32 v70, v70, v93
	s_waitcnt lgkmcnt(2)
	v_max_u32_e32 v64, v64, v94
	s_waitcnt lgkmcnt(1)
	v_max_u32_e32 v3, v3, v95
	s_waitcnt lgkmcnt(0)
	v_max_u32_e32 v72, v72, v96
	v_max_u32_e32 v71, v71, v91
	v_max_u32_e32 v2, v2, v90
	v_max_u32_e32 v65, v65, v89
	v_max_u32_e32 v73, v73, v88
	v_max_u32_e32 v74, v74, v87
	v_max_u32_e32 v63, v63, v86
	v_max_u32_e32 v68, v68, v77
	v_max_u32_e32 v66, v66, v76
	v_max_u32_e32 v69, v69, v75
	v_max_u32_e32 v0, v0, v1
	v_max_u32_e32 v1, v62, v65
	v_min_u32_e32 v62, v62, v65
	v_max_u32_e32 v65, v3, v73
	v_min_u32_e32 v3, v3, v73
	v_max_u32_e32 v73, v72, v74
	v_min_u32_e32 v72, v72, v74
	v_max_u32_e32 v74, v64, v63
	v_min_u32_e32 v63, v64, v63
	v_max_u32_e32 v64, v70, v68
	v_min_u32_e32 v68, v70, v68
	v_max_u32_e32 v70, v67, v66
	v_min_u32_e32 v66, v67, v66
	v_max_u32_e32 v67, v71, v69
	v_min_u32_e32 v69, v71, v69
	v_max_u32_e32 v71, v2, v0
	v_min_u32_e32 v0, v2, v0
	v_max_u32_e32 v2, v1, v64
	v_min_u32_e32 v1, v1, v64
	v_max_u32_e32 v64, v65, v70
	v_min_u32_e32 v65, v65, v70
	v_max_u32_e32 v70, v73, v67
	v_min_u32_e32 v67, v73, v67
	v_max_u32_e32 v73, v74, v71
	v_min_u32_e32 v71, v74, v71
	v_max_u32_e32 v74, v62, v68
	v_min_u32_e32 v62, v62, v68
	v_max_u32_e32 v68, v3, v66
	v_min_u32_e32 v3, v3, v66
	v_max_u32_e32 v66, v72, v69
	v_min_u32_e32 v69, v72, v69
	v_max_u32_e32 v72, v63, v0
	v_min_u32_e32 v0, v63, v0
	v_max_u32_e32 v63, v2, v70
	v_min_u32_e32 v2, v2, v70
	v_max_u32_e32 v70, v64, v73
	v_min_u32_e32 v64, v64, v73
	v_max_u32_e32 v86, v1, v67
	v_min_u32_e32 v1, v1, v67
	v_max_u32_e32 v67, v65, v71
	v_min_u32_e32 v65, v65, v71
	v_max_u32_e32 v87, v74, v66
	v_min_u32_e32 v66, v74, v66
	v_max_u32_e32 v88, v68, v72
	v_min_u32_e32 v89, v68, v72
	v_max_u32_e32 v90, v62, v69
	v_min_u32_e32 v62, v62, v69
	v_max_u32_e32 v91, v3, v0
	v_min_u32_e32 v0, v3, v0
	v_max_u32_e32 v77, v63, v70
	v_min_u32_e32 v76, v63, v70
	v_max_u32_e32 v75, v2, v64
	v_min_u32_e32 v74, v2, v64
	v_max_u32_e32 v73, v86, v67
	v_min_u32_e32 v72, v86, v67
	v_max_u32_e32 v71, v1, v65
	v_min_u32_e32 v70, v1, v65
	v_max_u32_e32 v69, v87, v88
	v_min_u32_e32 v68, v87, v88
	v_max_u32_e32 v67, v66, v89
	v_min_u32_e32 v66, v66, v89
	v_max_u32_e32 v63, v62, v0
	v_min_u32_e32 v62, v62, v0
	global_load_dwordx4 v[0:3], v[4:5], off offset:816
	global_load_dwordx4 v[86:89], v[4:5], off offset:800
	v_max_u32_e32 v65, v90, v91
	v_min_u32_e32 v64, v90, v91
	s_waitcnt vmcnt(2)
; __device__ __forceinline__ unsigned f2key(float f) { const unsigned u = __float_as_uint(f); return (u & 0x80000000u) ? ~u : (u | 0x80000000u); }
; __device__ __forceinline__ void peer_tile(const Args& A, LAS unsigned char* lds, int tile) {
;     ...
;                 { const bf16_t* sp = QRY + m * 2048 + hp * 128 + 32 * g;
;                   const u32x4 s0 = *(const u32x4*)sp, s1 = *(const u32x4*)(sp + 8), s2 = *(const u32x4*)(sp + 16), s3 = *(const u32x4*)(sp + 24);
;                   const unsigned sw[16] = {s0.x, s0.y, s0.z, s0.w, s1.x, s1.y, s1.z, s1.w, s2.x, s2.y, s2.z, s2.w, s3.x, s3.y, s3.z, s3.w};
; #pragma unroll
;                   for (int i = 0; i < 16; ++i) {
;                       const float lo = (float)__builtin_bit_cast(_Float16, (unsigned short)(sw[i] & 0xffffu)), hi = (float)__builtin_bit_cast(_Float16, (unsigned short)(sw[i] >> 16));
;                       const unsigned klo = (f2key(lo) & ~127u) | (unsigned)(127 - (32 * g + 2 * i)), khi = (f2key(hi) & ~127u) | (unsigned)(127 - (32 * g + 2 * i + 1));
;                       if (i < 8) { k0[2 * i] = klo; k0[2 * i + 1] = khi; } else { k1[2 * (i - 8)] = klo; k1[2 * (i - 8) + 1] = khi; } } }
;     ...
;                 for (int i = 0; i < 16; ++i) L2[p][i] = (g & 2) ? ((g & 1) ? LA[3][p][i] : LA[2][p][i]) : ((g & 1) ? LA[1][p][i] : LA[0][p][i]);
	v_cvt_f32_f16_sdwa v90, v82 dst_sel:DWORD dst_unused:UNUSED_PAD src0_sel:WORD_1
	v_cvt_f32_f16_e32 v82, v82
	v_cndmask_b32_e64 v38, v70, v38, s[0:1]
	v_cndmask_b32_e64 v37, v69, v37, s[0:1]
	v_not_b32_e32 v91, v90
	v_or_b32_e32 v92, 0x80000000, v90
	v_cmp_gt_i32_e32 vcc, 0, v90
	v_cndmask_b32_e64 v36, v68, v36, s[0:1]
	v_cndmask_b32_e64 v35, v67, v35, s[0:1]
	v_cndmask_b32_e32 v90, v92, v91, vcc
	v_not_b32_e32 v91, v82
	v_or_b32_e32 v92, 0x80000000, v82
	v_cmp_gt_i32_e32 vcc, 0, v82
	v_and_b32_e32 v90, 0xffffff80, v90
	v_sub_u32_e32 v90, v90, v15
	v_cndmask_b32_e32 v82, v92, v91, vcc
	v_cvt_f32_f16_sdwa v91, v83 dst_sel:DWORD dst_unused:UNUSED_PAD src0_sel:WORD_1
	v_cvt_f32_f16_e32 v83, v83
	v_and_b32_e32 v82, 0xffffff80, v82
	v_sub_u32_e32 v82, v82, v15
	v_not_b32_e32 v92, v91
	v_or_b32_e32 v93, 0x80000000, v91
	v_cmp_gt_i32_e32 vcc, 0, v91
	v_add_u32_e32 v90, 0x7e, v90
	v_add_u32_e32 v82, 0x7f, v82
	v_cndmask_b32_e32 v91, v93, v92, vcc
	v_not_b32_e32 v92, v83
	v_or_b32_e32 v93, 0x80000000, v83
	v_cmp_gt_i32_e32 vcc, 0, v83
	v_and_b32_e32 v91, 0xffffff80, v91
	v_sub_u32_e32 v91, v91, v14
	v_cndmask_b32_e32 v83, v93, v92, vcc
	v_cvt_f32_f16_sdwa v92, v84 dst_sel:DWORD dst_unused:UNUSED_PAD src0_sel:WORD_1
	v_cvt_f32_f16_e32 v84, v84
	v_and_b32_e32 v83, 0xffffff80, v83
	v_sub_u32_e32 v83, v83, v14
	v_not_b32_e32 v93, v92
	v_or_b32_e32 v94, 0x80000000, v92
	v_cmp_gt_i32_e32 vcc, 0, v92
	v_add_u32_e32 v91, 0x7e, v91
	v_add_u32_e32 v83, 0x7f, v83
	v_cndmask_b32_e32 v92, v94, v93, vcc
	v_not_b32_e32 v93, v84
	v_or_b32_e32 v94, 0x80000000, v84
	v_cmp_gt_i32_e32 vcc, 0, v84
	v_and_b32_e32 v92, 0xffffff80, v92
	v_sub_u32_e32 v92, v92, v12
	v_cndmask_b32_e32 v84, v94, v93, vcc
	v_cvt_f32_f16_sdwa v93, v85 dst_sel:DWORD dst_unused:UNUSED_PAD src0_sel:WORD_1
	v_cvt_f32_f16_e32 v85, v85
	v_and_b32_e32 v84, 0xffffff80, v84
	v_sub_u32_e32 v84, v84, v12
	v_not_b32_e32 v94, v93
	v_or_b32_e32 v95, 0x80000000, v93
	v_cmp_gt_i32_e32 vcc, 0, v93
	v_add_u32_e32 v92, 0x7e, v92
	v_add_u32_e32 v84, 0x7f, v84
	v_cndmask_b32_e32 v93, v95, v94, vcc
	v_not_b32_e32 v94, v85
	v_or_b32_e32 v95, 0x80000000, v85
	v_cmp_gt_i32_e32 vcc, 0, v85
	v_and_b32_e32 v93, 0xffffff80, v93
	v_sub_u32_e32 v93, v93, v10
	v_cndmask_b32_e32 v85, v95, v94, vcc
	v_cvt_f32_f16_sdwa v94, v78 dst_sel:DWORD dst_unused:UNUSED_PAD src0_sel:WORD_1
	v_cvt_f32_f16_e32 v78, v78
	v_and_b32_e32 v85, 0xffffff80, v85
	v_sub_u32_e32 v85, v85, v10
	v_not_b32_e32 v95, v94
	v_or_b32_e32 v96, 0x80000000, v94
	v_cmp_gt_i32_e32 vcc, 0, v94
	v_add_u32_e32 v93, 0x7e, v93
	v_add_u32_e32 v85, 0x7f, v85
	v_cndmask_b32_e32 v94, v96, v95, vcc
	v_not_b32_e32 v95, v78
	v_or_b32_e32 v96, 0x80000000, v78
	v_cmp_gt_i32_e32 vcc, 0, v78
	v_and_b32_e32 v94, 0xffffff80, v94
	v_sub_u32_e32 v94, v94, v8
	v_cndmask_b32_e32 v78, v96, v95, vcc
	v_cvt_f32_f16_sdwa v95, v79 dst_sel:DWORD dst_unused:UNUSED_PAD src0_sel:WORD_1
	v_cvt_f32_f16_e32 v79, v79
	v_and_b32_e32 v78, 0xffffff80, v78
	v_sub_u32_e32 v78, v78, v8
	v_not_b32_e32 v96, v95
	v_or_b32_e32 v97, 0x80000000, v95
	v_cmp_gt_i32_e32 vcc, 0, v95
	v_add_u32_e32 v94, 0x7e, v94
	v_add_u32_e32 v78, 0x7f, v78
	v_cndmask_b32_e32 v95, v97, v96, vcc
	v_not_b32_e32 v96, v79
	v_or_b32_e32 v97, 0x80000000, v79
	v_cmp_gt_i32_e32 vcc, 0, v79
	v_and_b32_e32 v95, 0xffffff80, v95
	v_sub_u32_e32 v95, v95, v16
	v_cndmask_b32_e32 v79, v97, v96, vcc
	v_cvt_f32_f16_sdwa v96, v80 dst_sel:DWORD dst_unused:UNUSED_PAD src0_sel:WORD_1
	v_cvt_f32_f16_e32 v80, v80
	v_and_b32_e32 v79, 0xffffff80, v79
	v_sub_u32_e32 v79, v79, v16
	v_not_b32_e32 v97, v96
	v_or_b32_e32 v98, 0x80000000, v96
	v_cmp_gt_i32_e32 vcc, 0, v96
	v_add_u32_e32 v95, 0x7e, v95
	v_add_u32_e32 v79, 0x7f, v79
	v_cndmask_b32_e32 v96, v98, v97, vcc
	v_not_b32_e32 v97, v80
	v_or_b32_e32 v98, 0x80000000, v80
	v_cmp_gt_i32_e32 vcc, 0, v80
	v_and_b32_e32 v96, 0xffffff80, v96
	v_sub_u32_e32 v96, v96, v17
	v_cndmask_b32_e32 v80, v98, v97, vcc
	v_cvt_f32_f16_sdwa v97, v81 dst_sel:DWORD dst_unused:UNUSED_PAD src0_sel:WORD_1
	v_cvt_f32_f16_e32 v81, v81
	v_and_b32_e32 v80, 0xffffff80, v80
	v_sub_u32_e32 v80, v80, v17
	v_not_b32_e32 v98, v97
	v_or_b32_e32 v99, 0x80000000, v97
	v_cmp_gt_i32_e32 vcc, 0, v97
	v_add_u32_e32 v96, 0x7e, v96
	v_add_u32_e32 v80, 0x7f, v80
	v_cndmask_b32_e32 v97, v99, v98, vcc
	v_not_b32_e32 v98, v81
	v_or_b32_e32 v99, 0x80000000, v81
	v_cmp_gt_i32_e32 vcc, 0, v81
	v_and_b32_e32 v97, 0xffffff80, v97
	v_sub_u32_e32 v97, v97, v18
	v_cndmask_b32_e32 v81, v99, v98, vcc
	s_waitcnt vmcnt(0)
; __device__ __forceinline__ unsigned f2key(float f) { const unsigned u = __float_as_uint(f); return (u & 0x80000000u) ? ~u : (u | 0x80000000u); }
; #define CE_DESC(a, b) do { const unsigned _mx = (a) > (b) ? (a) : (b), _mn = (a) > (b) ? (b) : (a); (a) = _mx; (b) = _mn; } while (0)
; __device__ __forceinline__ void sort16_desc(unsigned (&k)[16]) {
; #pragma unroll
;     for (int size = 2; size <= 16; size <<= 1)
; #pragma unroll
;         for (int stride = size >> 1; stride > 0; stride >>= 1)
; #pragma unroll
;             for (int i = 0; i < 16; ++i) { const int j = i ^ stride;
;                 if (j > i) { if ((i & size) == 0) CE_DESC(k[i], k[j]); else CE_DESC(k[j], k[i]); } }
; }
; __device__ __forceinline__ void peer_tile(const Args& A, LAS unsigned char* lds, int tile) {
;     ...
;                 { const bf16_t* sp = QRY + m * 2048 + hp * 128 + 32 * g;
;                   const u32x4 s0 = *(const u32x4*)sp, s1 = *(const u32x4*)(sp + 8), s2 = *(const u32x4*)(sp + 16), s3 = *(const u32x4*)(sp + 24);
;                   const unsigned sw[16] = {s0.x, s0.y, s0.z, s0.w, s1.x, s1.y, s1.z, s1.w, s2.x, s2.y, s2.z, s2.w, s3.x, s3.y, s3.z, s3.w};
; #pragma unroll
;                   for (int i = 0; i < 16; ++i) {
;                       const float lo = (float)__builtin_bit_cast(_Float16, (unsigned short)(sw[i] & 0xffffu)), hi = (float)__builtin_bit_cast(_Float16, (unsigned short)(sw[i] >> 16));
;                       const unsigned klo = (f2key(lo) & ~127u) | (unsigned)(127 - (32 * g + 2 * i)), khi = (f2key(hi) & ~127u) | (unsigned)(127 - (32 * g + 2 * i + 1));
;                       if (i < 8) { k0[2 * i] = klo; k0[2 * i + 1] = khi; } else { k1[2 * (i - 8)] = klo; k1[2 * (i - 8) + 1] = khi; } } }
;                 sort16_desc(k0); sort16_desc(k1); merge16(k0, k1);
	v_cvt_f32_f16_sdwa v98, v86 dst_sel:DWORD dst_unused:UNUSED_PAD src0_sel:WORD_1
	v_cvt_f32_f16_e32 v86, v86
	v_and_b32_e32 v81, 0xffffff80, v81
	v_sub_u32_e32 v81, v81, v18
	v_not_b32_e32 v99, v98
	v_or_b32_e32 v100, 0x80000000, v98
	v_cmp_gt_i32_e32 vcc, 0, v98
	v_add_u32_e32 v97, 0x7e, v97
	v_add_u32_e32 v81, 0x7f, v81
	v_cndmask_b32_e32 v98, v100, v99, vcc
	v_not_b32_e32 v99, v86
	v_or_b32_e32 v100, 0x80000000, v86
	v_cmp_gt_i32_e32 vcc, 0, v86
	v_and_b32_e32 v98, 0xffffff80, v98
	v_sub_u32_e32 v98, v98, v20
	v_cndmask_b32_e32 v86, v100, v99, vcc
	v_cvt_f32_f16_sdwa v99, v87 dst_sel:DWORD dst_unused:UNUSED_PAD src0_sel:WORD_1
	v_cvt_f32_f16_e32 v87, v87
	v_and_b32_e32 v86, 0xffffff80, v86
	v_sub_u32_e32 v86, v86, v20
	v_not_b32_e32 v100, v99
	v_or_b32_e32 v101, 0x80000000, v99
	v_cmp_gt_i32_e32 vcc, 0, v99
	v_add_u32_e32 v98, 0x7e, v98
	v_add_u32_e32 v86, 0x7f, v86
	v_cndmask_b32_e32 v99, v101, v100, vcc
	v_not_b32_e32 v100, v87
	v_or_b32_e32 v101, 0x80000000, v87
	v_cmp_gt_i32_e32 vcc, 0, v87
	v_and_b32_e32 v99, 0xffffff80, v99
	v_sub_u32_e32 v99, v99, v21
	v_cndmask_b32_e32 v87, v101, v100, vcc
	v_cvt_f32_f16_sdwa v100, v88 dst_sel:DWORD dst_unused:UNUSED_PAD src0_sel:WORD_1
	v_cvt_f32_f16_e32 v88, v88
	v_and_b32_e32 v87, 0xffffff80, v87
	v_sub_u32_e32 v87, v87, v21
	v_not_b32_e32 v101, v100
	v_or_b32_e32 v102, 0x80000000, v100
	v_cmp_gt_i32_e32 vcc, 0, v100
	v_add_u32_e32 v99, 0x7e, v99
	v_add_u32_e32 v87, 0x7f, v87
	v_cndmask_b32_e32 v100, v102, v101, vcc
	v_not_b32_e32 v101, v88
	v_or_b32_e32 v102, 0x80000000, v88
	v_cmp_gt_i32_e32 vcc, 0, v88
	v_and_b32_e32 v100, 0xffffff80, v100
	v_sub_u32_e32 v100, v100, v22
	v_cndmask_b32_e32 v88, v102, v101, vcc
	v_cvt_f32_f16_sdwa v101, v89 dst_sel:DWORD dst_unused:UNUSED_PAD src0_sel:WORD_1
	v_cvt_f32_f16_e32 v89, v89
	v_and_b32_e32 v88, 0xffffff80, v88
	v_sub_u32_e32 v88, v88, v22
	v_not_b32_e32 v102, v101
	v_or_b32_e32 v103, 0x80000000, v101
	v_cmp_gt_i32_e32 vcc, 0, v101
	v_add_u32_e32 v100, 0x7e, v100
	v_add_u32_e32 v88, 0x7f, v88
	v_cndmask_b32_e32 v101, v103, v102, vcc
	v_not_b32_e32 v102, v89
	v_or_b32_e32 v103, 0x80000000, v89
	v_cmp_gt_i32_e32 vcc, 0, v89
	v_and_b32_e32 v101, 0xffffff80, v101
	v_sub_u32_e32 v101, v101, v23
	v_cndmask_b32_e32 v89, v103, v102, vcc
	v_cvt_f32_f16_sdwa v102, v0 dst_sel:DWORD dst_unused:UNUSED_PAD src0_sel:WORD_1
	v_cvt_f32_f16_e32 v0, v0
	v_and_b32_e32 v89, 0xffffff80, v89
	v_sub_u32_e32 v89, v89, v23
	v_not_b32_e32 v103, v102
	v_or_b32_e32 v104, 0x80000000, v102
	v_cmp_gt_i32_e32 vcc, 0, v102
	v_add_u32_e32 v101, 0x7e, v101
	v_add_u32_e32 v89, 0x7f, v89
	v_cndmask_b32_e32 v102, v104, v103, vcc
	v_not_b32_e32 v103, v0
	v_or_b32_e32 v104, 0x80000000, v0
	v_cmp_gt_i32_e32 vcc, 0, v0
	v_and_b32_e32 v102, 0xffffff80, v102
	v_sub_u32_e32 v102, v102, v24
	v_cndmask_b32_e32 v0, v104, v103, vcc
	v_cvt_f32_f16_sdwa v103, v1 dst_sel:DWORD dst_unused:UNUSED_PAD src0_sel:WORD_1
	v_cvt_f32_f16_e32 v1, v1
	v_and_b32_e32 v0, 0xffffff80, v0
	v_sub_u32_e32 v0, v0, v24
	v_not_b32_e32 v104, v103
	v_or_b32_e32 v105, 0x80000000, v103
	v_cmp_gt_i32_e32 vcc, 0, v103
	v_add_u32_e32 v102, 0x7e, v102
	v_add_u32_e32 v0, 0x7f, v0
	v_cndmask_b32_e32 v103, v105, v104, vcc
	v_not_b32_e32 v104, v1
	v_or_b32_e32 v105, 0x80000000, v1
	v_cmp_gt_i32_e32 vcc, 0, v1
	v_and_b32_e32 v103, 0xffffff80, v103
	v_sub_u32_e32 v103, v103, v25
	v_cndmask_b32_e32 v1, v105, v104, vcc
	v_cvt_f32_f16_sdwa v104, v2 dst_sel:DWORD dst_unused:UNUSED_PAD src0_sel:WORD_1
	v_cvt_f32_f16_e32 v2, v2
	v_and_b32_e32 v1, 0xffffff80, v1
	v_sub_u32_e32 v1, v1, v25
	v_not_b32_e32 v105, v104
	v_or_b32_e32 v106, 0x80000000, v104
	v_cmp_gt_i32_e32 vcc, 0, v104
	v_add_u32_e32 v103, 0x7e, v103
	v_add_u32_e32 v1, 0x7f, v1
	v_cndmask_b32_e32 v104, v106, v105, vcc
	v_not_b32_e32 v105, v2
	v_or_b32_e32 v106, 0x80000000, v2
	v_cmp_gt_i32_e32 vcc, 0, v2
	v_and_b32_e32 v104, 0xffffff80, v104
	v_sub_u32_e32 v104, v104, v26
	v_cndmask_b32_e32 v2, v106, v105, vcc
	v_cvt_f32_f16_sdwa v105, v3 dst_sel:DWORD dst_unused:UNUSED_PAD src0_sel:WORD_1
	v_cvt_f32_f16_e32 v3, v3
	v_and_b32_e32 v2, 0xffffff80, v2
	v_sub_u32_e32 v2, v2, v26
	v_not_b32_e32 v106, v105
	v_or_b32_e32 v107, 0x80000000, v105
	v_cmp_gt_i32_e32 vcc, 0, v105
	v_add_u32_e32 v104, 0x7e, v104
	v_add_u32_e32 v2, 0x7f, v2
	v_cndmask_b32_e32 v105, v107, v106, vcc
	v_not_b32_e32 v106, v3
	v_or_b32_e32 v107, 0x80000000, v3
	v_cmp_gt_i32_e32 vcc, 0, v3
	v_and_b32_e32 v105, 0xffffff80, v105
	v_sub_u32_e32 v105, v105, v28
	v_cndmask_b32_e32 v3, v107, v106, vcc
	v_and_b32_e32 v3, 0xffffff80, v3
	v_sub_u32_e32 v3, v3, v28
	v_add_u32_e32 v105, 0x7e, v105
	v_add_u32_e32 v3, 0x7f, v3
	v_max_u32_e32 v106, v82, v90
	v_min_u32_e32 v82, v82, v90
	v_max_u32_e32 v90, v91, v83
	v_min_u32_e32 v83, v91, v83
	v_max_u32_e32 v91, v84, v92
	v_min_u32_e32 v84, v84, v92
	v_max_u32_e32 v92, v93, v85
	v_min_u32_e32 v85, v93, v85
	v_max_u32_e32 v93, v78, v94
	v_min_u32_e32 v78, v78, v94
	v_max_u32_e32 v94, v95, v79
	v_min_u32_e32 v79, v95, v79
	v_max_u32_e32 v95, v80, v96
	v_min_u32_e32 v80, v80, v96
	v_max_u32_e32 v96, v97, v81
	v_min_u32_e32 v81, v97, v81
	v_max_u32_e32 v115, v86, v98
	v_min_u32_e32 v86, v86, v98
	v_max_u32_e32 v98, v99, v87
	v_min_u32_e32 v87, v99, v87
	v_max_u32_e32 v99, v88, v100
	v_min_u32_e32 v88, v88, v100
	v_max_u32_e32 v100, v101, v89
	v_min_u32_e32 v89, v101, v89
	v_max_u32_e32 v101, v0, v102
	v_min_u32_e32 v0, v0, v102
	v_max_u32_e32 v102, v103, v1
	v_min_u32_e32 v1, v103, v1
	v_max_u32_e32 v103, v2, v104
	v_min_u32_e32 v2, v2, v104
	v_max_u32_e32 v104, v105, v3
	v_min_u32_e32 v3, v105, v3
	v_max_u32_e32 v97, v106, v83
	v_min_u32_e32 v83, v106, v83
	v_max_u32_e32 v106, v82, v90
; #define CE_DESC(a, b) do { const unsigned _mx = (a) > (b) ? (a) : (b), _mn = (a) > (b) ? (b) : (a); (a) = _mx; (b) = _mn; } while (0)
; __device__ __forceinline__ void sort16_desc(unsigned (&k)[16]) {
; #pragma unroll
;     for (int size = 2; size <= 16; size <<= 1)
; #pragma unroll
;         for (int stride = size >> 1; stride > 0; stride >>= 1)
; #pragma unroll
;             for (int i = 0; i < 16; ++i) { const int j = i ^ stride;
;                 if (j > i) { if ((i & size) == 0) CE_DESC(k[i], k[j]); else CE_DESC(k[j], k[i]); } }
; }
	v_min_u32_e32 v82, v82, v90
	v_max_u32_e32 v90, v85, v91
	v_min_u32_e32 v85, v85, v91
	v_max_u32_e32 v91, v92, v84
	v_min_u32_e32 v84, v92, v84
	v_max_u32_e32 v92, v93, v79
	v_min_u32_e32 v79, v93, v79
	v_max_u32_e32 v93, v78, v94
	v_min_u32_e32 v78, v78, v94
	v_max_u32_e32 v94, v81, v95
	v_min_u32_e32 v81, v81, v95
	v_max_u32_e32 v95, v96, v80
	v_min_u32_e32 v80, v96, v80
	v_max_u32_e32 v105, v115, v87
	v_min_u32_e32 v87, v115, v87
	v_max_u32_e32 v115, v86, v98
	v_min_u32_e32 v86, v86, v98
	v_max_u32_e32 v98, v89, v99
	v_min_u32_e32 v89, v89, v99
	v_max_u32_e32 v99, v100, v88
	v_min_u32_e32 v88, v100, v88
	v_max_u32_e32 v100, v101, v1
	v_min_u32_e32 v1, v101, v1
	v_max_u32_e32 v101, v0, v102
	v_min_u32_e32 v0, v0, v102
	v_max_u32_e32 v102, v3, v103
	v_min_u32_e32 v3, v3, v103
	v_max_u32_e32 v103, v104, v2
	v_min_u32_e32 v2, v104, v2
	v_max_u32_e32 v96, v97, v106
	v_min_u32_e32 v97, v97, v106
	v_max_u32_e32 v106, v83, v82
	v_min_u32_e32 v82, v83, v82
	v_max_u32_e32 v83, v84, v85
	v_min_u32_e32 v84, v84, v85
	v_max_u32_e32 v85, v91, v90
	v_min_u32_e32 v90, v91, v90
	v_max_u32_e32 v91, v92, v93
	v_min_u32_e32 v92, v92, v93
	v_max_u32_e32 v93, v79, v78
	v_min_u32_e32 v78, v79, v78
	v_max_u32_e32 v79, v80, v81
	v_min_u32_e32 v80, v80, v81
	v_max_u32_e32 v81, v95, v94
	v_min_u32_e32 v94, v95, v94
	v_max_u32_e32 v104, v105, v115
	v_min_u32_e32 v105, v105, v115
	v_max_u32_e32 v115, v87, v86
	v_min_u32_e32 v86, v87, v86
	v_max_u32_e32 v87, v88, v89
	v_min_u32_e32 v88, v88, v89
	v_max_u32_e32 v89, v99, v98
	v_min_u32_e32 v98, v99, v98
	v_max_u32_e32 v99, v100, v101
	v_min_u32_e32 v100, v100, v101
	v_max_u32_e32 v101, v1, v0
	v_min_u32_e32 v0, v1, v0
	v_max_u32_e32 v1, v2, v3
	v_min_u32_e32 v2, v2, v3
	v_max_u32_e32 v3, v103, v102
	v_min_u32_e32 v102, v103, v102
	v_max_u32_e32 v95, v96, v84
	v_min_u32_e32 v84, v96, v84
	v_max_u32_e32 v96, v97, v83
	v_min_u32_e32 v83, v97, v83
	v_max_u32_e32 v97, v106, v90
	v_min_u32_e32 v90, v106, v90
	v_max_u32_e32 v106, v82, v85
	v_min_u32_e32 v82, v82, v85
	v_max_u32_e32 v85, v80, v91
	v_min_u32_e32 v80, v80, v91
	v_max_u32_e32 v91, v79, v92
	v_min_u32_e32 v79, v79, v92
	v_max_u32_e32 v92, v94, v93
	v_min_u32_e32 v93, v94, v93
	v_max_u32_e32 v94, v81, v78
	v_min_u32_e32 v78, v81, v78
	v_max_u32_e32 v103, v104, v88
	v_min_u32_e32 v88, v104, v88
	v_max_u32_e32 v104, v105, v87
	v_min_u32_e32 v87, v105, v87
	v_max_u32_e32 v105, v115, v98
	v_min_u32_e32 v98, v115, v98
	v_max_u32_e32 v115, v86, v89
	v_min_u32_e32 v86, v86, v89
	v_max_u32_e32 v89, v2, v99
	v_min_u32_e32 v2, v2, v99
	v_max_u32_e32 v99, v1, v100
	v_min_u32_e32 v1, v1, v100
	v_max_u32_e32 v100, v102, v101
	v_min_u32_e32 v101, v102, v101
	v_max_u32_e32 v102, v3, v0
	v_min_u32_e32 v0, v3, v0
	v_max_u32_e32 v81, v95, v97
	v_min_u32_e32 v95, v95, v97
	v_max_u32_e32 v97, v96, v106
	v_min_u32_e32 v96, v96, v106
	v_max_u32_e32 v106, v84, v90
	v_min_u32_e32 v84, v84, v90
	v_max_u32_e32 v90, v83, v82
	v_min_u32_e32 v82, v83, v82
	v_max_u32_e32 v83, v93, v80
	v_min_u32_e32 v80, v93, v80
	v_max_u32_e32 v93, v78, v79
	v_min_u32_e32 v78, v78, v79
	v_max_u32_e32 v79, v92, v85
	v_min_u32_e32 v85, v92, v85
	v_max_u32_e32 v92, v94, v91
	v_min_u32_e32 v91, v94, v91
	v_max_u32_e32 v3, v103, v105
	v_min_u32_e32 v103, v103, v105
	v_max_u32_e32 v105, v104, v115
	v_min_u32_e32 v104, v104, v115
	v_max_u32_e32 v115, v88, v98
	v_min_u32_e32 v88, v88, v98
	v_max_u32_e32 v98, v87, v86
	v_min_u32_e32 v86, v87, v86
	v_max_u32_e32 v87, v101, v2
	v_min_u32_e32 v2, v101, v2
	v_max_u32_e32 v101, v0, v1
	v_min_u32_e32 v0, v0, v1
	v_max_u32_e32 v1, v100, v89
	v_min_u32_e32 v89, v100, v89
	v_max_u32_e32 v100, v102, v99
	v_min_u32_e32 v99, v102, v99
	v_max_u32_e32 v94, v81, v97
	v_min_u32_e32 v81, v81, v97
	v_max_u32_e32 v97, v95, v96
	v_min_u32_e32 v95, v95, v96
	v_max_u32_e32 v96, v106, v90
	v_min_u32_e32 v90, v106, v90
	v_max_u32_e32 v106, v84, v82
	v_min_u32_e32 v82, v84, v82
	v_max_u32_e32 v84, v78, v80
	v_min_u32_e32 v78, v78, v80
	v_max_u32_e32 v80, v93, v83
	v_min_u32_e32 v83, v93, v83
	v_max_u32_e32 v93, v91, v85
	v_min_u32_e32 v85, v91, v85
	v_max_u32_e32 v91, v92, v79
	v_min_u32_e32 v79, v92, v79
	v_max_u32_e32 v102, v3, v105
	v_min_u32_e32 v3, v3, v105
	v_max_u32_e32 v105, v103, v104
	v_min_u32_e32 v103, v103, v104
	v_max_u32_e32 v104, v115, v98
	v_min_u32_e32 v98, v115, v98
	v_max_u32_e32 v115, v88, v86
	v_min_u32_e32 v86, v88, v86
	v_max_u32_e32 v88, v0, v2
	v_min_u32_e32 v0, v0, v2
	v_max_u32_e32 v2, v101, v87
	v_min_u32_e32 v87, v101, v87
	v_max_u32_e32 v101, v99, v89
	v_min_u32_e32 v89, v99, v89
	v_max_u32_e32 v99, v100, v1
	v_min_u32_e32 v1, v100, v1
	v_max_u32_e32 v92, v94, v78
	v_min_u32_e32 v78, v94, v78
	v_max_u32_e32 v94, v81, v84
	v_min_u32_e32 v81, v81, v84
	v_max_u32_e32 v84, v97, v83
	v_min_u32_e32 v83, v97, v83
	v_max_u32_e32 v97, v95, v80
	v_min_u32_e32 v80, v95, v80
	v_max_u32_e32 v95, v96, v85
	v_min_u32_e32 v85, v96, v85
	v_max_u32_e32 v96, v90, v93
	v_min_u32_e32 v90, v90, v93
	v_max_u32_e32 v93, v106, v79
	v_min_u32_e32 v79, v106, v79
	v_max_u32_e32 v106, v82, v91
	v_min_u32_e32 v82, v82, v91
	v_max_u32_e32 v100, v102, v0
	v_min_u32_e32 v0, v102, v0
	v_max_u32_e32 v102, v3, v88
	v_min_u32_e32 v3, v3, v88
	v_max_u32_e32 v88, v105, v87
	v_min_u32_e32 v87, v105, v87
	v_max_u32_e32 v105, v103, v2
	v_min_u32_e32 v2, v103, v2
	v_max_u32_e32 v103, v104, v89
	v_min_u32_e32 v89, v104, v89
	v_max_u32_e32 v104, v98, v101
	v_min_u32_e32 v98, v98, v101
	v_max_u32_e32 v101, v115, v1
	v_min_u32_e32 v1, v115, v1
	v_max_u32_e32 v115, v86, v99
	v_min_u32_e32 v86, v86, v99
	v_max_u32_e32 v91, v92, v95
	v_min_u32_e32 v92, v92, v95
	v_max_u32_e32 v95, v94, v96
; #define CE_DESC(a, b) do { const unsigned _mx = (a) > (b) ? (a) : (b), _mn = (a) > (b) ? (b) : (a); (a) = _mx; (b) = _mn; } while (0)
; __device__ __forceinline__ void sort16_desc(unsigned (&k)[16]) {
; #pragma unroll
;     for (int size = 2; size <= 16; size <<= 1)
; #pragma unroll
;         for (int stride = size >> 1; stride > 0; stride >>= 1)
; #pragma unroll
;             for (int i = 0; i < 16; ++i) { const int j = i ^ stride;
;                 if (j > i) { if ((i & size) == 0) CE_DESC(k[i], k[j]); else CE_DESC(k[j], k[i]); } }
; }
; __device__ __forceinline__ void merge16(unsigned (&a)[16], const unsigned (&b)[16]) {
; #pragma unroll
;     for (int i = 0; i < 16; ++i) a[i] = a[i] > b[15 - i] ? a[i] : b[15 - i];
; #pragma unroll
;     for (int stride = 8; stride > 0; stride >>= 1)
; #pragma unroll
;         for (int i = 0; i < 16; ++i) { const int j = i ^ stride; if (j > i) CE_DESC(a[i], a[j]); }
; }
; __device__ __forceinline__ void peer_tile(const Args& A, LAS unsigned char* lds, int tile) {
;     ...
;                 for (int msk = 16; msk <= 32; msk <<= 1) {
; #pragma unroll
;                     for (int i = 0; i < 16; ++i) k1[i] = (unsigned)__shfl_xor((int)k0[i], msk);
;                     merge16(k0, k1); }
	v_min_u32_e32 v94, v94, v96
	v_max_u32_e32 v96, v84, v93
	v_min_u32_e32 v84, v84, v93
	v_max_u32_e32 v93, v97, v106
	v_min_u32_e32 v97, v97, v106
	v_max_u32_e32 v106, v78, v85
	v_min_u32_e32 v78, v78, v85
	v_max_u32_e32 v85, v81, v90
	v_min_u32_e32 v81, v81, v90
	v_max_u32_e32 v90, v83, v79
	v_min_u32_e32 v79, v83, v79
	v_max_u32_e32 v83, v80, v82
	v_min_u32_e32 v80, v80, v82
	v_max_u32_e32 v99, v100, v103
	v_min_u32_e32 v100, v100, v103
	v_max_u32_e32 v103, v102, v104
	v_min_u32_e32 v102, v102, v104
	v_max_u32_e32 v104, v88, v101
	v_min_u32_e32 v88, v88, v101
	v_max_u32_e32 v101, v105, v115
	v_min_u32_e32 v105, v105, v115
	v_max_u32_e32 v115, v0, v89
	v_min_u32_e32 v0, v0, v89
	v_max_u32_e32 v89, v3, v98
	v_min_u32_e32 v3, v3, v98
	v_max_u32_e32 v98, v87, v1
	v_min_u32_e32 v1, v87, v1
	v_max_u32_e32 v87, v2, v86
	v_min_u32_e32 v2, v2, v86
	v_max_u32_e32 v82, v91, v96
	v_min_u32_e32 v91, v91, v96
	v_max_u32_e32 v96, v95, v93
	v_min_u32_e32 v93, v95, v93
	v_max_u32_e32 v95, v92, v84
	v_min_u32_e32 v84, v92, v84
	v_max_u32_e32 v92, v94, v97
	v_min_u32_e32 v94, v94, v97
	v_max_u32_e32 v97, v106, v90
	v_min_u32_e32 v90, v106, v90
	v_max_u32_e32 v106, v85, v83
	v_min_u32_e32 v83, v85, v83
	v_max_u32_e32 v85, v78, v79
	v_min_u32_e32 v78, v78, v79
	v_max_u32_e32 v79, v81, v80
	v_min_u32_e32 v80, v81, v80
	v_max_u32_e32 v86, v99, v104
	v_min_u32_e32 v99, v99, v104
	v_max_u32_e32 v104, v103, v101
	v_min_u32_e32 v101, v103, v101
	v_max_u32_e32 v103, v100, v88
	v_min_u32_e32 v88, v100, v88
	v_max_u32_e32 v100, v102, v105
	v_min_u32_e32 v102, v102, v105
	v_max_u32_e32 v105, v115, v98
	v_min_u32_e32 v98, v115, v98
	v_max_u32_e32 v115, v89, v87
	v_min_u32_e32 v87, v89, v87
	v_max_u32_e32 v89, v0, v1
	v_min_u32_e32 v0, v0, v1
	v_max_u32_e32 v1, v3, v2
	v_min_u32_e32 v2, v3, v2
	v_min_u32_e32 v81, v82, v96
	v_min_u32_e32 v107, v91, v93
	v_min_u32_e32 v108, v95, v92
	v_min_u32_e32 v109, v84, v94
	v_min_u32_e32 v110, v97, v106
	v_min_u32_e32 v111, v90, v83
	v_min_u32_e32 v112, v85, v79
	v_min_u32_e32 v114, v78, v80
	v_min_u32_e32 v3, v86, v104
	v_min_u32_e32 v116, v99, v101
	v_min_u32_e32 v117, v103, v100
	v_min_u32_e32 v118, v88, v102
	v_min_u32_e32 v119, v105, v115
	v_min_u32_e32 v120, v98, v87
	v_min_u32_e32 v121, v89, v1
	v_min_u32_e32 v122, v0, v2
	v_max3_u32 v82, v82, v96, v122
	v_max3_u32 v0, v81, v0, v2
	v_max3_u32 v2, v91, v93, v121
	v_max3_u32 v1, v107, v89, v1
	v_max3_u32 v81, v95, v92, v120
	v_max3_u32 v87, v108, v98, v87
	v_max3_u32 v84, v84, v94, v119
	v_max3_u32 v89, v109, v105, v115
	v_max3_u32 v91, v97, v106, v118
	v_max3_u32 v88, v110, v88, v102
	v_max3_u32 v83, v90, v83, v117
	v_max3_u32 v90, v111, v103, v100
	v_max3_u32 v79, v85, v79, v116
	v_max3_u32 v85, v112, v99, v101
	v_max3_u32 v3, v78, v80, v3
	v_max3_u32 v78, v114, v86, v104
	v_max_u32_e32 v80, v82, v91
	v_min_u32_e32 v82, v82, v91
	v_max_u32_e32 v86, v0, v88
	v_min_u32_e32 v0, v0, v88
	v_max_u32_e32 v88, v2, v83
	v_min_u32_e32 v2, v2, v83
	v_max_u32_e32 v83, v1, v90
	v_min_u32_e32 v1, v1, v90
	v_max_u32_e32 v90, v81, v79
	v_min_u32_e32 v79, v81, v79
	v_max_u32_e32 v81, v87, v85
	v_min_u32_e32 v85, v87, v85
	v_max_u32_e32 v87, v84, v3
	v_min_u32_e32 v3, v84, v3
	v_max_u32_e32 v84, v89, v78
	v_min_u32_e32 v78, v89, v78
	v_max_u32_e32 v89, v80, v90
	v_min_u32_e32 v80, v80, v90
	v_max_u32_e32 v90, v86, v81
	v_min_u32_e32 v81, v86, v81
	v_max_u32_e32 v86, v88, v87
	v_min_u32_e32 v87, v88, v87
	v_max_u32_e32 v88, v83, v84
	v_min_u32_e32 v83, v83, v84
	v_max_u32_e32 v84, v82, v79
	v_min_u32_e32 v79, v82, v79
	v_max_u32_e32 v82, v0, v85
	v_min_u32_e32 v0, v0, v85
	v_max_u32_e32 v85, v2, v3
	v_min_u32_e32 v2, v2, v3
	v_max_u32_e32 v3, v1, v78
	v_min_u32_e32 v1, v1, v78
	v_max_u32_e32 v78, v89, v86
	v_min_u32_e32 v86, v89, v86
	v_max_u32_e32 v89, v90, v88
	v_min_u32_e32 v88, v90, v88
	v_max_u32_e32 v90, v80, v87
	v_min_u32_e32 v80, v80, v87
	v_max_u32_e32 v87, v81, v83
	v_min_u32_e32 v81, v81, v83
	v_max_u32_e32 v83, v84, v85
	v_min_u32_e32 v84, v84, v85
	v_max_u32_e32 v85, v82, v3
	v_min_u32_e32 v3, v82, v3
	v_max_u32_e32 v82, v79, v2
	v_min_u32_e32 v2, v79, v2
	v_max_u32_e32 v79, v0, v1
	v_min_u32_e32 v0, v0, v1
	v_max_u32_e32 v1, v78, v89
	v_min_u32_e32 v78, v78, v89
	v_max_u32_e32 v89, v86, v88
	v_min_u32_e32 v86, v86, v88
	v_max_u32_e32 v88, v90, v87
	v_min_u32_e32 v87, v90, v87
	v_max_u32_e32 v90, v80, v81
	v_min_u32_e32 v80, v80, v81
	v_max_u32_e32 v81, v83, v85
	v_min_u32_e32 v83, v83, v85
	v_max_u32_e32 v85, v84, v3
	v_min_u32_e32 v3, v84, v3
	v_max_u32_e32 v84, v82, v79
	v_min_u32_e32 v79, v82, v79
	v_max_u32_e32 v82, v2, v0
	v_min_u32_e32 v0, v2, v0
	ds_bpermute_b32 v2, v27, v1
	ds_bpermute_b32 v91, v27, v78
	ds_bpermute_b32 v92, v27, v89
	ds_bpermute_b32 v93, v27, v86
	ds_bpermute_b32 v94, v27, v88
	ds_bpermute_b32 v95, v27, v87
	ds_bpermute_b32 v96, v27, v90
	ds_bpermute_b32 v97, v27, v80
	ds_bpermute_b32 v98, v27, v81
	ds_bpermute_b32 v99, v27, v83
	ds_bpermute_b32 v100, v27, v85
	ds_bpermute_b32 v101, v27, v0
	ds_bpermute_b32 v102, v27, v82
	ds_bpermute_b32 v103, v27, v79
	ds_bpermute_b32 v104, v27, v84
	ds_bpermute_b32 v105, v27, v3
	s_waitcnt lgkmcnt(4)
	v_max_u32_e32 v1, v1, v101
	s_waitcnt lgkmcnt(3)
	v_max_u32_e32 v78, v78, v102
	s_waitcnt lgkmcnt(2)
	v_max_u32_e32 v89, v89, v103
	s_waitcnt lgkmcnt(1)
	v_max_u32_e32 v86, v86, v104
	s_waitcnt lgkmcnt(0)
; #define CE_DESC(a, b) do { const unsigned _mx = (a) > (b) ? (a) : (b), _mn = (a) > (b) ? (b) : (a); (a) = _mx; (b) = _mn; } while (0)
; __device__ __forceinline__ void merge16(unsigned (&a)[16], const unsigned (&b)[16]) {
; #pragma unroll
;     for (int i = 0; i < 16; ++i) a[i] = a[i] > b[15 - i] ? a[i] : b[15 - i];
; #pragma unroll
;     for (int stride = 8; stride > 0; stride >>= 1)
; #pragma unroll
;         for (int i = 0; i < 16; ++i) { const int j = i ^ stride; if (j > i) CE_DESC(a[i], a[j]); }
; }
; __device__ __forceinline__ void peer_tile(const Args& A, LAS unsigned char* lds, int tile) {
;     ...
;                 { const bf16_t* sp = QRY + m * 2048 + hp * 128 + 32 * g;
;                   const u32x4 s0 = *(const u32x4*)sp, s1 = *(const u32x4*)(sp + 8), s2 = *(const u32x4*)(sp + 16), s3 = *(const u32x4*)(sp + 24);
;     ...
;                 for (int msk = 16; msk <= 32; msk <<= 1) {
; #pragma unroll
;                     for (int i = 0; i < 16; ++i) k1[i] = (unsigned)__shfl_xor((int)k0[i], msk);
;                     merge16(k0, k1); }
	v_max_u32_e32 v88, v88, v105
	v_max_u32_e32 v87, v87, v100
	v_max_u32_e32 v90, v90, v99
	v_max_u32_e32 v80, v80, v98
	v_max_u32_e32 v81, v81, v97
	v_max_u32_e32 v83, v83, v96
	v_max_u32_e32 v85, v85, v95
	v_max_u32_e32 v3, v3, v94
	v_max_u32_e32 v84, v84, v93
	v_max_u32_e32 v79, v79, v92
	v_max_u32_e32 v82, v82, v91
	v_max_u32_e32 v0, v0, v2
	v_max_u32_e32 v2, v1, v81
	v_min_u32_e32 v1, v1, v81
	v_max_u32_e32 v81, v78, v83
	v_min_u32_e32 v78, v78, v83
	v_max_u32_e32 v83, v89, v85
	v_min_u32_e32 v85, v89, v85
	v_max_u32_e32 v89, v86, v3
	v_min_u32_e32 v3, v86, v3
	v_max_u32_e32 v86, v88, v84
	v_min_u32_e32 v84, v88, v84
	v_max_u32_e32 v88, v87, v79
	v_min_u32_e32 v79, v87, v79
	v_max_u32_e32 v87, v90, v82
	v_min_u32_e32 v82, v90, v82
	v_max_u32_e32 v90, v80, v0
	v_min_u32_e32 v0, v80, v0
	v_max_u32_e32 v80, v2, v86
	v_min_u32_e32 v2, v2, v86
	v_max_u32_e32 v86, v81, v88
	v_min_u32_e32 v81, v81, v88
	v_max_u32_e32 v88, v83, v87
	v_min_u32_e32 v83, v83, v87
	v_max_u32_e32 v87, v89, v90
	v_min_u32_e32 v89, v89, v90
	v_max_u32_e32 v90, v1, v84
	v_min_u32_e32 v1, v1, v84
	v_max_u32_e32 v84, v78, v79
	v_min_u32_e32 v78, v78, v79
	v_max_u32_e32 v79, v85, v82
	v_min_u32_e32 v82, v85, v82
	v_max_u32_e32 v85, v3, v0
	v_min_u32_e32 v0, v3, v0
	v_max_u32_e32 v3, v80, v88
	v_min_u32_e32 v80, v80, v88
	v_max_u32_e32 v88, v86, v87
	v_min_u32_e32 v86, v86, v87
	v_max_u32_e32 v87, v2, v83
	v_min_u32_e32 v2, v2, v83
	v_max_u32_e32 v83, v81, v89
	v_min_u32_e32 v81, v81, v89
	v_max_u32_e32 v89, v90, v79
	v_min_u32_e32 v79, v90, v79
	v_max_u32_e32 v90, v84, v85
	v_min_u32_e32 v84, v84, v85
	v_max_u32_e32 v85, v1, v82
	v_min_u32_e32 v1, v1, v82
	v_max_u32_e32 v82, v78, v0
	v_min_u32_e32 v0, v78, v0
	v_max_u32_e32 v78, v3, v88
	v_min_u32_e32 v3, v3, v88
	v_max_u32_e32 v88, v80, v86
	v_min_u32_e32 v80, v80, v86
	v_max_u32_e32 v86, v87, v83
	v_min_u32_e32 v83, v87, v83
	v_max_u32_e32 v87, v2, v81
	v_min_u32_e32 v2, v2, v81
	v_max_u32_e32 v81, v89, v90
	v_min_u32_e32 v89, v89, v90
	v_max_u32_e32 v90, v79, v84
	v_min_u32_e32 v79, v79, v84
	v_max_u32_e32 v84, v85, v82
	v_min_u32_e32 v82, v85, v82
	v_max_u32_e32 v85, v1, v0
	v_min_u32_e32 v0, v1, v0
	ds_bpermute_b32 v94, v29, v0
	ds_bpermute_b32 v1, v29, v78
	ds_bpermute_b32 v91, v29, v3
	ds_bpermute_b32 v92, v29, v88
	ds_bpermute_b32 v93, v29, v80
	s_waitcnt lgkmcnt(4)
	v_max_u32_e32 v78, v78, v94
	global_load_dwordx4 v[94:97], v[4:5], off offset:1040
	global_load_dwordx4 v[98:101], v[4:5], off offset:1024
	ds_bpermute_b32 v102, v29, v86
	ds_bpermute_b32 v103, v29, v83
	ds_bpermute_b32 v104, v29, v87
	ds_bpermute_b32 v105, v29, v2
	ds_bpermute_b32 v106, v29, v81
	ds_bpermute_b32 v107, v29, v89
	ds_bpermute_b32 v108, v29, v90
	ds_bpermute_b32 v109, v29, v79
	ds_bpermute_b32 v110, v29, v84
	ds_bpermute_b32 v111, v29, v85
	ds_bpermute_b32 v112, v29, v82
	s_waitcnt lgkmcnt(4)
	v_max_u32_e32 v83, v83, v108
	s_waitcnt lgkmcnt(3)
	v_max_u32_e32 v86, v86, v109
	s_waitcnt lgkmcnt(2)
	v_max_u32_e32 v80, v80, v110
	s_waitcnt lgkmcnt(1)
	v_max_u32_e32 v3, v3, v111
	s_waitcnt lgkmcnt(0)
	v_max_u32_e32 v88, v88, v112
	v_max_u32_e32 v87, v87, v107
	v_max_u32_e32 v2, v2, v106
	v_max_u32_e32 v81, v81, v105
	v_max_u32_e32 v89, v89, v104
	v_max_u32_e32 v90, v90, v103
	v_max_u32_e32 v79, v79, v102
	v_max_u32_e32 v84, v84, v93
	v_max_u32_e32 v82, v82, v92
	v_max_u32_e32 v85, v85, v91
	v_max_u32_e32 v0, v0, v1
	v_max_u32_e32 v1, v78, v81
	v_min_u32_e32 v78, v78, v81
	v_max_u32_e32 v81, v3, v89
	v_min_u32_e32 v3, v3, v89
	v_max_u32_e32 v89, v88, v90
	v_min_u32_e32 v88, v88, v90
	v_max_u32_e32 v90, v80, v79
	v_min_u32_e32 v79, v80, v79
	v_max_u32_e32 v80, v86, v84
	v_min_u32_e32 v84, v86, v84
	v_max_u32_e32 v86, v83, v82
	v_min_u32_e32 v82, v83, v82
	v_max_u32_e32 v83, v87, v85
	v_min_u32_e32 v85, v87, v85
	v_max_u32_e32 v87, v2, v0
	v_min_u32_e32 v0, v2, v0
	v_max_u32_e32 v2, v1, v80
	v_min_u32_e32 v1, v1, v80
	v_max_u32_e32 v80, v81, v86
	v_min_u32_e32 v81, v81, v86
	v_max_u32_e32 v86, v89, v83
	v_min_u32_e32 v83, v89, v83
	v_max_u32_e32 v89, v90, v87
	v_min_u32_e32 v87, v90, v87
	v_max_u32_e32 v90, v78, v84
	v_min_u32_e32 v78, v78, v84
	v_max_u32_e32 v84, v3, v82
	v_min_u32_e32 v3, v3, v82
	v_max_u32_e32 v82, v88, v85
	v_min_u32_e32 v85, v88, v85
	v_max_u32_e32 v88, v79, v0
	v_min_u32_e32 v0, v79, v0
	v_max_u32_e32 v79, v2, v86
	v_min_u32_e32 v2, v2, v86
	v_max_u32_e32 v86, v80, v89
	v_min_u32_e32 v80, v80, v89
	v_max_u32_e32 v102, v1, v83
	v_min_u32_e32 v1, v1, v83
	v_max_u32_e32 v83, v81, v87
	v_min_u32_e32 v81, v81, v87
	v_max_u32_e32 v103, v90, v82
	v_min_u32_e32 v82, v90, v82
	v_max_u32_e32 v104, v84, v88
	v_min_u32_e32 v105, v84, v88
	v_max_u32_e32 v106, v78, v85
	v_min_u32_e32 v78, v78, v85
	v_max_u32_e32 v107, v3, v0
	v_min_u32_e32 v0, v3, v0
	v_max_u32_e32 v93, v79, v86
	v_min_u32_e32 v92, v79, v86
	v_max_u32_e32 v91, v2, v80
	v_min_u32_e32 v90, v2, v80
	v_max_u32_e32 v89, v102, v83
	v_min_u32_e32 v88, v102, v83
	v_max_u32_e32 v87, v1, v81
	v_min_u32_e32 v86, v1, v81
	v_max_u32_e32 v85, v103, v104
	v_min_u32_e32 v84, v103, v104
	v_max_u32_e32 v83, v82, v105
	v_min_u32_e32 v82, v82, v105
	v_max_u32_e32 v79, v78, v0
	v_min_u32_e32 v78, v78, v0
	global_load_dwordx4 v[0:3], v[4:5], off offset:1072
	global_load_dwordx4 v[102:105], v[4:5], off offset:1056
	v_max_u32_e32 v81, v106, v107
	v_min_u32_e32 v80, v106, v107
	s_waitcnt vmcnt(2)
; __device__ __forceinline__ unsigned f2key(float f) { const unsigned u = __float_as_uint(f); return (u & 0x80000000u) ? ~u : (u | 0x80000000u); }
; __device__ __forceinline__ void peer_tile(const Args& A, LAS unsigned char* lds, int tile) {
;     ...
;                 { const bf16_t* sp = QRY + m * 2048 + hp * 128 + 32 * g;
;                   const u32x4 s0 = *(const u32x4*)sp, s1 = *(const u32x4*)(sp + 8), s2 = *(const u32x4*)(sp + 16), s3 = *(const u32x4*)(sp + 24);
;                   const unsigned sw[16] = {s0.x, s0.y, s0.z, s0.w, s1.x, s1.y, s1.z, s1.w, s2.x, s2.y, s2.z, s2.w, s3.x, s3.y, s3.z, s3.w};
; #pragma unroll
;                   for (int i = 0; i < 16; ++i) {
;                       const float lo = (float)__builtin_bit_cast(_Float16, (unsigned short)(sw[i] & 0xffffu)), hi = (float)__builtin_bit_cast(_Float16, (unsigned short)(sw[i] >> 16));
;                       const unsigned klo = (f2key(lo) & ~127u) | (unsigned)(127 - (32 * g + 2 * i)), khi = (f2key(hi) & ~127u) | (unsigned)(127 - (32 * g + 2 * i + 1));
;                       if (i < 8) { k0[2 * i] = klo; k0[2 * i + 1] = khi; } else { k1[2 * (i - 8)] = klo; k1[2 * (i - 8) + 1] = khi; } } }
;     ...
;                 for (int i = 0; i < 16; ++i) L2[p][i] = (g & 2) ? ((g & 1) ? LA[3][p][i] : LA[2][p][i]) : ((g & 1) ? LA[1][p][i] : LA[0][p][i]);
	v_cvt_f32_f16_sdwa v106, v98 dst_sel:DWORD dst_unused:UNUSED_PAD src0_sel:WORD_1
	v_cvt_f32_f16_e32 v98, v98
	v_cndmask_b32_e64 v34, v66, v34, s[0:1]
	v_cndmask_b32_e64 v33, v65, v33, s[0:1]
	v_not_b32_e32 v107, v106
	v_or_b32_e32 v108, 0x80000000, v106
	v_cmp_gt_i32_e32 vcc, 0, v106
	v_cndmask_b32_e64 v32, v64, v32, s[0:1]
	v_cndmask_b32_e64 v31, v63, v31, s[0:1]
	v_cndmask_b32_e32 v106, v108, v107, vcc
	v_not_b32_e32 v107, v98
	v_or_b32_e32 v108, 0x80000000, v98
	v_cmp_gt_i32_e32 vcc, 0, v98
	v_and_b32_e32 v106, 0xffffff80, v106
	v_sub_u32_e32 v106, v106, v15
	v_cndmask_b32_e32 v98, v108, v107, vcc
	v_cvt_f32_f16_sdwa v107, v99 dst_sel:DWORD dst_unused:UNUSED_PAD src0_sel:WORD_1
	v_cvt_f32_f16_e32 v99, v99
	v_and_b32_e32 v98, 0xffffff80, v98
	v_sub_u32_e32 v98, v98, v15
	v_not_b32_e32 v108, v107
	v_or_b32_e32 v109, 0x80000000, v107
	v_cmp_gt_i32_e32 vcc, 0, v107
	v_add_u32_e32 v106, 0x7e, v106
	v_add_u32_e32 v98, 0x7f, v98
	v_cndmask_b32_e32 v107, v109, v108, vcc
	v_not_b32_e32 v108, v99
	v_or_b32_e32 v109, 0x80000000, v99
	v_cmp_gt_i32_e32 vcc, 0, v99
	v_and_b32_e32 v107, 0xffffff80, v107
	v_sub_u32_e32 v107, v107, v14
	v_cndmask_b32_e32 v99, v109, v108, vcc
	v_cvt_f32_f16_sdwa v108, v100 dst_sel:DWORD dst_unused:UNUSED_PAD src0_sel:WORD_1
	v_cvt_f32_f16_e32 v100, v100
	v_and_b32_e32 v99, 0xffffff80, v99
	v_sub_u32_e32 v99, v99, v14
	v_not_b32_e32 v109, v108
	v_or_b32_e32 v110, 0x80000000, v108
	v_cmp_gt_i32_e32 vcc, 0, v108
	v_add_u32_e32 v107, 0x7e, v107
	v_add_u32_e32 v99, 0x7f, v99
	v_cndmask_b32_e32 v108, v110, v109, vcc
	v_not_b32_e32 v109, v100
	v_or_b32_e32 v110, 0x80000000, v100
	v_cmp_gt_i32_e32 vcc, 0, v100
	v_and_b32_e32 v108, 0xffffff80, v108
	v_sub_u32_e32 v108, v108, v12
	v_cndmask_b32_e32 v100, v110, v109, vcc
	v_cvt_f32_f16_sdwa v109, v101 dst_sel:DWORD dst_unused:UNUSED_PAD src0_sel:WORD_1
	v_cvt_f32_f16_e32 v101, v101
	v_and_b32_e32 v100, 0xffffff80, v100
	v_sub_u32_e32 v100, v100, v12
	v_not_b32_e32 v110, v109
	v_or_b32_e32 v111, 0x80000000, v109
	v_cmp_gt_i32_e32 vcc, 0, v109
	v_add_u32_e32 v108, 0x7e, v108
	v_add_u32_e32 v100, 0x7f, v100
	v_cndmask_b32_e32 v109, v111, v110, vcc
	v_not_b32_e32 v110, v101
	v_or_b32_e32 v111, 0x80000000, v101
	v_cmp_gt_i32_e32 vcc, 0, v101
	v_and_b32_e32 v109, 0xffffff80, v109
	v_sub_u32_e32 v109, v109, v10
	v_cndmask_b32_e32 v101, v111, v110, vcc
	v_cvt_f32_f16_sdwa v110, v94 dst_sel:DWORD dst_unused:UNUSED_PAD src0_sel:WORD_1
	v_cvt_f32_f16_e32 v94, v94
	v_and_b32_e32 v101, 0xffffff80, v101
	v_sub_u32_e32 v101, v101, v10
	v_not_b32_e32 v111, v110
	v_or_b32_e32 v112, 0x80000000, v110
	v_cmp_gt_i32_e32 vcc, 0, v110
	v_add_u32_e32 v109, 0x7e, v109
	v_add_u32_e32 v101, 0x7f, v101
	v_cndmask_b32_e32 v110, v112, v111, vcc
	v_not_b32_e32 v111, v94
	v_or_b32_e32 v112, 0x80000000, v94
	v_cmp_gt_i32_e32 vcc, 0, v94
	v_and_b32_e32 v110, 0xffffff80, v110
	v_sub_u32_e32 v110, v110, v8
	v_cndmask_b32_e32 v94, v112, v111, vcc
	v_cvt_f32_f16_sdwa v111, v95 dst_sel:DWORD dst_unused:UNUSED_PAD src0_sel:WORD_1
	v_cvt_f32_f16_e32 v95, v95
	v_and_b32_e32 v94, 0xffffff80, v94
	v_sub_u32_e32 v94, v94, v8
	v_not_b32_e32 v112, v111
	v_or_b32_e32 v114, 0x80000000, v111
	v_cmp_gt_i32_e32 vcc, 0, v111
	v_add_u32_e32 v110, 0x7e, v110
	v_add_u32_e32 v94, 0x7f, v94
	v_cndmask_b32_e32 v111, v114, v112, vcc
	v_not_b32_e32 v112, v95
	v_or_b32_e32 v114, 0x80000000, v95
	v_cmp_gt_i32_e32 vcc, 0, v95
	v_and_b32_e32 v111, 0xffffff80, v111
	v_sub_u32_e32 v111, v111, v16
	v_cndmask_b32_e32 v95, v114, v112, vcc
	v_cvt_f32_f16_sdwa v112, v96 dst_sel:DWORD dst_unused:UNUSED_PAD src0_sel:WORD_1
	v_cvt_f32_f16_e32 v96, v96
	v_and_b32_e32 v95, 0xffffff80, v95
	v_sub_u32_e32 v95, v95, v16
	v_not_b32_e32 v114, v112
	v_or_b32_e32 v115, 0x80000000, v112
	v_cmp_gt_i32_e32 vcc, 0, v112
	v_add_u32_e32 v111, 0x7e, v111
	v_add_u32_e32 v95, 0x7f, v95
	v_cndmask_b32_e32 v112, v115, v114, vcc
	v_not_b32_e32 v114, v96
	v_or_b32_e32 v115, 0x80000000, v96
	v_cmp_gt_i32_e32 vcc, 0, v96
	v_and_b32_e32 v112, 0xffffff80, v112
	v_sub_u32_e32 v112, v112, v17
	v_cndmask_b32_e32 v96, v115, v114, vcc
	v_cvt_f32_f16_sdwa v114, v97 dst_sel:DWORD dst_unused:UNUSED_PAD src0_sel:WORD_1
	v_cvt_f32_f16_e32 v97, v97
	v_and_b32_e32 v96, 0xffffff80, v96
	v_sub_u32_e32 v96, v96, v17
	v_not_b32_e32 v115, v114
	v_or_b32_e32 v116, 0x80000000, v114
	v_cmp_gt_i32_e32 vcc, 0, v114
	v_add_u32_e32 v112, 0x7e, v112
	v_add_u32_e32 v96, 0x7f, v96
	v_cndmask_b32_e32 v114, v116, v115, vcc
	v_not_b32_e32 v115, v97
	v_or_b32_e32 v116, 0x80000000, v97
	v_cmp_gt_i32_e32 vcc, 0, v97
	v_and_b32_e32 v114, 0xffffff80, v114
	v_sub_u32_e32 v114, v114, v18
	v_cndmask_b32_e32 v97, v116, v115, vcc
	s_waitcnt vmcnt(0)
; __device__ __forceinline__ unsigned f2key(float f) { const unsigned u = __float_as_uint(f); return (u & 0x80000000u) ? ~u : (u | 0x80000000u); }
; #define CE_DESC(a, b) do { const unsigned _mx = (a) > (b) ? (a) : (b), _mn = (a) > (b) ? (b) : (a); (a) = _mx; (b) = _mn; } while (0)
; __device__ __forceinline__ void sort16_desc(unsigned (&k)[16]) {
; #pragma unroll
;     for (int size = 2; size <= 16; size <<= 1)
; #pragma unroll
;         for (int stride = size >> 1; stride > 0; stride >>= 1)
; #pragma unroll
;             for (int i = 0; i < 16; ++i) { const int j = i ^ stride;
;                 if (j > i) { if ((i & size) == 0) CE_DESC(k[i], k[j]); else CE_DESC(k[j], k[i]); } }
; }
; __device__ __forceinline__ void peer_tile(const Args& A, LAS unsigned char* lds, int tile) {
;     ...
;                 { const bf16_t* sp = QRY + m * 2048 + hp * 128 + 32 * g;
;                   const u32x4 s0 = *(const u32x4*)sp, s1 = *(const u32x4*)(sp + 8), s2 = *(const u32x4*)(sp + 16), s3 = *(const u32x4*)(sp + 24);
;                   const unsigned sw[16] = {s0.x, s0.y, s0.z, s0.w, s1.x, s1.y, s1.z, s1.w, s2.x, s2.y, s2.z, s2.w, s3.x, s3.y, s3.z, s3.w};
; #pragma unroll
;                   for (int i = 0; i < 16; ++i) {
;                       const float lo = (float)__builtin_bit_cast(_Float16, (unsigned short)(sw[i] & 0xffffu)), hi = (float)__builtin_bit_cast(_Float16, (unsigned short)(sw[i] >> 16));
;                       const unsigned klo = (f2key(lo) & ~127u) | (unsigned)(127 - (32 * g + 2 * i)), khi = (f2key(hi) & ~127u) | (unsigned)(127 - (32 * g + 2 * i + 1));
;                       if (i < 8) { k0[2 * i] = klo; k0[2 * i + 1] = khi; } else { k1[2 * (i - 8)] = klo; k1[2 * (i - 8) + 1] = khi; } } }
;                 sort16_desc(k0); sort16_desc(k1); merge16(k0, k1);
	v_cvt_f32_f16_sdwa v115, v102 dst_sel:DWORD dst_unused:UNUSED_PAD src0_sel:WORD_1
	v_cvt_f32_f16_e32 v102, v102
	v_and_b32_e32 v97, 0xffffff80, v97
	v_sub_u32_e32 v97, v97, v18
	v_not_b32_e32 v116, v115
	v_or_b32_e32 v117, 0x80000000, v115
	v_cmp_gt_i32_e32 vcc, 0, v115
	v_add_u32_e32 v114, 0x7e, v114
	v_add_u32_e32 v97, 0x7f, v97
	v_cndmask_b32_e32 v115, v117, v116, vcc
	v_not_b32_e32 v116, v102
	v_or_b32_e32 v117, 0x80000000, v102
	v_cmp_gt_i32_e32 vcc, 0, v102
	v_and_b32_e32 v115, 0xffffff80, v115
	v_sub_u32_e32 v115, v115, v20
	v_cndmask_b32_e32 v102, v117, v116, vcc
	v_cvt_f32_f16_sdwa v116, v103 dst_sel:DWORD dst_unused:UNUSED_PAD src0_sel:WORD_1
	v_cvt_f32_f16_e32 v103, v103
	v_and_b32_e32 v102, 0xffffff80, v102
	v_sub_u32_e32 v102, v102, v20
	v_not_b32_e32 v117, v116
	v_or_b32_e32 v118, 0x80000000, v116
	v_cmp_gt_i32_e32 vcc, 0, v116
	v_add_u32_e32 v115, 0x7e, v115
	v_add_u32_e32 v102, 0x7f, v102
	v_cndmask_b32_e32 v116, v118, v117, vcc
	v_not_b32_e32 v117, v103
	v_or_b32_e32 v118, 0x80000000, v103
	v_cmp_gt_i32_e32 vcc, 0, v103
	v_and_b32_e32 v116, 0xffffff80, v116
	v_sub_u32_e32 v116, v116, v21
	v_cndmask_b32_e32 v103, v118, v117, vcc
	v_cvt_f32_f16_sdwa v117, v104 dst_sel:DWORD dst_unused:UNUSED_PAD src0_sel:WORD_1
	v_cvt_f32_f16_e32 v104, v104
	v_and_b32_e32 v103, 0xffffff80, v103
	v_sub_u32_e32 v103, v103, v21
	v_not_b32_e32 v118, v117
	v_or_b32_e32 v119, 0x80000000, v117
	v_cmp_gt_i32_e32 vcc, 0, v117
	v_add_u32_e32 v116, 0x7e, v116
	v_add_u32_e32 v103, 0x7f, v103
	v_cndmask_b32_e32 v117, v119, v118, vcc
	v_not_b32_e32 v118, v104
	v_or_b32_e32 v119, 0x80000000, v104
	v_cmp_gt_i32_e32 vcc, 0, v104
	v_and_b32_e32 v117, 0xffffff80, v117
	v_sub_u32_e32 v117, v117, v22
	v_cndmask_b32_e32 v104, v119, v118, vcc
	v_cvt_f32_f16_sdwa v118, v105 dst_sel:DWORD dst_unused:UNUSED_PAD src0_sel:WORD_1
	v_cvt_f32_f16_e32 v105, v105
	v_and_b32_e32 v104, 0xffffff80, v104
	v_sub_u32_e32 v104, v104, v22
	v_not_b32_e32 v119, v118
	v_or_b32_e32 v120, 0x80000000, v118
	v_cmp_gt_i32_e32 vcc, 0, v118
	v_add_u32_e32 v117, 0x7e, v117
	v_add_u32_e32 v104, 0x7f, v104
	v_cndmask_b32_e32 v118, v120, v119, vcc
	v_not_b32_e32 v119, v105
	v_or_b32_e32 v120, 0x80000000, v105
	v_cmp_gt_i32_e32 vcc, 0, v105
	v_and_b32_e32 v118, 0xffffff80, v118
	v_sub_u32_e32 v118, v118, v23
	v_cndmask_b32_e32 v105, v120, v119, vcc
	v_cvt_f32_f16_sdwa v119, v0 dst_sel:DWORD dst_unused:UNUSED_PAD src0_sel:WORD_1
	v_cvt_f32_f16_e32 v0, v0
	v_and_b32_e32 v105, 0xffffff80, v105
	v_sub_u32_e32 v105, v105, v23
	v_not_b32_e32 v120, v119
	v_or_b32_e32 v121, 0x80000000, v119
	v_cmp_gt_i32_e32 vcc, 0, v119
	v_add_u32_e32 v118, 0x7e, v118
	v_add_u32_e32 v105, 0x7f, v105
	v_cndmask_b32_e32 v119, v121, v120, vcc
	v_not_b32_e32 v120, v0
	v_or_b32_e32 v121, 0x80000000, v0
	v_cmp_gt_i32_e32 vcc, 0, v0
	v_and_b32_e32 v119, 0xffffff80, v119
	v_sub_u32_e32 v119, v119, v24
	v_cndmask_b32_e32 v0, v121, v120, vcc
	v_cvt_f32_f16_sdwa v120, v1 dst_sel:DWORD dst_unused:UNUSED_PAD src0_sel:WORD_1
	v_cvt_f32_f16_e32 v1, v1
	v_and_b32_e32 v0, 0xffffff80, v0
	v_sub_u32_e32 v0, v0, v24
	v_not_b32_e32 v121, v120
	v_or_b32_e32 v122, 0x80000000, v120
	v_cmp_gt_i32_e32 vcc, 0, v120
	v_add_u32_e32 v119, 0x7e, v119
	v_add_u32_e32 v0, 0x7f, v0
	v_cndmask_b32_e32 v120, v122, v121, vcc
	v_not_b32_e32 v121, v1
	v_or_b32_e32 v122, 0x80000000, v1
	v_cmp_gt_i32_e32 vcc, 0, v1
	v_and_b32_e32 v120, 0xffffff80, v120
	v_sub_u32_e32 v120, v120, v25
	v_cndmask_b32_e32 v1, v122, v121, vcc
	v_cvt_f32_f16_sdwa v121, v2 dst_sel:DWORD dst_unused:UNUSED_PAD src0_sel:WORD_1
	v_cvt_f32_f16_e32 v2, v2
	v_and_b32_e32 v1, 0xffffff80, v1
	v_sub_u32_e32 v1, v1, v25
	v_not_b32_e32 v122, v121
	v_or_b32_e32 v123, 0x80000000, v121
	v_cmp_gt_i32_e32 vcc, 0, v121
	v_add_u32_e32 v120, 0x7e, v120
	v_add_u32_e32 v1, 0x7f, v1
	v_cndmask_b32_e32 v121, v123, v122, vcc
	v_not_b32_e32 v122, v2
	v_or_b32_e32 v123, 0x80000000, v2
	v_cmp_gt_i32_e32 vcc, 0, v2
	v_and_b32_e32 v121, 0xffffff80, v121
	v_sub_u32_e32 v121, v121, v26
	v_cndmask_b32_e32 v2, v123, v122, vcc
	v_cvt_f32_f16_sdwa v122, v3 dst_sel:DWORD dst_unused:UNUSED_PAD src0_sel:WORD_1
	v_cvt_f32_f16_e32 v3, v3
	v_and_b32_e32 v2, 0xffffff80, v2
	v_sub_u32_e32 v2, v2, v26
	v_not_b32_e32 v123, v122
	v_or_b32_e32 v124, 0x80000000, v122
	v_cmp_gt_i32_e32 vcc, 0, v122
	v_add_u32_e32 v121, 0x7e, v121
	v_add_u32_e32 v2, 0x7f, v2
	v_cndmask_b32_e32 v122, v124, v123, vcc
	v_not_b32_e32 v123, v3
	v_or_b32_e32 v124, 0x80000000, v3
	v_cmp_gt_i32_e32 vcc, 0, v3
	v_and_b32_e32 v122, 0xffffff80, v122
	v_sub_u32_e32 v122, v122, v28
	v_cndmask_b32_e32 v3, v124, v123, vcc
	v_and_b32_e32 v3, 0xffffff80, v3
	v_sub_u32_e32 v3, v3, v28
	v_add_u32_e32 v122, 0x7e, v122
	v_add_u32_e32 v3, 0x7f, v3
	v_max_u32_e32 v123, v98, v106
	v_min_u32_e32 v98, v98, v106
	v_max_u32_e32 v106, v107, v99
	v_min_u32_e32 v99, v107, v99
	v_max_u32_e32 v107, v100, v108
	v_min_u32_e32 v100, v100, v108
	v_max_u32_e32 v108, v109, v101
	v_min_u32_e32 v101, v109, v101
	v_max_u32_e32 v109, v94, v110
	v_min_u32_e32 v94, v94, v110
	v_max_u32_e32 v110, v111, v95
	v_min_u32_e32 v95, v111, v95
	v_max_u32_e32 v111, v96, v112
	v_min_u32_e32 v96, v96, v112
	v_max_u32_e32 v112, v114, v97
	v_min_u32_e32 v97, v114, v97
	v_max_u32_e32 v131, v102, v115
	v_min_u32_e32 v102, v102, v115
	v_max_u32_e32 v115, v116, v103
	v_min_u32_e32 v103, v116, v103
	v_max_u32_e32 v116, v104, v117
	v_min_u32_e32 v104, v104, v117
	v_max_u32_e32 v117, v118, v105
	v_min_u32_e32 v105, v118, v105
	v_max_u32_e32 v118, v0, v119
	v_min_u32_e32 v0, v0, v119
	v_max_u32_e32 v119, v120, v1
	v_min_u32_e32 v1, v120, v1
	v_max_u32_e32 v120, v2, v121
	v_min_u32_e32 v2, v2, v121
; #define CE_DESC(a, b) do { const unsigned _mx = (a) > (b) ? (a) : (b), _mn = (a) > (b) ? (b) : (a); (a) = _mx; (b) = _mn; } while (0)
; __device__ __forceinline__ void sort16_desc(unsigned (&k)[16]) {
; #pragma unroll
;     for (int size = 2; size <= 16; size <<= 1)
; #pragma unroll
;         for (int stride = size >> 1; stride > 0; stride >>= 1)
; #pragma unroll
;             for (int i = 0; i < 16; ++i) { const int j = i ^ stride;
;                 if (j > i) { if ((i & size) == 0) CE_DESC(k[i], k[j]); else CE_DESC(k[j], k[i]); } }
; }
	v_max_u32_e32 v121, v122, v3
	v_min_u32_e32 v3, v122, v3
	v_max_u32_e32 v114, v123, v99
	v_min_u32_e32 v99, v123, v99
	v_max_u32_e32 v123, v98, v106
	v_min_u32_e32 v98, v98, v106
	v_max_u32_e32 v106, v101, v107
	v_min_u32_e32 v101, v101, v107
	v_max_u32_e32 v107, v108, v100
	v_min_u32_e32 v100, v108, v100
	v_max_u32_e32 v108, v109, v95
	v_min_u32_e32 v95, v109, v95
	v_max_u32_e32 v109, v94, v110
	v_min_u32_e32 v94, v94, v110
	v_max_u32_e32 v110, v97, v111
	v_min_u32_e32 v97, v97, v111
	v_max_u32_e32 v111, v112, v96
	v_min_u32_e32 v96, v112, v96
	v_max_u32_e32 v122, v131, v103
	v_min_u32_e32 v103, v131, v103
	v_max_u32_e32 v131, v102, v115
	v_min_u32_e32 v102, v102, v115
	v_max_u32_e32 v115, v105, v116
	v_min_u32_e32 v105, v105, v116
	v_max_u32_e32 v116, v117, v104
	v_min_u32_e32 v104, v117, v104
	v_max_u32_e32 v117, v118, v1
	v_min_u32_e32 v1, v118, v1
	v_max_u32_e32 v118, v0, v119
	v_min_u32_e32 v0, v0, v119
	v_max_u32_e32 v119, v3, v120
	v_min_u32_e32 v3, v3, v120
	v_max_u32_e32 v120, v121, v2
	v_min_u32_e32 v2, v121, v2
	v_max_u32_e32 v112, v114, v123
	v_min_u32_e32 v114, v114, v123
	v_max_u32_e32 v123, v99, v98
	v_min_u32_e32 v98, v99, v98
	v_max_u32_e32 v99, v100, v101
	v_min_u32_e32 v100, v100, v101
	v_max_u32_e32 v101, v107, v106
	v_min_u32_e32 v106, v107, v106
	v_max_u32_e32 v107, v108, v109
	v_min_u32_e32 v108, v108, v109
	v_max_u32_e32 v109, v95, v94
	v_min_u32_e32 v94, v95, v94
	v_max_u32_e32 v95, v96, v97
	v_min_u32_e32 v96, v96, v97
	v_max_u32_e32 v97, v111, v110
	v_min_u32_e32 v110, v111, v110
	v_max_u32_e32 v121, v122, v131
	v_min_u32_e32 v122, v122, v131
	v_max_u32_e32 v131, v103, v102
	v_min_u32_e32 v102, v103, v102
	v_max_u32_e32 v103, v104, v105
	v_min_u32_e32 v104, v104, v105
	v_max_u32_e32 v105, v116, v115
	v_min_u32_e32 v115, v116, v115
	v_max_u32_e32 v116, v117, v118
	v_min_u32_e32 v117, v117, v118
	v_max_u32_e32 v118, v1, v0
	v_min_u32_e32 v0, v1, v0
	v_max_u32_e32 v1, v2, v3
	v_min_u32_e32 v2, v2, v3
	v_max_u32_e32 v3, v120, v119
	v_min_u32_e32 v119, v120, v119
	v_max_u32_e32 v111, v112, v100
	v_min_u32_e32 v100, v112, v100
	v_max_u32_e32 v112, v114, v99
	v_min_u32_e32 v99, v114, v99
	v_max_u32_e32 v114, v123, v106
	v_min_u32_e32 v106, v123, v106
	v_max_u32_e32 v123, v98, v101
	v_min_u32_e32 v98, v98, v101
	v_max_u32_e32 v101, v96, v107
	v_min_u32_e32 v96, v96, v107
	v_max_u32_e32 v107, v95, v108
	v_min_u32_e32 v95, v95, v108
	v_max_u32_e32 v108, v110, v109
	v_min_u32_e32 v109, v110, v109
	v_max_u32_e32 v110, v97, v94
	v_min_u32_e32 v94, v97, v94
	v_max_u32_e32 v120, v121, v104
	v_min_u32_e32 v104, v121, v104
	v_max_u32_e32 v121, v122, v103
	v_min_u32_e32 v103, v122, v103
	v_max_u32_e32 v122, v131, v115
	v_min_u32_e32 v115, v131, v115
	v_max_u32_e32 v131, v102, v105
	v_min_u32_e32 v102, v102, v105
	v_max_u32_e32 v105, v2, v116
	v_min_u32_e32 v2, v2, v116
	v_max_u32_e32 v116, v1, v117
	v_min_u32_e32 v1, v1, v117
	v_max_u32_e32 v117, v119, v118
	v_min_u32_e32 v118, v119, v118
	v_max_u32_e32 v119, v3, v0
	v_min_u32_e32 v0, v3, v0
	v_max_u32_e32 v97, v111, v114
	v_min_u32_e32 v111, v111, v114
	v_max_u32_e32 v114, v112, v123
	v_min_u32_e32 v112, v112, v123
	v_max_u32_e32 v123, v100, v106
	v_min_u32_e32 v100, v100, v106
	v_max_u32_e32 v106, v99, v98
	v_min_u32_e32 v98, v99, v98
	v_max_u32_e32 v99, v109, v96
	v_min_u32_e32 v96, v109, v96
	v_max_u32_e32 v109, v94, v95
	v_min_u32_e32 v94, v94, v95
	v_max_u32_e32 v95, v108, v101
	v_min_u32_e32 v101, v108, v101
	v_max_u32_e32 v108, v110, v107
	v_min_u32_e32 v107, v110, v107
	v_max_u32_e32 v3, v120, v122
	v_min_u32_e32 v120, v120, v122
	v_max_u32_e32 v122, v121, v131
	v_min_u32_e32 v121, v121, v131
	v_max_u32_e32 v131, v104, v115
	v_min_u32_e32 v104, v104, v115
	v_max_u32_e32 v115, v103, v102
	v_min_u32_e32 v102, v103, v102
	v_max_u32_e32 v103, v118, v2
	v_min_u32_e32 v2, v118, v2
	v_max_u32_e32 v118, v0, v1
	v_min_u32_e32 v0, v0, v1
	v_max_u32_e32 v1, v117, v105
	v_min_u32_e32 v105, v117, v105
	v_max_u32_e32 v117, v119, v116
	v_min_u32_e32 v116, v119, v116
	v_max_u32_e32 v110, v97, v114
	v_min_u32_e32 v97, v97, v114
	v_max_u32_e32 v114, v111, v112
	v_min_u32_e32 v111, v111, v112
	v_max_u32_e32 v112, v123, v106
	v_min_u32_e32 v106, v123, v106
	v_max_u32_e32 v123, v100, v98
	v_min_u32_e32 v98, v100, v98
	v_max_u32_e32 v100, v94, v96
	v_min_u32_e32 v94, v94, v96
	v_max_u32_e32 v96, v109, v99
	v_min_u32_e32 v99, v109, v99
	v_max_u32_e32 v109, v107, v101
	v_min_u32_e32 v101, v107, v101
	v_max_u32_e32 v107, v108, v95
	v_min_u32_e32 v95, v108, v95
	v_max_u32_e32 v119, v3, v122
	v_min_u32_e32 v3, v3, v122
	v_max_u32_e32 v122, v120, v121
	v_min_u32_e32 v120, v120, v121
	v_max_u32_e32 v121, v131, v115
	v_min_u32_e32 v115, v131, v115
	v_max_u32_e32 v131, v104, v102
	v_min_u32_e32 v102, v104, v102
	v_max_u32_e32 v104, v0, v2
	v_min_u32_e32 v0, v0, v2
	v_max_u32_e32 v2, v118, v103
	v_min_u32_e32 v103, v118, v103
	v_max_u32_e32 v118, v116, v105
	v_min_u32_e32 v105, v116, v105
	v_max_u32_e32 v116, v117, v1
	v_min_u32_e32 v1, v117, v1
	v_max_u32_e32 v108, v110, v94
	v_min_u32_e32 v94, v110, v94
	v_max_u32_e32 v110, v97, v100
	v_min_u32_e32 v97, v97, v100
	v_max_u32_e32 v100, v114, v99
	v_min_u32_e32 v99, v114, v99
	v_max_u32_e32 v114, v111, v96
	v_min_u32_e32 v96, v111, v96
	v_max_u32_e32 v111, v112, v101
	v_min_u32_e32 v101, v112, v101
	v_max_u32_e32 v112, v106, v109
	v_min_u32_e32 v106, v106, v109
	v_max_u32_e32 v109, v123, v95
	v_min_u32_e32 v95, v123, v95
	v_max_u32_e32 v123, v98, v107
	v_min_u32_e32 v98, v98, v107
	v_max_u32_e32 v117, v119, v0
	v_min_u32_e32 v0, v119, v0
	v_max_u32_e32 v119, v3, v104
	v_min_u32_e32 v3, v3, v104
	v_max_u32_e32 v104, v122, v103
	v_min_u32_e32 v103, v122, v103
; #define CE_DESC(a, b) do { const unsigned _mx = (a) > (b) ? (a) : (b), _mn = (a) > (b) ? (b) : (a); (a) = _mx; (b) = _mn; } while (0)
; __device__ __forceinline__ void sort16_desc(unsigned (&k)[16]) {
; #pragma unroll
;     for (int size = 2; size <= 16; size <<= 1)
; #pragma unroll
;         for (int stride = size >> 1; stride > 0; stride >>= 1)
; #pragma unroll
;             for (int i = 0; i < 16; ++i) { const int j = i ^ stride;
;                 if (j > i) { if ((i & size) == 0) CE_DESC(k[i], k[j]); else CE_DESC(k[j], k[i]); } }
; }
; __device__ __forceinline__ void merge16(unsigned (&a)[16], const unsigned (&b)[16]) {
; #pragma unroll
;     for (int i = 0; i < 16; ++i) a[i] = a[i] > b[15 - i] ? a[i] : b[15 - i];
; #pragma unroll
;     for (int stride = 8; stride > 0; stride >>= 1)
; #pragma unroll
;         for (int i = 0; i < 16; ++i) { const int j = i ^ stride; if (j > i) CE_DESC(a[i], a[j]); }
; }
; __device__ __forceinline__ void peer_tile(const Args& A, LAS unsigned char* lds, int tile) {
;     ...
;                 for (int msk = 16; msk <= 32; msk <<= 1) {
; #pragma unroll
;                     for (int i = 0; i < 16; ++i) k1[i] = (unsigned)__shfl_xor((int)k0[i], msk);
;                     merge16(k0, k1); }
	v_max_u32_e32 v122, v120, v2
	v_min_u32_e32 v2, v120, v2
	v_max_u32_e32 v120, v121, v105
	v_min_u32_e32 v105, v121, v105
	v_max_u32_e32 v121, v115, v118
	v_min_u32_e32 v115, v115, v118
	v_max_u32_e32 v118, v131, v1
	v_min_u32_e32 v1, v131, v1
	v_max_u32_e32 v131, v102, v116
	v_min_u32_e32 v102, v102, v116
	v_max_u32_e32 v107, v108, v111
	v_min_u32_e32 v108, v108, v111
	v_max_u32_e32 v111, v110, v112
	v_min_u32_e32 v110, v110, v112
	v_max_u32_e32 v112, v100, v109
	v_min_u32_e32 v100, v100, v109
	v_max_u32_e32 v109, v114, v123
	v_min_u32_e32 v114, v114, v123
	v_max_u32_e32 v123, v94, v101
	v_min_u32_e32 v94, v94, v101
	v_max_u32_e32 v101, v97, v106
	v_min_u32_e32 v97, v97, v106
	v_max_u32_e32 v106, v99, v95
	v_min_u32_e32 v95, v99, v95
	v_max_u32_e32 v99, v96, v98
	v_min_u32_e32 v96, v96, v98
	v_max_u32_e32 v116, v117, v120
	v_min_u32_e32 v117, v117, v120
	v_max_u32_e32 v120, v119, v121
	v_min_u32_e32 v119, v119, v121
	v_max_u32_e32 v121, v104, v118
	v_min_u32_e32 v104, v104, v118
	v_max_u32_e32 v118, v122, v131
	v_min_u32_e32 v122, v122, v131
	v_max_u32_e32 v131, v0, v105
	v_min_u32_e32 v0, v0, v105
	v_max_u32_e32 v105, v3, v115
	v_min_u32_e32 v3, v3, v115
	v_max_u32_e32 v115, v103, v1
	v_min_u32_e32 v1, v103, v1
	v_max_u32_e32 v103, v2, v102
	v_min_u32_e32 v2, v2, v102
	v_max_u32_e32 v98, v107, v112
	v_min_u32_e32 v107, v107, v112
	v_max_u32_e32 v112, v111, v109
	v_min_u32_e32 v109, v111, v109
	v_max_u32_e32 v111, v108, v100
	v_min_u32_e32 v100, v108, v100
	v_max_u32_e32 v108, v110, v114
	v_min_u32_e32 v110, v110, v114
	v_max_u32_e32 v114, v123, v106
	v_min_u32_e32 v106, v123, v106
	v_max_u32_e32 v123, v101, v99
	v_min_u32_e32 v99, v101, v99
	v_max_u32_e32 v101, v94, v95
	v_min_u32_e32 v94, v94, v95
	v_max_u32_e32 v95, v97, v96
	v_min_u32_e32 v96, v97, v96
	v_max_u32_e32 v102, v116, v121
	v_min_u32_e32 v116, v116, v121
	v_max_u32_e32 v121, v120, v118
	v_min_u32_e32 v118, v120, v118
	v_max_u32_e32 v120, v117, v104
	v_min_u32_e32 v104, v117, v104
	v_max_u32_e32 v117, v119, v122
	v_min_u32_e32 v119, v119, v122
	v_max_u32_e32 v122, v131, v115
	v_min_u32_e32 v115, v131, v115
	v_max_u32_e32 v131, v105, v103
	v_min_u32_e32 v103, v105, v103
	v_max_u32_e32 v105, v0, v1
	v_min_u32_e32 v0, v0, v1
	v_max_u32_e32 v1, v3, v2
	v_min_u32_e32 v2, v3, v2
	v_min_u32_e32 v97, v98, v112
	v_min_u32_e32 v124, v107, v109
	v_min_u32_e32 v125, v111, v108
	v_min_u32_e32 v126, v100, v110
	v_min_u32_e32 v127, v114, v123
	v_min_u32_e32 v128, v106, v99
	v_min_u32_e32 v129, v101, v95
	v_min_u32_e32 v130, v94, v96
	v_min_u32_e32 v3, v102, v121
	v_min_u32_e32 v132, v116, v118
	v_min_u32_e32 v133, v120, v117
	v_min_u32_e32 v134, v104, v119
	v_min_u32_e32 v135, v122, v131
	v_min_u32_e32 v136, v115, v103
	v_min_u32_e32 v137, v105, v1
	v_min_u32_e32 v138, v0, v2
	v_max3_u32 v98, v98, v112, v138
	v_max3_u32 v0, v97, v0, v2
	v_max3_u32 v2, v107, v109, v137
	v_max3_u32 v1, v124, v105, v1
	v_max3_u32 v97, v111, v108, v136
	v_max3_u32 v103, v125, v115, v103
	v_max3_u32 v100, v100, v110, v135
	v_max3_u32 v105, v126, v122, v131
	v_max3_u32 v107, v114, v123, v134
	v_max3_u32 v104, v127, v104, v119
	v_max3_u32 v99, v106, v99, v133
	v_max3_u32 v106, v128, v120, v117
	v_max3_u32 v95, v101, v95, v132
	v_max3_u32 v101, v129, v116, v118
	v_max3_u32 v3, v94, v96, v3
	v_max3_u32 v94, v130, v102, v121
	v_max_u32_e32 v96, v98, v107
	v_min_u32_e32 v98, v98, v107
	v_max_u32_e32 v102, v0, v104
	v_min_u32_e32 v0, v0, v104
	v_max_u32_e32 v104, v2, v99
	v_min_u32_e32 v2, v2, v99
	v_max_u32_e32 v99, v1, v106
	v_min_u32_e32 v1, v1, v106
	v_max_u32_e32 v106, v97, v95
	v_min_u32_e32 v95, v97, v95
	v_max_u32_e32 v97, v103, v101
	v_min_u32_e32 v101, v103, v101
	v_max_u32_e32 v103, v100, v3
	v_min_u32_e32 v3, v100, v3
	v_max_u32_e32 v100, v105, v94
	v_min_u32_e32 v94, v105, v94
	v_max_u32_e32 v105, v96, v106
	v_min_u32_e32 v96, v96, v106
	v_max_u32_e32 v106, v102, v97
	v_min_u32_e32 v97, v102, v97
	v_max_u32_e32 v102, v104, v103
	v_min_u32_e32 v103, v104, v103
	v_max_u32_e32 v104, v99, v100
	v_min_u32_e32 v99, v99, v100
	v_max_u32_e32 v100, v98, v95
	v_min_u32_e32 v95, v98, v95
	v_max_u32_e32 v98, v0, v101
	v_min_u32_e32 v0, v0, v101
	v_max_u32_e32 v101, v2, v3
	v_min_u32_e32 v2, v2, v3
	v_max_u32_e32 v3, v1, v94
	v_min_u32_e32 v1, v1, v94
	v_max_u32_e32 v94, v105, v102
	v_min_u32_e32 v102, v105, v102
	v_max_u32_e32 v105, v106, v104
	v_min_u32_e32 v104, v106, v104
	v_max_u32_e32 v106, v96, v103
	v_min_u32_e32 v96, v96, v103
	v_max_u32_e32 v103, v97, v99
	v_min_u32_e32 v97, v97, v99
	v_max_u32_e32 v99, v100, v101
	v_min_u32_e32 v100, v100, v101
	v_max_u32_e32 v101, v98, v3
	v_min_u32_e32 v3, v98, v3
	v_max_u32_e32 v98, v95, v2
	v_min_u32_e32 v2, v95, v2
	v_max_u32_e32 v95, v0, v1
	v_min_u32_e32 v0, v0, v1
	v_max_u32_e32 v1, v94, v105
	v_min_u32_e32 v94, v94, v105
	v_max_u32_e32 v105, v102, v104
	v_min_u32_e32 v102, v102, v104
	v_max_u32_e32 v104, v106, v103
	v_min_u32_e32 v103, v106, v103
	v_max_u32_e32 v106, v96, v97
	v_min_u32_e32 v96, v96, v97
	v_max_u32_e32 v97, v99, v101
	v_min_u32_e32 v99, v99, v101
	v_max_u32_e32 v101, v100, v3
	v_min_u32_e32 v3, v100, v3
	v_max_u32_e32 v100, v98, v95
	v_min_u32_e32 v95, v98, v95
	v_max_u32_e32 v98, v2, v0
	v_min_u32_e32 v0, v2, v0
	ds_bpermute_b32 v2, v27, v1
	ds_bpermute_b32 v107, v27, v94
	ds_bpermute_b32 v108, v27, v105
	ds_bpermute_b32 v109, v27, v102
	ds_bpermute_b32 v110, v27, v104
	ds_bpermute_b32 v111, v27, v103
	ds_bpermute_b32 v112, v27, v106
	ds_bpermute_b32 v114, v27, v96
	ds_bpermute_b32 v115, v27, v97
	ds_bpermute_b32 v116, v27, v99
	ds_bpermute_b32 v117, v27, v101
	ds_bpermute_b32 v118, v27, v0
	ds_bpermute_b32 v119, v27, v98
	ds_bpermute_b32 v120, v27, v95
	ds_bpermute_b32 v121, v27, v100
	ds_bpermute_b32 v122, v27, v3
	s_waitcnt lgkmcnt(4)
; #define CE_DESC(a, b) do { const unsigned _mx = (a) > (b) ? (a) : (b), _mn = (a) > (b) ? (b) : (a); (a) = _mx; (b) = _mn; } while (0)
; __device__ __forceinline__ void merge16(unsigned (&a)[16], const unsigned (&b)[16]) {
; #pragma unroll
;     for (int i = 0; i < 16; ++i) a[i] = a[i] > b[15 - i] ? a[i] : b[15 - i];
; #pragma unroll
;     for (int stride = 8; stride > 0; stride >>= 1)
; #pragma unroll
;         for (int i = 0; i < 16; ++i) { const int j = i ^ stride; if (j > i) CE_DESC(a[i], a[j]); }
; __device__ __forceinline__ void peer_tile(const Args& A, LAS unsigned char* lds, int tile) {
;     ...
;                 for (int msk = 16; msk <= 32; msk <<= 1) {
; #pragma unroll
;                     for (int i = 0; i < 16; ++i) k1[i] = (unsigned)__shfl_xor((int)k0[i], msk);
;                     merge16(k0, k1); }
	v_max_u32_e32 v1, v1, v118
	s_waitcnt lgkmcnt(3)
	v_max_u32_e32 v94, v94, v119
	s_waitcnt lgkmcnt(2)
	v_max_u32_e32 v105, v105, v120
	s_waitcnt lgkmcnt(1)
	v_max_u32_e32 v102, v102, v121
	s_waitcnt lgkmcnt(0)
	v_max_u32_e32 v104, v104, v122
	v_max_u32_e32 v103, v103, v117
	v_max_u32_e32 v106, v106, v116
	v_max_u32_e32 v96, v96, v115
	v_max_u32_e32 v97, v97, v114
	v_max_u32_e32 v99, v99, v112
	v_max_u32_e32 v101, v101, v111
	v_max_u32_e32 v3, v3, v110
	v_max_u32_e32 v100, v100, v109
	v_max_u32_e32 v95, v95, v108
	v_max_u32_e32 v98, v98, v107
	v_max_u32_e32 v0, v0, v2
	v_max_u32_e32 v2, v1, v97
	v_min_u32_e32 v1, v1, v97
	v_max_u32_e32 v97, v94, v99
	v_min_u32_e32 v94, v94, v99
	v_max_u32_e32 v99, v105, v101
	v_min_u32_e32 v101, v105, v101
	v_max_u32_e32 v105, v102, v3
	v_min_u32_e32 v3, v102, v3
	v_max_u32_e32 v102, v104, v100
	v_min_u32_e32 v100, v104, v100
	v_max_u32_e32 v104, v103, v95
	v_min_u32_e32 v95, v103, v95
	v_max_u32_e32 v103, v106, v98
	v_min_u32_e32 v98, v106, v98
	v_max_u32_e32 v106, v96, v0
	v_min_u32_e32 v0, v96, v0
	v_max_u32_e32 v96, v2, v102
	v_min_u32_e32 v2, v2, v102
	v_max_u32_e32 v102, v97, v104
	v_min_u32_e32 v97, v97, v104
	v_max_u32_e32 v104, v99, v103
	v_min_u32_e32 v99, v99, v103
	v_max_u32_e32 v103, v105, v106
	v_min_u32_e32 v105, v105, v106
	v_max_u32_e32 v106, v1, v100
	v_min_u32_e32 v1, v1, v100
	v_max_u32_e32 v100, v94, v95
	v_min_u32_e32 v94, v94, v95
	v_max_u32_e32 v95, v101, v98
	v_min_u32_e32 v98, v101, v98
	v_max_u32_e32 v101, v3, v0
	v_min_u32_e32 v0, v3, v0
	v_max_u32_e32 v3, v96, v104
	v_min_u32_e32 v96, v96, v104
	v_max_u32_e32 v104, v102, v103
	v_min_u32_e32 v102, v102, v103
	v_max_u32_e32 v103, v2, v99
	v_min_u32_e32 v2, v2, v99
	v_max_u32_e32 v99, v97, v105
	v_min_u32_e32 v97, v97, v105
	v_max_u32_e32 v105, v106, v95
	v_min_u32_e32 v95, v106, v95
	v_max_u32_e32 v106, v100, v101
	v_min_u32_e32 v100, v100, v101
	v_max_u32_e32 v101, v1, v98
	v_min_u32_e32 v1, v1, v98
	v_max_u32_e32 v98, v94, v0
	v_min_u32_e32 v0, v94, v0
	v_max_u32_e32 v94, v3, v104
	v_min_u32_e32 v3, v3, v104
	v_max_u32_e32 v104, v96, v102
	v_min_u32_e32 v96, v96, v102
	v_max_u32_e32 v102, v103, v99
	v_min_u32_e32 v99, v103, v99
	v_max_u32_e32 v103, v2, v97
	v_min_u32_e32 v2, v2, v97
	v_max_u32_e32 v97, v105, v106
	v_min_u32_e32 v105, v105, v106
	v_max_u32_e32 v106, v95, v100
	v_min_u32_e32 v95, v95, v100
	v_max_u32_e32 v100, v101, v98
	v_min_u32_e32 v98, v101, v98
	v_max_u32_e32 v101, v1, v0
	v_min_u32_e32 v0, v1, v0
	ds_bpermute_b32 v114, v29, v0
	ds_bpermute_b32 v1, v29, v94
	ds_bpermute_b32 v107, v29, v3
	ds_bpermute_b32 v108, v29, v104
	ds_bpermute_b32 v109, v29, v96
	s_waitcnt lgkmcnt(4)
	v_max_u32_e32 v94, v94, v114
	global_load_dwordx4 v[114:117], v[4:5], off offset:1296
	global_load_dwordx4 v[118:121], v[4:5], off offset:1280
	ds_bpermute_b32 v110, v29, v102
	ds_bpermute_b32 v111, v29, v99
	ds_bpermute_b32 v112, v29, v103
	ds_bpermute_b32 v122, v29, v2
	ds_bpermute_b32 v123, v29, v97
	ds_bpermute_b32 v124, v29, v105
	ds_bpermute_b32 v125, v29, v106
	ds_bpermute_b32 v126, v29, v95
	ds_bpermute_b32 v127, v29, v100
	ds_bpermute_b32 v128, v29, v101
	ds_bpermute_b32 v129, v29, v98
	s_waitcnt lgkmcnt(4)
	v_max_u32_e32 v99, v99, v125
	s_waitcnt lgkmcnt(3)
	v_max_u32_e32 v102, v102, v126
	s_waitcnt lgkmcnt(2)
	v_max_u32_e32 v96, v96, v127
	s_waitcnt lgkmcnt(1)
	v_max_u32_e32 v3, v3, v128
	s_waitcnt lgkmcnt(0)
	v_max_u32_e32 v104, v104, v129
	v_max_u32_e32 v103, v103, v124
	v_max_u32_e32 v2, v2, v123
	v_max_u32_e32 v97, v97, v122
	v_max_u32_e32 v105, v105, v112
	v_max_u32_e32 v106, v106, v111
	v_max_u32_e32 v95, v95, v110
	v_max_u32_e32 v100, v100, v109
	v_max_u32_e32 v98, v98, v108
	v_max_u32_e32 v101, v101, v107
	v_max_u32_e32 v0, v0, v1
	v_max_u32_e32 v1, v94, v97
	v_min_u32_e32 v94, v94, v97
	v_max_u32_e32 v97, v3, v105
	v_min_u32_e32 v3, v3, v105
	v_max_u32_e32 v105, v104, v106
	v_min_u32_e32 v104, v104, v106
	v_max_u32_e32 v106, v96, v95
	v_min_u32_e32 v95, v96, v95
	v_max_u32_e32 v96, v102, v100
	v_min_u32_e32 v100, v102, v100
	v_max_u32_e32 v102, v99, v98
	v_min_u32_e32 v98, v99, v98
	v_max_u32_e32 v99, v103, v101
	v_min_u32_e32 v101, v103, v101
	v_max_u32_e32 v103, v2, v0
	v_min_u32_e32 v0, v2, v0
	v_max_u32_e32 v2, v1, v96
	v_min_u32_e32 v1, v1, v96
	v_max_u32_e32 v96, v97, v102
	v_min_u32_e32 v97, v97, v102
	v_max_u32_e32 v102, v105, v99
	v_min_u32_e32 v99, v105, v99
	v_max_u32_e32 v105, v106, v103
	v_min_u32_e32 v103, v106, v103
	v_max_u32_e32 v106, v94, v100
	v_min_u32_e32 v94, v94, v100
	v_max_u32_e32 v100, v3, v98
	v_min_u32_e32 v3, v3, v98
	v_max_u32_e32 v98, v104, v101
	v_min_u32_e32 v101, v104, v101
	v_max_u32_e32 v104, v95, v0
	v_min_u32_e32 v0, v95, v0
	v_max_u32_e32 v95, v2, v102
	v_min_u32_e32 v2, v2, v102
	v_max_u32_e32 v102, v96, v105
	v_min_u32_e32 v96, v96, v105
	v_max_u32_e32 v110, v1, v99
	v_min_u32_e32 v1, v1, v99
	v_max_u32_e32 v99, v97, v103
	v_min_u32_e32 v97, v97, v103
	v_max_u32_e32 v111, v106, v98
	v_min_u32_e32 v98, v106, v98
	v_min_u32_e32 v122, v100, v104
	v_max_u32_e32 v123, v94, v101
	v_min_u32_e32 v94, v94, v101
	v_max_u32_e32 v124, v3, v0
	v_min_u32_e32 v0, v3, v0
	v_max_u32_e32 v112, v100, v104
	v_max_u32_e32 v109, v95, v102
	v_min_u32_e32 v108, v95, v102
	v_max_u32_e32 v107, v2, v96
	v_min_u32_e32 v106, v2, v96
	v_max_u32_e32 v105, v110, v99
	v_min_u32_e32 v104, v110, v99
	v_max_u32_e32 v103, v1, v97
	v_min_u32_e32 v102, v1, v97
	v_max_u32_e32 v99, v98, v122
	v_min_u32_e32 v98, v98, v122
	v_max_u32_e32 v97, v123, v124
	v_min_u32_e32 v96, v123, v124
	v_max_u32_e32 v95, v94, v0
	v_min_u32_e32 v94, v94, v0
	global_load_dwordx4 v[0:3], v[4:5], off offset:1328
	global_load_dwordx4 v[122:125], v[4:5], off offset:1312
	s_waitcnt vmcnt(2)
; __device__ __forceinline__ unsigned f2key(float f) { const unsigned u = __float_as_uint(f); return (u & 0x80000000u) ? ~u : (u | 0x80000000u); }
; __device__ __forceinline__ void peer_tile(const Args& A, LAS unsigned char* lds, int tile) {
;     ...
;                 { const bf16_t* sp = QRY + m * 2048 + hp * 128 + 32 * g;
;                   const u32x4 s0 = *(const u32x4*)sp, s1 = *(const u32x4*)(sp + 8), s2 = *(const u32x4*)(sp + 16), s3 = *(const u32x4*)(sp + 24);
;                   const unsigned sw[16] = {s0.x, s0.y, s0.z, s0.w, s1.x, s1.y, s1.z, s1.w, s2.x, s2.y, s2.z, s2.w, s3.x, s3.y, s3.z, s3.w};
; #pragma unroll
;                   for (int i = 0; i < 16; ++i) {
;                       const float lo = (float)__builtin_bit_cast(_Float16, (unsigned short)(sw[i] & 0xffffu)), hi = (float)__builtin_bit_cast(_Float16, (unsigned short)(sw[i] >> 16));
;                       const unsigned klo = (f2key(lo) & ~127u) | (unsigned)(127 - (32 * g + 2 * i)), khi = (f2key(hi) & ~127u) | (unsigned)(127 - (32 * g + 2 * i + 1));
;                       if (i < 8) { k0[2 * i] = klo; k0[2 * i + 1] = khi; } else { k1[2 * (i - 8)] = klo; k1[2 * (i - 8) + 1] = khi; } } }
	v_cvt_f32_f16_sdwa v110, v118 dst_sel:DWORD dst_unused:UNUSED_PAD src0_sel:WORD_1
	v_max_u32_e32 v101, v111, v112
	v_min_u32_e32 v100, v111, v112
	v_cvt_f32_f16_e32 v111, v118
	v_not_b32_e32 v112, v110
	v_or_b32_e32 v118, 0x80000000, v110
	v_cmp_gt_i32_e32 vcc, 0, v110
	v_cndmask_b32_e64 v30, v62, v30, s[0:1]
	s_nop 0
	v_cndmask_b32_e32 v110, v118, v112, vcc
	v_not_b32_e32 v112, v111
	v_or_b32_e32 v118, 0x80000000, v111
	v_cmp_gt_i32_e32 vcc, 0, v111
	v_and_b32_e32 v110, 0xffffff80, v110
	v_sub_u32_e32 v110, v110, v15
	v_cndmask_b32_e32 v111, v118, v112, vcc
	v_cvt_f32_f16_sdwa v112, v119 dst_sel:DWORD dst_unused:UNUSED_PAD src0_sel:WORD_1
	v_cvt_f32_f16_e32 v118, v119
	v_and_b32_e32 v111, 0xffffff80, v111
	v_sub_u32_e32 v111, v111, v15
	v_not_b32_e32 v119, v112
	v_or_b32_e32 v126, 0x80000000, v112
	v_cmp_gt_i32_e32 vcc, 0, v112
	v_add_u32_e32 v110, 0x7e, v110
	v_add_u32_e32 v111, 0x7f, v111
	v_cndmask_b32_e32 v112, v126, v119, vcc
	v_not_b32_e32 v119, v118
	v_or_b32_e32 v126, 0x80000000, v118
	v_cmp_gt_i32_e32 vcc, 0, v118
	v_and_b32_e32 v112, 0xffffff80, v112
	v_sub_u32_e32 v112, v112, v14
	v_cndmask_b32_e32 v118, v126, v119, vcc
	v_cvt_f32_f16_sdwa v119, v120 dst_sel:DWORD dst_unused:UNUSED_PAD src0_sel:WORD_1
	v_cvt_f32_f16_e32 v120, v120
	v_and_b32_e32 v118, 0xffffff80, v118
	v_sub_u32_e32 v118, v118, v14
	v_not_b32_e32 v126, v119
	v_or_b32_e32 v127, 0x80000000, v119
	v_cmp_gt_i32_e32 vcc, 0, v119
	v_add_u32_e32 v112, 0x7e, v112
	v_add_u32_e32 v118, 0x7f, v118
	v_cndmask_b32_e32 v119, v127, v126, vcc
	v_not_b32_e32 v126, v120
	v_or_b32_e32 v127, 0x80000000, v120
	v_cmp_gt_i32_e32 vcc, 0, v120
	v_and_b32_e32 v119, 0xffffff80, v119
	v_sub_u32_e32 v119, v119, v12
	v_cndmask_b32_e32 v120, v127, v126, vcc
	v_cvt_f32_f16_sdwa v126, v121 dst_sel:DWORD dst_unused:UNUSED_PAD src0_sel:WORD_1
	v_cvt_f32_f16_e32 v121, v121
	v_and_b32_e32 v120, 0xffffff80, v120
	v_sub_u32_e32 v120, v120, v12
	v_not_b32_e32 v127, v126
	v_or_b32_e32 v128, 0x80000000, v126
	v_cmp_gt_i32_e32 vcc, 0, v126
	v_add_u32_e32 v119, 0x7e, v119
	v_add_u32_e32 v120, 0x7f, v120
	v_cndmask_b32_e32 v126, v128, v127, vcc
	v_not_b32_e32 v127, v121
	v_or_b32_e32 v128, 0x80000000, v121
	v_cmp_gt_i32_e32 vcc, 0, v121
	v_and_b32_e32 v126, 0xffffff80, v126
	v_sub_u32_e32 v126, v126, v10
	v_cndmask_b32_e32 v121, v128, v127, vcc
	v_cvt_f32_f16_sdwa v127, v114 dst_sel:DWORD dst_unused:UNUSED_PAD src0_sel:WORD_1
	v_cvt_f32_f16_e32 v114, v114
	v_and_b32_e32 v121, 0xffffff80, v121
	v_sub_u32_e32 v121, v121, v10
	v_not_b32_e32 v128, v127
	v_or_b32_e32 v129, 0x80000000, v127
	v_cmp_gt_i32_e32 vcc, 0, v127
	v_add_u32_e32 v126, 0x7e, v126
	v_add_u32_e32 v121, 0x7f, v121
	v_cndmask_b32_e32 v127, v129, v128, vcc
	v_not_b32_e32 v128, v114
	v_or_b32_e32 v129, 0x80000000, v114
	v_cmp_gt_i32_e32 vcc, 0, v114
	v_and_b32_e32 v127, 0xffffff80, v127
	v_sub_u32_e32 v127, v127, v8
	v_cndmask_b32_e32 v114, v129, v128, vcc
	v_cvt_f32_f16_sdwa v128, v115 dst_sel:DWORD dst_unused:UNUSED_PAD src0_sel:WORD_1
	v_cvt_f32_f16_e32 v115, v115
	v_and_b32_e32 v114, 0xffffff80, v114
	v_sub_u32_e32 v114, v114, v8
	v_not_b32_e32 v129, v128
	v_or_b32_e32 v130, 0x80000000, v128
	v_cmp_gt_i32_e32 vcc, 0, v128
	v_add_u32_e32 v127, 0x7e, v127
	v_add_u32_e32 v114, 0x7f, v114
	v_cndmask_b32_e32 v128, v130, v129, vcc
	v_not_b32_e32 v129, v115
	v_or_b32_e32 v130, 0x80000000, v115
	v_cmp_gt_i32_e32 vcc, 0, v115
	v_and_b32_e32 v128, 0xffffff80, v128
	v_sub_u32_e32 v128, v128, v16
	v_cndmask_b32_e32 v115, v130, v129, vcc
	v_cvt_f32_f16_sdwa v129, v116 dst_sel:DWORD dst_unused:UNUSED_PAD src0_sel:WORD_1
	v_cvt_f32_f16_e32 v116, v116
	v_and_b32_e32 v115, 0xffffff80, v115
	v_sub_u32_e32 v115, v115, v16
	v_not_b32_e32 v130, v129
	v_or_b32_e32 v131, 0x80000000, v129
	v_cmp_gt_i32_e32 vcc, 0, v129
	v_add_u32_e32 v128, 0x7e, v128
	v_add_u32_e32 v115, 0x7f, v115
	v_cndmask_b32_e32 v129, v131, v130, vcc
	v_not_b32_e32 v130, v116
	v_or_b32_e32 v131, 0x80000000, v116
	v_cmp_gt_i32_e32 vcc, 0, v116
	v_and_b32_e32 v129, 0xffffff80, v129
	v_sub_u32_e32 v129, v129, v17
	v_cndmask_b32_e32 v116, v131, v130, vcc
	v_cvt_f32_f16_sdwa v130, v117 dst_sel:DWORD dst_unused:UNUSED_PAD src0_sel:WORD_1
	v_cvt_f32_f16_e32 v117, v117
	v_and_b32_e32 v116, 0xffffff80, v116
	v_sub_u32_e32 v116, v116, v17
	v_not_b32_e32 v131, v130
	v_or_b32_e32 v132, 0x80000000, v130
	v_cmp_gt_i32_e32 vcc, 0, v130
	v_add_u32_e32 v129, 0x7e, v129
	v_add_u32_e32 v116, 0x7f, v116
	v_cndmask_b32_e32 v130, v132, v131, vcc
	v_not_b32_e32 v131, v117
	v_or_b32_e32 v132, 0x80000000, v117
	v_cmp_gt_i32_e32 vcc, 0, v117
	v_and_b32_e32 v130, 0xffffff80, v130
	v_sub_u32_e32 v130, v130, v18
	v_cndmask_b32_e32 v117, v132, v131, vcc
	s_waitcnt vmcnt(0)
; __device__ __forceinline__ unsigned f2key(float f) { const unsigned u = __float_as_uint(f); return (u & 0x80000000u) ? ~u : (u | 0x80000000u); }
; #define CE_DESC(a, b) do { const unsigned _mx = (a) > (b) ? (a) : (b), _mn = (a) > (b) ? (b) : (a); (a) = _mx; (b) = _mn; } while (0)
; __device__ __forceinline__ void sort16_desc(unsigned (&k)[16]) {
; #pragma unroll
;     for (int size = 2; size <= 16; size <<= 1)
; #pragma unroll
;         for (int stride = size >> 1; stride > 0; stride >>= 1)
; #pragma unroll
;             for (int i = 0; i < 16; ++i) { const int j = i ^ stride;
;                 if (j > i) { if ((i & size) == 0) CE_DESC(k[i], k[j]); else CE_DESC(k[j], k[i]); } }
; __device__ __forceinline__ void peer_tile(const Args& A, LAS unsigned char* lds, int tile) {
;     ...
;                       const float lo = (float)__builtin_bit_cast(_Float16, (unsigned short)(sw[i] & 0xffffu)), hi = (float)__builtin_bit_cast(_Float16, (unsigned short)(sw[i] >> 16));
;                       const unsigned klo = (f2key(lo) & ~127u) | (unsigned)(127 - (32 * g + 2 * i)), khi = (f2key(hi) & ~127u) | (unsigned)(127 - (32 * g + 2 * i + 1));
;                       if (i < 8) { k0[2 * i] = klo; k0[2 * i + 1] = khi; } else { k1[2 * (i - 8)] = klo; k1[2 * (i - 8) + 1] = khi; } } }
	v_cvt_f32_f16_sdwa v131, v122 dst_sel:DWORD dst_unused:UNUSED_PAD src0_sel:WORD_1
	v_cvt_f32_f16_e32 v122, v122
	v_and_b32_e32 v117, 0xffffff80, v117
	v_sub_u32_e32 v117, v117, v18
	v_not_b32_e32 v132, v131
	v_or_b32_e32 v133, 0x80000000, v131
	v_cmp_gt_i32_e32 vcc, 0, v131
	v_add_u32_e32 v130, 0x7e, v130
	v_add_u32_e32 v117, 0x7f, v117
	v_cndmask_b32_e32 v131, v133, v132, vcc
	v_not_b32_e32 v132, v122
	v_or_b32_e32 v133, 0x80000000, v122
	v_cmp_gt_i32_e32 vcc, 0, v122
	v_and_b32_e32 v131, 0xffffff80, v131
	v_sub_u32_e32 v131, v131, v20
	v_cndmask_b32_e32 v122, v133, v132, vcc
	v_cvt_f32_f16_sdwa v132, v123 dst_sel:DWORD dst_unused:UNUSED_PAD src0_sel:WORD_1
	v_cvt_f32_f16_e32 v123, v123
	v_and_b32_e32 v122, 0xffffff80, v122
	v_sub_u32_e32 v122, v122, v20
	v_not_b32_e32 v133, v132
	v_or_b32_e32 v134, 0x80000000, v132
	v_cmp_gt_i32_e32 vcc, 0, v132
	v_add_u32_e32 v131, 0x7e, v131
	v_add_u32_e32 v122, 0x7f, v122
	v_cndmask_b32_e32 v132, v134, v133, vcc
	v_not_b32_e32 v133, v123
	v_or_b32_e32 v134, 0x80000000, v123
	v_cmp_gt_i32_e32 vcc, 0, v123
	v_and_b32_e32 v132, 0xffffff80, v132
	v_sub_u32_e32 v132, v132, v21
	v_cndmask_b32_e32 v123, v134, v133, vcc
	v_cvt_f32_f16_sdwa v133, v124 dst_sel:DWORD dst_unused:UNUSED_PAD src0_sel:WORD_1
	v_cvt_f32_f16_e32 v124, v124
	v_and_b32_e32 v123, 0xffffff80, v123
	v_sub_u32_e32 v123, v123, v21
	v_not_b32_e32 v134, v133
	v_or_b32_e32 v135, 0x80000000, v133
	v_cmp_gt_i32_e32 vcc, 0, v133
	v_add_u32_e32 v132, 0x7e, v132
	v_add_u32_e32 v123, 0x7f, v123
	v_cndmask_b32_e32 v133, v135, v134, vcc
	v_not_b32_e32 v134, v124
	v_or_b32_e32 v135, 0x80000000, v124
	v_cmp_gt_i32_e32 vcc, 0, v124
	v_and_b32_e32 v133, 0xffffff80, v133
	v_sub_u32_e32 v133, v133, v22
	v_cndmask_b32_e32 v124, v135, v134, vcc
	v_cvt_f32_f16_sdwa v134, v125 dst_sel:DWORD dst_unused:UNUSED_PAD src0_sel:WORD_1
	v_cvt_f32_f16_e32 v125, v125
	v_and_b32_e32 v124, 0xffffff80, v124
	v_sub_u32_e32 v124, v124, v22
	v_not_b32_e32 v135, v134
	v_or_b32_e32 v136, 0x80000000, v134
	v_cmp_gt_i32_e32 vcc, 0, v134
	v_add_u32_e32 v133, 0x7e, v133
	v_add_u32_e32 v124, 0x7f, v124
	v_cndmask_b32_e32 v134, v136, v135, vcc
	v_not_b32_e32 v135, v125
	v_or_b32_e32 v136, 0x80000000, v125
	v_cmp_gt_i32_e32 vcc, 0, v125
	v_and_b32_e32 v134, 0xffffff80, v134
	v_sub_u32_e32 v134, v134, v23
	v_cndmask_b32_e32 v125, v136, v135, vcc
	v_cvt_f32_f16_sdwa v135, v0 dst_sel:DWORD dst_unused:UNUSED_PAD src0_sel:WORD_1
	v_cvt_f32_f16_e32 v0, v0
	v_and_b32_e32 v125, 0xffffff80, v125
	v_sub_u32_e32 v125, v125, v23
	v_not_b32_e32 v136, v135
	v_or_b32_e32 v137, 0x80000000, v135
	v_cmp_gt_i32_e32 vcc, 0, v135
	v_add_u32_e32 v134, 0x7e, v134
	v_add_u32_e32 v125, 0x7f, v125
	v_cndmask_b32_e32 v135, v137, v136, vcc
	v_not_b32_e32 v136, v0
	v_or_b32_e32 v137, 0x80000000, v0
	v_cmp_gt_i32_e32 vcc, 0, v0
	v_and_b32_e32 v135, 0xffffff80, v135
	v_sub_u32_e32 v135, v135, v24
	v_cndmask_b32_e32 v0, v137, v136, vcc
	v_cvt_f32_f16_sdwa v136, v1 dst_sel:DWORD dst_unused:UNUSED_PAD src0_sel:WORD_1
	v_cvt_f32_f16_e32 v1, v1
	v_and_b32_e32 v0, 0xffffff80, v0
	v_sub_u32_e32 v0, v0, v24
	v_not_b32_e32 v137, v136
	v_or_b32_e32 v138, 0x80000000, v136
	v_cmp_gt_i32_e32 vcc, 0, v136
	v_add_u32_e32 v135, 0x7e, v135
	v_add_u32_e32 v0, 0x7f, v0
	v_cndmask_b32_e32 v136, v138, v137, vcc
	v_not_b32_e32 v137, v1
	v_or_b32_e32 v138, 0x80000000, v1
	v_cmp_gt_i32_e32 vcc, 0, v1
	v_and_b32_e32 v136, 0xffffff80, v136
	v_sub_u32_e32 v136, v136, v25
	v_cndmask_b32_e32 v1, v138, v137, vcc
	v_cvt_f32_f16_sdwa v137, v2 dst_sel:DWORD dst_unused:UNUSED_PAD src0_sel:WORD_1
	v_cvt_f32_f16_e32 v2, v2
	v_and_b32_e32 v1, 0xffffff80, v1
	v_sub_u32_e32 v1, v1, v25
	v_not_b32_e32 v138, v137
	v_or_b32_e32 v139, 0x80000000, v137
	v_cmp_gt_i32_e32 vcc, 0, v137
	v_add_u32_e32 v136, 0x7e, v136
	v_add_u32_e32 v1, 0x7f, v1
	v_cndmask_b32_e32 v137, v139, v138, vcc
	v_not_b32_e32 v138, v2
	v_or_b32_e32 v139, 0x80000000, v2
	v_cmp_gt_i32_e32 vcc, 0, v2
	v_and_b32_e32 v137, 0xffffff80, v137
	v_sub_u32_e32 v137, v137, v26
	v_cndmask_b32_e32 v2, v139, v138, vcc
	v_cvt_f32_f16_sdwa v138, v3 dst_sel:DWORD dst_unused:UNUSED_PAD src0_sel:WORD_1
	v_cvt_f32_f16_e32 v3, v3
	v_and_b32_e32 v2, 0xffffff80, v2
	v_sub_u32_e32 v2, v2, v26
	v_not_b32_e32 v139, v138
	v_or_b32_e32 v140, 0x80000000, v138
	v_cmp_gt_i32_e32 vcc, 0, v138
	v_add_u32_e32 v137, 0x7e, v137
	v_add_u32_e32 v2, 0x7f, v2
	v_cndmask_b32_e32 v138, v140, v139, vcc
	v_not_b32_e32 v139, v3
	v_or_b32_e32 v140, 0x80000000, v3
	v_cmp_gt_i32_e32 vcc, 0, v3
	v_and_b32_e32 v138, 0xffffff80, v138
	v_sub_u32_e32 v138, v138, v28
	v_cndmask_b32_e32 v3, v140, v139, vcc
	v_and_b32_e32 v3, 0xffffff80, v3
	v_sub_u32_e32 v3, v3, v28
	v_add_u32_e32 v138, 0x7e, v138
	v_add_u32_e32 v3, 0x7f, v3
	v_max_u32_e32 v139, v111, v110
	v_min_u32_e32 v110, v111, v110
	v_max_u32_e32 v111, v112, v118
	v_min_u32_e32 v112, v112, v118
	v_max_u32_e32 v118, v120, v119
	v_min_u32_e32 v119, v120, v119
	v_max_u32_e32 v120, v126, v121
	v_min_u32_e32 v121, v126, v121
	v_max_u32_e32 v126, v114, v127
	v_min_u32_e32 v114, v114, v127
	v_max_u32_e32 v127, v128, v115
	v_min_u32_e32 v115, v128, v115
	v_max_u32_e32 v128, v116, v129
	v_min_u32_e32 v116, v116, v129
	v_max_u32_e32 v129, v130, v117
	v_min_u32_e32 v117, v130, v117
	v_max_u32_e32 v147, v122, v131
	v_min_u32_e32 v122, v122, v131
	v_max_u32_e32 v131, v132, v123
	v_min_u32_e32 v123, v132, v123
	v_max_u32_e32 v132, v124, v133
	v_min_u32_e32 v124, v124, v133
	v_max_u32_e32 v133, v134, v125
	v_min_u32_e32 v125, v134, v125
	v_max_u32_e32 v134, v0, v135
	v_min_u32_e32 v0, v0, v135
	v_max_u32_e32 v135, v136, v1
	v_min_u32_e32 v1, v136, v1
	v_max_u32_e32 v136, v2, v137
	v_min_u32_e32 v2, v2, v137
; #define CE_DESC(a, b) do { const unsigned _mx = (a) > (b) ? (a) : (b), _mn = (a) > (b) ? (b) : (a); (a) = _mx; (b) = _mn; } while (0)
; __device__ __forceinline__ void sort16_desc(unsigned (&k)[16]) {
; #pragma unroll
;     for (int size = 2; size <= 16; size <<= 1)
; #pragma unroll
;         for (int stride = size >> 1; stride > 0; stride >>= 1)
; #pragma unroll
;             for (int i = 0; i < 16; ++i) { const int j = i ^ stride;
;                 if (j > i) { if ((i & size) == 0) CE_DESC(k[i], k[j]); else CE_DESC(k[j], k[i]); } }
	v_max_u32_e32 v137, v138, v3
	v_min_u32_e32 v3, v138, v3
	v_max_u32_e32 v130, v139, v112
	v_min_u32_e32 v112, v139, v112
	v_max_u32_e32 v139, v110, v111
	v_min_u32_e32 v110, v110, v111
	v_max_u32_e32 v111, v121, v118
	v_min_u32_e32 v118, v121, v118
	v_max_u32_e32 v121, v120, v119
	v_min_u32_e32 v119, v120, v119
	v_max_u32_e32 v120, v126, v115
	v_min_u32_e32 v115, v126, v115
	v_max_u32_e32 v126, v114, v127
	v_min_u32_e32 v114, v114, v127
	v_max_u32_e32 v127, v117, v128
	v_min_u32_e32 v117, v117, v128
	v_max_u32_e32 v128, v129, v116
	v_min_u32_e32 v116, v129, v116
	v_max_u32_e32 v138, v147, v123
	v_min_u32_e32 v123, v147, v123
	v_max_u32_e32 v147, v122, v131
	v_min_u32_e32 v122, v122, v131
	v_max_u32_e32 v131, v125, v132
	v_min_u32_e32 v125, v125, v132
	v_max_u32_e32 v132, v133, v124
	v_min_u32_e32 v124, v133, v124
	v_max_u32_e32 v133, v134, v1
	v_min_u32_e32 v1, v134, v1
	v_max_u32_e32 v134, v0, v135
	v_min_u32_e32 v0, v0, v135
	v_max_u32_e32 v135, v3, v136
	v_min_u32_e32 v3, v3, v136
	v_max_u32_e32 v136, v137, v2
	v_min_u32_e32 v2, v137, v2
	v_max_u32_e32 v129, v130, v139
	v_min_u32_e32 v130, v130, v139
	v_max_u32_e32 v139, v112, v110
	v_min_u32_e32 v110, v112, v110
	v_max_u32_e32 v112, v119, v118
	v_min_u32_e32 v118, v119, v118
	v_max_u32_e32 v119, v121, v111
	v_min_u32_e32 v111, v121, v111
	v_max_u32_e32 v121, v120, v126
	v_min_u32_e32 v120, v120, v126
	v_max_u32_e32 v126, v115, v114
	v_min_u32_e32 v114, v115, v114
	v_max_u32_e32 v115, v116, v117
	v_min_u32_e32 v116, v116, v117
	v_max_u32_e32 v117, v128, v127
	v_min_u32_e32 v127, v128, v127
	v_max_u32_e32 v137, v138, v147
	v_min_u32_e32 v138, v138, v147
	v_max_u32_e32 v147, v123, v122
	v_min_u32_e32 v122, v123, v122
	v_max_u32_e32 v123, v124, v125
	v_min_u32_e32 v124, v124, v125
	v_max_u32_e32 v125, v132, v131
	v_min_u32_e32 v131, v132, v131
	v_max_u32_e32 v132, v133, v134
	v_min_u32_e32 v133, v133, v134
	v_max_u32_e32 v134, v1, v0
	v_min_u32_e32 v0, v1, v0
	v_max_u32_e32 v1, v2, v3
	v_min_u32_e32 v2, v2, v3
	v_max_u32_e32 v3, v136, v135
	v_min_u32_e32 v135, v136, v135
	v_max_u32_e32 v128, v129, v118
	v_min_u32_e32 v118, v129, v118
	v_max_u32_e32 v129, v130, v112
	v_min_u32_e32 v112, v130, v112
	v_max_u32_e32 v130, v139, v111
	v_min_u32_e32 v111, v139, v111
	v_max_u32_e32 v139, v110, v119
	v_min_u32_e32 v110, v110, v119
	v_max_u32_e32 v119, v116, v121
	v_min_u32_e32 v116, v116, v121
	v_max_u32_e32 v121, v115, v120
	v_min_u32_e32 v115, v115, v120
	v_max_u32_e32 v120, v127, v126
	v_min_u32_e32 v126, v127, v126
	v_max_u32_e32 v127, v117, v114
	v_min_u32_e32 v114, v117, v114
	v_max_u32_e32 v136, v137, v124
	v_min_u32_e32 v124, v137, v124
	v_max_u32_e32 v137, v138, v123
	v_min_u32_e32 v123, v138, v123
	v_max_u32_e32 v138, v147, v131
	v_min_u32_e32 v131, v147, v131
	v_max_u32_e32 v147, v122, v125
	v_min_u32_e32 v122, v122, v125
	v_max_u32_e32 v125, v2, v132
	v_min_u32_e32 v2, v2, v132
	v_max_u32_e32 v132, v1, v133
	v_min_u32_e32 v1, v1, v133
	v_max_u32_e32 v133, v135, v134
	v_min_u32_e32 v134, v135, v134
	v_max_u32_e32 v135, v3, v0
	v_min_u32_e32 v0, v3, v0
	v_max_u32_e32 v117, v128, v130
	v_min_u32_e32 v128, v128, v130
	v_max_u32_e32 v130, v129, v139
	v_min_u32_e32 v129, v129, v139
	v_max_u32_e32 v139, v118, v111
	v_min_u32_e32 v111, v118, v111
	v_max_u32_e32 v118, v112, v110
	v_min_u32_e32 v110, v112, v110
	v_max_u32_e32 v112, v126, v116
	v_min_u32_e32 v116, v126, v116
	v_max_u32_e32 v126, v114, v115
	v_min_u32_e32 v114, v114, v115
	v_max_u32_e32 v115, v120, v119
	v_min_u32_e32 v119, v120, v119
	v_max_u32_e32 v120, v127, v121
	v_min_u32_e32 v121, v127, v121
	v_max_u32_e32 v3, v136, v138
	v_min_u32_e32 v136, v136, v138
	v_max_u32_e32 v138, v137, v147
	v_min_u32_e32 v137, v137, v147
	v_max_u32_e32 v147, v124, v131
	v_min_u32_e32 v124, v124, v131
	v_max_u32_e32 v131, v123, v122
	v_min_u32_e32 v122, v123, v122
	v_max_u32_e32 v123, v134, v2
	v_min_u32_e32 v2, v134, v2
	v_max_u32_e32 v134, v0, v1
	v_min_u32_e32 v0, v0, v1
	v_max_u32_e32 v1, v133, v125
	v_min_u32_e32 v125, v133, v125
	v_max_u32_e32 v133, v135, v132
	v_min_u32_e32 v132, v135, v132
	v_max_u32_e32 v127, v117, v130
	v_min_u32_e32 v117, v117, v130
	v_max_u32_e32 v130, v128, v129
	v_min_u32_e32 v128, v128, v129
	v_max_u32_e32 v129, v139, v118
	v_min_u32_e32 v118, v139, v118
	v_max_u32_e32 v139, v111, v110
	v_min_u32_e32 v110, v111, v110
	v_max_u32_e32 v111, v114, v116
	v_min_u32_e32 v114, v114, v116
	v_max_u32_e32 v116, v126, v112
	v_min_u32_e32 v112, v126, v112
	v_max_u32_e32 v126, v121, v119
	v_min_u32_e32 v119, v121, v119
	v_max_u32_e32 v121, v120, v115
	v_min_u32_e32 v115, v120, v115
	v_max_u32_e32 v135, v3, v138
	v_min_u32_e32 v3, v3, v138
	v_max_u32_e32 v138, v136, v137
	v_min_u32_e32 v136, v136, v137
	v_max_u32_e32 v137, v147, v131
	v_min_u32_e32 v131, v147, v131
	v_max_u32_e32 v147, v124, v122
	v_min_u32_e32 v122, v124, v122
	v_max_u32_e32 v124, v0, v2
	v_min_u32_e32 v0, v0, v2
	v_max_u32_e32 v2, v134, v123
	v_min_u32_e32 v123, v134, v123
	v_max_u32_e32 v134, v132, v125
	v_min_u32_e32 v125, v132, v125
	v_max_u32_e32 v132, v133, v1
	v_min_u32_e32 v1, v133, v1
	v_max_u32_e32 v120, v127, v114
	v_min_u32_e32 v114, v127, v114
	v_max_u32_e32 v127, v117, v111
	v_min_u32_e32 v111, v117, v111
	v_max_u32_e32 v117, v130, v112
	v_min_u32_e32 v112, v130, v112
	v_max_u32_e32 v130, v128, v116
	v_min_u32_e32 v116, v128, v116
	v_max_u32_e32 v128, v129, v119
	v_min_u32_e32 v119, v129, v119
	v_max_u32_e32 v129, v118, v126
	v_min_u32_e32 v118, v118, v126
	v_max_u32_e32 v126, v139, v115
	v_min_u32_e32 v115, v139, v115
	v_max_u32_e32 v139, v110, v121
	v_min_u32_e32 v110, v110, v121
	v_max_u32_e32 v133, v135, v0
	v_min_u32_e32 v0, v135, v0
; #define CE_DESC(a, b) do { const unsigned _mx = (a) > (b) ? (a) : (b), _mn = (a) > (b) ? (b) : (a); (a) = _mx; (b) = _mn; } while (0)
; __device__ __forceinline__ void sort16_desc(unsigned (&k)[16]) {
; #pragma unroll
;     for (int size = 2; size <= 16; size <<= 1)
; #pragma unroll
;         for (int stride = size >> 1; stride > 0; stride >>= 1)
; #pragma unroll
;             for (int i = 0; i < 16; ++i) { const int j = i ^ stride;
;                 if (j > i) { if ((i & size) == 0) CE_DESC(k[i], k[j]); else CE_DESC(k[j], k[i]); } }
; }
; __device__ __forceinline__ void merge16(unsigned (&a)[16], const unsigned (&b)[16]) {
; #pragma unroll
;     for (int i = 0; i < 16; ++i) a[i] = a[i] > b[15 - i] ? a[i] : b[15 - i];
; #pragma unroll
;     for (int stride = 8; stride > 0; stride >>= 1)
; #pragma unroll
;         for (int i = 0; i < 16; ++i) { const int j = i ^ stride; if (j > i) CE_DESC(a[i], a[j]); }
; }
; __device__ __forceinline__ void peer_tile(const Args& A, LAS unsigned char* lds, int tile) {
;     ...
;                 sort16_desc(k0); sort16_desc(k1); merge16(k0, k1);
; #pragma unroll
;                 for (int msk = 16; msk <= 32; msk <<= 1) {
; #pragma unroll
;                     for (int i = 0; i < 16; ++i) k1[i] = (unsigned)__shfl_xor((int)k0[i], msk);
;                     merge16(k0, k1); }
	v_max_u32_e32 v135, v3, v124
	v_min_u32_e32 v3, v3, v124
	v_max_u32_e32 v124, v138, v123
	v_min_u32_e32 v123, v138, v123
	v_max_u32_e32 v138, v136, v2
	v_min_u32_e32 v2, v136, v2
	v_max_u32_e32 v136, v137, v125
	v_min_u32_e32 v125, v137, v125
	v_max_u32_e32 v137, v131, v134
	v_min_u32_e32 v131, v131, v134
	v_max_u32_e32 v134, v147, v1
	v_min_u32_e32 v1, v147, v1
	v_max_u32_e32 v147, v122, v132
	v_min_u32_e32 v122, v122, v132
	v_max_u32_e32 v121, v120, v128
	v_min_u32_e32 v120, v120, v128
	v_max_u32_e32 v128, v127, v129
	v_min_u32_e32 v127, v127, v129
	v_max_u32_e32 v129, v117, v126
	v_min_u32_e32 v117, v117, v126
	v_max_u32_e32 v126, v130, v139
	v_min_u32_e32 v130, v130, v139
	v_max_u32_e32 v139, v114, v119
	v_min_u32_e32 v114, v114, v119
	v_max_u32_e32 v119, v111, v118
	v_min_u32_e32 v111, v111, v118
	v_max_u32_e32 v118, v112, v115
	v_min_u32_e32 v112, v112, v115
	v_max_u32_e32 v115, v116, v110
	v_min_u32_e32 v110, v116, v110
	v_max_u32_e32 v132, v133, v136
	v_min_u32_e32 v133, v133, v136
	v_max_u32_e32 v136, v135, v137
	v_min_u32_e32 v135, v135, v137
	v_max_u32_e32 v137, v124, v134
	v_min_u32_e32 v124, v124, v134
	v_max_u32_e32 v134, v138, v147
	v_min_u32_e32 v138, v138, v147
	v_max_u32_e32 v147, v0, v125
	v_min_u32_e32 v0, v0, v125
	v_max_u32_e32 v125, v3, v131
	v_min_u32_e32 v3, v3, v131
	v_max_u32_e32 v131, v123, v1
	v_min_u32_e32 v1, v123, v1
	v_max_u32_e32 v123, v2, v122
	v_min_u32_e32 v2, v2, v122
	v_max_u32_e32 v116, v121, v129
	v_min_u32_e32 v121, v121, v129
	v_max_u32_e32 v129, v128, v126
	v_min_u32_e32 v126, v128, v126
	v_max_u32_e32 v128, v120, v117
	v_min_u32_e32 v117, v120, v117
	v_max_u32_e32 v120, v127, v130
	v_min_u32_e32 v127, v127, v130
	v_max_u32_e32 v130, v139, v118
	v_min_u32_e32 v118, v139, v118
	v_max_u32_e32 v139, v119, v115
	v_min_u32_e32 v115, v119, v115
	v_max_u32_e32 v119, v114, v112
	v_min_u32_e32 v112, v114, v112
	v_max_u32_e32 v114, v111, v110
	v_min_u32_e32 v110, v111, v110
	v_max_u32_e32 v122, v132, v137
	v_min_u32_e32 v132, v132, v137
	v_max_u32_e32 v137, v136, v134
	v_min_u32_e32 v134, v136, v134
	v_max_u32_e32 v136, v133, v124
	v_min_u32_e32 v124, v133, v124
	v_max_u32_e32 v133, v135, v138
	v_min_u32_e32 v135, v135, v138
	v_max_u32_e32 v138, v147, v131
	v_min_u32_e32 v131, v147, v131
	v_max_u32_e32 v147, v125, v123
	v_min_u32_e32 v123, v125, v123
	v_max_u32_e32 v125, v0, v1
	v_min_u32_e32 v0, v0, v1
	v_max_u32_e32 v1, v3, v2
	v_min_u32_e32 v2, v3, v2
	v_min_u32_e32 v111, v116, v129
	v_min_u32_e32 v140, v121, v126
	v_min_u32_e32 v141, v128, v120
	v_min_u32_e32 v142, v117, v127
	v_min_u32_e32 v143, v130, v139
	v_min_u32_e32 v144, v118, v115
	v_min_u32_e32 v145, v119, v114
	v_min_u32_e32 v146, v112, v110
	v_min_u32_e32 v3, v122, v137
	v_min_u32_e32 v148, v132, v134
	v_min_u32_e32 v149, v136, v133
	v_min_u32_e32 v150, v124, v135
	v_min_u32_e32 v151, v138, v147
	v_min_u32_e32 v152, v131, v123
	v_min_u32_e32 v153, v125, v1
	v_min_u32_e32 v154, v0, v2
	v_max3_u32 v116, v116, v129, v154
	v_max3_u32 v0, v111, v0, v2
	v_max3_u32 v2, v121, v126, v153
	v_max3_u32 v1, v140, v125, v1
	v_max3_u32 v111, v128, v120, v152
	v_max3_u32 v120, v141, v131, v123
	v_max3_u32 v117, v117, v127, v151
	v_max3_u32 v121, v142, v138, v147
	v_max3_u32 v123, v130, v139, v150
	v_max3_u32 v124, v143, v124, v135
	v_max3_u32 v115, v118, v115, v149
	v_max3_u32 v118, v144, v136, v133
	v_max3_u32 v114, v119, v114, v148
	v_max3_u32 v119, v145, v132, v134
	v_max3_u32 v3, v112, v110, v3
	v_max3_u32 v110, v146, v122, v137
	v_max_u32_e32 v112, v116, v123
	v_min_u32_e32 v116, v116, v123
	v_max_u32_e32 v122, v0, v124
	v_min_u32_e32 v0, v0, v124
	v_max_u32_e32 v123, v2, v115
	v_min_u32_e32 v2, v2, v115
	v_max_u32_e32 v115, v1, v118
	v_min_u32_e32 v1, v1, v118
	v_max_u32_e32 v118, v111, v114
	v_min_u32_e32 v111, v111, v114
	v_max_u32_e32 v114, v120, v119
	v_min_u32_e32 v119, v120, v119
	v_max_u32_e32 v120, v117, v3
	v_min_u32_e32 v3, v117, v3
	v_max_u32_e32 v117, v121, v110
	v_min_u32_e32 v110, v121, v110
	v_max_u32_e32 v121, v112, v118
	v_min_u32_e32 v112, v112, v118
	v_max_u32_e32 v118, v122, v114
	v_min_u32_e32 v114, v122, v114
	v_max_u32_e32 v122, v123, v120
	v_min_u32_e32 v120, v123, v120
	v_max_u32_e32 v123, v115, v117
	v_min_u32_e32 v115, v115, v117
	v_max_u32_e32 v117, v116, v111
	v_min_u32_e32 v111, v116, v111
	v_max_u32_e32 v116, v0, v119
	v_min_u32_e32 v0, v0, v119
	v_max_u32_e32 v119, v2, v3
	v_min_u32_e32 v2, v2, v3
	v_max_u32_e32 v3, v1, v110
	v_min_u32_e32 v1, v1, v110
	v_max_u32_e32 v110, v121, v122
	v_min_u32_e32 v121, v121, v122
	v_max_u32_e32 v122, v118, v123
	v_min_u32_e32 v118, v118, v123
	v_max_u32_e32 v123, v112, v120
	v_min_u32_e32 v112, v112, v120
	v_max_u32_e32 v120, v114, v115
	v_min_u32_e32 v114, v114, v115
	v_max_u32_e32 v115, v117, v119
	v_min_u32_e32 v117, v117, v119
	v_max_u32_e32 v119, v116, v3
	v_min_u32_e32 v3, v116, v3
	v_max_u32_e32 v116, v111, v2
	v_min_u32_e32 v2, v111, v2
	v_max_u32_e32 v111, v0, v1
	v_min_u32_e32 v0, v0, v1
	v_max_u32_e32 v1, v110, v122
	v_min_u32_e32 v110, v110, v122
	v_max_u32_e32 v122, v121, v118
	v_min_u32_e32 v118, v121, v118
	v_max_u32_e32 v121, v123, v120
	v_min_u32_e32 v120, v123, v120
	v_max_u32_e32 v123, v112, v114
	v_min_u32_e32 v112, v112, v114
	v_max_u32_e32 v114, v115, v119
	v_min_u32_e32 v115, v115, v119
	v_max_u32_e32 v119, v117, v3
	v_min_u32_e32 v3, v117, v3
	v_max_u32_e32 v117, v116, v111
	v_min_u32_e32 v111, v116, v111
	v_max_u32_e32 v116, v2, v0
	v_min_u32_e32 v0, v2, v0
	ds_bpermute_b32 v2, v27, v1
	ds_bpermute_b32 v124, v27, v110
	ds_bpermute_b32 v125, v27, v122
	ds_bpermute_b32 v126, v27, v118
	ds_bpermute_b32 v127, v27, v121
	ds_bpermute_b32 v128, v27, v120
	ds_bpermute_b32 v129, v27, v123
	ds_bpermute_b32 v130, v27, v112
	ds_bpermute_b32 v131, v27, v114
	ds_bpermute_b32 v132, v27, v115
	ds_bpermute_b32 v133, v27, v119
	ds_bpermute_b32 v134, v27, v0
	ds_bpermute_b32 v135, v27, v116
	ds_bpermute_b32 v136, v27, v111
	ds_bpermute_b32 v137, v27, v117
	ds_bpermute_b32 v138, v27, v3
	s_waitcnt lgkmcnt(4)
; #define CE_DESC(a, b) do { const unsigned _mx = (a) > (b) ? (a) : (b), _mn = (a) > (b) ? (b) : (a); (a) = _mx; (b) = _mn; } while (0)
; __device__ __forceinline__ void merge16(unsigned (&a)[16], const unsigned (&b)[16]) {
; #pragma unroll
;     for (int i = 0; i < 16; ++i) a[i] = a[i] > b[15 - i] ? a[i] : b[15 - i];
; #pragma unroll
;     for (int stride = 8; stride > 0; stride >>= 1)
; #pragma unroll
;         for (int i = 0; i < 16; ++i) { const int j = i ^ stride; if (j > i) CE_DESC(a[i], a[j]); }
; __device__ __forceinline__ void peer_tile(const Args& A, LAS unsigned char* lds, int tile) {
;     ...
;                 for (int msk = 16; msk <= 32; msk <<= 1) {
; #pragma unroll
;                     for (int i = 0; i < 16; ++i) k1[i] = (unsigned)__shfl_xor((int)k0[i], msk);
;                     merge16(k0, k1); }
	v_max_u32_e32 v1, v1, v134
	s_waitcnt lgkmcnt(3)
	v_max_u32_e32 v110, v110, v135
	s_waitcnt lgkmcnt(2)
	v_max_u32_e32 v122, v122, v136
	s_waitcnt lgkmcnt(1)
	v_max_u32_e32 v118, v118, v137
	s_waitcnt lgkmcnt(0)
	v_max_u32_e32 v121, v121, v138
	v_max_u32_e32 v120, v120, v133
	v_max_u32_e32 v123, v123, v132
	v_max_u32_e32 v112, v112, v131
	v_max_u32_e32 v114, v114, v130
	v_max_u32_e32 v115, v115, v129
	v_max_u32_e32 v119, v119, v128
	v_max_u32_e32 v3, v3, v127
	v_max_u32_e32 v117, v117, v126
	v_max_u32_e32 v111, v111, v125
	v_max_u32_e32 v116, v116, v124
	v_max_u32_e32 v0, v0, v2
	v_max_u32_e32 v2, v1, v114
	v_min_u32_e32 v1, v1, v114
	v_max_u32_e32 v114, v110, v115
	v_min_u32_e32 v110, v110, v115
	v_max_u32_e32 v115, v122, v119
	v_min_u32_e32 v119, v122, v119
	v_max_u32_e32 v122, v118, v3
	v_min_u32_e32 v3, v118, v3
	v_max_u32_e32 v118, v121, v117
	v_min_u32_e32 v117, v121, v117
	v_max_u32_e32 v121, v120, v111
	v_min_u32_e32 v111, v120, v111
	v_max_u32_e32 v120, v123, v116
	v_min_u32_e32 v116, v123, v116
	v_max_u32_e32 v123, v112, v0
	v_min_u32_e32 v0, v112, v0
	v_max_u32_e32 v112, v2, v118
	v_min_u32_e32 v2, v2, v118
	v_max_u32_e32 v118, v114, v121
	v_min_u32_e32 v114, v114, v121
	v_max_u32_e32 v121, v115, v120
	v_min_u32_e32 v115, v115, v120
	v_max_u32_e32 v120, v122, v123
	v_min_u32_e32 v122, v122, v123
	v_max_u32_e32 v123, v1, v117
	v_min_u32_e32 v1, v1, v117
	v_max_u32_e32 v117, v110, v111
	v_min_u32_e32 v110, v110, v111
	v_max_u32_e32 v111, v119, v116
	v_min_u32_e32 v116, v119, v116
	v_max_u32_e32 v119, v3, v0
	v_min_u32_e32 v0, v3, v0
	v_max_u32_e32 v3, v112, v121
	v_min_u32_e32 v112, v112, v121
	v_max_u32_e32 v121, v118, v120
	v_min_u32_e32 v118, v118, v120
	v_max_u32_e32 v120, v2, v115
	v_min_u32_e32 v2, v2, v115
	v_max_u32_e32 v115, v114, v122
	v_min_u32_e32 v114, v114, v122
	v_max_u32_e32 v122, v123, v111
	v_min_u32_e32 v111, v123, v111
	v_max_u32_e32 v123, v117, v119
	v_min_u32_e32 v117, v117, v119
	v_max_u32_e32 v119, v1, v116
	v_min_u32_e32 v1, v1, v116
	v_max_u32_e32 v116, v110, v0
	v_min_u32_e32 v0, v110, v0
	v_max_u32_e32 v110, v3, v121
	v_min_u32_e32 v3, v3, v121
	v_max_u32_e32 v121, v112, v118
	v_min_u32_e32 v112, v112, v118
	v_max_u32_e32 v118, v120, v115
	v_min_u32_e32 v115, v120, v115
	v_max_u32_e32 v120, v2, v114
	v_min_u32_e32 v2, v2, v114
	v_max_u32_e32 v114, v122, v123
	v_min_u32_e32 v122, v122, v123
	v_max_u32_e32 v123, v111, v117
	v_min_u32_e32 v111, v111, v117
	v_max_u32_e32 v117, v119, v116
	v_min_u32_e32 v116, v119, v116
	v_max_u32_e32 v119, v1, v0
	v_min_u32_e32 v0, v1, v0
	ds_bpermute_b32 v128, v29, v0
	ds_bpermute_b32 v1, v29, v110
	ds_bpermute_b32 v124, v29, v3
	ds_bpermute_b32 v125, v29, v121
	ds_bpermute_b32 v126, v29, v112
	s_waitcnt lgkmcnt(4)
	v_max_u32_e32 v110, v110, v128
	global_load_dwordx4 v[128:131], v[4:5], off offset:1552
	global_load_dwordx4 v[132:135], v[4:5], off offset:1536
	ds_bpermute_b32 v127, v29, v118
	ds_bpermute_b32 v136, v29, v115
	ds_bpermute_b32 v137, v29, v120
	ds_bpermute_b32 v138, v29, v2
	ds_bpermute_b32 v139, v29, v114
	ds_bpermute_b32 v140, v29, v122
	ds_bpermute_b32 v141, v29, v123
	ds_bpermute_b32 v142, v29, v111
	ds_bpermute_b32 v143, v29, v117
	ds_bpermute_b32 v144, v29, v119
	ds_bpermute_b32 v145, v29, v116
	s_waitcnt lgkmcnt(4)
	v_max_u32_e32 v115, v115, v141
	s_waitcnt lgkmcnt(3)
	v_max_u32_e32 v118, v118, v142
	s_waitcnt lgkmcnt(2)
	v_max_u32_e32 v112, v112, v143
	s_waitcnt lgkmcnt(1)
	v_max_u32_e32 v3, v3, v144
	s_waitcnt lgkmcnt(0)
	v_max_u32_e32 v121, v121, v145
	v_max_u32_e32 v120, v120, v140
	v_max_u32_e32 v2, v2, v139
	v_max_u32_e32 v114, v114, v138
	v_max_u32_e32 v122, v122, v137
	v_max_u32_e32 v123, v123, v136
	v_max_u32_e32 v111, v111, v127
	v_max_u32_e32 v117, v117, v126
	v_max_u32_e32 v116, v116, v125
	v_max_u32_e32 v119, v119, v124
	v_max_u32_e32 v0, v0, v1
	v_max_u32_e32 v1, v110, v114
	v_min_u32_e32 v110, v110, v114
	v_max_u32_e32 v114, v3, v122
	v_min_u32_e32 v3, v3, v122
	v_max_u32_e32 v122, v121, v123
	v_min_u32_e32 v121, v121, v123
	v_max_u32_e32 v123, v112, v111
	v_min_u32_e32 v111, v112, v111
	v_max_u32_e32 v112, v118, v117
	v_min_u32_e32 v117, v118, v117
	v_max_u32_e32 v118, v115, v116
	v_min_u32_e32 v115, v115, v116
	v_max_u32_e32 v116, v120, v119
	v_min_u32_e32 v119, v120, v119
	v_max_u32_e32 v120, v2, v0
	v_min_u32_e32 v0, v2, v0
	v_max_u32_e32 v2, v1, v112
	v_min_u32_e32 v1, v1, v112
	v_max_u32_e32 v112, v114, v118
	v_min_u32_e32 v114, v114, v118
	v_max_u32_e32 v118, v122, v116
	v_min_u32_e32 v116, v122, v116
	v_max_u32_e32 v122, v123, v120
	v_min_u32_e32 v120, v123, v120
	v_max_u32_e32 v123, v110, v117
	v_min_u32_e32 v110, v110, v117
	v_max_u32_e32 v117, v3, v115
	v_min_u32_e32 v3, v3, v115
	v_max_u32_e32 v115, v121, v119
	v_min_u32_e32 v119, v121, v119
	v_max_u32_e32 v121, v111, v0
	v_min_u32_e32 v0, v111, v0
	v_max_u32_e32 v111, v2, v118
	v_min_u32_e32 v2, v2, v118
	v_max_u32_e32 v118, v112, v122
	v_min_u32_e32 v112, v112, v122
	v_max_u32_e32 v127, v1, v116
	v_min_u32_e32 v1, v1, v116
	v_max_u32_e32 v116, v114, v120
	v_min_u32_e32 v114, v114, v120
	v_max_u32_e32 v136, v123, v115
	v_min_u32_e32 v115, v123, v115
	v_max_u32_e32 v137, v117, v121
	v_min_u32_e32 v138, v117, v121
	v_max_u32_e32 v139, v110, v119
	v_min_u32_e32 v110, v110, v119
	v_max_u32_e32 v140, v3, v0
	v_min_u32_e32 v0, v3, v0
	v_max_u32_e32 v126, v111, v118
	v_min_u32_e32 v125, v111, v118
	v_max_u32_e32 v124, v2, v112
	v_min_u32_e32 v123, v2, v112
	v_max_u32_e32 v122, v127, v116
	v_min_u32_e32 v121, v127, v116
	v_max_u32_e32 v120, v1, v114
	v_min_u32_e32 v119, v1, v114
	v_max_u32_e32 v118, v136, v137
	v_min_u32_e32 v117, v136, v137
	v_max_u32_e32 v116, v115, v138
	v_min_u32_e32 v115, v115, v138
	v_max_u32_e32 v114, v139, v140
	v_min_u32_e32 v112, v139, v140
	v_max_u32_e32 v111, v110, v0
	v_min_u32_e32 v110, v110, v0
	global_load_dwordx4 v[0:3], v[4:5], off offset:1584
	global_load_dwordx4 v[136:139], v[4:5], off offset:1568
	s_waitcnt vmcnt(2)
; __device__ __forceinline__ unsigned f2key(float f) { const unsigned u = __float_as_uint(f); return (u & 0x80000000u) ? ~u : (u | 0x80000000u); }
; __device__ __forceinline__ void peer_tile(const Args& A, LAS unsigned char* lds, int tile) {
;     ...
;                 { const bf16_t* sp = QRY + m * 2048 + hp * 128 + 32 * g;
;                   const u32x4 s0 = *(const u32x4*)sp, s1 = *(const u32x4*)(sp + 8), s2 = *(const u32x4*)(sp + 16), s3 = *(const u32x4*)(sp + 24);
;                   const unsigned sw[16] = {s0.x, s0.y, s0.z, s0.w, s1.x, s1.y, s1.z, s1.w, s2.x, s2.y, s2.z, s2.w, s3.x, s3.y, s3.z, s3.w};
; #pragma unroll
;                   for (int i = 0; i < 16; ++i) {
;                       const float lo = (float)__builtin_bit_cast(_Float16, (unsigned short)(sw[i] & 0xffffu)), hi = (float)__builtin_bit_cast(_Float16, (unsigned short)(sw[i] >> 16));
;                       const unsigned klo = (f2key(lo) & ~127u) | (unsigned)(127 - (32 * g + 2 * i)), khi = (f2key(hi) & ~127u) | (unsigned)(127 - (32 * g + 2 * i + 1));
;                       if (i < 8) { k0[2 * i] = klo; k0[2 * i + 1] = khi; } else { k1[2 * (i - 8)] = klo; k1[2 * (i - 8) + 1] = khi; } } }
	v_cvt_f32_f16_sdwa v127, v132 dst_sel:DWORD dst_unused:UNUSED_PAD src0_sel:WORD_1
	v_cvt_f32_f16_e32 v132, v132
	v_not_b32_e32 v140, v127
	v_or_b32_e32 v141, 0x80000000, v127
	v_cmp_gt_i32_e32 vcc, 0, v127
	s_nop 1
	v_cndmask_b32_e32 v127, v141, v140, vcc
	v_not_b32_e32 v140, v132
	v_or_b32_e32 v141, 0x80000000, v132
	v_cmp_gt_i32_e32 vcc, 0, v132
	v_and_b32_e32 v127, 0xffffff80, v127
	v_sub_u32_e32 v127, v127, v15
	v_cndmask_b32_e32 v132, v141, v140, vcc
	v_cvt_f32_f16_sdwa v140, v133 dst_sel:DWORD dst_unused:UNUSED_PAD src0_sel:WORD_1
	v_cvt_f32_f16_e32 v133, v133
	v_and_b32_e32 v132, 0xffffff80, v132
	v_sub_u32_e32 v132, v132, v15
	v_not_b32_e32 v141, v140
	v_or_b32_e32 v142, 0x80000000, v140
	v_cmp_gt_i32_e32 vcc, 0, v140
	v_add_u32_e32 v127, 0x7e, v127
	v_add_u32_e32 v132, 0x7f, v132
	v_cndmask_b32_e32 v140, v142, v141, vcc
	v_not_b32_e32 v141, v133
	v_or_b32_e32 v142, 0x80000000, v133
	v_cmp_gt_i32_e32 vcc, 0, v133
	v_and_b32_e32 v140, 0xffffff80, v140
	v_sub_u32_e32 v140, v140, v14
	v_cndmask_b32_e32 v133, v142, v141, vcc
	v_cvt_f32_f16_sdwa v141, v134 dst_sel:DWORD dst_unused:UNUSED_PAD src0_sel:WORD_1
	v_cvt_f32_f16_e32 v134, v134
	v_and_b32_e32 v133, 0xffffff80, v133
	v_sub_u32_e32 v133, v133, v14
	v_not_b32_e32 v142, v141
	v_or_b32_e32 v143, 0x80000000, v141
	v_cmp_gt_i32_e32 vcc, 0, v141
	v_add_u32_e32 v140, 0x7e, v140
	v_add_u32_e32 v133, 0x7f, v133
	v_cndmask_b32_e32 v141, v143, v142, vcc
	v_not_b32_e32 v142, v134
	v_or_b32_e32 v143, 0x80000000, v134
	v_cmp_gt_i32_e32 vcc, 0, v134
	v_and_b32_e32 v141, 0xffffff80, v141
	v_sub_u32_e32 v141, v141, v12
	v_cndmask_b32_e32 v134, v143, v142, vcc
	v_cvt_f32_f16_sdwa v142, v135 dst_sel:DWORD dst_unused:UNUSED_PAD src0_sel:WORD_1
	v_cvt_f32_f16_e32 v135, v135
	v_and_b32_e32 v134, 0xffffff80, v134
	v_sub_u32_e32 v134, v134, v12
	v_not_b32_e32 v143, v142
	v_or_b32_e32 v144, 0x80000000, v142
	v_cmp_gt_i32_e32 vcc, 0, v142
	v_add_u32_e32 v141, 0x7e, v141
	v_add_u32_e32 v134, 0x7f, v134
	v_cndmask_b32_e32 v142, v144, v143, vcc
	v_not_b32_e32 v143, v135
	v_or_b32_e32 v144, 0x80000000, v135
	v_cmp_gt_i32_e32 vcc, 0, v135
	v_and_b32_e32 v142, 0xffffff80, v142
	v_sub_u32_e32 v142, v142, v10
	v_cndmask_b32_e32 v135, v144, v143, vcc
	v_cvt_f32_f16_sdwa v143, v128 dst_sel:DWORD dst_unused:UNUSED_PAD src0_sel:WORD_1
	v_cvt_f32_f16_e32 v128, v128
	v_and_b32_e32 v135, 0xffffff80, v135
	v_sub_u32_e32 v135, v135, v10
	v_not_b32_e32 v144, v143
	v_or_b32_e32 v145, 0x80000000, v143
	v_cmp_gt_i32_e32 vcc, 0, v143
	v_add_u32_e32 v142, 0x7e, v142
	v_add_u32_e32 v135, 0x7f, v135
	v_cndmask_b32_e32 v143, v145, v144, vcc
	v_not_b32_e32 v144, v128
	v_or_b32_e32 v145, 0x80000000, v128
	v_cmp_gt_i32_e32 vcc, 0, v128
	v_and_b32_e32 v143, 0xffffff80, v143
	v_sub_u32_e32 v143, v143, v8
	v_cndmask_b32_e32 v128, v145, v144, vcc
	v_cvt_f32_f16_sdwa v144, v129 dst_sel:DWORD dst_unused:UNUSED_PAD src0_sel:WORD_1
	v_cvt_f32_f16_e32 v129, v129
	v_and_b32_e32 v128, 0xffffff80, v128
	v_sub_u32_e32 v128, v128, v8
	v_not_b32_e32 v145, v144
	v_or_b32_e32 v146, 0x80000000, v144
	v_cmp_gt_i32_e32 vcc, 0, v144
	v_add_u32_e32 v143, 0x7e, v143
	v_add_u32_e32 v128, 0x7f, v128
	v_cndmask_b32_e32 v144, v146, v145, vcc
	v_not_b32_e32 v145, v129
	v_or_b32_e32 v146, 0x80000000, v129
	v_cmp_gt_i32_e32 vcc, 0, v129
	v_and_b32_e32 v144, 0xffffff80, v144
	v_sub_u32_e32 v144, v144, v16
	v_cndmask_b32_e32 v129, v146, v145, vcc
	v_cvt_f32_f16_sdwa v145, v130 dst_sel:DWORD dst_unused:UNUSED_PAD src0_sel:WORD_1
	v_cvt_f32_f16_e32 v130, v130
	v_and_b32_e32 v129, 0xffffff80, v129
	v_sub_u32_e32 v129, v129, v16
	v_not_b32_e32 v146, v145
	v_or_b32_e32 v147, 0x80000000, v145
	v_cmp_gt_i32_e32 vcc, 0, v145
	v_add_u32_e32 v144, 0x7e, v144
	v_add_u32_e32 v129, 0x7f, v129
	v_cndmask_b32_e32 v145, v147, v146, vcc
	v_not_b32_e32 v146, v130
	v_or_b32_e32 v147, 0x80000000, v130
	v_cmp_gt_i32_e32 vcc, 0, v130
	v_and_b32_e32 v145, 0xffffff80, v145
	v_sub_u32_e32 v145, v145, v17
	v_cndmask_b32_e32 v130, v147, v146, vcc
	v_cvt_f32_f16_sdwa v146, v131 dst_sel:DWORD dst_unused:UNUSED_PAD src0_sel:WORD_1
	v_cvt_f32_f16_e32 v131, v131
	v_and_b32_e32 v130, 0xffffff80, v130
	v_sub_u32_e32 v130, v130, v17
	v_not_b32_e32 v147, v146
	v_or_b32_e32 v148, 0x80000000, v146
	v_cmp_gt_i32_e32 vcc, 0, v146
	v_add_u32_e32 v145, 0x7e, v145
	v_add_u32_e32 v130, 0x7f, v130
	v_cndmask_b32_e32 v146, v148, v147, vcc
	v_not_b32_e32 v147, v131
	v_or_b32_e32 v148, 0x80000000, v131
	v_cmp_gt_i32_e32 vcc, 0, v131
	v_and_b32_e32 v146, 0xffffff80, v146
	v_sub_u32_e32 v146, v146, v18
	v_cndmask_b32_e32 v131, v148, v147, vcc
	s_waitcnt vmcnt(0)
; __device__ __forceinline__ unsigned f2key(float f) { const unsigned u = __float_as_uint(f); return (u & 0x80000000u) ? ~u : (u | 0x80000000u); }
; #define CE_DESC(a, b) do { const unsigned _mx = (a) > (b) ? (a) : (b), _mn = (a) > (b) ? (b) : (a); (a) = _mx; (b) = _mn; } while (0)
; __device__ __forceinline__ void sort16_desc(unsigned (&k)[16]) {
; #pragma unroll
;     for (int size = 2; size <= 16; size <<= 1)
; #pragma unroll
;         for (int stride = size >> 1; stride > 0; stride >>= 1)
; #pragma unroll
;             for (int i = 0; i < 16; ++i) { const int j = i ^ stride;
;                 if (j > i) { if ((i & size) == 0) CE_DESC(k[i], k[j]); else CE_DESC(k[j], k[i]); } }
; __device__ __forceinline__ void peer_tile(const Args& A, LAS unsigned char* lds, int tile) {
;     ...
;                       const float lo = (float)__builtin_bit_cast(_Float16, (unsigned short)(sw[i] & 0xffffu)), hi = (float)__builtin_bit_cast(_Float16, (unsigned short)(sw[i] >> 16));
;                       const unsigned klo = (f2key(lo) & ~127u) | (unsigned)(127 - (32 * g + 2 * i)), khi = (f2key(hi) & ~127u) | (unsigned)(127 - (32 * g + 2 * i + 1));
;                       if (i < 8) { k0[2 * i] = klo; k0[2 * i + 1] = khi; } else { k1[2 * (i - 8)] = klo; k1[2 * (i - 8) + 1] = khi; } } }
	v_cvt_f32_f16_sdwa v147, v136 dst_sel:DWORD dst_unused:UNUSED_PAD src0_sel:WORD_1
	v_cvt_f32_f16_e32 v136, v136
	v_and_b32_e32 v131, 0xffffff80, v131
	v_sub_u32_e32 v131, v131, v18
	v_not_b32_e32 v148, v147
	v_or_b32_e32 v149, 0x80000000, v147
	v_cmp_gt_i32_e32 vcc, 0, v147
	v_add_u32_e32 v146, 0x7e, v146
	v_add_u32_e32 v131, 0x7f, v131
	v_cndmask_b32_e32 v147, v149, v148, vcc
	v_not_b32_e32 v148, v136
	v_or_b32_e32 v149, 0x80000000, v136
	v_cmp_gt_i32_e32 vcc, 0, v136
	v_and_b32_e32 v147, 0xffffff80, v147
	v_sub_u32_e32 v147, v147, v20
	v_cndmask_b32_e32 v136, v149, v148, vcc
	v_cvt_f32_f16_sdwa v148, v137 dst_sel:DWORD dst_unused:UNUSED_PAD src0_sel:WORD_1
	v_cvt_f32_f16_e32 v137, v137
	v_and_b32_e32 v136, 0xffffff80, v136
	v_sub_u32_e32 v136, v136, v20
	v_not_b32_e32 v149, v148
	v_or_b32_e32 v150, 0x80000000, v148
	v_cmp_gt_i32_e32 vcc, 0, v148
	v_add_u32_e32 v147, 0x7e, v147
	v_add_u32_e32 v136, 0x7f, v136
	v_cndmask_b32_e32 v148, v150, v149, vcc
	v_not_b32_e32 v149, v137
	v_or_b32_e32 v150, 0x80000000, v137
	v_cmp_gt_i32_e32 vcc, 0, v137
	v_and_b32_e32 v148, 0xffffff80, v148
	v_sub_u32_e32 v148, v148, v21
	v_cndmask_b32_e32 v137, v150, v149, vcc
	v_cvt_f32_f16_sdwa v149, v138 dst_sel:DWORD dst_unused:UNUSED_PAD src0_sel:WORD_1
	v_cvt_f32_f16_e32 v138, v138
	v_and_b32_e32 v137, 0xffffff80, v137
	v_sub_u32_e32 v137, v137, v21
	v_not_b32_e32 v150, v149
	v_or_b32_e32 v151, 0x80000000, v149
	v_cmp_gt_i32_e32 vcc, 0, v149
	v_add_u32_e32 v148, 0x7e, v148
	v_add_u32_e32 v137, 0x7f, v137
	v_cndmask_b32_e32 v149, v151, v150, vcc
	v_not_b32_e32 v150, v138
	v_or_b32_e32 v151, 0x80000000, v138
	v_cmp_gt_i32_e32 vcc, 0, v138
	v_and_b32_e32 v149, 0xffffff80, v149
	v_sub_u32_e32 v149, v149, v22
	v_cndmask_b32_e32 v138, v151, v150, vcc
	v_cvt_f32_f16_sdwa v150, v139 dst_sel:DWORD dst_unused:UNUSED_PAD src0_sel:WORD_1
	v_cvt_f32_f16_e32 v139, v139
	v_and_b32_e32 v138, 0xffffff80, v138
	v_sub_u32_e32 v138, v138, v22
	v_not_b32_e32 v151, v150
	v_or_b32_e32 v152, 0x80000000, v150
	v_cmp_gt_i32_e32 vcc, 0, v150
	v_add_u32_e32 v149, 0x7e, v149
	v_add_u32_e32 v138, 0x7f, v138
	v_cndmask_b32_e32 v150, v152, v151, vcc
	v_not_b32_e32 v151, v139
	v_or_b32_e32 v152, 0x80000000, v139
	v_cmp_gt_i32_e32 vcc, 0, v139
	v_and_b32_e32 v150, 0xffffff80, v150
	v_sub_u32_e32 v150, v150, v23
	v_cndmask_b32_e32 v139, v152, v151, vcc
	v_cvt_f32_f16_sdwa v151, v0 dst_sel:DWORD dst_unused:UNUSED_PAD src0_sel:WORD_1
	v_cvt_f32_f16_e32 v0, v0
	v_and_b32_e32 v139, 0xffffff80, v139
	v_sub_u32_e32 v139, v139, v23
	v_not_b32_e32 v152, v151
	v_or_b32_e32 v153, 0x80000000, v151
	v_cmp_gt_i32_e32 vcc, 0, v151
	v_add_u32_e32 v150, 0x7e, v150
	v_add_u32_e32 v139, 0x7f, v139
	v_cndmask_b32_e32 v151, v153, v152, vcc
	v_not_b32_e32 v152, v0
	v_or_b32_e32 v153, 0x80000000, v0
	v_cmp_gt_i32_e32 vcc, 0, v0
	v_and_b32_e32 v151, 0xffffff80, v151
	v_sub_u32_e32 v151, v151, v24
	v_cndmask_b32_e32 v0, v153, v152, vcc
	v_cvt_f32_f16_sdwa v152, v1 dst_sel:DWORD dst_unused:UNUSED_PAD src0_sel:WORD_1
	v_cvt_f32_f16_e32 v1, v1
	v_and_b32_e32 v0, 0xffffff80, v0
	v_sub_u32_e32 v0, v0, v24
	v_not_b32_e32 v153, v152
	v_or_b32_e32 v154, 0x80000000, v152
	v_cmp_gt_i32_e32 vcc, 0, v152
	v_add_u32_e32 v151, 0x7e, v151
	v_add_u32_e32 v0, 0x7f, v0
	v_cndmask_b32_e32 v152, v154, v153, vcc
	v_not_b32_e32 v153, v1
	v_or_b32_e32 v154, 0x80000000, v1
	v_cmp_gt_i32_e32 vcc, 0, v1
	v_and_b32_e32 v152, 0xffffff80, v152
	v_sub_u32_e32 v152, v152, v25
	v_cndmask_b32_e32 v1, v154, v153, vcc
	v_cvt_f32_f16_sdwa v153, v2 dst_sel:DWORD dst_unused:UNUSED_PAD src0_sel:WORD_1
	v_cvt_f32_f16_e32 v2, v2
	v_and_b32_e32 v1, 0xffffff80, v1
	v_sub_u32_e32 v1, v1, v25
	v_not_b32_e32 v154, v153
	v_or_b32_e32 v155, 0x80000000, v153
	v_cmp_gt_i32_e32 vcc, 0, v153
	v_add_u32_e32 v152, 0x7e, v152
	v_add_u32_e32 v1, 0x7f, v1
	v_cndmask_b32_e32 v153, v155, v154, vcc
	v_not_b32_e32 v154, v2
	v_or_b32_e32 v155, 0x80000000, v2
	v_cmp_gt_i32_e32 vcc, 0, v2
	v_and_b32_e32 v153, 0xffffff80, v153
	v_sub_u32_e32 v153, v153, v26
	v_cndmask_b32_e32 v2, v155, v154, vcc
	v_cvt_f32_f16_sdwa v154, v3 dst_sel:DWORD dst_unused:UNUSED_PAD src0_sel:WORD_1
	v_cvt_f32_f16_e32 v3, v3
	v_and_b32_e32 v2, 0xffffff80, v2
	v_sub_u32_e32 v2, v2, v26
	v_not_b32_e32 v155, v154
	v_or_b32_e32 v156, 0x80000000, v154
	v_cmp_gt_i32_e32 vcc, 0, v154
	v_add_u32_e32 v153, 0x7e, v153
	v_add_u32_e32 v2, 0x7f, v2
	v_cndmask_b32_e32 v154, v156, v155, vcc
	v_not_b32_e32 v155, v3
	v_or_b32_e32 v156, 0x80000000, v3
	v_cmp_gt_i32_e32 vcc, 0, v3
	v_and_b32_e32 v154, 0xffffff80, v154
	v_sub_u32_e32 v154, v154, v28
	v_cndmask_b32_e32 v3, v156, v155, vcc
	v_and_b32_e32 v3, 0xffffff80, v3
	v_sub_u32_e32 v3, v3, v28
	v_add_u32_e32 v154, 0x7e, v154
	v_add_u32_e32 v3, 0x7f, v3
	v_max_u32_e32 v155, v132, v127
	v_min_u32_e32 v127, v132, v127
	v_max_u32_e32 v132, v140, v133
	v_min_u32_e32 v133, v140, v133
	v_max_u32_e32 v140, v134, v141
	v_min_u32_e32 v134, v134, v141
	v_max_u32_e32 v141, v142, v135
	v_min_u32_e32 v135, v142, v135
	v_max_u32_e32 v142, v128, v143
	v_min_u32_e32 v128, v128, v143
	v_max_u32_e32 v143, v144, v129
	v_min_u32_e32 v129, v144, v129
	v_max_u32_e32 v144, v130, v145
	v_min_u32_e32 v130, v130, v145
	v_max_u32_e32 v145, v146, v131
	v_min_u32_e32 v131, v146, v131
	v_max_u32_e32 v163, v136, v147
	v_min_u32_e32 v136, v136, v147
	v_max_u32_e32 v147, v148, v137
	v_min_u32_e32 v137, v148, v137
	v_max_u32_e32 v148, v138, v149
	v_min_u32_e32 v138, v138, v149
	v_max_u32_e32 v149, v150, v139
	v_min_u32_e32 v139, v150, v139
	v_max_u32_e32 v150, v0, v151
	v_min_u32_e32 v0, v0, v151
	v_max_u32_e32 v151, v152, v1
	v_min_u32_e32 v1, v152, v1
	v_max_u32_e32 v152, v2, v153
	v_min_u32_e32 v2, v2, v153
; #define CE_DESC(a, b) do { const unsigned _mx = (a) > (b) ? (a) : (b), _mn = (a) > (b) ? (b) : (a); (a) = _mx; (b) = _mn; } while (0)
; __device__ __forceinline__ void sort16_desc(unsigned (&k)[16]) {
; #pragma unroll
;     for (int size = 2; size <= 16; size <<= 1)
; #pragma unroll
;         for (int stride = size >> 1; stride > 0; stride >>= 1)
; #pragma unroll
;             for (int i = 0; i < 16; ++i) { const int j = i ^ stride;
;                 if (j > i) { if ((i & size) == 0) CE_DESC(k[i], k[j]); else CE_DESC(k[j], k[i]); } }
	v_max_u32_e32 v153, v154, v3
	v_min_u32_e32 v3, v154, v3
	v_max_u32_e32 v146, v155, v133
	v_min_u32_e32 v133, v155, v133
	v_max_u32_e32 v155, v127, v132
	v_min_u32_e32 v127, v127, v132
	v_max_u32_e32 v132, v135, v140
	v_min_u32_e32 v135, v135, v140
	v_max_u32_e32 v140, v141, v134
	v_min_u32_e32 v134, v141, v134
	v_max_u32_e32 v141, v142, v129
	v_min_u32_e32 v129, v142, v129
	v_max_u32_e32 v142, v128, v143
	v_min_u32_e32 v128, v128, v143
	v_max_u32_e32 v143, v131, v144
	v_min_u32_e32 v131, v131, v144
	v_max_u32_e32 v144, v145, v130
	v_min_u32_e32 v130, v145, v130
	v_max_u32_e32 v154, v163, v137
	v_min_u32_e32 v137, v163, v137
	v_max_u32_e32 v163, v136, v147
	v_min_u32_e32 v136, v136, v147
	v_max_u32_e32 v147, v139, v148
	v_min_u32_e32 v139, v139, v148
	v_max_u32_e32 v148, v149, v138
	v_min_u32_e32 v138, v149, v138
	v_max_u32_e32 v149, v150, v1
	v_min_u32_e32 v1, v150, v1
	v_max_u32_e32 v150, v0, v151
	v_min_u32_e32 v0, v0, v151
	v_max_u32_e32 v151, v3, v152
	v_min_u32_e32 v3, v3, v152
	v_max_u32_e32 v152, v153, v2
	v_min_u32_e32 v2, v153, v2
	v_max_u32_e32 v145, v146, v155
	v_min_u32_e32 v146, v146, v155
	v_max_u32_e32 v155, v133, v127
	v_min_u32_e32 v127, v133, v127
	v_max_u32_e32 v133, v134, v135
	v_min_u32_e32 v134, v134, v135
	v_max_u32_e32 v135, v140, v132
	v_min_u32_e32 v132, v140, v132
	v_max_u32_e32 v140, v141, v142
	v_min_u32_e32 v141, v141, v142
	v_max_u32_e32 v142, v129, v128
	v_min_u32_e32 v128, v129, v128
	v_max_u32_e32 v129, v130, v131
	v_min_u32_e32 v130, v130, v131
	v_max_u32_e32 v131, v144, v143
	v_min_u32_e32 v143, v144, v143
	v_max_u32_e32 v153, v154, v163
	v_min_u32_e32 v154, v154, v163
	v_max_u32_e32 v163, v137, v136
	v_min_u32_e32 v136, v137, v136
	v_max_u32_e32 v137, v138, v139
	v_min_u32_e32 v138, v138, v139
	v_max_u32_e32 v139, v148, v147
	v_min_u32_e32 v147, v148, v147
	v_max_u32_e32 v148, v149, v150
	v_min_u32_e32 v149, v149, v150
	v_max_u32_e32 v150, v1, v0
	v_min_u32_e32 v0, v1, v0
	v_max_u32_e32 v1, v2, v3
	v_min_u32_e32 v2, v2, v3
	v_max_u32_e32 v3, v152, v151
	v_min_u32_e32 v151, v152, v151
	v_max_u32_e32 v144, v145, v134
	v_min_u32_e32 v134, v145, v134
	v_max_u32_e32 v145, v146, v133
	v_min_u32_e32 v133, v146, v133
	v_max_u32_e32 v146, v155, v132
	v_min_u32_e32 v132, v155, v132
	v_max_u32_e32 v155, v127, v135
	v_min_u32_e32 v127, v127, v135
	v_max_u32_e32 v135, v130, v140
	v_min_u32_e32 v130, v130, v140
	v_max_u32_e32 v140, v129, v141
	v_min_u32_e32 v129, v129, v141
	v_max_u32_e32 v141, v143, v142
	v_min_u32_e32 v142, v143, v142
	v_max_u32_e32 v143, v131, v128
	v_min_u32_e32 v128, v131, v128
	v_max_u32_e32 v152, v153, v138
	v_min_u32_e32 v138, v153, v138
	v_max_u32_e32 v153, v154, v137
	v_min_u32_e32 v137, v154, v137
	v_max_u32_e32 v154, v163, v147
	v_min_u32_e32 v147, v163, v147
	v_max_u32_e32 v163, v136, v139
	v_min_u32_e32 v136, v136, v139
	v_max_u32_e32 v139, v2, v148
	v_min_u32_e32 v2, v2, v148
	v_max_u32_e32 v148, v1, v149
	v_min_u32_e32 v1, v1, v149
	v_max_u32_e32 v149, v151, v150
	v_min_u32_e32 v150, v151, v150
	v_max_u32_e32 v151, v3, v0
	v_min_u32_e32 v0, v3, v0
	v_max_u32_e32 v131, v144, v146
	v_min_u32_e32 v144, v144, v146
	v_max_u32_e32 v146, v145, v155
	v_min_u32_e32 v145, v145, v155
	v_max_u32_e32 v155, v134, v132
	v_min_u32_e32 v132, v134, v132
	v_max_u32_e32 v134, v133, v127
	v_min_u32_e32 v127, v133, v127
	v_max_u32_e32 v133, v142, v130
	v_min_u32_e32 v130, v142, v130
	v_max_u32_e32 v142, v128, v129
	v_min_u32_e32 v128, v128, v129
	v_max_u32_e32 v129, v141, v135
	v_min_u32_e32 v135, v141, v135
	v_max_u32_e32 v141, v143, v140
	v_min_u32_e32 v140, v143, v140
	v_max_u32_e32 v3, v152, v154
	v_min_u32_e32 v152, v152, v154
	v_max_u32_e32 v154, v153, v163
	v_min_u32_e32 v153, v153, v163
	v_max_u32_e32 v163, v138, v147
	v_min_u32_e32 v138, v138, v147
	v_max_u32_e32 v147, v137, v136
	v_min_u32_e32 v136, v137, v136
	v_max_u32_e32 v137, v150, v2
	v_min_u32_e32 v2, v150, v2
	v_max_u32_e32 v150, v0, v1
	v_min_u32_e32 v0, v0, v1
	v_max_u32_e32 v1, v149, v139
	v_min_u32_e32 v139, v149, v139
	v_max_u32_e32 v149, v151, v148
	v_min_u32_e32 v148, v151, v148
	v_max_u32_e32 v143, v131, v146
	v_min_u32_e32 v131, v131, v146
	v_max_u32_e32 v146, v144, v145
	v_min_u32_e32 v144, v144, v145
	v_max_u32_e32 v145, v155, v134
	v_min_u32_e32 v134, v155, v134
	v_max_u32_e32 v155, v132, v127
	v_min_u32_e32 v127, v132, v127
	v_max_u32_e32 v132, v128, v130
	v_min_u32_e32 v128, v128, v130
	v_max_u32_e32 v130, v142, v133
	v_min_u32_e32 v133, v142, v133
	v_max_u32_e32 v142, v140, v135
	v_min_u32_e32 v135, v140, v135
	v_max_u32_e32 v140, v141, v129
	v_min_u32_e32 v129, v141, v129
	v_max_u32_e32 v151, v3, v154
	v_min_u32_e32 v3, v3, v154
	v_max_u32_e32 v154, v152, v153
	v_min_u32_e32 v152, v152, v153
	v_max_u32_e32 v153, v163, v147
	v_min_u32_e32 v147, v163, v147
	v_max_u32_e32 v163, v138, v136
	v_min_u32_e32 v136, v138, v136
	v_max_u32_e32 v138, v0, v2
	v_min_u32_e32 v0, v0, v2
	v_max_u32_e32 v2, v150, v137
	v_min_u32_e32 v137, v150, v137
	v_max_u32_e32 v150, v148, v139
	v_min_u32_e32 v139, v148, v139
	v_max_u32_e32 v148, v149, v1
	v_min_u32_e32 v1, v149, v1
	v_max_u32_e32 v141, v143, v128
	v_min_u32_e32 v128, v143, v128
	v_max_u32_e32 v143, v131, v132
	v_min_u32_e32 v131, v131, v132
	v_max_u32_e32 v132, v146, v133
	v_min_u32_e32 v133, v146, v133
	v_max_u32_e32 v146, v144, v130
	v_min_u32_e32 v130, v144, v130
	v_max_u32_e32 v144, v145, v135
	v_min_u32_e32 v135, v145, v135
	v_max_u32_e32 v145, v134, v142
	v_min_u32_e32 v134, v134, v142
	v_max_u32_e32 v142, v155, v129
	v_min_u32_e32 v129, v155, v129
	v_max_u32_e32 v155, v127, v140
	v_min_u32_e32 v127, v127, v140
	v_max_u32_e32 v149, v151, v0
	v_min_u32_e32 v0, v151, v0
; #define CE_DESC(a, b) do { const unsigned _mx = (a) > (b) ? (a) : (b), _mn = (a) > (b) ? (b) : (a); (a) = _mx; (b) = _mn; } while (0)
; __device__ __forceinline__ void sort16_desc(unsigned (&k)[16]) {
; #pragma unroll
;     for (int size = 2; size <= 16; size <<= 1)
; #pragma unroll
;         for (int stride = size >> 1; stride > 0; stride >>= 1)
; #pragma unroll
;             for (int i = 0; i < 16; ++i) { const int j = i ^ stride;
;                 if (j > i) { if ((i & size) == 0) CE_DESC(k[i], k[j]); else CE_DESC(k[j], k[i]); } }
; }
; __device__ __forceinline__ void merge16(unsigned (&a)[16], const unsigned (&b)[16]) {
; #pragma unroll
;     for (int i = 0; i < 16; ++i) a[i] = a[i] > b[15 - i] ? a[i] : b[15 - i];
; #pragma unroll
;     for (int stride = 8; stride > 0; stride >>= 1)
; #pragma unroll
;         for (int i = 0; i < 16; ++i) { const int j = i ^ stride; if (j > i) CE_DESC(a[i], a[j]); }
; }
; __device__ __forceinline__ void peer_tile(const Args& A, LAS unsigned char* lds, int tile) {
;     ...
;                 sort16_desc(k0); sort16_desc(k1); merge16(k0, k1);
; #pragma unroll
;                 for (int msk = 16; msk <= 32; msk <<= 1) {
; #pragma unroll
;                     for (int i = 0; i < 16; ++i) k1[i] = (unsigned)__shfl_xor((int)k0[i], msk);
;                     merge16(k0, k1); }
	v_max_u32_e32 v151, v3, v138
	v_min_u32_e32 v3, v3, v138
	v_max_u32_e32 v138, v154, v137
	v_min_u32_e32 v137, v154, v137
	v_max_u32_e32 v154, v152, v2
	v_min_u32_e32 v2, v152, v2
	v_max_u32_e32 v152, v153, v139
	v_min_u32_e32 v139, v153, v139
	v_max_u32_e32 v153, v147, v150
	v_min_u32_e32 v147, v147, v150
	v_max_u32_e32 v150, v163, v1
	v_min_u32_e32 v1, v163, v1
	v_max_u32_e32 v163, v136, v148
	v_min_u32_e32 v136, v136, v148
	v_max_u32_e32 v140, v141, v144
	v_min_u32_e32 v141, v141, v144
	v_max_u32_e32 v144, v143, v145
	v_min_u32_e32 v143, v143, v145
	v_max_u32_e32 v145, v132, v142
	v_min_u32_e32 v132, v132, v142
	v_max_u32_e32 v142, v146, v155
	v_min_u32_e32 v146, v146, v155
	v_max_u32_e32 v155, v128, v135
	v_min_u32_e32 v128, v128, v135
	v_max_u32_e32 v135, v131, v134
	v_min_u32_e32 v131, v131, v134
	v_max_u32_e32 v134, v133, v129
	v_min_u32_e32 v129, v133, v129
	v_max_u32_e32 v133, v130, v127
	v_min_u32_e32 v127, v130, v127
	v_max_u32_e32 v148, v149, v152
	v_min_u32_e32 v149, v149, v152
	v_max_u32_e32 v152, v151, v153
	v_min_u32_e32 v151, v151, v153
	v_max_u32_e32 v153, v138, v150
	v_min_u32_e32 v138, v138, v150
	v_max_u32_e32 v150, v154, v163
	v_min_u32_e32 v154, v154, v163
	v_max_u32_e32 v163, v0, v139
	v_min_u32_e32 v0, v0, v139
	v_max_u32_e32 v139, v3, v147
	v_min_u32_e32 v3, v3, v147
	v_max_u32_e32 v147, v137, v1
	v_min_u32_e32 v1, v137, v1
	v_max_u32_e32 v137, v2, v136
	v_min_u32_e32 v2, v2, v136
	v_max_u32_e32 v130, v140, v145
	v_min_u32_e32 v140, v140, v145
	v_max_u32_e32 v145, v144, v142
	v_min_u32_e32 v142, v144, v142
	v_max_u32_e32 v144, v141, v132
	v_min_u32_e32 v132, v141, v132
	v_max_u32_e32 v141, v143, v146
	v_min_u32_e32 v143, v143, v146
	v_max_u32_e32 v146, v155, v134
	v_min_u32_e32 v134, v155, v134
	v_max_u32_e32 v155, v135, v133
	v_min_u32_e32 v133, v135, v133
	v_max_u32_e32 v135, v128, v129
	v_min_u32_e32 v128, v128, v129
	v_max_u32_e32 v129, v131, v127
	v_min_u32_e32 v127, v131, v127
	v_max_u32_e32 v136, v148, v153
	v_min_u32_e32 v148, v148, v153
	v_max_u32_e32 v153, v152, v150
	v_min_u32_e32 v150, v152, v150
	v_max_u32_e32 v152, v149, v138
	v_min_u32_e32 v138, v149, v138
	v_max_u32_e32 v149, v151, v154
	v_min_u32_e32 v151, v151, v154
	v_max_u32_e32 v154, v163, v147
	v_min_u32_e32 v147, v163, v147
	v_max_u32_e32 v163, v139, v137
	v_min_u32_e32 v137, v139, v137
	v_max_u32_e32 v139, v0, v1
	v_min_u32_e32 v0, v0, v1
	v_max_u32_e32 v1, v3, v2
	v_min_u32_e32 v2, v3, v2
	v_min_u32_e32 v131, v130, v145
	v_min_u32_e32 v156, v140, v142
	v_min_u32_e32 v157, v144, v141
	v_min_u32_e32 v158, v132, v143
	v_min_u32_e32 v159, v146, v155
	v_min_u32_e32 v160, v134, v133
	v_min_u32_e32 v161, v135, v129
	v_min_u32_e32 v162, v128, v127
	v_min_u32_e32 v3, v136, v153
	v_min_u32_e32 v164, v148, v150
	v_min_u32_e32 v165, v152, v149
	v_min_u32_e32 v166, v138, v151
	v_min_u32_e32 v167, v154, v163
	v_min_u32_e32 v168, v147, v137
	v_min_u32_e32 v169, v139, v1
	v_min_u32_e32 v170, v0, v2
	v_max3_u32 v130, v130, v145, v170
	v_max3_u32 v0, v131, v0, v2
	v_max3_u32 v2, v140, v142, v169
	v_max3_u32 v1, v156, v139, v1
	v_max3_u32 v131, v144, v141, v168
	v_max3_u32 v137, v157, v147, v137
	v_max3_u32 v132, v132, v143, v167
	v_max3_u32 v139, v158, v154, v163
	v_max3_u32 v140, v146, v155, v166
	v_max3_u32 v138, v159, v138, v151
	v_max3_u32 v133, v134, v133, v165
	v_max3_u32 v134, v160, v152, v149
	v_max3_u32 v129, v135, v129, v164
	v_max3_u32 v135, v161, v148, v150
	v_max3_u32 v3, v128, v127, v3
	v_max3_u32 v127, v162, v136, v153
	v_max_u32_e32 v128, v130, v140
	v_min_u32_e32 v130, v130, v140
	v_max_u32_e32 v136, v0, v138
	v_min_u32_e32 v0, v0, v138
	v_max_u32_e32 v138, v2, v133
	v_min_u32_e32 v2, v2, v133
	v_max_u32_e32 v133, v1, v134
	v_min_u32_e32 v1, v1, v134
	v_max_u32_e32 v134, v131, v129
	v_min_u32_e32 v129, v131, v129
	v_max_u32_e32 v131, v137, v135
	v_min_u32_e32 v135, v137, v135
	v_max_u32_e32 v137, v132, v3
	v_min_u32_e32 v3, v132, v3
	v_max_u32_e32 v132, v139, v127
	v_min_u32_e32 v127, v139, v127
	v_max_u32_e32 v139, v128, v134
	v_min_u32_e32 v128, v128, v134
	v_max_u32_e32 v134, v136, v131
	v_min_u32_e32 v131, v136, v131
	v_max_u32_e32 v136, v138, v137
	v_min_u32_e32 v137, v138, v137
	v_max_u32_e32 v138, v133, v132
	v_min_u32_e32 v132, v133, v132
	v_max_u32_e32 v133, v130, v129
	v_min_u32_e32 v129, v130, v129
	v_max_u32_e32 v130, v0, v135
	v_min_u32_e32 v0, v0, v135
	v_max_u32_e32 v135, v2, v3
	v_min_u32_e32 v2, v2, v3
	v_max_u32_e32 v3, v1, v127
	v_min_u32_e32 v1, v1, v127
	v_max_u32_e32 v127, v139, v136
	v_min_u32_e32 v136, v139, v136
	v_max_u32_e32 v139, v134, v138
	v_min_u32_e32 v134, v134, v138
	v_max_u32_e32 v138, v128, v137
	v_min_u32_e32 v128, v128, v137
	v_max_u32_e32 v137, v131, v132
	v_min_u32_e32 v131, v131, v132
	v_max_u32_e32 v132, v133, v135
	v_min_u32_e32 v133, v133, v135
	v_max_u32_e32 v135, v130, v3
	v_min_u32_e32 v3, v130, v3
	v_max_u32_e32 v130, v129, v2
	v_min_u32_e32 v2, v129, v2
	v_max_u32_e32 v129, v0, v1
	v_min_u32_e32 v0, v0, v1
	v_max_u32_e32 v1, v127, v139
	v_min_u32_e32 v127, v127, v139
	v_max_u32_e32 v139, v136, v134
	v_min_u32_e32 v134, v136, v134
	v_max_u32_e32 v136, v138, v137
	v_min_u32_e32 v137, v138, v137
	v_max_u32_e32 v138, v128, v131
	v_min_u32_e32 v128, v128, v131
	v_max_u32_e32 v131, v132, v135
	v_min_u32_e32 v132, v132, v135
	v_max_u32_e32 v135, v133, v3
	v_min_u32_e32 v3, v133, v3
	v_max_u32_e32 v133, v130, v129
	v_min_u32_e32 v129, v130, v129
	v_max_u32_e32 v130, v2, v0
	v_min_u32_e32 v0, v2, v0
	ds_bpermute_b32 v2, v27, v1
	ds_bpermute_b32 v140, v27, v127
	ds_bpermute_b32 v141, v27, v139
	ds_bpermute_b32 v142, v27, v134
	ds_bpermute_b32 v143, v27, v136
	ds_bpermute_b32 v144, v27, v137
	ds_bpermute_b32 v145, v27, v138
	ds_bpermute_b32 v146, v27, v128
	ds_bpermute_b32 v147, v27, v131
	ds_bpermute_b32 v148, v27, v132
	ds_bpermute_b32 v149, v27, v135
	ds_bpermute_b32 v150, v27, v0
	ds_bpermute_b32 v151, v27, v130
	ds_bpermute_b32 v152, v27, v129
	ds_bpermute_b32 v153, v27, v133
	ds_bpermute_b32 v154, v27, v3
	s_waitcnt lgkmcnt(4)
; #define CE_DESC(a, b) do { const unsigned _mx = (a) > (b) ? (a) : (b), _mn = (a) > (b) ? (b) : (a); (a) = _mx; (b) = _mn; } while (0)
; __device__ __forceinline__ void merge16(unsigned (&a)[16], const unsigned (&b)[16]) {
; #pragma unroll
;     for (int i = 0; i < 16; ++i) a[i] = a[i] > b[15 - i] ? a[i] : b[15 - i];
; #pragma unroll
;     for (int stride = 8; stride > 0; stride >>= 1)
; #pragma unroll
;         for (int i = 0; i < 16; ++i) { const int j = i ^ stride; if (j > i) CE_DESC(a[i], a[j]); }
; __device__ __forceinline__ void peer_tile(const Args& A, LAS unsigned char* lds, int tile) {
;     ...
;                 for (int msk = 16; msk <= 32; msk <<= 1) {
; #pragma unroll
;                     for (int i = 0; i < 16; ++i) k1[i] = (unsigned)__shfl_xor((int)k0[i], msk);
;                     merge16(k0, k1); }
	v_max_u32_e32 v1, v1, v150
	s_waitcnt lgkmcnt(3)
	v_max_u32_e32 v127, v127, v151
	s_waitcnt lgkmcnt(2)
	v_max_u32_e32 v139, v139, v152
	s_waitcnt lgkmcnt(1)
	v_max_u32_e32 v134, v134, v153
	s_waitcnt lgkmcnt(0)
	v_max_u32_e32 v136, v136, v154
	v_max_u32_e32 v137, v137, v149
	v_max_u32_e32 v138, v138, v148
	v_max_u32_e32 v128, v128, v147
	v_max_u32_e32 v131, v131, v146
	v_max_u32_e32 v132, v132, v145
	v_max_u32_e32 v135, v135, v144
	v_max_u32_e32 v3, v3, v143
	v_max_u32_e32 v133, v133, v142
	v_max_u32_e32 v129, v129, v141
	v_max_u32_e32 v130, v130, v140
	v_max_u32_e32 v0, v0, v2
	v_max_u32_e32 v2, v1, v131
	v_min_u32_e32 v1, v1, v131
	v_max_u32_e32 v131, v127, v132
	v_min_u32_e32 v127, v127, v132
	v_max_u32_e32 v132, v139, v135
	v_min_u32_e32 v135, v139, v135
	v_max_u32_e32 v139, v134, v3
	v_min_u32_e32 v3, v134, v3
	v_max_u32_e32 v134, v136, v133
	v_min_u32_e32 v133, v136, v133
	v_max_u32_e32 v136, v137, v129
	v_min_u32_e32 v129, v137, v129
	v_max_u32_e32 v137, v138, v130
	v_min_u32_e32 v130, v138, v130
	v_max_u32_e32 v138, v128, v0
	v_min_u32_e32 v0, v128, v0
	v_max_u32_e32 v128, v2, v134
	v_min_u32_e32 v2, v2, v134
	v_max_u32_e32 v134, v131, v136
	v_min_u32_e32 v131, v131, v136
	v_max_u32_e32 v136, v132, v137
	v_min_u32_e32 v132, v132, v137
	v_max_u32_e32 v137, v139, v138
	v_min_u32_e32 v138, v139, v138
	v_max_u32_e32 v139, v1, v133
	v_min_u32_e32 v1, v1, v133
	v_max_u32_e32 v133, v127, v129
	v_min_u32_e32 v127, v127, v129
	v_max_u32_e32 v129, v135, v130
	v_min_u32_e32 v130, v135, v130
	v_max_u32_e32 v135, v3, v0
	v_min_u32_e32 v0, v3, v0
	v_max_u32_e32 v3, v128, v136
	v_min_u32_e32 v128, v128, v136
	v_max_u32_e32 v136, v134, v137
	v_min_u32_e32 v134, v134, v137
	v_max_u32_e32 v137, v2, v132
	v_min_u32_e32 v2, v2, v132
	v_max_u32_e32 v132, v131, v138
	v_min_u32_e32 v131, v131, v138
	v_max_u32_e32 v138, v139, v129
	v_min_u32_e32 v129, v139, v129
	v_max_u32_e32 v139, v133, v135
	v_min_u32_e32 v133, v133, v135
	v_max_u32_e32 v135, v1, v130
	v_min_u32_e32 v1, v1, v130
	v_max_u32_e32 v130, v127, v0
	v_min_u32_e32 v0, v127, v0
	v_max_u32_e32 v127, v3, v136
	v_min_u32_e32 v3, v3, v136
	v_max_u32_e32 v136, v128, v134
	v_min_u32_e32 v128, v128, v134
	v_max_u32_e32 v134, v137, v132
	v_min_u32_e32 v132, v137, v132
	v_max_u32_e32 v137, v2, v131
	v_min_u32_e32 v2, v2, v131
	v_max_u32_e32 v131, v138, v139
	v_min_u32_e32 v138, v138, v139
	v_max_u32_e32 v139, v129, v133
	v_min_u32_e32 v129, v129, v133
	v_max_u32_e32 v133, v135, v130
	v_min_u32_e32 v130, v135, v130
	v_max_u32_e32 v135, v1, v0
	v_min_u32_e32 v0, v1, v0
	ds_bpermute_b32 v144, v29, v0
	ds_bpermute_b32 v1, v29, v127
	ds_bpermute_b32 v140, v29, v3
	ds_bpermute_b32 v141, v29, v136
	ds_bpermute_b32 v142, v29, v128
	s_waitcnt lgkmcnt(4)
	v_max_u32_e32 v127, v127, v144
	global_load_dwordx4 v[144:147], v[4:5], off offset:1808
	global_load_dwordx4 v[148:151], v[4:5], off offset:1792
	ds_bpermute_b32 v143, v29, v134
	ds_bpermute_b32 v152, v29, v132
	ds_bpermute_b32 v153, v29, v137
	ds_bpermute_b32 v154, v29, v2
	ds_bpermute_b32 v155, v29, v131
	ds_bpermute_b32 v156, v29, v138
	ds_bpermute_b32 v157, v29, v139
	ds_bpermute_b32 v158, v29, v129
	ds_bpermute_b32 v159, v29, v133
	ds_bpermute_b32 v160, v29, v135
	ds_bpermute_b32 v161, v29, v130
	s_waitcnt lgkmcnt(4)
	v_max_u32_e32 v132, v132, v157
	s_waitcnt lgkmcnt(3)
	v_max_u32_e32 v134, v134, v158
	s_waitcnt lgkmcnt(2)
	v_max_u32_e32 v128, v128, v159
	s_waitcnt lgkmcnt(1)
	v_max_u32_e32 v3, v3, v160
	s_waitcnt lgkmcnt(0)
	v_max_u32_e32 v136, v136, v161
	v_max_u32_e32 v137, v137, v156
	v_max_u32_e32 v2, v2, v155
	v_max_u32_e32 v131, v131, v154
	v_max_u32_e32 v138, v138, v153
	v_max_u32_e32 v139, v139, v152
	v_max_u32_e32 v129, v129, v143
	v_max_u32_e32 v133, v133, v142
	v_max_u32_e32 v130, v130, v141
	v_max_u32_e32 v135, v135, v140
	v_max_u32_e32 v0, v0, v1
	v_max_u32_e32 v1, v127, v131
	v_min_u32_e32 v127, v127, v131
	v_max_u32_e32 v131, v3, v138
	v_min_u32_e32 v3, v3, v138
	v_max_u32_e32 v138, v136, v139
	v_min_u32_e32 v136, v136, v139
	v_max_u32_e32 v139, v128, v129
	v_min_u32_e32 v128, v128, v129
	v_max_u32_e32 v129, v134, v133
	v_min_u32_e32 v133, v134, v133
	v_max_u32_e32 v134, v132, v130
	v_min_u32_e32 v130, v132, v130
	v_max_u32_e32 v132, v137, v135
	v_min_u32_e32 v135, v137, v135
	v_max_u32_e32 v137, v2, v0
	v_min_u32_e32 v0, v2, v0
	v_max_u32_e32 v2, v1, v129
	v_min_u32_e32 v1, v1, v129
	v_max_u32_e32 v129, v131, v134
	v_min_u32_e32 v131, v131, v134
	v_max_u32_e32 v134, v138, v132
	v_min_u32_e32 v132, v138, v132
	v_max_u32_e32 v138, v139, v137
	v_min_u32_e32 v137, v139, v137
	v_max_u32_e32 v139, v127, v133
	v_min_u32_e32 v127, v127, v133
	v_max_u32_e32 v133, v3, v130
	v_min_u32_e32 v3, v3, v130
	v_max_u32_e32 v130, v136, v135
	v_min_u32_e32 v135, v136, v135
	v_max_u32_e32 v136, v128, v0
	v_min_u32_e32 v0, v128, v0
	v_max_u32_e32 v128, v2, v134
	v_min_u32_e32 v2, v2, v134
	v_max_u32_e32 v134, v129, v138
	v_min_u32_e32 v129, v129, v138
	v_max_u32_e32 v143, v1, v132
	v_min_u32_e32 v1, v1, v132
	v_max_u32_e32 v132, v131, v137
	v_min_u32_e32 v131, v131, v137
	v_max_u32_e32 v152, v139, v130
	v_min_u32_e32 v130, v139, v130
	v_max_u32_e32 v153, v133, v136
	v_min_u32_e32 v154, v133, v136
	v_max_u32_e32 v155, v127, v135
	v_min_u32_e32 v127, v127, v135
	v_max_u32_e32 v156, v3, v0
	v_min_u32_e32 v0, v3, v0
	v_max_u32_e32 v142, v128, v134
	v_min_u32_e32 v141, v128, v134
	v_max_u32_e32 v140, v2, v129
	v_min_u32_e32 v139, v2, v129
	v_max_u32_e32 v138, v143, v132
	v_min_u32_e32 v137, v143, v132
	v_max_u32_e32 v136, v1, v131
	v_min_u32_e32 v135, v1, v131
	v_max_u32_e32 v134, v152, v153
	v_min_u32_e32 v133, v152, v153
	v_max_u32_e32 v132, v130, v154
	v_min_u32_e32 v131, v130, v154
	v_max_u32_e32 v130, v155, v156
	v_min_u32_e32 v129, v155, v156
	v_max_u32_e32 v128, v127, v0
	v_min_u32_e32 v127, v127, v0
	global_load_dwordx4 v[0:3], v[4:5], off offset:1840
	global_load_dwordx4 v[152:155], v[4:5], off offset:1824
	s_waitcnt vmcnt(2)
; __device__ __forceinline__ unsigned f2key(float f) { const unsigned u = __float_as_uint(f); return (u & 0x80000000u) ? ~u : (u | 0x80000000u); }
; __device__ __forceinline__ void peer_tile(const Args& A, LAS unsigned char* lds, int tile) {
;     ...
;                 { const bf16_t* sp = QRY + m * 2048 + hp * 128 + 32 * g;
;                   const u32x4 s0 = *(const u32x4*)sp, s1 = *(const u32x4*)(sp + 8), s2 = *(const u32x4*)(sp + 16), s3 = *(const u32x4*)(sp + 24);
;                   const unsigned sw[16] = {s0.x, s0.y, s0.z, s0.w, s1.x, s1.y, s1.z, s1.w, s2.x, s2.y, s2.z, s2.w, s3.x, s3.y, s3.z, s3.w};
; #pragma unroll
;                   for (int i = 0; i < 16; ++i) {
;                       const float lo = (float)__builtin_bit_cast(_Float16, (unsigned short)(sw[i] & 0xffffu)), hi = (float)__builtin_bit_cast(_Float16, (unsigned short)(sw[i] >> 16));
;                       const unsigned klo = (f2key(lo) & ~127u) | (unsigned)(127 - (32 * g + 2 * i)), khi = (f2key(hi) & ~127u) | (unsigned)(127 - (32 * g + 2 * i + 1));
;                       if (i < 8) { k0[2 * i] = klo; k0[2 * i + 1] = khi; } else { k1[2 * (i - 8)] = klo; k1[2 * (i - 8) + 1] = khi; } } }
	v_cvt_f32_f16_sdwa v143, v148 dst_sel:DWORD dst_unused:UNUSED_PAD src0_sel:WORD_1
	v_cvt_f32_f16_e32 v4, v148
	v_not_b32_e32 v5, v143
	v_or_b32_e32 v148, 0x80000000, v143
	v_cmp_gt_i32_e32 vcc, 0, v143
	v_not_b32_e32 v143, v4
	s_nop 0
	v_cndmask_b32_e32 v5, v148, v5, vcc
	v_or_b32_e32 v148, 0x80000000, v4
	v_cmp_gt_i32_e32 vcc, 0, v4
	v_and_b32_e32 v5, 0xffffff80, v5
	v_sub_u32_e32 v5, v5, v15
	v_cndmask_b32_e32 v4, v148, v143, vcc
	v_and_b32_e32 v4, 0xffffff80, v4
	v_cvt_f32_f16_sdwa v143, v149 dst_sel:DWORD dst_unused:UNUSED_PAD src0_sel:WORD_1
	v_sub_u32_e32 v4, v4, v15
	v_cvt_f32_f16_e32 v15, v149
	v_add_u32_e32 v5, 0x7e, v5
	v_not_b32_e32 v148, v143
	v_or_b32_e32 v149, 0x80000000, v143
	v_cmp_gt_i32_e32 vcc, 0, v143
	v_add_u32_e32 v4, 0x7f, v4
	s_nop 0
	v_cndmask_b32_e32 v143, v149, v148, vcc
	v_not_b32_e32 v148, v15
	v_or_b32_e32 v149, 0x80000000, v15
	v_cmp_gt_i32_e32 vcc, 0, v15
	v_and_b32_e32 v143, 0xffffff80, v143
	v_sub_u32_e32 v143, v143, v14
	v_cndmask_b32_e32 v15, v149, v148, vcc
	v_and_b32_e32 v15, 0xffffff80, v15
	v_cvt_f32_f16_sdwa v148, v150 dst_sel:DWORD dst_unused:UNUSED_PAD src0_sel:WORD_1
	v_sub_u32_e32 v14, v15, v14
	v_cvt_f32_f16_e32 v15, v150
	v_add_u32_e32 v143, 0x7e, v143
	v_not_b32_e32 v149, v148
	v_or_b32_e32 v150, 0x80000000, v148
	v_cmp_gt_i32_e32 vcc, 0, v148
	v_add_u32_e32 v14, 0x7f, v14
	s_nop 0
	v_cndmask_b32_e32 v148, v150, v149, vcc
	v_not_b32_e32 v149, v15
	v_or_b32_e32 v150, 0x80000000, v15
	v_cmp_gt_i32_e32 vcc, 0, v15
	v_and_b32_e32 v148, 0xffffff80, v148
	v_sub_u32_e32 v148, v148, v12
	v_cndmask_b32_e32 v15, v150, v149, vcc
	v_and_b32_e32 v15, 0xffffff80, v15
	v_cvt_f32_f16_sdwa v149, v151 dst_sel:DWORD dst_unused:UNUSED_PAD src0_sel:WORD_1
	v_sub_u32_e32 v12, v15, v12
	v_cvt_f32_f16_e32 v15, v151
	v_add_u32_e32 v148, 0x7e, v148
	v_not_b32_e32 v150, v149
	v_or_b32_e32 v151, 0x80000000, v149
	v_cmp_gt_i32_e32 vcc, 0, v149
	v_add_u32_e32 v12, 0x7f, v12
	s_nop 0
	v_cndmask_b32_e32 v149, v151, v150, vcc
	v_not_b32_e32 v150, v15
	v_or_b32_e32 v151, 0x80000000, v15
	v_cmp_gt_i32_e32 vcc, 0, v15
	v_and_b32_e32 v149, 0xffffff80, v149
	v_sub_u32_e32 v149, v149, v10
	v_cndmask_b32_e32 v15, v151, v150, vcc
	v_and_b32_e32 v15, 0xffffff80, v15
	v_cvt_f32_f16_sdwa v150, v144 dst_sel:DWORD dst_unused:UNUSED_PAD src0_sel:WORD_1
	v_sub_u32_e32 v10, v15, v10
	v_cvt_f32_f16_e32 v15, v144
	v_add_u32_e32 v149, 0x7e, v149
	v_not_b32_e32 v144, v150
	v_or_b32_e32 v151, 0x80000000, v150
	v_cmp_gt_i32_e32 vcc, 0, v150
	v_not_b32_e32 v150, v15
	v_add_u32_e32 v10, 0x7f, v10
	v_cndmask_b32_e32 v144, v151, v144, vcc
	v_or_b32_e32 v151, 0x80000000, v15
	v_cmp_gt_i32_e32 vcc, 0, v15
	v_and_b32_e32 v144, 0xffffff80, v144
	v_sub_u32_e32 v144, v144, v8
	v_cndmask_b32_e32 v15, v151, v150, vcc
	v_and_b32_e32 v15, 0xffffff80, v15
	v_cvt_f32_f16_sdwa v150, v145 dst_sel:DWORD dst_unused:UNUSED_PAD src0_sel:WORD_1
	v_sub_u32_e32 v8, v15, v8
	v_cvt_f32_f16_e32 v15, v145
	v_add_u32_e32 v144, 0x7e, v144
	v_not_b32_e32 v145, v150
	v_or_b32_e32 v151, 0x80000000, v150
	v_cmp_gt_i32_e32 vcc, 0, v150
	v_not_b32_e32 v150, v15
	v_add_u32_e32 v8, 0x7f, v8
	v_cndmask_b32_e32 v145, v151, v145, vcc
	v_or_b32_e32 v151, 0x80000000, v15
	v_cmp_gt_i32_e32 vcc, 0, v15
	v_and_b32_e32 v145, 0xffffff80, v145
	v_sub_u32_e32 v145, v145, v16
	v_cndmask_b32_e32 v15, v151, v150, vcc
	v_and_b32_e32 v15, 0xffffff80, v15
	v_cvt_f32_f16_sdwa v150, v146 dst_sel:DWORD dst_unused:UNUSED_PAD src0_sel:WORD_1
	v_sub_u32_e32 v15, v15, v16
	v_cvt_f32_f16_e32 v16, v146
	v_add_u32_e32 v145, 0x7e, v145
	v_not_b32_e32 v146, v150
	v_or_b32_e32 v151, 0x80000000, v150
	v_cmp_gt_i32_e32 vcc, 0, v150
	v_not_b32_e32 v150, v16
	v_add_u32_e32 v15, 0x7f, v15
	v_cndmask_b32_e32 v146, v151, v146, vcc
	v_or_b32_e32 v151, 0x80000000, v16
	v_cmp_gt_i32_e32 vcc, 0, v16
	v_and_b32_e32 v146, 0xffffff80, v146
	v_sub_u32_e32 v146, v146, v17
	v_cndmask_b32_e32 v16, v151, v150, vcc
	v_and_b32_e32 v16, 0xffffff80, v16
	v_cvt_f32_f16_sdwa v150, v147 dst_sel:DWORD dst_unused:UNUSED_PAD src0_sel:WORD_1
	v_sub_u32_e32 v16, v16, v17
	v_cvt_f32_f16_e32 v17, v147
	v_add_u32_e32 v146, 0x7e, v146
	v_not_b32_e32 v147, v150
	v_or_b32_e32 v151, 0x80000000, v150
	v_cmp_gt_i32_e32 vcc, 0, v150
	v_not_b32_e32 v150, v17
	v_add_u32_e32 v16, 0x7f, v16
	v_cndmask_b32_e32 v147, v151, v147, vcc
	v_or_b32_e32 v151, 0x80000000, v17
	v_cmp_gt_i32_e32 vcc, 0, v17
	v_and_b32_e32 v147, 0xffffff80, v147
	v_sub_u32_e32 v147, v147, v18
	v_cndmask_b32_e32 v17, v151, v150, vcc
	v_and_b32_e32 v17, 0xffffff80, v17
	s_waitcnt vmcnt(0)
; __device__ __forceinline__ unsigned f2key(float f) { const unsigned u = __float_as_uint(f); return (u & 0x80000000u) ? ~u : (u | 0x80000000u); }
; #define CE_DESC(a, b) do { const unsigned _mx = (a) > (b) ? (a) : (b), _mn = (a) > (b) ? (b) : (a); (a) = _mx; (b) = _mn; } while (0)
; __device__ __forceinline__ void sort16_desc(unsigned (&k)[16]) {
; #pragma unroll
;     for (int size = 2; size <= 16; size <<= 1)
; #pragma unroll
;         for (int stride = size >> 1; stride > 0; stride >>= 1)
; #pragma unroll
;             for (int i = 0; i < 16; ++i) { const int j = i ^ stride;
;                 if (j > i) { if ((i & size) == 0) CE_DESC(k[i], k[j]); else CE_DESC(k[j], k[i]); } }
; __device__ __forceinline__ void peer_tile(const Args& A, LAS unsigned char* lds, int tile) {
;     ...
;                       const float lo = (float)__builtin_bit_cast(_Float16, (unsigned short)(sw[i] & 0xffffu)), hi = (float)__builtin_bit_cast(_Float16, (unsigned short)(sw[i] >> 16));
;                       const unsigned klo = (f2key(lo) & ~127u) | (unsigned)(127 - (32 * g + 2 * i)), khi = (f2key(hi) & ~127u) | (unsigned)(127 - (32 * g + 2 * i + 1));
;                       if (i < 8) { k0[2 * i] = klo; k0[2 * i + 1] = khi; } else { k1[2 * (i - 8)] = klo; k1[2 * (i - 8) + 1] = khi; } } }
	v_cvt_f32_f16_sdwa v150, v152 dst_sel:DWORD dst_unused:UNUSED_PAD src0_sel:WORD_1
	v_sub_u32_e32 v17, v17, v18
	v_cvt_f32_f16_e32 v18, v152
	v_add_u32_e32 v147, 0x7e, v147
	v_not_b32_e32 v151, v150
	v_or_b32_e32 v152, 0x80000000, v150
	v_cmp_gt_i32_e32 vcc, 0, v150
	v_add_u32_e32 v17, 0x7f, v17
	s_nop 0
	v_cndmask_b32_e32 v150, v152, v151, vcc
	v_not_b32_e32 v151, v18
	v_or_b32_e32 v152, 0x80000000, v18
	v_cmp_gt_i32_e32 vcc, 0, v18
	v_and_b32_e32 v150, 0xffffff80, v150
	v_sub_u32_e32 v150, v150, v20
	v_cndmask_b32_e32 v18, v152, v151, vcc
	v_and_b32_e32 v18, 0xffffff80, v18
	v_cvt_f32_f16_sdwa v151, v153 dst_sel:DWORD dst_unused:UNUSED_PAD src0_sel:WORD_1
	v_sub_u32_e32 v18, v18, v20
	v_cvt_f32_f16_e32 v20, v153
	v_add_u32_e32 v150, 0x7e, v150
	v_not_b32_e32 v152, v151
	v_or_b32_e32 v153, 0x80000000, v151
	v_cmp_gt_i32_e32 vcc, 0, v151
	v_add_u32_e32 v18, 0x7f, v18
	v_max_u32_e32 v161, v18, v150
	v_cndmask_b32_e32 v151, v153, v152, vcc
	v_not_b32_e32 v152, v20
	v_or_b32_e32 v153, 0x80000000, v20
	v_cmp_gt_i32_e32 vcc, 0, v20
	v_and_b32_e32 v151, 0xffffff80, v151
	v_sub_u32_e32 v151, v151, v21
	v_cndmask_b32_e32 v20, v153, v152, vcc
	v_and_b32_e32 v20, 0xffffff80, v20
	v_cvt_f32_f16_sdwa v152, v154 dst_sel:DWORD dst_unused:UNUSED_PAD src0_sel:WORD_1
	v_sub_u32_e32 v20, v20, v21
	v_cvt_f32_f16_e32 v21, v154
	v_add_u32_e32 v151, 0x7e, v151
	v_not_b32_e32 v153, v152
	v_or_b32_e32 v154, 0x80000000, v152
	v_cmp_gt_i32_e32 vcc, 0, v152
	v_add_u32_e32 v20, 0x7f, v20
	v_min_u32_e32 v18, v18, v150
	v_cndmask_b32_e32 v152, v154, v153, vcc
	v_not_b32_e32 v153, v21
	v_or_b32_e32 v154, 0x80000000, v21
	v_cmp_gt_i32_e32 vcc, 0, v21
	v_and_b32_e32 v152, 0xffffff80, v152
	v_sub_u32_e32 v152, v152, v22
	v_cndmask_b32_e32 v21, v154, v153, vcc
	v_and_b32_e32 v21, 0xffffff80, v21
	v_cvt_f32_f16_sdwa v153, v155 dst_sel:DWORD dst_unused:UNUSED_PAD src0_sel:WORD_1
	v_sub_u32_e32 v21, v21, v22
	v_cvt_f32_f16_e32 v22, v155
	v_add_u32_e32 v152, 0x7e, v152
	v_not_b32_e32 v154, v153
	v_or_b32_e32 v155, 0x80000000, v153
	v_cmp_gt_i32_e32 vcc, 0, v153
	v_add_u32_e32 v21, 0x7f, v21
	v_max_u32_e32 v150, v151, v20
	v_cndmask_b32_e32 v153, v155, v154, vcc
	v_not_b32_e32 v154, v22
	v_or_b32_e32 v155, 0x80000000, v22
	v_cmp_gt_i32_e32 vcc, 0, v22
	v_and_b32_e32 v153, 0xffffff80, v153
	v_sub_u32_e32 v153, v153, v23
	v_cndmask_b32_e32 v22, v155, v154, vcc
	v_cvt_f32_f16_sdwa v154, v0 dst_sel:DWORD dst_unused:UNUSED_PAD src0_sel:WORD_1
	v_cvt_f32_f16_e32 v0, v0
	v_and_b32_e32 v22, 0xffffff80, v22
	v_sub_u32_e32 v22, v22, v23
	v_not_b32_e32 v23, v154
	v_or_b32_e32 v155, 0x80000000, v154
	v_cmp_gt_i32_e32 vcc, 0, v154
	v_not_b32_e32 v154, v0
	v_add_u32_e32 v153, 0x7e, v153
	v_cndmask_b32_e32 v23, v155, v23, vcc
	v_or_b32_e32 v155, 0x80000000, v0
	v_cmp_gt_i32_e32 vcc, 0, v0
	v_and_b32_e32 v23, 0xffffff80, v23
	v_sub_u32_e32 v23, v23, v24
	v_cndmask_b32_e32 v0, v155, v154, vcc
	v_cvt_f32_f16_sdwa v154, v1 dst_sel:DWORD dst_unused:UNUSED_PAD src0_sel:WORD_1
	v_cvt_f32_f16_e32 v1, v1
	v_and_b32_e32 v0, 0xffffff80, v0
	v_sub_u32_e32 v0, v0, v24
	v_not_b32_e32 v24, v154
	v_or_b32_e32 v155, 0x80000000, v154
	v_cmp_gt_i32_e32 vcc, 0, v154
	v_not_b32_e32 v154, v1
	v_add_u32_e32 v22, 0x7f, v22
	v_cndmask_b32_e32 v24, v155, v24, vcc
	v_or_b32_e32 v155, 0x80000000, v1
	v_cmp_gt_i32_e32 vcc, 0, v1
	v_and_b32_e32 v24, 0xffffff80, v24
	v_sub_u32_e32 v24, v24, v25
	v_cndmask_b32_e32 v1, v155, v154, vcc
	v_cvt_f32_f16_sdwa v154, v2 dst_sel:DWORD dst_unused:UNUSED_PAD src0_sel:WORD_1
	v_cvt_f32_f16_e32 v2, v2
	v_and_b32_e32 v1, 0xffffff80, v1
	v_sub_u32_e32 v1, v1, v25
	v_not_b32_e32 v25, v154
	v_or_b32_e32 v155, 0x80000000, v154
	v_cmp_gt_i32_e32 vcc, 0, v154
	v_not_b32_e32 v154, v2
	v_add_u32_e32 v23, 0x7e, v23
	v_cndmask_b32_e32 v25, v155, v25, vcc
	v_or_b32_e32 v155, 0x80000000, v2
	v_cmp_gt_i32_e32 vcc, 0, v2
	v_and_b32_e32 v25, 0xffffff80, v25
	v_sub_u32_e32 v25, v25, v26
	v_cndmask_b32_e32 v2, v155, v154, vcc
	v_cvt_f32_f16_sdwa v154, v3 dst_sel:DWORD dst_unused:UNUSED_PAD src0_sel:WORD_1
	v_cvt_f32_f16_e32 v3, v3
	v_and_b32_e32 v2, 0xffffff80, v2
	v_sub_u32_e32 v2, v2, v26
	v_not_b32_e32 v26, v154
	v_or_b32_e32 v155, 0x80000000, v154
	v_cmp_gt_i32_e32 vcc, 0, v154
	v_not_b32_e32 v154, v3
	v_add_u32_e32 v0, 0x7f, v0
	v_cndmask_b32_e32 v26, v155, v26, vcc
	v_or_b32_e32 v155, 0x80000000, v3
	v_cmp_gt_i32_e32 vcc, 0, v3
	v_and_b32_e32 v26, 0xffffff80, v26
	v_sub_u32_e32 v26, v26, v28
	v_cndmask_b32_e32 v3, v155, v154, vcc
	v_and_b32_e32 v3, 0xffffff80, v3
	v_sub_u32_e32 v3, v3, v28
	v_add_u32_e32 v24, 0x7e, v24
	v_add_u32_e32 v1, 0x7f, v1
	v_add_u32_e32 v25, 0x7e, v25
	v_add_u32_e32 v2, 0x7f, v2
	v_add_u32_e32 v26, 0x7e, v26
	v_add_u32_e32 v3, 0x7f, v3
	v_max_u32_e32 v28, v4, v5
	v_min_u32_e32 v4, v4, v5
	v_max_u32_e32 v5, v143, v14
	v_min_u32_e32 v14, v143, v14
	v_max_u32_e32 v143, v12, v148
	v_min_u32_e32 v12, v12, v148
	v_max_u32_e32 v148, v149, v10
	v_min_u32_e32 v10, v149, v10
	v_max_u32_e32 v149, v8, v144
	v_min_u32_e32 v8, v8, v144
	v_max_u32_e32 v144, v145, v15
	v_min_u32_e32 v15, v145, v15
	v_max_u32_e32 v145, v16, v146
	v_min_u32_e32 v16, v16, v146
	v_max_u32_e32 v146, v147, v17
	v_min_u32_e32 v17, v147, v17
	v_min_u32_e32 v20, v151, v20
	v_max_u32_e32 v151, v21, v152
	v_min_u32_e32 v21, v21, v152
	v_max_u32_e32 v152, v153, v22
	v_min_u32_e32 v22, v153, v22
	v_max_u32_e32 v153, v0, v23
	v_min_u32_e32 v0, v0, v23
	v_max_u32_e32 v23, v24, v1
	v_min_u32_e32 v1, v24, v1
	v_max_u32_e32 v24, v2, v25
	v_min_u32_e32 v2, v2, v25
	v_max_u32_e32 v25, v26, v3
	v_min_u32_e32 v3, v26, v3
	v_max_u32_e32 v147, v28, v14
	v_min_u32_e32 v14, v28, v14
	v_max_u32_e32 v28, v4, v5
	v_min_u32_e32 v4, v4, v5
; #define CE_DESC(a, b) do { const unsigned _mx = (a) > (b) ? (a) : (b), _mn = (a) > (b) ? (b) : (a); (a) = _mx; (b) = _mn; } while (0)
; __device__ __forceinline__ void sort16_desc(unsigned (&k)[16]) {
; #pragma unroll
;     for (int size = 2; size <= 16; size <<= 1)
; #pragma unroll
;         for (int stride = size >> 1; stride > 0; stride >>= 1)
; #pragma unroll
;             for (int i = 0; i < 16; ++i) { const int j = i ^ stride;
;                 if (j > i) { if ((i & size) == 0) CE_DESC(k[i], k[j]); else CE_DESC(k[j], k[i]); } }
	v_max_u32_e32 v5, v10, v143
	v_min_u32_e32 v10, v10, v143
	v_max_u32_e32 v143, v148, v12
	v_min_u32_e32 v12, v148, v12
	v_max_u32_e32 v148, v149, v15
	v_min_u32_e32 v15, v149, v15
	v_max_u32_e32 v149, v8, v144
	v_min_u32_e32 v8, v8, v144
	v_max_u32_e32 v144, v17, v145
	v_min_u32_e32 v17, v17, v145
	v_max_u32_e32 v145, v146, v16
	v_min_u32_e32 v16, v146, v16
	v_max_u32_e32 v26, v161, v20
	v_min_u32_e32 v20, v161, v20
	v_max_u32_e32 v161, v18, v150
	v_min_u32_e32 v18, v18, v150
	v_max_u32_e32 v150, v22, v151
	v_min_u32_e32 v22, v22, v151
	v_max_u32_e32 v151, v152, v21
	v_min_u32_e32 v21, v152, v21
	v_max_u32_e32 v152, v153, v1
	v_min_u32_e32 v1, v153, v1
	v_max_u32_e32 v153, v0, v23
	v_min_u32_e32 v0, v0, v23
	v_max_u32_e32 v23, v3, v24
	v_min_u32_e32 v3, v3, v24
	v_max_u32_e32 v24, v25, v2
	v_min_u32_e32 v2, v25, v2
	v_max_u32_e32 v146, v147, v28
	v_min_u32_e32 v28, v147, v28
	v_max_u32_e32 v147, v14, v4
	v_min_u32_e32 v4, v14, v4
	v_max_u32_e32 v14, v12, v10
	v_min_u32_e32 v10, v12, v10
	v_max_u32_e32 v12, v143, v5
	v_min_u32_e32 v5, v143, v5
	v_max_u32_e32 v143, v148, v149
	v_min_u32_e32 v148, v148, v149
	v_max_u32_e32 v149, v15, v8
	v_min_u32_e32 v8, v15, v8
	v_max_u32_e32 v15, v16, v17
	v_min_u32_e32 v16, v16, v17
	v_max_u32_e32 v17, v145, v144
	v_min_u32_e32 v144, v145, v144
	v_max_u32_e32 v25, v26, v161
	v_min_u32_e32 v26, v26, v161
	v_max_u32_e32 v161, v20, v18
	v_min_u32_e32 v18, v20, v18
	v_max_u32_e32 v20, v21, v22
	v_min_u32_e32 v21, v21, v22
	v_max_u32_e32 v22, v151, v150
	v_min_u32_e32 v150, v151, v150
	v_max_u32_e32 v151, v152, v153
	v_min_u32_e32 v152, v152, v153
	v_max_u32_e32 v153, v1, v0
	v_min_u32_e32 v0, v1, v0
	v_max_u32_e32 v1, v2, v3
	v_min_u32_e32 v2, v2, v3
	v_max_u32_e32 v3, v24, v23
	v_min_u32_e32 v23, v24, v23
	v_max_u32_e32 v145, v146, v10
	v_min_u32_e32 v10, v146, v10
	v_max_u32_e32 v146, v28, v14
	v_min_u32_e32 v14, v28, v14
	v_max_u32_e32 v28, v147, v5
	v_min_u32_e32 v5, v147, v5
	v_max_u32_e32 v147, v4, v12
	v_min_u32_e32 v4, v4, v12
	v_max_u32_e32 v12, v16, v143
	v_min_u32_e32 v16, v16, v143
	v_max_u32_e32 v143, v15, v148
	v_min_u32_e32 v15, v15, v148
	v_max_u32_e32 v148, v144, v149
	v_min_u32_e32 v144, v144, v149
	v_max_u32_e32 v149, v17, v8
	v_min_u32_e32 v8, v17, v8
	v_max_u32_e32 v24, v25, v21
	v_min_u32_e32 v21, v25, v21
	v_max_u32_e32 v25, v26, v20
	v_min_u32_e32 v20, v26, v20
	v_max_u32_e32 v26, v161, v150
	v_min_u32_e32 v150, v161, v150
	v_max_u32_e32 v161, v18, v22
	v_min_u32_e32 v18, v18, v22
	v_max_u32_e32 v22, v2, v151
	v_min_u32_e32 v2, v2, v151
	v_max_u32_e32 v151, v1, v152
	v_min_u32_e32 v1, v1, v152
	v_max_u32_e32 v152, v23, v153
	v_min_u32_e32 v23, v23, v153
	v_max_u32_e32 v153, v3, v0
	v_min_u32_e32 v0, v3, v0
	v_max_u32_e32 v17, v145, v28
	v_min_u32_e32 v28, v145, v28
	v_max_u32_e32 v145, v146, v147
	v_min_u32_e32 v146, v146, v147
	v_max_u32_e32 v147, v10, v5
	v_min_u32_e32 v5, v10, v5
	v_max_u32_e32 v10, v14, v4
	v_min_u32_e32 v4, v14, v4
	v_max_u32_e32 v14, v144, v16
	v_min_u32_e32 v16, v144, v16
	v_max_u32_e32 v144, v8, v15
	v_min_u32_e32 v8, v8, v15
	v_max_u32_e32 v15, v148, v12
	v_min_u32_e32 v12, v148, v12
	v_max_u32_e32 v148, v149, v143
	v_min_u32_e32 v143, v149, v143
	v_max_u32_e32 v3, v24, v26
	v_min_u32_e32 v24, v24, v26
	v_max_u32_e32 v26, v25, v161
	v_min_u32_e32 v25, v25, v161
	v_max_u32_e32 v161, v21, v150
	v_min_u32_e32 v21, v21, v150
	v_max_u32_e32 v150, v20, v18
	v_min_u32_e32 v18, v20, v18
	v_max_u32_e32 v20, v23, v2
	v_min_u32_e32 v2, v23, v2
	v_max_u32_e32 v23, v0, v1
	v_min_u32_e32 v0, v0, v1
	v_max_u32_e32 v1, v152, v22
	v_min_u32_e32 v22, v152, v22
	v_max_u32_e32 v152, v153, v151
	v_min_u32_e32 v151, v153, v151
	v_max_u32_e32 v149, v17, v145
	v_min_u32_e32 v17, v17, v145
	v_max_u32_e32 v145, v28, v146
	v_min_u32_e32 v28, v28, v146
	v_max_u32_e32 v146, v147, v10
	v_min_u32_e32 v10, v147, v10
	v_max_u32_e32 v147, v5, v4
	v_min_u32_e32 v4, v5, v4
	v_max_u32_e32 v5, v8, v16
	v_min_u32_e32 v8, v8, v16
	v_max_u32_e32 v16, v144, v14
	v_min_u32_e32 v14, v144, v14
	v_max_u32_e32 v144, v143, v12
	v_min_u32_e32 v12, v143, v12
	v_max_u32_e32 v143, v148, v15
	v_min_u32_e32 v15, v148, v15
	v_max_u32_e32 v153, v3, v26
	v_min_u32_e32 v3, v3, v26
	v_max_u32_e32 v26, v24, v25
	v_min_u32_e32 v24, v24, v25
	v_max_u32_e32 v25, v161, v150
	v_min_u32_e32 v150, v161, v150
	v_max_u32_e32 v161, v21, v18
	v_min_u32_e32 v18, v21, v18
	v_max_u32_e32 v21, v0, v2
	v_min_u32_e32 v0, v0, v2
	v_max_u32_e32 v2, v23, v20
	v_min_u32_e32 v20, v23, v20
	v_max_u32_e32 v23, v151, v22
	v_min_u32_e32 v22, v151, v22
	v_max_u32_e32 v151, v152, v1
	v_min_u32_e32 v1, v152, v1
	v_max_u32_e32 v148, v149, v8
	v_min_u32_e32 v8, v149, v8
	v_max_u32_e32 v149, v17, v5
	v_min_u32_e32 v5, v17, v5
	v_max_u32_e32 v17, v145, v14
	v_min_u32_e32 v14, v145, v14
	v_max_u32_e32 v145, v28, v16
	v_min_u32_e32 v16, v28, v16
	v_max_u32_e32 v28, v146, v12
	v_min_u32_e32 v12, v146, v12
	v_max_u32_e32 v146, v10, v144
	v_min_u32_e32 v10, v10, v144
	v_max_u32_e32 v144, v147, v15
	v_min_u32_e32 v15, v147, v15
	v_max_u32_e32 v147, v4, v143
	v_min_u32_e32 v4, v4, v143
	v_max_u32_e32 v152, v153, v0
	v_min_u32_e32 v0, v153, v0
	v_max_u32_e32 v153, v3, v21
	v_min_u32_e32 v3, v3, v21
	v_max_u32_e32 v21, v26, v20
	v_min_u32_e32 v20, v26, v20
	v_max_u32_e32 v26, v24, v2
	v_min_u32_e32 v2, v24, v2
	v_max_u32_e32 v24, v25, v22
	v_min_u32_e32 v22, v25, v22
	v_max_u32_e32 v25, v150, v23
	v_min_u32_e32 v23, v150, v23
	v_max_u32_e32 v150, v161, v1
	v_min_u32_e32 v1, v161, v1
	v_max_u32_e32 v161, v18, v151
	v_min_u32_e32 v18, v18, v151
	v_max_u32_e32 v143, v148, v28
	v_min_u32_e32 v28, v148, v28
	v_max_u32_e32 v148, v149, v146
	v_min_u32_e32 v146, v149, v146
; #define CE_DESC(a, b) do { const unsigned _mx = (a) > (b) ? (a) : (b), _mn = (a) > (b) ? (b) : (a); (a) = _mx; (b) = _mn; } while (0)
; __device__ __forceinline__ void sort16_desc(unsigned (&k)[16]) {
; #pragma unroll
;     for (int size = 2; size <= 16; size <<= 1)
; #pragma unroll
;         for (int stride = size >> 1; stride > 0; stride >>= 1)
; #pragma unroll
;             for (int i = 0; i < 16; ++i) { const int j = i ^ stride;
;                 if (j > i) { if ((i & size) == 0) CE_DESC(k[i], k[j]); else CE_DESC(k[j], k[i]); } }
; }
; __device__ __forceinline__ void merge16(unsigned (&a)[16], const unsigned (&b)[16]) {
; #pragma unroll
;     for (int i = 0; i < 16; ++i) a[i] = a[i] > b[15 - i] ? a[i] : b[15 - i];
; #pragma unroll
;     for (int stride = 8; stride > 0; stride >>= 1)
; #pragma unroll
;         for (int i = 0; i < 16; ++i) { const int j = i ^ stride; if (j > i) CE_DESC(a[i], a[j]); }
; }
; __device__ __forceinline__ void peer_tile(const Args& A, LAS unsigned char* lds, int tile) {
;     ...
;                 sort16_desc(k0); sort16_desc(k1); merge16(k0, k1);
; #pragma unroll
;                 for (int msk = 16; msk <= 32; msk <<= 1) {
; #pragma unroll
;                     for (int i = 0; i < 16; ++i) k1[i] = (unsigned)__shfl_xor((int)k0[i], msk);
;                     merge16(k0, k1); }
	v_max_u32_e32 v149, v17, v144
	v_min_u32_e32 v17, v17, v144
	v_max_u32_e32 v144, v145, v147
	v_min_u32_e32 v145, v145, v147
	v_max_u32_e32 v147, v8, v12
	v_min_u32_e32 v8, v8, v12
	v_max_u32_e32 v12, v5, v10
	v_min_u32_e32 v5, v5, v10
	v_max_u32_e32 v10, v14, v15
	v_min_u32_e32 v14, v14, v15
	v_max_u32_e32 v15, v16, v4
	v_min_u32_e32 v4, v16, v4
	v_max_u32_e32 v151, v152, v24
	v_min_u32_e32 v24, v152, v24
	v_max_u32_e32 v152, v153, v25
	v_min_u32_e32 v25, v153, v25
	v_max_u32_e32 v153, v21, v150
	v_min_u32_e32 v21, v21, v150
	v_max_u32_e32 v150, v26, v161
	v_min_u32_e32 v26, v26, v161
	v_max_u32_e32 v161, v0, v22
	v_min_u32_e32 v0, v0, v22
	v_max_u32_e32 v22, v3, v23
	v_min_u32_e32 v3, v3, v23
	v_max_u32_e32 v23, v20, v1
	v_min_u32_e32 v1, v20, v1
	v_max_u32_e32 v20, v2, v18
	v_min_u32_e32 v2, v2, v18
	v_max_u32_e32 v16, v143, v149
	v_min_u32_e32 v143, v143, v149
	v_max_u32_e32 v149, v148, v144
	v_min_u32_e32 v144, v148, v144
	v_max_u32_e32 v148, v28, v17
	v_min_u32_e32 v17, v28, v17
	v_max_u32_e32 v28, v146, v145
	v_min_u32_e32 v145, v146, v145
	v_max_u32_e32 v146, v147, v10
	v_min_u32_e32 v10, v147, v10
	v_max_u32_e32 v147, v12, v15
	v_min_u32_e32 v12, v12, v15
	v_max_u32_e32 v15, v8, v14
	v_min_u32_e32 v8, v8, v14
	v_max_u32_e32 v14, v5, v4
	v_min_u32_e32 v4, v5, v4
	v_max_u32_e32 v18, v151, v153
	v_min_u32_e32 v151, v151, v153
	v_max_u32_e32 v153, v152, v150
	v_min_u32_e32 v150, v152, v150
	v_max_u32_e32 v152, v24, v21
	v_min_u32_e32 v21, v24, v21
	v_max_u32_e32 v24, v25, v26
	v_min_u32_e32 v25, v25, v26
	v_max_u32_e32 v26, v161, v23
	v_min_u32_e32 v23, v161, v23
	v_max_u32_e32 v161, v22, v20
	v_min_u32_e32 v20, v22, v20
	v_max_u32_e32 v22, v0, v1
	v_min_u32_e32 v0, v0, v1
	v_max_u32_e32 v1, v3, v2
	v_min_u32_e32 v2, v3, v2
	v_min_u32_e32 v5, v16, v149
	v_min_u32_e32 v154, v143, v144
	v_min_u32_e32 v155, v148, v28
	v_min_u32_e32 v156, v17, v145
	v_min_u32_e32 v157, v146, v147
	v_min_u32_e32 v158, v10, v12
	v_min_u32_e32 v159, v15, v14
	v_min_u32_e32 v160, v8, v4
	v_min_u32_e32 v3, v18, v153
	v_min_u32_e32 v162, v151, v150
	v_min_u32_e32 v163, v152, v24
	v_min_u32_e32 v164, v21, v25
	v_min_u32_e32 v165, v26, v161
	v_min_u32_e32 v166, v23, v20
	v_min_u32_e32 v167, v22, v1
	v_min_u32_e32 v168, v0, v2
	v_max3_u32 v16, v16, v149, v168
	v_max3_u32 v0, v5, v0, v2
	v_max3_u32 v2, v143, v144, v167
	v_max3_u32 v1, v154, v22, v1
	v_max3_u32 v5, v148, v28, v166
	v_max3_u32 v20, v155, v23, v20
	v_max3_u32 v17, v17, v145, v165
	v_max3_u32 v22, v156, v26, v161
	v_max3_u32 v23, v146, v147, v164
	v_max3_u32 v21, v157, v21, v25
	v_max3_u32 v10, v10, v12, v163
	v_max3_u32 v12, v158, v152, v24
	v_max3_u32 v14, v15, v14, v162
	v_max3_u32 v15, v159, v151, v150
	v_max3_u32 v3, v8, v4, v3
	v_max3_u32 v4, v160, v18, v153
	v_max_u32_e32 v8, v16, v23
	v_min_u32_e32 v16, v16, v23
	v_max_u32_e32 v18, v0, v21
	v_min_u32_e32 v0, v0, v21
	v_max_u32_e32 v21, v2, v10
	v_min_u32_e32 v2, v2, v10
	v_max_u32_e32 v10, v1, v12
	v_min_u32_e32 v1, v1, v12
	v_max_u32_e32 v12, v5, v14
	v_min_u32_e32 v5, v5, v14
	v_max_u32_e32 v14, v20, v15
	v_min_u32_e32 v15, v20, v15
	v_max_u32_e32 v20, v17, v3
	v_min_u32_e32 v3, v17, v3
	v_max_u32_e32 v17, v22, v4
	v_min_u32_e32 v4, v22, v4
	v_max_u32_e32 v22, v8, v12
	v_min_u32_e32 v8, v8, v12
	v_max_u32_e32 v12, v18, v14
	v_min_u32_e32 v14, v18, v14
	v_max_u32_e32 v18, v21, v20
	v_min_u32_e32 v20, v21, v20
	v_max_u32_e32 v21, v10, v17
	v_min_u32_e32 v10, v10, v17
	v_max_u32_e32 v17, v16, v5
	v_min_u32_e32 v5, v16, v5
	v_max_u32_e32 v16, v0, v15
	v_min_u32_e32 v0, v0, v15
	v_max_u32_e32 v15, v2, v3
	v_min_u32_e32 v2, v2, v3
	v_max_u32_e32 v3, v1, v4
	v_min_u32_e32 v1, v1, v4
	v_max_u32_e32 v4, v22, v18
	v_min_u32_e32 v18, v22, v18
	v_max_u32_e32 v22, v12, v21
	v_min_u32_e32 v12, v12, v21
	v_max_u32_e32 v21, v8, v20
	v_min_u32_e32 v8, v8, v20
	v_max_u32_e32 v20, v14, v10
	v_min_u32_e32 v10, v14, v10
	v_max_u32_e32 v14, v17, v15
	v_min_u32_e32 v15, v17, v15
	v_max_u32_e32 v17, v16, v3
	v_min_u32_e32 v3, v16, v3
	v_max_u32_e32 v16, v5, v2
	v_min_u32_e32 v2, v5, v2
	v_max_u32_e32 v5, v0, v1
	v_min_u32_e32 v0, v0, v1
	v_max_u32_e32 v1, v4, v22
	v_min_u32_e32 v4, v4, v22
	v_max_u32_e32 v22, v18, v12
	v_min_u32_e32 v12, v18, v12
	v_max_u32_e32 v18, v21, v20
	v_min_u32_e32 v20, v21, v20
	v_max_u32_e32 v21, v8, v10
	v_min_u32_e32 v8, v8, v10
	v_max_u32_e32 v10, v14, v17
	v_min_u32_e32 v14, v14, v17
	v_max_u32_e32 v17, v15, v3
	v_min_u32_e32 v3, v15, v3
	v_max_u32_e32 v15, v16, v5
	v_min_u32_e32 v5, v16, v5
	v_max_u32_e32 v16, v2, v0
	v_min_u32_e32 v0, v2, v0
	ds_bpermute_b32 v2, v27, v1
	ds_bpermute_b32 v23, v27, v4
	ds_bpermute_b32 v24, v27, v22
	ds_bpermute_b32 v25, v27, v12
	ds_bpermute_b32 v26, v27, v18
	ds_bpermute_b32 v28, v27, v20
	ds_bpermute_b32 v143, v27, v21
	ds_bpermute_b32 v144, v27, v8
	ds_bpermute_b32 v145, v27, v10
	ds_bpermute_b32 v146, v27, v14
	ds_bpermute_b32 v147, v27, v17
	ds_bpermute_b32 v148, v27, v0
	ds_bpermute_b32 v149, v27, v16
	ds_bpermute_b32 v150, v27, v5
	ds_bpermute_b32 v151, v27, v15
	ds_bpermute_b32 v27, v27, v3
	s_waitcnt lgkmcnt(4)
	v_max_u32_e32 v1, v1, v148
	s_waitcnt lgkmcnt(3)
	v_max_u32_e32 v4, v4, v149
	s_waitcnt lgkmcnt(2)
	v_max_u32_e32 v22, v22, v150
	s_waitcnt lgkmcnt(1)
	v_max_u32_e32 v12, v12, v151
	s_waitcnt lgkmcnt(0)
; __device__ __forceinline__ float key2f(unsigned k) { const unsigned u = (k & 0x80000000u) ? (k & 0x7fffffffu) : ~k; return __uint_as_float(u); }
; #define CE_DESC(a, b) do { const unsigned _mx = (a) > (b) ? (a) : (b), _mn = (a) > (b) ? (b) : (a); (a) = _mx; (b) = _mn; } while (0)
; __device__ __forceinline__ void merge16(unsigned (&a)[16], const unsigned (&b)[16]) {
; #pragma unroll
;     for (int i = 0; i < 16; ++i) a[i] = a[i] > b[15 - i] ? a[i] : b[15 - i];
; #pragma unroll
;     for (int stride = 8; stride > 0; stride >>= 1)
; #pragma unroll
;         for (int i = 0; i < 16; ++i) { const int j = i ^ stride; if (j > i) CE_DESC(a[i], a[j]); }
; __device__ __forceinline__ void peer_tile(const Args& A, LAS unsigned char* lds, int tile) {
;     ...
;             const int h = 4 * hg + g;
;             unsigned L2[2][16];
; #pragma unroll
;             for (int p = 0; p < 2; ++p)
; #pragma unroll
;                 for (int i = 0; i < 16; ++i) L2[p][i] = (g & 2) ? ((g & 1) ? LA[3][p][i] : LA[2][p][i]) : ((g & 1) ? LA[1][p][i] : LA[0][p][i]);
;             float va[16], vb[16];
; #pragma unroll
;             for (int i = 0; i < 16; ++i) { va[i] = key2f(L2[0][i] & ~127u); vb[i] = key2f(L2[1][i] & ~127u); idx[i] = 127u - (L2[0][i] & 127u); idx[16 + i] = 127u - (L2[1][i] & 127u); }
	v_max_u32_e32 v18, v18, v27
	v_max_u32_e32 v20, v20, v147
	v_max_u32_e32 v21, v21, v146
	v_max_u32_e32 v8, v8, v145
	v_max_u32_e32 v10, v10, v144
	v_max_u32_e32 v14, v14, v143
	v_max_u32_e32 v17, v17, v28
	v_max_u32_e32 v3, v3, v26
	v_max_u32_e32 v15, v15, v25
	v_max_u32_e32 v5, v5, v24
	v_max_u32_e32 v16, v16, v23
	v_max_u32_e32 v0, v0, v2
	v_max_u32_e32 v2, v1, v10
	v_min_u32_e32 v1, v1, v10
	v_max_u32_e32 v10, v4, v14
	v_min_u32_e32 v4, v4, v14
	v_max_u32_e32 v14, v22, v17
	v_min_u32_e32 v17, v22, v17
	v_max_u32_e32 v22, v12, v3
	v_min_u32_e32 v3, v12, v3
	v_max_u32_e32 v12, v18, v15
	v_min_u32_e32 v15, v18, v15
	v_max_u32_e32 v18, v20, v5
	v_min_u32_e32 v5, v20, v5
	v_max_u32_e32 v20, v21, v16
	v_min_u32_e32 v16, v21, v16
	v_max_u32_e32 v21, v8, v0
	v_min_u32_e32 v0, v8, v0
	v_max_u32_e32 v8, v2, v12
	v_min_u32_e32 v2, v2, v12
	v_max_u32_e32 v12, v10, v18
	v_min_u32_e32 v10, v10, v18
	v_max_u32_e32 v18, v14, v20
	v_min_u32_e32 v14, v14, v20
	v_max_u32_e32 v20, v22, v21
	v_min_u32_e32 v21, v22, v21
	v_max_u32_e32 v22, v1, v15
	v_min_u32_e32 v1, v1, v15
	v_max_u32_e32 v15, v4, v5
	v_min_u32_e32 v4, v4, v5
	v_max_u32_e32 v5, v17, v16
	v_min_u32_e32 v16, v17, v16
	v_max_u32_e32 v17, v3, v0
	v_min_u32_e32 v0, v3, v0
	v_max_u32_e32 v3, v8, v18
	v_min_u32_e32 v8, v8, v18
	v_max_u32_e32 v18, v12, v20
	v_min_u32_e32 v12, v12, v20
	v_max_u32_e32 v20, v2, v14
	v_min_u32_e32 v2, v2, v14
	v_max_u32_e32 v14, v10, v21
	v_min_u32_e32 v10, v10, v21
	v_max_u32_e32 v21, v22, v5
	v_min_u32_e32 v5, v22, v5
	v_max_u32_e32 v22, v15, v17
	v_min_u32_e32 v15, v15, v17
	v_max_u32_e32 v17, v1, v16
	v_min_u32_e32 v1, v1, v16
	v_max_u32_e32 v16, v4, v0
	v_min_u32_e32 v0, v4, v0
	v_max_u32_e32 v4, v3, v18
	v_min_u32_e32 v3, v3, v18
	v_max_u32_e32 v18, v8, v12
	v_min_u32_e32 v8, v8, v12
	v_max_u32_e32 v12, v20, v14
	v_min_u32_e32 v14, v20, v14
	v_max_u32_e32 v20, v2, v10
	v_min_u32_e32 v2, v2, v10
	v_max_u32_e32 v10, v21, v22
	v_min_u32_e32 v21, v21, v22
	v_max_u32_e32 v22, v5, v15
	v_min_u32_e32 v5, v5, v15
	v_max_u32_e32 v15, v17, v16
	v_min_u32_e32 v16, v17, v16
	v_max_u32_e32 v17, v1, v0
	v_min_u32_e32 v0, v1, v0
	ds_bpermute_b32 v1, v29, v4
	ds_bpermute_b32 v23, v29, v3
	ds_bpermute_b32 v24, v29, v18
	ds_bpermute_b32 v25, v29, v8
	ds_bpermute_b32 v26, v29, v12
	ds_bpermute_b32 v27, v29, v14
	ds_bpermute_b32 v28, v29, v20
	ds_bpermute_b32 v143, v29, v2
	ds_bpermute_b32 v144, v29, v10
	ds_bpermute_b32 v145, v29, v21
	ds_bpermute_b32 v146, v29, v22
	ds_bpermute_b32 v147, v29, v0
	ds_bpermute_b32 v148, v29, v17
	ds_bpermute_b32 v149, v29, v16
	ds_bpermute_b32 v150, v29, v15
	ds_bpermute_b32 v29, v29, v5
	s_waitcnt lgkmcnt(4)
	v_max_u32_e32 v4, v4, v147
	s_waitcnt lgkmcnt(3)
	v_max_u32_e32 v3, v3, v148
	s_waitcnt lgkmcnt(2)
	v_max_u32_e32 v18, v18, v149
	s_waitcnt lgkmcnt(1)
	v_max_u32_e32 v8, v8, v150
	s_waitcnt lgkmcnt(0)
	v_max_u32_e32 v12, v12, v29
	v_max_u32_e32 v14, v14, v146
	v_max_u32_e32 v20, v20, v145
	v_max_u32_e32 v2, v2, v144
	v_max_u32_e32 v10, v10, v143
	v_max_u32_e32 v21, v21, v28
	v_max_u32_e32 v22, v22, v27
	v_max_u32_e32 v5, v5, v26
	v_max_u32_e32 v15, v15, v25
	v_max_u32_e32 v16, v16, v24
	v_max_u32_e32 v17, v17, v23
	v_max_u32_e32 v0, v0, v1
	v_max_u32_e32 v1, v4, v10
	v_min_u32_e32 v4, v4, v10
	v_max_u32_e32 v10, v3, v21
	v_min_u32_e32 v3, v3, v21
	v_max_u32_e32 v21, v18, v22
	v_min_u32_e32 v18, v18, v22
	v_max_u32_e32 v22, v8, v5
	v_min_u32_e32 v5, v8, v5
	v_max_u32_e32 v8, v12, v15
	v_min_u32_e32 v12, v12, v15
	v_max_u32_e32 v15, v14, v16
	v_min_u32_e32 v14, v14, v16
	v_max_u32_e32 v16, v20, v17
	v_min_u32_e32 v17, v20, v17
	v_max_u32_e32 v20, v2, v0
	v_min_u32_e32 v0, v2, v0
	v_max_u32_e32 v2, v1, v8
	v_min_u32_e32 v1, v1, v8
	v_max_u32_e32 v8, v10, v15
	v_min_u32_e32 v10, v10, v15
	v_max_u32_e32 v15, v21, v16
	v_min_u32_e32 v16, v21, v16
	v_max_u32_e32 v21, v22, v20
	v_min_u32_e32 v20, v22, v20
	v_max_u32_e32 v22, v4, v12
	v_min_u32_e32 v4, v4, v12
	v_max_u32_e32 v12, v3, v14
	v_min_u32_e32 v3, v3, v14
	v_max_u32_e32 v14, v18, v17
	v_min_u32_e32 v17, v18, v17
	v_max_u32_e32 v18, v5, v0
	v_min_u32_e32 v0, v5, v0
	v_max_u32_e32 v5, v2, v15
	v_min_u32_e32 v2, v2, v15
	v_max_u32_e32 v15, v8, v21
	v_min_u32_e32 v8, v8, v21
	v_max_u32_e32 v21, v1, v16
	v_min_u32_e32 v1, v1, v16
	v_max_u32_e32 v16, v10, v20
	v_min_u32_e32 v10, v10, v20
	v_max_u32_e32 v20, v22, v14
	v_min_u32_e32 v14, v22, v14
	v_max_u32_e32 v22, v12, v18
	v_min_u32_e32 v12, v12, v18
	v_max_u32_e32 v18, v4, v17
	v_min_u32_e32 v4, v4, v17
	v_max_u32_e32 v17, v3, v0
	v_min_u32_e32 v0, v3, v0
	v_max_u32_e32 v3, v5, v15
	v_min_u32_e32 v5, v5, v15
	v_max_u32_e32 v15, v2, v8
	v_min_u32_e32 v2, v2, v8
	v_max_u32_e32 v8, v21, v16
	v_min_u32_e32 v16, v21, v16
	v_max_u32_e32 v21, v1, v10
	v_min_u32_e32 v1, v1, v10
	v_max_u32_e32 v10, v20, v22
	v_min_u32_e32 v20, v20, v22
	v_max_u32_e32 v22, v14, v12
	v_min_u32_e32 v12, v14, v12
	v_max_u32_e32 v14, v18, v17
	v_min_u32_e32 v17, v18, v17
	v_max_u32_e32 v18, v4, v0
	v_min_u32_e32 v0, v4, v0
	v_and_b32_e32 v4, 16, v19
	v_cmp_eq_u32_e32 vcc, 0, v4
	v_cndmask_b32_e64 v23, v77, v45, s[0:1]
	v_cndmask_b32_e64 v24, v76, v44, s[0:1]
	v_cndmask_b32_e32 v4, v142, v109, vcc
	v_cndmask_b32_e64 v4, v4, v23, s[4:5]
	v_cndmask_b32_e32 v23, v141, v108, vcc
	v_cndmask_b32_e64 v23, v23, v24, s[4:5]
	v_cndmask_b32_e32 v24, v140, v107, vcc
	v_cndmask_b32_e64 v25, v75, v43, s[0:1]
	v_cndmask_b32_e64 v24, v24, v25, s[4:5]
	v_cndmask_b32_e32 v25, v139, v106, vcc
	v_cndmask_b32_e64 v26, v74, v42, s[0:1]
	v_cndmask_b32_e64 v25, v25, v26, s[4:5]
	v_cndmask_b32_e32 v26, v138, v105, vcc
	v_cndmask_b32_e64 v27, v73, v41, s[0:1]
	v_cndmask_b32_e64 v26, v26, v27, s[4:5]
; __device__ __forceinline__ float key2f(unsigned k) { const unsigned u = (k & 0x80000000u) ? (k & 0x7fffffffu) : ~k; return __uint_as_float(u); }
; #define CK(i, j) ((f2key(va[i] + vb[j]) & ~255u) | (unsigned)(255 - (16 * (i) + (j))))
; __device__ __forceinline__ void peer_tile(const Args& A, LAS unsigned char* lds, int tile) {
;     ...
;                 for (int i = 0; i < 16; ++i) L2[p][i] = (g & 2) ? ((g & 1) ? LA[3][p][i] : LA[2][p][i]) : ((g & 1) ? LA[1][p][i] : LA[0][p][i]);
;             float va[16], vb[16];
; #pragma unroll
;             for (int i = 0; i < 16; ++i) { va[i] = key2f(L2[0][i] & ~127u); vb[i] = key2f(L2[1][i] & ~127u); idx[i] = 127u - (L2[0][i] & 127u); idx[16 + i] = 127u - (L2[1][i] & 127u); }
;     ...
;             unsigned Lf[16], Bt[16];
; #pragma unroll
;             for (int j = 0; j < 16; ++j) Lf[j] = CK(0, j);
	v_cndmask_b32_e32 v27, v137, v104, vcc
	v_cndmask_b32_e64 v28, v72, v40, s[0:1]
	v_cndmask_b32_e64 v27, v27, v28, s[4:5]
	v_cndmask_b32_e32 v28, v136, v103, vcc
	v_cndmask_b32_e64 v29, v71, v39, s[0:1]
	v_cndmask_b32_e64 v28, v28, v29, s[4:5]
	v_cndmask_b32_e32 v29, v135, v102, vcc
	v_cndmask_b32_e64 v29, v29, v38, s[4:5]
	v_cndmask_b32_e32 v38, v134, v101, vcc
	v_cndmask_b32_e64 v37, v38, v37, s[4:5]
	v_cndmask_b32_e32 v38, v133, v100, vcc
	v_cndmask_b32_e64 v36, v38, v36, s[4:5]
	v_cndmask_b32_e32 v38, v132, v99, vcc
	v_cndmask_b32_e64 v38, v38, v35, s[4:5]
	v_cndmask_b32_e32 v35, v131, v98, vcc
	v_cndmask_b32_e64 v39, v35, v34, s[4:5]
	v_cndmask_b32_e32 v34, v130, v97, vcc
	v_cndmask_b32_e64 v33, v34, v33, s[4:5]
	v_cndmask_b32_e32 v34, v129, v96, vcc
	v_cndmask_b32_e64 v40, v34, v32, s[4:5]
	v_cndmask_b32_e32 v32, v128, v95, vcc
	v_cndmask_b32_e64 v42, v32, v31, s[4:5]
	v_cndmask_b32_e32 v31, v127, v94, vcc
	v_cndmask_b32_e64 v43, v31, v30, s[4:5]
	v_cndmask_b32_e32 v3, v3, v126, vcc
	v_cndmask_b32_e64 v30, v93, v61, s[0:1]
	v_cndmask_b32_e64 v3, v3, v30, s[4:5]
	v_cndmask_b32_e32 v5, v5, v125, vcc
	v_cndmask_b32_e64 v30, v92, v60, s[0:1]
	v_cndmask_b32_e64 v30, v5, v30, s[4:5]
	v_cndmask_b32_e32 v5, v15, v124, vcc
	v_cndmask_b32_e64 v15, v91, v59, s[0:1]
	v_cndmask_b32_e64 v15, v5, v15, s[4:5]
	v_cndmask_b32_e32 v2, v2, v123, vcc
	v_cndmask_b32_e64 v5, v90, v58, s[0:1]
	v_cndmask_b32_e64 v31, v2, v5, s[4:5]
	v_cndmask_b32_e32 v2, v8, v122, vcc
	v_cndmask_b32_e64 v5, v89, v57, s[0:1]
	v_cndmask_b32_e64 v8, v2, v5, s[4:5]
	v_cndmask_b32_e32 v2, v16, v121, vcc
	v_cndmask_b32_e64 v5, v88, v56, s[0:1]
	v_cndmask_b32_e64 v32, v2, v5, s[4:5]
	v_cndmask_b32_e32 v2, v21, v120, vcc
	v_cndmask_b32_e64 v5, v87, v55, s[0:1]
	v_cndmask_b32_e64 v21, v2, v5, s[4:5]
	v_cndmask_b32_e32 v1, v1, v119, vcc
	v_cndmask_b32_e64 v2, v86, v54, s[0:1]
	v_cndmask_b32_e64 v34, v1, v2, s[4:5]
	v_cndmask_b32_e32 v1, v10, v118, vcc
	v_cndmask_b32_e64 v2, v85, v53, s[0:1]
	v_cndmask_b32_e64 v41, v1, v2, s[4:5]
	v_cndmask_b32_e32 v1, v20, v117, vcc
	v_cndmask_b32_e64 v2, v84, v52, s[0:1]
	v_cndmask_b32_e64 v44, v1, v2, s[4:5]
	v_cndmask_b32_e32 v1, v22, v116, vcc
	v_cndmask_b32_e64 v2, v83, v51, s[0:1]
	v_cndmask_b32_e64 v45, v1, v2, s[4:5]
	v_cndmask_b32_e32 v1, v12, v115, vcc
	v_cndmask_b32_e64 v2, v82, v50, s[0:1]
	v_cndmask_b32_e64 v50, v1, v2, s[4:5]
	v_cndmask_b32_e32 v1, v14, v114, vcc
	v_cndmask_b32_e64 v2, v81, v49, s[0:1]
	v_cndmask_b32_e64 v49, v1, v2, s[4:5]
	v_cndmask_b32_e32 v1, v17, v112, vcc
	v_cndmask_b32_e64 v2, v80, v48, s[0:1]
	v_cndmask_b32_e64 v48, v1, v2, s[4:5]
	v_cndmask_b32_e32 v1, v18, v111, vcc
	v_cndmask_b32_e64 v2, v79, v47, s[0:1]
	v_cndmask_b32_e64 v47, v1, v2, s[4:5]
	v_cndmask_b32_e32 v0, v0, v110, vcc
	v_cndmask_b32_e64 v1, v78, v46, s[0:1]
	v_cndmask_b32_e64 v46, v0, v1, s[4:5]
	v_and_b32_e32 v0, 0x7fffff80, v4
	v_bitop3_b32 v1, v4, s19, v4 bitop3:0xcf
	v_cmp_gt_i32_e32 vcc, 0, v4
	v_bitop3_b32 v2, v4, s19, v4 bitop3:0xc
	v_bitop3_b32 v4, v23, s19, v23 bitop3:0xcf
	v_cndmask_b32_e32 v20, v1, v0, vcc
	v_and_b32_e32 v0, 0x7fffff80, v3
	v_bitop3_b32 v1, v3, s19, v3 bitop3:0xcf
	v_cmp_gt_i32_e32 vcc, 0, v3
	v_add_u32_e32 v5, 0, v6
	v_bitop3_b32 v3, v3, s19, v3 bitop3:0xc
	v_cndmask_b32_e32 v1, v1, v0, vcc
	v_and_b32_e32 v0, 0x7fffff80, v23
	v_cmp_gt_i32_e32 vcc, 0, v23
	v_bitop3_b32 v14, v31, s19, v31 bitop3:0xcf
	v_bitop3_b32 v6, v24, s19, v24 bitop3:0xc
	v_cndmask_b32_e32 v18, v4, v0, vcc
	v_and_b32_e32 v0, 0x7fffff80, v30
	v_bitop3_b32 v4, v30, s19, v30 bitop3:0xcf
	v_cmp_gt_i32_e32 vcc, 0, v30
	v_bitop3_b32 v10, v15, s19, v15 bitop3:0xc
	v_bitop3_b32 v16, v32, s19, v32 bitop3:0xcf
	v_cndmask_b32_e32 v0, v4, v0, vcc
	v_bitop3_b32 v4, v23, s19, v23 bitop3:0xc
	ds_write2_b32 v5, v2, v4 offset1:1
	v_bitop3_b32 v2, v30, s19, v30 bitop3:0xc
	ds_write2_b32 v5, v3, v2 offset0:16 offset1:17
	v_and_b32_e32 v2, 0x7fffff80, v24
	v_bitop3_b32 v3, v24, s19, v24 bitop3:0xcf
	v_cmp_gt_i32_e32 vcc, 0, v24
	v_bitop3_b32 v4, v25, s19, v25 bitop3:0xcf
	v_bitop3_b32 v22, v29, s19, v29 bitop3:0xcf
	v_cndmask_b32_e32 v12, v3, v2, vcc
	v_and_b32_e32 v2, 0x7fffff80, v15
	v_bitop3_b32 v3, v15, s19, v15 bitop3:0xcf
	v_cmp_gt_i32_e32 vcc, 0, v15
	v_bitop3_b32 v15, v27, s19, v27 bitop3:0xcf
	v_bitop3_b32 v24, v34, s19, v34 bitop3:0xcf
	v_cndmask_b32_e32 v3, v3, v2, vcc
	v_and_b32_e32 v2, 0x7fffff80, v25
	v_cmp_gt_i32_e32 vcc, 0, v25
	s_nop 1
	v_cndmask_b32_e32 v4, v4, v2, vcc
	v_and_b32_e32 v2, 0x7fffff80, v31
	v_cmp_gt_i32_e32 vcc, 0, v31
	s_nop 1
	v_cndmask_b32_e32 v2, v14, v2, vcc
	v_bitop3_b32 v14, v25, s19, v25 bitop3:0xc
	ds_write2_b32 v5, v6, v14 offset0:2 offset1:3
	v_bitop3_b32 v6, v31, s19, v31 bitop3:0xc
	ds_write2_b32 v5, v10, v6 offset0:18 offset1:19
	v_and_b32_e32 v6, 0x7fffff80, v26
	v_bitop3_b32 v10, v26, s19, v26 bitop3:0xcf
	v_cmp_gt_i32_e32 vcc, 0, v26
	v_bitop3_b32 v25, v36, s19, v36 bitop3:0xcf
	s_nop 0
	v_cndmask_b32_e32 v14, v10, v6, vcc
	v_and_b32_e32 v6, 0x7fffff80, v8
	v_bitop3_b32 v10, v8, s19, v8 bitop3:0xcf
	v_cmp_gt_i32_e32 vcc, 0, v8
	v_bitop3_b32 v8, v8, s19, v8 bitop3:0xc
	s_nop 0
	v_cndmask_b32_e32 v17, v10, v6, vcc
	v_and_b32_e32 v10, 0x7fffff80, v27
	v_cmp_gt_i32_e32 vcc, 0, v27
	v_bitop3_b32 v6, v26, s19, v26 bitop3:0xc
	v_bitop3_b32 v26, v43, s19, v43 bitop3:0xcf
	v_cndmask_b32_e32 v10, v15, v10, vcc
	v_and_b32_e32 v15, 0x7fffff80, v32
	v_cmp_gt_i32_e32 vcc, 0, v32
	s_nop 1
	v_cndmask_b32_e32 v16, v16, v15, vcc
	v_bitop3_b32 v15, v27, s19, v27 bitop3:0xc
	ds_write2_b32 v5, v6, v15 offset0:4 offset1:5
	v_bitop3_b32 v6, v32, s19, v32 bitop3:0xc
	ds_write2_b32 v5, v8, v6 offset0:20 offset1:21
	v_and_b32_e32 v6, 0x7fffff80, v28
; __device__ __forceinline__ float key2f(unsigned k) { const unsigned u = (k & 0x80000000u) ? (k & 0x7fffffffu) : ~k; return __uint_as_float(u); }
; #define CK(i, j) ((f2key(va[i] + vb[j]) & ~255u) | (unsigned)(255 - (16 * (i) + (j))))
; __device__ __forceinline__ void peer_tile(const Args& A, LAS unsigned char* lds, int tile) {
;     ...
;             for (int i = 0; i < 16; ++i) { va[i] = key2f(L2[0][i] & ~127u); vb[i] = key2f(L2[1][i] & ~127u); idx[i] = 127u - (L2[0][i] & 127u); idx[16 + i] = 127u - (L2[1][i] & 127u); }
;     ...
;             unsigned Lf[16], Bt[16];
; #pragma unroll
;             for (int j = 0; j < 16; ++j) Lf[j] = CK(0, j);
; #pragma unroll
;             for (int j = 0; j < 8; ++j) Bt[j] = CK(1, j);
	v_bitop3_b32 v8, v28, s19, v28 bitop3:0xcf
	v_cmp_gt_i32_e32 vcc, 0, v28
	v_bitop3_b32 v15, v21, s19, v21 bitop3:0xcf
	s_nop 0
	v_cndmask_b32_e32 v8, v8, v6, vcc
	v_and_b32_e32 v6, 0x7fffff80, v21
	v_cmp_gt_i32_e32 vcc, 0, v21
	v_bitop3_b32 v21, v21, s19, v21 bitop3:0xc
	s_nop 0
	v_cndmask_b32_e32 v23, v15, v6, vcc
	v_and_b32_e32 v6, 0x7fffff80, v29
	v_cmp_gt_i32_e32 vcc, 0, v29
	v_bitop3_b32 v15, v28, s19, v28 bitop3:0xc
	s_nop 0
	v_cndmask_b32_e32 v6, v22, v6, vcc
	v_and_b32_e32 v22, 0x7fffff80, v34
	v_cmp_gt_i32_e32 vcc, 0, v34
	s_nop 1
	v_cndmask_b32_e32 v22, v24, v22, vcc
	v_bitop3_b32 v24, v29, s19, v29 bitop3:0xc
	ds_write2_b32 v5, v15, v24 offset0:6 offset1:7
	v_bitop3_b32 v15, v34, s19, v34 bitop3:0xc
	ds_write2_b32 v5, v21, v15 offset0:22 offset1:23
	v_and_b32_e32 v15, 0x7fffff80, v37
	v_bitop3_b32 v21, v37, s19, v37 bitop3:0xcf
	v_cmp_gt_i32_e32 vcc, 0, v37
	v_and_b32_e32 v24, 0x7fffff80, v36
	s_nop 0
	v_cndmask_b32_e32 v27, v21, v15, vcc
	v_and_b32_e32 v15, 0x7fffff80, v41
	v_bitop3_b32 v21, v41, s19, v41 bitop3:0xcf
	v_cmp_gt_i32_e32 vcc, 0, v41
	s_nop 1
	v_cndmask_b32_e32 v35, v21, v15, vcc
	v_cmp_gt_i32_e32 vcc, 0, v36
	v_bitop3_b32 v15, v37, s19, v37 bitop3:0xc
	v_bitop3_b32 v21, v41, s19, v41 bitop3:0xc
	v_cndmask_b32_e32 v28, v25, v24, vcc
	v_and_b32_e32 v24, 0x7fffff80, v44
	v_bitop3_b32 v25, v44, s19, v44 bitop3:0xcf
	v_cmp_gt_i32_e32 vcc, 0, v44
	s_nop 1
	v_cndmask_b32_e32 v34, v25, v24, vcc
	v_bitop3_b32 v24, v36, s19, v36 bitop3:0xc
	ds_write2_b32 v5, v15, v24 offset0:8 offset1:9
	v_bitop3_b32 v15, v44, s19, v44 bitop3:0xc
	ds_write2_b32 v5, v21, v15 offset0:24 offset1:25
	v_and_b32_e32 v15, 0x7fffff80, v38
	v_bitop3_b32 v21, v38, s19, v38 bitop3:0xcf
	v_cmp_gt_i32_e32 vcc, 0, v38
	v_and_b32_e32 v24, 0x7fffff80, v39
	v_bitop3_b32 v25, v39, s19, v39 bitop3:0xcf
	v_cndmask_b32_e32 v29, v21, v15, vcc
	v_and_b32_e32 v15, 0x7fffff80, v45
	v_bitop3_b32 v21, v45, s19, v45 bitop3:0xcf
	v_cmp_gt_i32_e32 vcc, 0, v45
	s_nop 1
	v_cndmask_b32_e32 v37, v21, v15, vcc
	v_cmp_gt_i32_e32 vcc, 0, v39
	v_bitop3_b32 v15, v38, s19, v38 bitop3:0xc
	v_bitop3_b32 v21, v45, s19, v45 bitop3:0xc
	v_cndmask_b32_e32 v30, v25, v24, vcc
	v_and_b32_e32 v24, 0x7fffff80, v50
	v_bitop3_b32 v25, v50, s19, v50 bitop3:0xcf
	v_cmp_gt_i32_e32 vcc, 0, v50
	s_nop 1
	v_cndmask_b32_e32 v36, v25, v24, vcc
	v_bitop3_b32 v24, v39, s19, v39 bitop3:0xc
	ds_write2_b32 v5, v15, v24 offset0:10 offset1:11
	v_bitop3_b32 v15, v50, s19, v50 bitop3:0xc
	ds_write2_b32 v5, v21, v15 offset0:26 offset1:27
	v_and_b32_e32 v15, 0x7fffff80, v33
	v_bitop3_b32 v21, v33, s19, v33 bitop3:0xcf
	v_cmp_gt_i32_e32 vcc, 0, v33
	v_and_b32_e32 v24, 0x7fffff80, v40
	v_bitop3_b32 v25, v40, s19, v40 bitop3:0xcf
	v_cndmask_b32_e32 v31, v21, v15, vcc
	v_and_b32_e32 v15, 0x7fffff80, v49
	v_bitop3_b32 v21, v49, s19, v49 bitop3:0xcf
	v_cmp_gt_i32_e32 vcc, 0, v49
	s_nop 1
	v_cndmask_b32_e32 v39, v21, v15, vcc
	v_cmp_gt_i32_e32 vcc, 0, v40
	v_bitop3_b32 v15, v33, s19, v33 bitop3:0xc
	v_bitop3_b32 v21, v49, s19, v49 bitop3:0xc
	v_cndmask_b32_e32 v32, v25, v24, vcc
	v_and_b32_e32 v24, 0x7fffff80, v48
	v_bitop3_b32 v25, v48, s19, v48 bitop3:0xcf
	v_cmp_gt_i32_e32 vcc, 0, v48
	v_bitop3_b32 v33, v46, s19, v46 bitop3:0xcf
	s_nop 0
	v_cndmask_b32_e32 v38, v25, v24, vcc
	v_bitop3_b32 v24, v40, s19, v40 bitop3:0xc
	ds_write2_b32 v5, v15, v24 offset0:12 offset1:13
	v_bitop3_b32 v15, v48, s19, v48 bitop3:0xc
	ds_write2_b32 v5, v21, v15 offset0:28 offset1:29
	v_and_b32_e32 v15, 0x7fffff80, v42
	v_bitop3_b32 v21, v42, s19, v42 bitop3:0xcf
	v_cmp_gt_i32_e32 vcc, 0, v42
	v_and_b32_e32 v24, 0x7fffff80, v43
	s_nop 0
	v_cndmask_b32_e32 v25, v21, v15, vcc
	v_and_b32_e32 v15, 0x7fffff80, v47
	v_bitop3_b32 v21, v47, s19, v47 bitop3:0xcf
	v_cmp_gt_i32_e32 vcc, 0, v47
	s_nop 1
	v_cndmask_b32_e32 v41, v21, v15, vcc
	v_cmp_gt_i32_e32 vcc, 0, v43
	v_bitop3_b32 v21, v47, s19, v47 bitop3:0xc
	v_bitop3_b32 v15, v42, s19, v42 bitop3:0xc
	v_cndmask_b32_e32 v26, v26, v24, vcc
	v_and_b32_e32 v24, 0x7fffff80, v46
	v_cmp_gt_i32_e32 vcc, 0, v46
	v_pk_add_f32 v[34:35], v[20:21], v[34:35] op_sel_hi:[0,1]
	s_nop 0
	v_cndmask_b32_e32 v40, v33, v24, vcc
	v_bitop3_b32 v24, v43, s19, v43 bitop3:0xc
	v_pk_add_f32 v[42:43], v[20:21], v[0:1] op_sel_hi:[0,1]
	ds_write2_b32 v5, v15, v24 offset0:14 offset1:15
	v_not_b32_e32 v15, v43
	v_or_b32_e32 v33, 0x80000000, v43
	v_cmp_gt_i32_e32 vcc, 0, v43
	v_or_b32_e32 v43, 0x80000000, v42
	v_bitop3_b32 v24, v46, s19, v46 bitop3:0xc
	v_cndmask_b32_e32 v15, v33, v15, vcc
	v_or_b32_e32 v33, 0xff, v15
	v_not_b32_e32 v15, v42
	v_cmp_gt_i32_e32 vcc, 0, v42
	ds_write2_b32 v5, v21, v24 offset0:30 offset1:31
	s_waitcnt lgkmcnt(0)
; #define CK(i, j) ((f2key(va[i] + vb[j]) & ~255u) | (unsigned)(255 - (16 * (i) + (j))))
; __device__ __forceinline__ void peer_tile(const Args& A, LAS unsigned char* lds, int tile) {
;     ...
;             unsigned Lf[16], Bt[16];
; #pragma unroll
;             for (int j = 0; j < 16; ++j) Lf[j] = CK(0, j);
; #pragma unroll
;             for (int j = 0; j < 8; ++j) Bt[j] = CK(1, j);
; #pragma unroll
;             for (int j = 0; j < 5; ++j) Bt[8 + j] = CK(2, j);
	s_nop 0
	v_cndmask_b32_e32 v15, v43, v15, vcc
	v_and_b32_e32 v15, 0xffffff00, v15
	v_pk_add_f32 v[42:43], v[20:21], v[2:3] op_sel_hi:[0,1]
	v_or_b32_e32 v44, 0xfe, v15
	v_not_b32_e32 v15, v43
	v_or_b32_e32 v45, 0x80000000, v43
	v_cmp_gt_i32_e32 vcc, 0, v43
	v_or_b32_e32 v43, 0x80000000, v42
	s_nop 0
	v_cndmask_b32_e32 v15, v45, v15, vcc
	v_and_b32_e32 v15, 0xffffff00, v15
	v_or_b32_e32 v45, 0xfd, v15
	v_not_b32_e32 v15, v42
	v_cmp_gt_i32_e32 vcc, 0, v42
	s_nop 1
	v_cndmask_b32_e32 v15, v43, v15, vcc
	v_and_b32_e32 v15, 0xffffff00, v15
	v_pk_add_f32 v[42:43], v[20:21], v[16:17] op_sel_hi:[0,1]
	v_or_b32_e32 v46, 0xfc, v15
	v_not_b32_e32 v15, v43
	v_or_b32_e32 v47, 0x80000000, v43
	v_cmp_gt_i32_e32 vcc, 0, v43
	v_or_b32_e32 v43, 0x80000000, v42
	s_nop 0
	v_cndmask_b32_e32 v15, v47, v15, vcc
	v_and_b32_e32 v15, 0xffffff00, v15
	v_or_b32_e32 v47, 0xfb, v15
	v_not_b32_e32 v15, v42
	v_cmp_gt_i32_e32 vcc, 0, v42
	s_nop 1
	v_cndmask_b32_e32 v15, v43, v15, vcc
	v_and_b32_e32 v15, 0xffffff00, v15
	v_pk_add_f32 v[42:43], v[20:21], v[22:23] op_sel_hi:[0,1]
	v_or_b32_e32 v48, 0xfa, v15
	v_not_b32_e32 v15, v43
	v_or_b32_e32 v49, 0x80000000, v43
	v_cmp_gt_i32_e32 vcc, 0, v43
	v_pk_add_f32 v[22:23], v[18:19], v[22:23] op_sel_hi:[0,1]
	s_nop 0
	v_cndmask_b32_e32 v15, v49, v15, vcc
	v_and_b32_e32 v15, 0xffffff00, v15
	v_or_b32_e32 v43, 0xf9, v15
	v_not_b32_e32 v15, v42
	v_or_b32_e32 v49, 0x80000000, v42
	v_cmp_gt_i32_e32 vcc, 0, v42
	s_nop 1
	v_cndmask_b32_e32 v15, v49, v15, vcc
	v_and_b32_e32 v15, 0xffffff00, v15
	v_or_b32_e32 v42, 0xf8, v15
	v_not_b32_e32 v15, v35
	v_or_b32_e32 v49, 0x80000000, v35
	v_cmp_gt_i32_e32 vcc, 0, v35
	v_or_b32_e32 v35, 0x80000000, v34
	s_nop 0
	v_cndmask_b32_e32 v15, v49, v15, vcc
	v_and_b32_e32 v15, 0xffffff00, v15
	v_or_b32_e32 v49, 0xf7, v15
	v_not_b32_e32 v15, v34
	v_cmp_gt_i32_e32 vcc, 0, v34
	s_nop 1
	v_cndmask_b32_e32 v15, v35, v15, vcc
	v_and_b32_e32 v15, 0xffffff00, v15
	v_pk_add_f32 v[34:35], v[20:21], v[36:37] op_sel_hi:[0,1]
	v_or_b32_e32 v50, 0xf6, v15
	v_not_b32_e32 v15, v35
	v_or_b32_e32 v36, 0x80000000, v35
	v_cmp_gt_i32_e32 vcc, 0, v35
	v_or_b32_e32 v35, 0x80000000, v34
	s_nop 0
	v_cndmask_b32_e32 v15, v36, v15, vcc
	v_and_b32_e32 v15, 0xffffff00, v15
	v_or_b32_e32 v36, 0xf5, v15
	v_not_b32_e32 v15, v34
	v_cmp_gt_i32_e32 vcc, 0, v34
	s_nop 1
	v_cndmask_b32_e32 v15, v35, v15, vcc
	v_and_b32_e32 v15, 0xffffff00, v15
	v_pk_add_f32 v[34:35], v[20:21], v[38:39] op_sel_hi:[0,1]
	v_or_b32_e32 v37, 0xf4, v15
	v_not_b32_e32 v15, v35
	v_or_b32_e32 v38, 0x80000000, v35
	v_cmp_gt_i32_e32 vcc, 0, v35
	v_or_b32_e32 v35, 0x80000000, v34
	s_nop 0
	v_cndmask_b32_e32 v15, v38, v15, vcc
	v_and_b32_e32 v15, 0xffffff00, v15
	v_or_b32_e32 v38, 0xf3, v15
	v_not_b32_e32 v15, v34
	v_cmp_gt_i32_e32 vcc, 0, v34
	s_nop 1
	v_cndmask_b32_e32 v15, v35, v15, vcc
	v_and_b32_e32 v15, 0xffffff00, v15
	v_pk_add_f32 v[34:35], v[20:21], v[40:41] op_sel_hi:[0,1]
	v_or_b32_e32 v39, 0xf2, v15
	v_not_b32_e32 v15, v35
	v_or_b32_e32 v20, 0x80000000, v35
	v_cmp_gt_i32_e32 vcc, 0, v35
	v_or_b32_e32 v35, 0x80000000, v34
	s_nop 0
	v_cndmask_b32_e32 v15, v20, v15, vcc
	v_and_b32_e32 v15, 0xffffff00, v15
	v_or_b32_e32 v20, 0xf1, v15
	v_not_b32_e32 v15, v34
	v_cmp_gt_i32_e32 vcc, 0, v34
	s_nop 1
	v_cndmask_b32_e32 v15, v35, v15, vcc
	v_and_b32_e32 v15, 0xffffff00, v15
	v_pk_add_f32 v[34:35], v[18:19], v[0:1] op_sel_hi:[0,1]
	v_or_b32_e32 v40, 0xf0, v15
	v_not_b32_e32 v15, v35
	v_or_b32_e32 v41, 0x80000000, v35
	v_cmp_gt_i32_e32 vcc, 0, v35
	v_or_b32_e32 v35, 0x80000000, v34
	s_nop 0
	v_cndmask_b32_e32 v15, v41, v15, vcc
	v_and_b32_e32 v15, 0xffffff00, v15
	v_or_b32_e32 v41, 0xef, v15
	v_not_b32_e32 v15, v34
	v_cmp_gt_i32_e32 vcc, 0, v34
	s_nop 1
	v_cndmask_b32_e32 v15, v35, v15, vcc
	v_and_b32_e32 v15, 0xffffff00, v15
	v_pk_add_f32 v[34:35], v[18:19], v[2:3] op_sel_hi:[0,1]
	v_or_b32_e32 v51, 0xee, v15
	v_not_b32_e32 v15, v35
	v_or_b32_e32 v52, 0x80000000, v35
	v_cmp_gt_i32_e32 vcc, 0, v35
	v_or_b32_e32 v35, 0x80000000, v34
	s_nop 0
	v_cndmask_b32_e32 v15, v52, v15, vcc
	v_and_b32_e32 v15, 0xffffff00, v15
	v_or_b32_e32 v52, 0xed, v15
	v_not_b32_e32 v15, v34
	v_cmp_gt_i32_e32 vcc, 0, v34
	s_nop 1
	v_cndmask_b32_e32 v15, v35, v15, vcc
	v_and_b32_e32 v15, 0xffffff00, v15
	v_pk_add_f32 v[34:35], v[18:19], v[16:17] op_sel_hi:[0,1]
	v_or_b32_e32 v53, 0xec, v15
	v_not_b32_e32 v15, v35
	v_or_b32_e32 v16, 0x80000000, v35
	v_cmp_gt_i32_e32 vcc, 0, v35
	s_nop 1
	v_cndmask_b32_e32 v15, v16, v15, vcc
	v_and_b32_e32 v15, 0xffffff00, v15
	v_or_b32_e32 v35, 0xeb, v15
	v_not_b32_e32 v15, v34
	v_or_b32_e32 v16, 0x80000000, v34
	v_cmp_gt_i32_e32 vcc, 0, v34
	s_nop 1
	v_cndmask_b32_e32 v15, v16, v15, vcc
	v_and_b32_e32 v15, 0xffffff00, v15
	v_or_b32_e32 v34, 0xea, v15
	v_not_b32_e32 v15, v23
	v_or_b32_e32 v16, 0x80000000, v23
	v_cmp_gt_i32_e32 vcc, 0, v23
	s_nop 1
	v_cndmask_b32_e32 v15, v16, v15, vcc
	v_and_b32_e32 v15, 0xffffff00, v15
	v_or_b32_e32 v18, 0xe9, v15
	v_not_b32_e32 v15, v22
	v_or_b32_e32 v16, 0x80000000, v22
	v_cmp_gt_i32_e32 vcc, 0, v22
	v_pk_add_f32 v[22:23], v[12:13], v[0:1] op_sel_hi:[0,1]
	s_nop 0
	v_cndmask_b32_e32 v15, v16, v15, vcc
	v_and_b32_e32 v15, 0xffffff00, v15
	v_or_b32_e32 v54, 0xe8, v15
	v_not_b32_e32 v15, v23
	v_or_b32_e32 v16, 0x80000000, v23
	v_cmp_gt_i32_e32 vcc, 0, v23
	s_nop 1
	v_cndmask_b32_e32 v15, v16, v15, vcc
	v_and_b32_e32 v15, 0xffffff00, v15
	v_or_b32_e32 v55, 0xdf, v15
	v_not_b32_e32 v15, v22
	v_or_b32_e32 v16, 0x80000000, v22
	v_cmp_gt_i32_e32 vcc, 0, v22
	v_pk_add_f32 v[22:23], v[12:13], v[2:3] op_sel_hi:[0,1]
	v_lshl_add_u32 v13, v13, 10, s35
	v_cndmask_b32_e32 v15, v16, v15, vcc
	v_and_b32_e32 v15, 0xffffff00, v15
; #define CE_DESC(a, b) do { const unsigned _mx = (a) > (b) ? (a) : (b), _mn = (a) > (b) ? (b) : (a); (a) = _mx; (b) = _mn; } while (0)
; #define CK(i, j) ((f2key(va[i] + vb[j]) & ~255u) | (unsigned)(255 - (16 * (i) + (j))))
; __device__ __forceinline__ void sort16_desc(unsigned (&k)[16]) {
; #pragma unroll
;     for (int size = 2; size <= 16; size <<= 1)
; #pragma unroll
;         for (int stride = size >> 1; stride > 0; stride >>= 1)
; #pragma unroll
;             for (int i = 0; i < 16; ++i) { const int j = i ^ stride;
;                 if (j > i) { if ((i & size) == 0) CE_DESC(k[i], k[j]); else CE_DESC(k[j], k[i]); } }
; __device__ __forceinline__ void peer_tile(const Args& A, LAS unsigned char* lds, int tile) {
;     ...
;             for (int j = 0; j < 5; ++j) Bt[8 + j] = CK(2, j);
; #pragma unroll
;             for (int j = 0; j < 3; ++j) Bt[13 + j] = CK(4, j);
;             sort16_desc(Bt); merge16(Lf, Bt);
	v_or_b32_e32 v56, 0xde, v15
	v_not_b32_e32 v15, v23
	v_or_b32_e32 v16, 0x80000000, v23
	v_cmp_gt_i32_e32 vcc, 0, v23
	s_nop 1
	v_cndmask_b32_e32 v15, v16, v15, vcc
	v_and_b32_e32 v15, 0xffffff00, v15
	v_or_b32_e32 v23, 0xdd, v15
	v_not_b32_e32 v15, v22
	v_or_b32_e32 v16, 0x80000000, v22
	v_cmp_gt_i32_e32 vcc, 0, v22
	s_nop 1
	v_cndmask_b32_e32 v15, v16, v15, vcc
	v_and_b32_e32 v15, 0xffffff00, v15
	v_or_b32_e32 v22, 0xdc, v15
	v_mov_b32_e32 v15, v12
	v_mov_b32_e32 v16, v1
	v_pk_add_f32 v[16:17], v[14:15], v[16:17]
	s_nop 0
	v_not_b32_e32 v12, v17
	v_or_b32_e32 v15, 0x80000000, v17
	v_cmp_gt_i32_e32 vcc, 0, v17
	v_or_b32_e32 v17, 0x80000000, v16
	s_nop 0
	v_cndmask_b32_e32 v12, v15, v12, vcc
	v_not_b32_e32 v15, v16
	v_cmp_gt_i32_e32 vcc, 0, v16
	v_mov_b32_e32 v16, v3
	v_and_b32_e32 v12, 0xffffff00, v12
	v_cndmask_b32_e32 v15, v17, v15, vcc
	v_and_b32_e32 v15, 0xffffff00, v15
	v_mov_b32_e32 v17, v0
	v_or_b32_e32 v57, 0xbf, v15
	v_pk_add_f32 v[14:15], v[14:15], v[16:17] op_sel_hi:[0,1]
	v_not_b32_e32 v16, v15
	v_or_b32_e32 v17, 0x80000000, v15
	v_cmp_gt_i32_e32 vcc, 0, v15
	v_or_b32_e32 v12, 0xdb, v12
	v_pk_add_f32 v[2:3], v[4:5], v[2:3] op_sel_hi:[0,1]
	v_cndmask_b32_e32 v15, v17, v16, vcc
	v_not_b32_e32 v16, v14
	v_or_b32_e32 v17, 0x80000000, v14
	v_cmp_gt_i32_e32 vcc, 0, v14
	v_and_b32_e32 v15, 0xffffff00, v15
	v_or_b32_e32 v15, 0xbe, v15
	v_cndmask_b32_e32 v14, v17, v16, vcc
	v_and_b32_e32 v14, 0xffffff00, v14
	v_or_b32_e32 v14, 0xbd, v14
	v_max_u32_e32 v16, v41, v51
	v_min_u32_e32 v17, v41, v51
	v_max_u32_e32 v41, v53, v52
	v_min_u32_e32 v51, v53, v52
	v_max_u32_e32 v52, v35, v34
	v_min_u32_e32 v34, v35, v34
	v_max_u32_e32 v35, v54, v18
	v_min_u32_e32 v18, v54, v18
	v_max_u32_e32 v53, v55, v56
	v_min_u32_e32 v54, v55, v56
	v_max_u32_e32 v55, v22, v23
	v_min_u32_e32 v22, v22, v23
	v_max_u32_e32 v23, v12, v57
	v_min_u32_e32 v12, v12, v57
	v_max_u32_e32 v56, v14, v15
	v_min_u32_e32 v14, v14, v15
	v_max_u32_e32 v15, v16, v51
	v_min_u32_e32 v16, v16, v51
	v_max_u32_e32 v51, v17, v41
	v_min_u32_e32 v17, v17, v41
	v_max_u32_e32 v41, v18, v52
	v_min_u32_e32 v18, v18, v52
	v_max_u32_e32 v52, v35, v34
	v_min_u32_e32 v34, v35, v34
	v_max_u32_e32 v35, v53, v22
	v_min_u32_e32 v22, v53, v22
	v_max_u32_e32 v53, v54, v55
	v_min_u32_e32 v54, v54, v55
	v_max_u32_e32 v55, v14, v23
	v_min_u32_e32 v14, v14, v23
	v_max_u32_e32 v23, v56, v12
	v_min_u32_e32 v12, v56, v12
	v_max_u32_e32 v56, v15, v51
	v_min_u32_e32 v15, v15, v51
	v_max_u32_e32 v51, v16, v17
	v_min_u32_e32 v16, v16, v17
	v_max_u32_e32 v17, v34, v18
	v_min_u32_e32 v18, v34, v18
	v_max_u32_e32 v34, v52, v41
	v_min_u32_e32 v41, v52, v41
	v_max_u32_e32 v52, v35, v53
	v_min_u32_e32 v35, v35, v53
	v_max_u32_e32 v53, v22, v54
	v_min_u32_e32 v22, v22, v54
	v_max_u32_e32 v54, v12, v14
	v_min_u32_e32 v12, v12, v14
	v_max_u32_e32 v14, v23, v55
	v_min_u32_e32 v23, v23, v55
	v_max_u32_e32 v55, v56, v18
	v_min_u32_e32 v18, v56, v18
	v_max_u32_e32 v56, v15, v17
	v_min_u32_e32 v15, v15, v17
	v_max_u32_e32 v17, v51, v41
	v_min_u32_e32 v41, v51, v41
	v_max_u32_e32 v51, v16, v34
	v_min_u32_e32 v16, v16, v34
	v_max_u32_e32 v34, v12, v52
	v_min_u32_e32 v12, v12, v52
	v_max_u32_e32 v52, v54, v35
	v_min_u32_e32 v35, v54, v35
	v_max_u32_e32 v54, v23, v53
	v_min_u32_e32 v23, v23, v53
	v_max_u32_e32 v53, v14, v22
	v_min_u32_e32 v14, v14, v22
	v_max_u32_e32 v22, v55, v17
	v_min_u32_e32 v17, v55, v17
	v_max_u32_e32 v55, v56, v51
	v_min_u32_e32 v51, v56, v51
	v_max_u32_e32 v56, v18, v41
	v_min_u32_e32 v18, v18, v41
	v_max_u32_e32 v41, v15, v16
	v_min_u32_e32 v15, v15, v16
	v_max_u32_e32 v16, v23, v12
	v_min_u32_e32 v12, v23, v12
	v_max_u32_e32 v23, v14, v35
	v_min_u32_e32 v14, v14, v35
	v_max_u32_e32 v35, v54, v34
	v_min_u32_e32 v34, v54, v34
	v_max_u32_e32 v54, v53, v52
	v_min_u32_e32 v52, v53, v52
	v_max_u32_e32 v53, v22, v55
	v_min_u32_e32 v22, v22, v55
	v_max_u32_e32 v55, v17, v51
	v_min_u32_e32 v17, v17, v51
	v_max_u32_e32 v51, v56, v41
	v_min_u32_e32 v41, v56, v41
	v_max_u32_e32 v56, v18, v15
	v_min_u32_e32 v15, v18, v15
	v_max_u32_e32 v18, v14, v12
	v_min_u32_e32 v12, v14, v12
	v_max_u32_e32 v14, v23, v16
	v_min_u32_e32 v16, v23, v16
	v_max_u32_e32 v23, v52, v34
	v_min_u32_e32 v34, v52, v34
	v_max_u32_e32 v52, v54, v35
	v_min_u32_e32 v35, v54, v35
	v_max_u32_e32 v54, v53, v12
	v_min_u32_e32 v12, v53, v12
	v_max_u32_e32 v53, v22, v18
	v_min_u32_e32 v18, v22, v18
	v_max_u32_e32 v22, v55, v16
	v_min_u32_e32 v16, v55, v16
	v_max_u32_e32 v55, v17, v14
	v_min_u32_e32 v14, v17, v14
	v_max_u32_e32 v17, v51, v34
	v_min_u32_e32 v34, v51, v34
	v_max_u32_e32 v51, v41, v23
	v_min_u32_e32 v23, v41, v23
	v_max_u32_e32 v41, v56, v35
	v_min_u32_e32 v35, v56, v35
	v_max_u32_e32 v56, v15, v52
	v_min_u32_e32 v15, v15, v52
	v_max_u32_e32 v52, v54, v17
	v_min_u32_e32 v17, v54, v17
	v_max_u32_e32 v54, v53, v51
	v_min_u32_e32 v51, v53, v51
	v_max_u32_e32 v53, v22, v41
	v_min_u32_e32 v22, v22, v41
	v_max_u32_e32 v41, v55, v56
	v_min_u32_e32 v55, v55, v56
	v_max_u32_e32 v56, v12, v34
	v_min_u32_e32 v12, v12, v34
	v_max_u32_e32 v34, v18, v23
	v_min_u32_e32 v18, v18, v23
	v_max_u32_e32 v23, v16, v35
	v_min_u32_e32 v16, v16, v35
	v_max_u32_e32 v35, v14, v15
	v_min_u32_e32 v14, v14, v15
	v_max_u32_e32 v15, v52, v53
	v_min_u32_e32 v52, v52, v53
	v_max_u32_e32 v53, v54, v41
	v_min_u32_e32 v41, v54, v41
	v_max_u32_e32 v54, v17, v22
	v_min_u32_e32 v17, v17, v22
	v_max_u32_e32 v22, v51, v55
	v_min_u32_e32 v51, v51, v55
	v_max_u32_e32 v55, v56, v23
	v_min_u32_e32 v23, v56, v23
	v_max_u32_e32 v56, v34, v35
	v_min_u32_e32 v34, v34, v35
	v_max_u32_e32 v35, v12, v16
	v_min_u32_e32 v12, v12, v16
	v_max_u32_e32 v16, v18, v14
	v_min_u32_e32 v14, v18, v14
; #define CE_DESC(a, b) do { const unsigned _mx = (a) > (b) ? (a) : (b), _mn = (a) > (b) ? (b) : (a); (a) = _mx; (b) = _mn; } while (0)
; #define CK(i, j) ((f2key(va[i] + vb[j]) & ~255u) | (unsigned)(255 - (16 * (i) + (j))))
; __device__ __forceinline__ void merge16(unsigned (&a)[16], const unsigned (&b)[16]) {
; #pragma unroll
;     for (int i = 0; i < 16; ++i) a[i] = a[i] > b[15 - i] ? a[i] : b[15 - i];
; #pragma unroll
;     for (int stride = 8; stride > 0; stride >>= 1)
; #pragma unroll
;         for (int i = 0; i < 16; ++i) { const int j = i ^ stride; if (j > i) CE_DESC(a[i], a[j]); }
; }
; __device__ __forceinline__ void peer_tile(const Args& A, LAS unsigned char* lds, int tile) {
;     ...
;             sort16_desc(Bt); merge16(Lf, Bt);
; #pragma unroll
;             for (int j = 0; j < 4; ++j) Bt[j] = CK(3, j);
;             Bt[4] = CK(5, 0); Bt[5] = CK(5, 1); Bt[6] = CK(6, 0); Bt[7] = CK(6, 1); Bt[8] = CK(7, 0); Bt[9] = CK(7, 1);
;             Bt[10] = CK(8, 0); Bt[11] = CK(9, 0); Bt[12] = CK(10, 0); Bt[13] = CK(11, 0); Bt[14] = CK(12, 0); Bt[15] = CK(13, 0);
	v_min_u32_e32 v18, v15, v53
	v_min_u32_e32 v57, v52, v41
	v_min_u32_e32 v58, v54, v22
	v_min_u32_e32 v59, v17, v51
	v_min_u32_e32 v60, v55, v56
	v_min_u32_e32 v61, v23, v34
	v_min_u32_e32 v62, v35, v16
	v_min_u32_e32 v63, v12, v14
	v_max_u32_e32 v33, v33, v63
	v_max3_u32 v12, v44, v12, v14
	v_max_u32_e32 v14, v45, v62
	v_max3_u32 v16, v46, v35, v16
	v_max_u32_e32 v35, v47, v61
	v_max3_u32 v23, v48, v23, v34
	v_max_u32_e32 v34, v43, v60
	v_max3_u32 v42, v42, v55, v56
	v_max_u32_e32 v43, v49, v59
	v_max3_u32 v17, v50, v17, v51
	v_max_u32_e32 v36, v36, v58
	v_max3_u32 v22, v37, v54, v22
	v_max_u32_e32 v37, v38, v57
	v_max3_u32 v38, v39, v52, v41
	v_max_u32_e32 v18, v20, v18
	v_max3_u32 v15, v40, v15, v53
	v_max_u32_e32 v20, v33, v43
	v_min_u32_e32 v33, v33, v43
	v_max_u32_e32 v39, v12, v17
	v_min_u32_e32 v12, v12, v17
	v_max_u32_e32 v17, v14, v36
	v_min_u32_e32 v14, v14, v36
	v_max_u32_e32 v36, v16, v22
	v_min_u32_e32 v16, v16, v22
	v_max_u32_e32 v22, v35, v37
	v_min_u32_e32 v35, v35, v37
	v_max_u32_e32 v37, v23, v38
	v_min_u32_e32 v23, v23, v38
	v_max_u32_e32 v38, v34, v18
	v_min_u32_e32 v18, v34, v18
	v_max_u32_e32 v34, v42, v15
	v_min_u32_e32 v15, v42, v15
	v_max_u32_e32 v40, v20, v22
	v_min_u32_e32 v20, v20, v22
	v_max_u32_e32 v22, v39, v37
	v_min_u32_e32 v37, v39, v37
	v_max_u32_e32 v39, v17, v38
	v_min_u32_e32 v17, v17, v38
	v_max_u32_e32 v38, v36, v34
	v_min_u32_e32 v34, v36, v34
	v_max_u32_e32 v36, v33, v35
	v_min_u32_e32 v33, v33, v35
	v_max_u32_e32 v35, v12, v23
	v_min_u32_e32 v12, v12, v23
	v_max_u32_e32 v23, v14, v18
	v_min_u32_e32 v14, v14, v18
	v_max_u32_e32 v18, v16, v15
	v_min_u32_e32 v15, v16, v15
	v_max_u32_e32 v16, v40, v39
	v_min_u32_e32 v39, v40, v39
	v_max_u32_e32 v40, v22, v38
	v_min_u32_e32 v22, v22, v38
	v_max_u32_e32 v38, v20, v17
	v_min_u32_e32 v17, v20, v17
	v_max_u32_e32 v20, v37, v34
	v_min_u32_e32 v34, v37, v34
	v_max_u32_e32 v37, v36, v23
	v_min_u32_e32 v23, v36, v23
	v_max_u32_e32 v36, v35, v18
	v_min_u32_e32 v18, v35, v18
	v_max_u32_e32 v35, v33, v14
	v_min_u32_e32 v33, v33, v14
	v_max_u32_e32 v41, v12, v15
	v_min_u32_e32 v12, v12, v15
	v_pk_add_f32 v[14:15], v[4:5], v[0:1] op_sel_hi:[0,1]
	v_not_b32_e32 v50, v15
	v_or_b32_e32 v51, 0x80000000, v15
	v_cmp_gt_i32_e32 vcc, 0, v15
	v_not_b32_e32 v4, v3
	v_min_u32_e32 v42, v16, v40
	v_cndmask_b32_e32 v15, v51, v50, vcc
	v_not_b32_e32 v50, v14
	v_or_b32_e32 v51, 0x80000000, v14
	v_cmp_gt_i32_e32 vcc, 0, v14
	v_and_b32_e32 v15, 0xffffff00, v15
	v_or_b32_e32 v15, 0xcf, v15
	v_cndmask_b32_e32 v14, v51, v50, vcc
	v_or_b32_e32 v50, 0x80000000, v3
	v_cmp_gt_i32_e32 vcc, 0, v3
	v_and_b32_e32 v14, 0xffffff00, v14
	v_or_b32_e32 v14, 0xce, v14
	v_cndmask_b32_e32 v3, v50, v4, vcc
	v_and_b32_e32 v3, 0xffffff00, v3
	v_or_b32_e32 v4, 0xcd, v3
	v_not_b32_e32 v3, v2
	v_or_b32_e32 v50, 0x80000000, v2
	v_cmp_gt_i32_e32 vcc, 0, v2
	v_min_u32_e32 v43, v39, v22
	v_min_u32_e32 v44, v38, v20
	v_cndmask_b32_e32 v2, v50, v3, vcc
	v_and_b32_e32 v2, 0xffffff00, v2
	v_or_b32_e32 v50, 0xcc, v2
	v_pk_add_f32 v[2:3], v[10:11], v[0:1] op_sel_hi:[0,1]
	v_not_b32_e32 v10, v3
	v_or_b32_e32 v51, 0x80000000, v3
	v_cmp_gt_i32_e32 vcc, 0, v3
	v_min_u32_e32 v45, v17, v34
	v_min_u32_e32 v46, v37, v36
	v_cndmask_b32_e32 v3, v51, v10, vcc
	v_and_b32_e32 v3, 0xffffff00, v3
	v_or_b32_e32 v10, 0xaf, v3
	v_not_b32_e32 v3, v2
	v_or_b32_e32 v51, 0x80000000, v2
	v_cmp_gt_i32_e32 vcc, 0, v2
	v_min_u32_e32 v47, v23, v18
	v_min_u32_e32 v48, v35, v41
	v_cndmask_b32_e32 v2, v51, v3, vcc
	v_and_b32_e32 v2, 0xffffff00, v2
	v_or_b32_e32 v51, 0xae, v2
	v_pk_add_f32 v[2:3], v[8:9], v[0:1] op_sel_hi:[0,1]
	v_not_b32_e32 v8, v3
	v_or_b32_e32 v52, 0x80000000, v3
	v_cmp_gt_i32_e32 vcc, 0, v3
	v_min_u32_e32 v49, v33, v12
	v_lshlrev_b32_e32 v11, 9, v11
	v_cndmask_b32_e32 v3, v52, v8, vcc
	v_and_b32_e32 v3, 0xffffff00, v3
	v_or_b32_e32 v8, 0x9f, v3
	v_not_b32_e32 v3, v2
	v_or_b32_e32 v52, 0x80000000, v2
	v_cmp_gt_i32_e32 vcc, 0, v2
	s_nop 1
	v_cndmask_b32_e32 v2, v52, v3, vcc
	v_and_b32_e32 v2, 0xffffff00, v2
	v_or_b32_e32 v52, 0x9e, v2
	v_pk_add_f32 v[2:3], v[6:7], v[0:1] op_sel_hi:[0,1]
	v_not_b32_e32 v0, v3
	v_or_b32_e32 v6, 0x80000000, v3
	v_cmp_gt_i32_e32 vcc, 0, v3
	v_not_b32_e32 v3, v2
	s_nop 0
	v_cndmask_b32_e32 v0, v6, v0, vcc
	v_or_b32_e32 v6, 0x80000000, v2
	v_cmp_gt_i32_e32 vcc, 0, v2
	v_and_b32_e32 v0, 0xffffff00, v0
	v_or_b32_e32 v0, 0x8f, v0
	v_cndmask_b32_e32 v2, v6, v3, vcc
	v_add_f32_e32 v3, v27, v1
	v_not_b32_e32 v6, v3
	v_or_b32_e32 v27, 0x80000000, v3
	v_cmp_gt_i32_e32 vcc, 0, v3
	v_and_b32_e32 v2, 0xffffff00, v2
	v_or_b32_e32 v2, 0x8e, v2
	v_cndmask_b32_e32 v3, v27, v6, vcc
	v_add_f32_e32 v6, v28, v1
	v_not_b32_e32 v27, v6
	v_or_b32_e32 v28, 0x80000000, v6
	v_cmp_gt_i32_e32 vcc, 0, v6
	v_and_b32_e32 v3, 0xffffff00, v3
	v_or_b32_e32 v3, 0x7f, v3
	v_cndmask_b32_e32 v6, v28, v27, vcc
	v_add_f32_e32 v27, v29, v1
	v_not_b32_e32 v28, v27
	v_or_b32_e32 v29, 0x80000000, v27
	v_cmp_gt_i32_e32 vcc, 0, v27
	v_and_b32_e32 v6, 0xffffff00, v6
	v_or_b32_e32 v6, 0x6f, v6
	v_cndmask_b32_e32 v27, v29, v28, vcc
	v_add_f32_e32 v28, v30, v1
	v_not_b32_e32 v29, v28
	v_or_b32_e32 v30, 0x80000000, v28
	v_cmp_gt_i32_e32 vcc, 0, v28
	v_and_b32_e32 v27, 0xffffff00, v27
	v_or_b32_e32 v27, 0x5f, v27
	v_cndmask_b32_e32 v28, v30, v29, vcc
	v_add_f32_e32 v29, v31, v1
	v_not_b32_e32 v30, v29
	v_or_b32_e32 v31, 0x80000000, v29
	v_cmp_gt_i32_e32 vcc, 0, v29
	v_and_b32_e32 v28, 0xffffff00, v28
	v_or_b32_e32 v28, 0x4f, v28
	v_cndmask_b32_e32 v29, v31, v30, vcc
	v_add_f32_e32 v30, v32, v1
	v_not_b32_e32 v31, v30
	v_or_b32_e32 v32, 0x80000000, v30
	v_cmp_gt_i32_e32 vcc, 0, v30
	v_and_or_b32 v29, v29, s34, 63
	s_nop 0
	v_cndmask_b32_e32 v30, v32, v31, vcc
; #define CE_DESC(a, b) do { const unsigned _mx = (a) > (b) ? (a) : (b), _mn = (a) > (b) ? (b) : (a); (a) = _mx; (b) = _mn; } while (0)
; __device__ __forceinline__ void sort16_desc(unsigned (&k)[16]) {
; #pragma unroll
;     for (int size = 2; size <= 16; size <<= 1)
; #pragma unroll
;         for (int stride = size >> 1; stride > 0; stride >>= 1)
; #pragma unroll
;             for (int i = 0; i < 16; ++i) { const int j = i ^ stride;
;                 if (j > i) { if ((i & size) == 0) CE_DESC(k[i], k[j]); else CE_DESC(k[j], k[i]); } }
; }
; __device__ __forceinline__ void merge16(unsigned (&a)[16], const unsigned (&b)[16]) {
; #pragma unroll
;     for (int i = 0; i < 16; ++i) a[i] = a[i] > b[15 - i] ? a[i] : b[15 - i];
; #pragma unroll
;     for (int stride = 8; stride > 0; stride >>= 1)
; #pragma unroll
;         for (int i = 0; i < 16; ++i) { const int j = i ^ stride; if (j > i) CE_DESC(a[i], a[j]); }
; }
; __device__ __forceinline__ void peer_tile(const Args& A, LAS unsigned char* lds, int tile) {
;     ...
;             sort16_desc(Bt); merge16(Lf, Bt);
	v_and_or_b32 v30, v30, s34, 47
	v_max_u32_e32 v31, v15, v14
	v_min_u32_e32 v14, v15, v14
	v_max_u32_e32 v15, v50, v4
	v_min_u32_e32 v4, v50, v4
	v_max_u32_e32 v32, v10, v51
	v_min_u32_e32 v10, v10, v51
	v_max_u32_e32 v50, v52, v8
	v_min_u32_e32 v8, v52, v8
	v_max_u32_e32 v51, v0, v2
	v_min_u32_e32 v0, v0, v2
	v_max_u32_e32 v2, v6, v3
	v_min_u32_e32 v3, v6, v3
	v_max_u32_e32 v6, v27, v28
	v_min_u32_e32 v27, v27, v28
	v_max_u32_e32 v28, v30, v29
	v_min_u32_e32 v29, v30, v29
	v_max_u32_e32 v30, v31, v4
	v_min_u32_e32 v4, v31, v4
	v_max_u32_e32 v31, v14, v15
	v_min_u32_e32 v14, v14, v15
	v_max_u32_e32 v15, v8, v32
	v_min_u32_e32 v8, v8, v32
	v_max_u32_e32 v32, v50, v10
	v_min_u32_e32 v10, v50, v10
	v_max_u32_e32 v50, v51, v3
	v_min_u32_e32 v3, v51, v3
	v_max_u32_e32 v51, v0, v2
	v_min_u32_e32 v0, v0, v2
	v_max_u32_e32 v2, v29, v6
	v_min_u32_e32 v6, v29, v6
	v_max_u32_e32 v29, v28, v27
	v_min_u32_e32 v27, v28, v27
	v_max_u32_e32 v28, v30, v31
	v_min_u32_e32 v30, v30, v31
	v_max_u32_e32 v31, v4, v14
	v_min_u32_e32 v4, v4, v14
	v_max_u32_e32 v14, v10, v8
	v_min_u32_e32 v8, v10, v8
	v_max_u32_e32 v10, v32, v15
	v_min_u32_e32 v15, v32, v15
	v_max_u32_e32 v32, v50, v51
	v_min_u32_e32 v50, v50, v51
	v_max_u32_e32 v51, v3, v0
	v_min_u32_e32 v0, v3, v0
	v_max_u32_e32 v3, v27, v6
	v_min_u32_e32 v6, v27, v6
	v_max_u32_e32 v27, v29, v2
	v_min_u32_e32 v2, v29, v2
	v_max_u32_e32 v29, v28, v8
	v_min_u32_e32 v8, v28, v8
	v_max_u32_e32 v28, v30, v14
	v_min_u32_e32 v14, v30, v14
	v_max_u32_e32 v30, v31, v15
	v_min_u32_e32 v15, v31, v15
	v_max_u32_e32 v31, v4, v10
	v_min_u32_e32 v4, v4, v10
	v_max_u32_e32 v10, v6, v32
	v_min_u32_e32 v6, v6, v32
	v_max_u32_e32 v32, v3, v50
	v_min_u32_e32 v3, v3, v50
	v_max_u32_e32 v50, v2, v51
	v_min_u32_e32 v2, v2, v51
	v_max_u32_e32 v51, v27, v0
	v_min_u32_e32 v0, v27, v0
	v_max_u32_e32 v27, v29, v30
	v_min_u32_e32 v29, v29, v30
	v_max_u32_e32 v30, v28, v31
	v_min_u32_e32 v28, v28, v31
	v_max_u32_e32 v31, v8, v15
	v_min_u32_e32 v8, v8, v15
	v_max_u32_e32 v15, v14, v4
	v_min_u32_e32 v4, v14, v4
	v_max_u32_e32 v14, v2, v6
	v_min_u32_e32 v2, v2, v6
	v_max_u32_e32 v6, v0, v3
	v_min_u32_e32 v0, v0, v3
	v_max_u32_e32 v3, v50, v10
	v_min_u32_e32 v10, v50, v10
	v_max_u32_e32 v50, v51, v32
	v_min_u32_e32 v32, v51, v32
	v_max_u32_e32 v51, v27, v30
	v_min_u32_e32 v27, v27, v30
	v_max_u32_e32 v30, v29, v28
	v_min_u32_e32 v28, v29, v28
	v_max_u32_e32 v29, v31, v15
	v_min_u32_e32 v15, v31, v15
	v_max_u32_e32 v31, v8, v4
	v_min_u32_e32 v4, v8, v4
	v_max_u32_e32 v8, v0, v2
	v_min_u32_e32 v0, v0, v2
	v_max_u32_e32 v2, v6, v14
	v_min_u32_e32 v6, v6, v14
	v_max_u32_e32 v14, v32, v10
	v_min_u32_e32 v10, v32, v10
	v_max_u32_e32 v32, v50, v3
	v_min_u32_e32 v3, v50, v3
	v_max_u32_e32 v50, v51, v0
	v_min_u32_e32 v0, v51, v0
	v_max_u32_e32 v51, v27, v8
	v_min_u32_e32 v8, v27, v8
	v_max_u32_e32 v27, v30, v6
	v_min_u32_e32 v6, v30, v6
	v_max_u32_e32 v30, v28, v2
	v_min_u32_e32 v2, v28, v2
	v_max_u32_e32 v28, v29, v10
	v_min_u32_e32 v10, v29, v10
	v_max_u32_e32 v29, v15, v14
	v_min_u32_e32 v14, v15, v14
	v_max_u32_e32 v15, v31, v3
	v_min_u32_e32 v3, v31, v3
	v_max_u32_e32 v31, v4, v32
	v_min_u32_e32 v4, v4, v32
	v_max_u32_e32 v32, v50, v28
	v_min_u32_e32 v28, v50, v28
	v_max_u32_e32 v50, v51, v29
	v_min_u32_e32 v29, v51, v29
	v_max_u32_e32 v51, v27, v15
	v_min_u32_e32 v15, v27, v15
	v_max_u32_e32 v27, v30, v31
	v_min_u32_e32 v30, v30, v31
	v_max_u32_e32 v31, v0, v10
	v_min_u32_e32 v0, v0, v10
	v_max_u32_e32 v10, v8, v14
	v_min_u32_e32 v8, v8, v14
	v_max_u32_e32 v14, v6, v3
	v_min_u32_e32 v3, v6, v3
	v_max_u32_e32 v6, v2, v4
	v_min_u32_e32 v2, v2, v4
	v_max_u32_e32 v4, v32, v51
	v_min_u32_e32 v32, v32, v51
	v_max_u32_e32 v51, v50, v27
	v_min_u32_e32 v27, v50, v27
	v_max_u32_e32 v50, v28, v15
	v_min_u32_e32 v15, v28, v15
	v_max_u32_e32 v28, v29, v30
	v_min_u32_e32 v29, v29, v30
	v_max_u32_e32 v30, v31, v14
	v_min_u32_e32 v14, v31, v14
	v_max_u32_e32 v31, v10, v6
	v_min_u32_e32 v6, v10, v6
	v_max_u32_e32 v10, v0, v3
	v_min_u32_e32 v0, v0, v3
	v_max_u32_e32 v3, v8, v2
	v_min_u32_e32 v2, v8, v2
	v_min_u32_e32 v8, v4, v51
	v_min_u32_e32 v52, v32, v27
	v_min_u32_e32 v53, v50, v28
	v_min_u32_e32 v54, v15, v29
	v_min_u32_e32 v55, v30, v31
	v_min_u32_e32 v56, v14, v6
	v_min_u32_e32 v57, v10, v3
	v_min_u32_e32 v58, v0, v2
	v_max3_u32 v16, v16, v40, v58
	v_max3_u32 v0, v42, v0, v2
	v_max3_u32 v2, v39, v22, v57
	v_max3_u32 v3, v43, v10, v3
	v_max3_u32 v10, v38, v20, v56
	v_max3_u32 v6, v44, v14, v6
	v_max3_u32 v14, v17, v34, v55
	v_max3_u32 v17, v45, v30, v31
	v_max3_u32 v20, v37, v36, v54
	v_max3_u32 v15, v46, v15, v29
	v_max3_u32 v18, v23, v18, v53
	v_max3_u32 v22, v47, v50, v28
	v_max3_u32 v23, v35, v41, v52
	v_max3_u32 v27, v48, v32, v27
	v_max3_u32 v8, v33, v12, v8
	v_max3_u32 v4, v49, v4, v51
	v_max_u32_e32 v12, v16, v20
	v_min_u32_e32 v16, v16, v20
	v_max_u32_e32 v20, v0, v15
	v_min_u32_e32 v0, v0, v15
	v_max_u32_e32 v15, v2, v18
	v_min_u32_e32 v2, v2, v18
	v_max_u32_e32 v18, v3, v22
	v_min_u32_e32 v3, v3, v22
	v_max_u32_e32 v22, v10, v23
	v_min_u32_e32 v10, v10, v23
	v_max_u32_e32 v23, v6, v27
	v_min_u32_e32 v6, v6, v27
	v_max_u32_e32 v27, v14, v8
	v_min_u32_e32 v8, v14, v8
	v_max_u32_e32 v14, v17, v4
	v_min_u32_e32 v4, v17, v4
	v_max_u32_e32 v17, v12, v22
	v_min_u32_e32 v12, v12, v22
	v_max_u32_e32 v22, v20, v23
	v_min_u32_e32 v20, v20, v23
	v_max_u32_e32 v23, v15, v27
	v_min_u32_e32 v15, v15, v27
	v_max_u32_e32 v27, v18, v14
	v_min_u32_e32 v14, v18, v14
	v_max_u32_e32 v18, v16, v10
	v_min_u32_e32 v10, v16, v10
	v_max_u32_e32 v16, v0, v6
	v_min_u32_e32 v0, v0, v6
	v_max_u32_e32 v6, v2, v8
	v_min_u32_e32 v2, v2, v8
	v_max_u32_e32 v8, v3, v4
; __device__ __forceinline__ float key2f(unsigned k) { const unsigned u = (k & 0x80000000u) ? (k & 0x7fffffffu) : ~k; return __uint_as_float(u); }
; #define CE_DESC(a, b) do { const unsigned _mx = (a) > (b) ? (a) : (b), _mn = (a) > (b) ? (b) : (a); (a) = _mx; (b) = _mn; } while (0)
; #define CK(i, j) ((f2key(va[i] + vb[j]) & ~255u) | (unsigned)(255 - (16 * (i) + (j))))
; __device__ __forceinline__ void peer_tile(const Args& A, LAS unsigned char* lds, int tile) {
;     ...
;             sort16_desc(Bt); merge16(Lf, Bt);
; #pragma unroll
;             for (int j = 0; j < 4; ++j) Bt[j] = CK(3, j);
;             Bt[4] = CK(5, 0); Bt[5] = CK(5, 1); Bt[6] = CK(6, 0); Bt[7] = CK(6, 1); Bt[8] = CK(7, 0); Bt[9] = CK(7, 1);
;             Bt[10] = CK(8, 0); Bt[11] = CK(9, 0); Bt[12] = CK(10, 0); Bt[13] = CK(11, 0); Bt[14] = CK(12, 0); Bt[15] = CK(13, 0);
;             sort16_desc(Bt); merge16(Lf, Bt);
;             { unsigned x0 = CK(14, 0), x1 = CK(15, 0);
; #pragma unroll
;               for (int i = 0; i < 16; ++i) CE_DESC(Lf[i], x0);
; #pragma unroll
;               for (int i = 0; i < 16; ++i) CE_DESC(Lf[i], x1); }
;     ...
;             float fv[16], den = 0.f; const float f0 = key2f(Lf[0] & ~255u);
; #pragma unroll
;             for (int k = 0; k < 16; ++k) { fv[k] = __expf(key2f(Lf[k] & ~255u) - f0); den += fv[k]; }
	v_min_u32_e32 v3, v3, v4
	v_max_u32_e32 v4, v17, v23
	v_min_u32_e32 v17, v17, v23
	v_max_u32_e32 v23, v22, v27
	v_min_u32_e32 v22, v22, v27
	v_max_u32_e32 v27, v12, v15
	v_min_u32_e32 v12, v12, v15
	v_max_u32_e32 v15, v20, v14
	v_min_u32_e32 v14, v20, v14
	v_max_u32_e32 v20, v18, v6
	v_min_u32_e32 v6, v18, v6
	v_max_u32_e32 v18, v16, v8
	v_min_u32_e32 v8, v16, v8
	v_max_u32_e32 v16, v10, v2
	v_min_u32_e32 v2, v10, v2
	v_max_u32_e32 v10, v0, v3
	v_min_u32_e32 v0, v0, v3
	v_max_u32_e32 v41, v2, v0
	v_min_u32_e32 v0, v2, v0
	v_add_f32_e32 v2, v25, v1
	v_not_b32_e32 v25, v2
	v_or_b32_e32 v42, 0x80000000, v2
	v_cmp_gt_i32_e32 vcc, 0, v2
	v_add_f32_e32 v1, v26, v1
	v_max_u32_e32 v3, v4, v23
	v_cndmask_b32_e32 v2, v42, v25, vcc
	v_and_or_b32 v2, v2, s34, 31
	v_not_b32_e32 v25, v1
	v_or_b32_e32 v26, 0x80000000, v1
	v_cmp_gt_i32_e32 vcc, 0, v1
	v_min_u32_e32 v28, v4, v23
	v_max_u32_e32 v29, v17, v22
	v_cndmask_b32_e32 v1, v26, v25, vcc
	v_max_u32_e32 v25, v3, v2
	v_min_u32_e32 v3, v3, v2
	v_min_u32_e32 v3, v28, v3
	v_min_u32_e32 v30, v17, v22
	v_med3_u32 v2, v4, v23, v2
	v_min_u32_e32 v23, v29, v3
	v_max_u32_e32 v31, v27, v15
	v_max_u32_e32 v4, v29, v3
	v_med3_u32 v3, v17, v22, v3
	v_min_u32_e32 v17, v30, v23
	v_min_u32_e32 v32, v27, v15
	v_min_u32_e32 v23, v31, v17
	v_max_u32_e32 v33, v12, v14
	v_max_u32_e32 v22, v31, v17
	v_med3_u32 v15, v27, v15, v17
	v_min_u32_e32 v17, v32, v23
	v_min_u32_e32 v34, v12, v14
	v_min_u32_e32 v26, v33, v17
	v_max_u32_e32 v35, v20, v18
	v_med3_u32 v12, v12, v14, v17
	v_min_u32_e32 v14, v34, v26
	v_min_u32_e32 v36, v20, v18
	v_min_u32_e32 v26, v35, v14
	v_max_u32_e32 v37, v6, v8
	v_max_u32_e32 v23, v33, v17
	v_max_u32_e32 v17, v35, v14
	v_med3_u32 v14, v20, v18, v14
	v_min_u32_e32 v18, v36, v26
	v_min_u32_e32 v38, v6, v8
	v_min_u32_e32 v26, v37, v18
	v_max_u32_e32 v39, v16, v10
	v_med3_u32 v6, v6, v8, v18
	v_min_u32_e32 v8, v38, v26
	v_min_u32_e32 v40, v16, v10
	v_min_u32_e32 v26, v39, v8
	v_and_or_b32 v1, v1, s34, 15
	v_max_u32_e32 v20, v37, v18
	v_max_u32_e32 v18, v39, v8
	v_med3_u32 v8, v16, v10, v8
	v_min_u32_e32 v10, v40, v26
	v_max_u32_e32 v26, v25, v1
	v_min_u32_e32 v1, v25, v1
	v_max_u32_e32 v25, v2, v1
	v_min_u32_e32 v1, v2, v1
	v_max_u32_e32 v2, v4, v1
	v_min_u32_e32 v1, v4, v1
	v_max_u32_e32 v4, v3, v1
	v_min_u32_e32 v1, v3, v1
	v_max_u32_e32 v3, v22, v1
	v_min_u32_e32 v1, v22, v1
	v_max_u32_e32 v22, v15, v1
	v_min_u32_e32 v1, v15, v1
	v_max_u32_e32 v15, v23, v1
	v_min_u32_e32 v1, v23, v1
	v_max_u32_e32 v23, v12, v1
	v_min_u32_e32 v1, v12, v1
	v_max_u32_e32 v12, v17, v1
	v_min_u32_e32 v1, v17, v1
	v_max_u32_e32 v17, v14, v1
	v_min_u32_e32 v1, v14, v1
	v_max_u32_e32 v14, v20, v1
	v_min_u32_e32 v1, v20, v1
	v_max_u32_e32 v20, v6, v1
	v_min_u32_e32 v1, v6, v1
	v_max_u32_e32 v6, v18, v1
	v_min_u32_e32 v1, v18, v1
	v_max_u32_e32 v16, v41, v10
	v_max_u32_e32 v18, v8, v1
	v_min_u32_e32 v1, v8, v1
	v_min_u32_e32 v10, v41, v10
	v_max_u32_e32 v8, v16, v1
	v_min_u32_e32 v1, v16, v1
	v_max3_u32 v10, v0, v10, v1
	v_and_b32_e32 v0, 0x7fffff00, v26
	v_bitop3_b32 v1, v26, s33, v26 bitop3:0xcf
	v_cmp_gt_i32_e32 vcc, 0, v26
	v_and_b32_e32 v16, 0x7fffff00, v25
	v_bitop3_b32 v27, v25, s33, v25 bitop3:0xcf
	v_cndmask_b32_e32 v0, v1, v0, vcc
	v_cmp_gt_i32_e32 vcc, 0, v25
	v_sub_f32_e32 v1, v0, v0
	v_bitop3_b32 v28, v2, s33, v2 bitop3:0xcf
	v_cndmask_b32_e32 v16, v27, v16, vcc
	v_and_b32_e32 v27, 0x7fffff00, v2
	v_cmp_gt_i32_e32 vcc, 0, v2
	v_mul_f32_e32 v1, 0x3fb8aa3b, v1
	v_sub_f32_e32 v16, v16, v0
	v_cndmask_b32_e32 v27, v28, v27, vcc
	v_and_b32_e32 v28, 0x7fffff00, v4
	v_bitop3_b32 v29, v4, s33, v4 bitop3:0xcf
	v_cmp_gt_i32_e32 vcc, 0, v4
	v_exp_f32_e32 v1, v1
	v_mul_f32_e32 v16, 0x3fb8aa3b, v16
	v_sub_f32_e32 v27, v27, v0
	v_cndmask_b32_e32 v28, v29, v28, vcc
	v_and_b32_e32 v30, 0x7fffff00, v3
	v_bitop3_b32 v31, v3, s33, v3 bitop3:0xcf
	v_cmp_gt_i32_e32 vcc, 0, v3
	v_exp_f32_e32 v16, v16
	v_mul_f32_e32 v27, 0x3fb8aa3b, v27
	v_sub_f32_e32 v28, v28, v0
	v_cndmask_b32_e32 v30, v31, v30, vcc
	v_and_b32_e32 v31, 0x7fffff00, v22
	v_bitop3_b32 v32, v22, s33, v22 bitop3:0xcf
	v_cmp_gt_i32_e32 vcc, 0, v22
	v_exp_f32_e32 v27, v27
	v_mul_f32_e32 v28, 0x3fb8aa3b, v28
	v_sub_f32_e32 v30, v30, v0
	v_cndmask_b32_e32 v31, v32, v31, vcc
	v_and_b32_e32 v32, 0x7fffff00, v15
	v_bitop3_b32 v33, v15, s33, v15 bitop3:0xcf
	v_cmp_gt_i32_e32 vcc, 0, v15
	v_exp_f32_e32 v28, v28
	v_mul_f32_e32 v30, 0x3fb8aa3b, v30
	v_sub_f32_e32 v31, v31, v0
	v_cndmask_b32_e32 v32, v33, v32, vcc
	v_and_b32_e32 v33, 0x7fffff00, v23
	v_bitop3_b32 v34, v23, s33, v23 bitop3:0xcf
	v_cmp_gt_i32_e32 vcc, 0, v23
	v_add_f32_e32 v29, 0, v1
	v_exp_f32_e32 v30, v30
	v_mul_f32_e32 v31, 0x3fb8aa3b, v31
	v_sub_f32_e32 v32, v32, v0
	v_cndmask_b32_e32 v33, v34, v33, vcc
	v_and_b32_e32 v34, 0x7fffff00, v12
	v_bitop3_b32 v35, v12, s33, v12 bitop3:0xcf
	v_cmp_gt_i32_e32 vcc, 0, v12
	v_add_f32_e32 v29, v29, v16
	v_exp_f32_e32 v31, v31
	v_mul_f32_e32 v32, 0x3fb8aa3b, v32
	v_sub_f32_e32 v33, v33, v0
	v_cndmask_b32_e32 v34, v35, v34, vcc
	v_and_b32_e32 v35, 0x7fffff00, v17
	v_bitop3_b32 v36, v17, s33, v17 bitop3:0xcf
	v_cmp_gt_i32_e32 vcc, 0, v17
	v_add_f32_e32 v29, v29, v27
	v_exp_f32_e32 v32, v32
	v_mul_f32_e32 v33, 0x3fb8aa3b, v33
	v_sub_f32_e32 v34, v34, v0
	v_cndmask_b32_e32 v35, v36, v35, vcc
	v_and_b32_e32 v36, 0x7fffff00, v14
	v_bitop3_b32 v37, v14, s33, v14 bitop3:0xcf
	v_cmp_gt_i32_e32 vcc, 0, v14
	v_add_f32_e32 v29, v29, v28
	v_exp_f32_e32 v33, v33
	v_mul_f32_e32 v34, 0x3fb8aa3b, v34
	v_sub_f32_e32 v35, v35, v0
	v_cndmask_b32_e32 v36, v37, v36, vcc
	v_and_b32_e32 v37, 0x7fffff00, v20
	v_bitop3_b32 v38, v20, s33, v20 bitop3:0xcf
	v_cmp_gt_i32_e32 vcc, 0, v20
	v_add_f32_e32 v29, v29, v30
; #define LDS_WAIT() asm volatile("s_waitcnt lgkmcnt(0)" ::: "memory")
; __device__ __forceinline__ float key2f(unsigned k) { const unsigned u = (k & 0x80000000u) ? (k & 0x7fffffffu) : ~k; return __uint_as_float(u); }
; __device__ __forceinline__ void peer_tile(const Args& A, LAS unsigned char* lds, int tile) {
;     ...
;             float fv[16], den = 0.f; const float f0 = key2f(Lf[0] & ~255u);
; #pragma unroll
;             for (int k = 0; k < 16; ++k) { fv[k] = __expf(key2f(Lf[k] & ~255u) - f0); den += fv[k]; }
;             const float rden = 1.f / den;
;             LDS_WAIT();
; #pragma unroll
;             for (int k = 0; k < 16; ++k) { const unsigned code = 255u - (Lf[k] & 255u); const unsigned e = idx[code >> 4] * 128u + idx[16 + (code & 15u)];
;                 u32x2 sv; sv.x = e; sv.y = __float_as_uint(fv[k] * rden); SEL[(tl * 8 + h) * 16 + k] = sv; }
	v_exp_f32_e32 v34, v34
	v_mul_f32_e32 v35, 0x3fb8aa3b, v35
	v_sub_f32_e32 v36, v36, v0
	v_cndmask_b32_e32 v37, v38, v37, vcc
	v_and_b32_e32 v38, 0x7fffff00, v6
	v_bitop3_b32 v39, v6, s33, v6 bitop3:0xcf
	v_cmp_gt_i32_e32 vcc, 0, v6
	v_add_f32_e32 v29, v29, v31
	v_exp_f32_e32 v35, v35
	v_mul_f32_e32 v36, 0x3fb8aa3b, v36
	v_sub_f32_e32 v37, v37, v0
	v_cndmask_b32_e32 v38, v39, v38, vcc
	v_and_b32_e32 v39, 0x7fffff00, v18
	v_bitop3_b32 v40, v18, s33, v18 bitop3:0xcf
	v_cmp_gt_i32_e32 vcc, 0, v18
	v_add_f32_e32 v29, v29, v32
	v_exp_f32_e32 v36, v36
	v_mul_f32_e32 v37, 0x3fb8aa3b, v37
	v_sub_f32_e32 v38, v38, v0
	v_cndmask_b32_e32 v39, v40, v39, vcc
	v_and_b32_e32 v40, 0x7fffff00, v8
	v_bitop3_b32 v41, v8, s33, v8 bitop3:0xcf
	v_cmp_gt_i32_e32 vcc, 0, v8
	v_add_f32_e32 v29, v29, v33
	v_exp_f32_e32 v37, v37
	v_mul_f32_e32 v38, 0x3fb8aa3b, v38
	v_sub_f32_e32 v39, v39, v0
	v_cndmask_b32_e32 v40, v41, v40, vcc
	v_and_b32_e32 v41, 0x7fffff00, v10
	v_bitop3_b32 v42, v10, s33, v10 bitop3:0xcf
	v_cmp_gt_i32_e32 vcc, 0, v10
	v_add_f32_e32 v29, v29, v34
	v_exp_f32_e32 v38, v38
	v_mul_f32_e32 v39, 0x3fb8aa3b, v39
	v_sub_f32_e32 v40, v40, v0
	v_cndmask_b32_e32 v41, v42, v41, vcc
	v_add_f32_e32 v29, v29, v35
	v_exp_f32_e32 v39, v39
	v_mul_f32_e32 v40, 0x3fb8aa3b, v40
	v_sub_f32_e32 v0, v41, v0
	v_add_f32_e32 v29, v29, v36
	v_exp_f32_e32 v40, v40
	v_mul_f32_e32 v0, 0x3fb8aa3b, v0
	v_add_f32_e32 v29, v29, v37
	v_exp_f32_e32 v41, v0
	v_add_f32_e32 v0, v29, v38
	v_add_f32_e32 v0, v0, v39
	v_add_f32_e32 v0, v0, v40
	v_add_f32_e32 v0, v0, v41
	v_div_scale_f32 v29, s[0:1], v0, v0, 1.0
	v_rcp_f32_e32 v42, v29
	v_not_b32_e32 v21, v26
	v_not_b32_e32 v24, v25
	v_fma_f32 v43, -v29, v42, 1.0
	v_fmac_f32_e32 v42, v43, v42
	v_div_scale_f32 v43, vcc, 1.0, v0, 1.0
	v_mul_f32_e32 v44, v43, v42
	v_fma_f32 v45, -v29, v44, v43
	v_fmac_f32_e32 v44, v45, v42
	v_fma_f32 v29, -v29, v44, v43
	v_div_fmas_f32 v29, v29, v42, v44
	v_div_fixup_f32 v29, v29, v0, 1.0
	v_and_b32_e32 v0, 48, v19
	v_lshrrev_b32_e32 v19, 2, v21
	v_and_b32_e32 v19, 60, v19
	v_bitop3_b32 v21, v26, 15, v26 bitop3:0xc
	v_add_u32_e32 v19, v5, v19
	v_lshl_add_u32 v21, v21, 2, v5
	ds_read_b32 v19, v19
	ds_read_b32 v21, v21 offset:64
	v_lshlrev_b32_e32 v0, 3, v0
	v_add3_u32 v11, v13, v11, v0
	v_mul_f32_e32 v1, v1, v29
	v_not_b32_e32 v13, v2
	s_waitcnt lgkmcnt(0)
	v_lshl_add_u32 v0, v19, 7, v21
	ds_write_b64 v11, v[0:1]
	v_lshrrev_b32_e32 v0, 2, v24
	v_and_b32_e32 v0, 60, v0
	v_bitop3_b32 v1, v25, 15, v25 bitop3:0xc
	v_add_u32_e32 v0, v5, v0
	v_lshl_add_u32 v1, v1, 2, v5
	ds_read_b32 v0, v0
	ds_read_b32 v1, v1 offset:64
	v_cmp_eq_u32_e32 vcc, 0, v9
	s_waitcnt lgkmcnt(0)
	v_lshl_add_u32 v0, v0, 7, v1
	v_mul_f32_e32 v1, v16, v29
	ds_write_b64 v11, v[0:1] offset:8
	v_lshrrev_b32_e32 v0, 2, v13
	v_and_b32_e32 v0, 60, v0
	v_bitop3_b32 v1, v2, 15, v2 bitop3:0xc
	v_add_u32_e32 v0, v5, v0
	v_lshl_add_u32 v1, v1, 2, v5
	ds_read_b32 v0, v0
	ds_read_b32 v1, v1 offset:64
	v_not_b32_e32 v2, v4
	s_waitcnt lgkmcnt(0)
	v_lshl_add_u32 v0, v0, 7, v1
	v_mul_f32_e32 v1, v27, v29
	ds_write_b64 v11, v[0:1] offset:16
	v_lshrrev_b32_e32 v0, 2, v2
	v_and_b32_e32 v0, 60, v0
	v_bitop3_b32 v1, v4, 15, v4 bitop3:0xc
	v_add_u32_e32 v0, v5, v0
	v_lshl_add_u32 v1, v1, 2, v5
	ds_read_b32 v0, v0
	ds_read_b32 v1, v1 offset:64
	v_not_b32_e32 v2, v3
	v_mul_lo_u32 v4, v7, s36
	s_waitcnt lgkmcnt(0)
	v_lshl_add_u32 v0, v0, 7, v1
	v_mul_f32_e32 v1, v28, v29
	ds_write_b64 v11, v[0:1] offset:24
	v_lshrrev_b32_e32 v0, 2, v2
	v_and_b32_e32 v0, 60, v0
	v_bitop3_b32 v1, v3, 15, v3 bitop3:0xc
	v_add_u32_e32 v0, v5, v0
	v_lshl_add_u32 v1, v1, 2, v5
	ds_read_b32 v0, v0
	ds_read_b32 v1, v1 offset:64
	v_not_b32_e32 v2, v22
	s_waitcnt lgkmcnt(0)
	v_lshl_add_u32 v0, v0, 7, v1
	v_mul_f32_e32 v1, v30, v29
	ds_write_b64 v11, v[0:1] offset:32
	v_lshrrev_b32_e32 v0, 2, v2
	v_and_b32_e32 v0, 60, v0
	v_bitop3_b32 v1, v22, 15, v22 bitop3:0xc
	v_add_u32_e32 v0, v5, v0
	v_lshl_add_u32 v1, v1, 2, v5
	ds_read_b32 v0, v0
	ds_read_b32 v1, v1 offset:64
	v_not_b32_e32 v2, v15
	s_waitcnt lgkmcnt(0)
	v_lshl_add_u32 v0, v0, 7, v1
	v_mul_f32_e32 v1, v31, v29
	ds_write_b64 v11, v[0:1] offset:40
	v_lshrrev_b32_e32 v0, 2, v2
	v_and_b32_e32 v0, 60, v0
	v_bitop3_b32 v1, v15, 15, v15 bitop3:0xc
	v_add_u32_e32 v0, v5, v0
	v_lshl_add_u32 v1, v1, 2, v5
	ds_read_b32 v0, v0
	ds_read_b32 v1, v1 offset:64
	v_not_b32_e32 v2, v23
	s_waitcnt lgkmcnt(0)
	v_lshl_add_u32 v0, v0, 7, v1
	v_mul_f32_e32 v1, v32, v29
	ds_write_b64 v11, v[0:1] offset:48
	v_lshrrev_b32_e32 v0, 2, v2
	v_and_b32_e32 v0, 60, v0
	v_bitop3_b32 v1, v23, 15, v23 bitop3:0xc
	v_add_u32_e32 v0, v5, v0
	v_lshl_add_u32 v1, v1, 2, v5
	ds_read_b32 v0, v0
	ds_read_b32 v1, v1 offset:64
	v_not_b32_e32 v2, v12
	s_waitcnt lgkmcnt(0)
	v_lshl_add_u32 v0, v0, 7, v1
	v_mul_f32_e32 v1, v33, v29
	ds_write_b64 v11, v[0:1] offset:56
	v_lshrrev_b32_e32 v0, 2, v2
	v_and_b32_e32 v0, 60, v0
	v_bitop3_b32 v1, v12, 15, v12 bitop3:0xc
	v_add_u32_e32 v0, v5, v0
	v_lshl_add_u32 v1, v1, 2, v5
	ds_read_b32 v0, v0
	ds_read_b32 v1, v1 offset:64
	v_not_b32_e32 v2, v17
	s_waitcnt lgkmcnt(0)
	v_lshl_add_u32 v0, v0, 7, v1
	v_mul_f32_e32 v1, v34, v29
	ds_write_b64 v11, v[0:1] offset:64
	v_lshrrev_b32_e32 v0, 2, v2
	v_and_b32_e32 v0, 60, v0
	v_bitop3_b32 v1, v17, 15, v17 bitop3:0xc
	v_add_u32_e32 v0, v5, v0
	v_lshl_add_u32 v1, v1, 2, v5
	ds_read_b32 v0, v0
	ds_read_b32 v1, v1 offset:64
	v_not_b32_e32 v2, v14
	s_waitcnt lgkmcnt(0)
	v_lshl_add_u32 v0, v0, 7, v1
	v_mul_f32_e32 v1, v35, v29
	ds_write_b64 v11, v[0:1] offset:72
	v_lshrrev_b32_e32 v0, 2, v2
	v_and_b32_e32 v0, 60, v0
	v_bitop3_b32 v1, v14, 15, v14 bitop3:0xc
	v_add_u32_e32 v0, v5, v0
	v_lshl_add_u32 v1, v1, 2, v5
	ds_read_b32 v0, v0
	ds_read_b32 v1, v1 offset:64
	v_not_b32_e32 v2, v20
	s_waitcnt lgkmcnt(0)
; #define LAS __attribute__((address_space(3)))
; __device__ __forceinline__ unsigned pk2(float lo, float hi) { const f32x2 v = {lo, hi}; const bf16x2_t b = __builtin_convertvector(v, bf16x2_t); return __builtin_bit_cast(unsigned, b); }
; __device__ __forceinline__ float bflo(unsigned u) { return __uint_as_float(u << 16); }
; __device__ __forceinline__ float bfhi(unsigned u) { return __uint_as_float(u & 0xffff0000u); }
; __device__ __forceinline__ void peer_tile(const Args& A, LAS unsigned char* lds, int tile) {
;     ...
;             for (int k = 0; k < 16; ++k) { const unsigned code = 255u - (Lf[k] & 255u); const unsigned e = idx[code >> 4] * 128u + idx[16 + (code & 15u)];
;                 u32x2 sv; sv.x = e; sv.y = __float_as_uint(fv[k] * rden); SEL[(tl * 8 + h) * 16 + k] = sv; }
;         }
;     }
;     __syncthreads();
;     const unsigned char* T8 = A.ws + WS_T8; const float* SC = (const float*)(A.ws + WS_SC);
;     LAS u32x2* SORT = (LAS u32x2*)(lds + PE_IDX);
;     LAS int* OFFS = (LAS int*)(lds + PE_SEL + 65536);
;     ...
;     const unsigned char* T8v = T8 + (size_t)16384 * 1024;
;     const bf16_t* A3 = (const bf16_t*)(A.ws + WS_A3); const float* RSq = (const float*)(A.ws + WS_RS);
;     for (int pass = 0; pass < 2; ++pass) {
;         const int tb = 8 * w + 4 * pass;
;         u32x4 xpa[4], xpb[4]; f32x2 oacc[4][8];
; #pragma unroll
;         for (int tk = 0; tk < 4; ++tk) { const size_t m = (size_t)tile * 64 + tb + tk;
;             { const u32x4 ra = *(const u32x4*)(A3 + m * 1024 + 16 * lane), rb = *(const u32x4*)(A3 + m * 1024 + 16 * lane + 8);
;               float xr_; { const f32x4 p0 = *(const f32x4*)(RSq + m * 16), p1 = *(const f32x4*)(RSq + m * 16 + 4), p2 = *(const f32x4*)(RSq + m * 16 + 8), p3 = *(const f32x4*)(RSq + m * 16 + 12);
;                 const f32x4 ps = (p0 + p1) + (p2 + p3); xr_ = rsqrtf(((ps[0] + ps[1]) + (ps[2] + ps[3])) * (1.f / 1024.f) + 1e-6f); }
;               const unsigned rr[8] = {ra.x, ra.y, ra.z, ra.w, rb.x, rb.y, rb.z, rb.w}; unsigned hh[8];
;               const float* sp = MOD + (int)(m >> 11) * 6144 + 3072 + 16 * lane;
; #pragma unroll
;               for (int q = 0; q < 8; ++q) { const f32x2 sh = *(const f32x2*)(sp + 2 * q); hh[q] = pk2(bflo(rr[q]) * xr_ + sh[0], bfhi(rr[q]) * xr_ + sh[1]); }
;               xpa[tk] = (u32x4){hh[0], hh[1], hh[2], hh[3]}; xpb[tk] = (u32x4){hh[4], hh[5], hh[6], hh[7]}; }
	v_lshl_add_u32 v0, v0, 7, v1
	v_mul_f32_e32 v1, v36, v29
	ds_write_b64 v11, v[0:1] offset:80
	v_lshrrev_b32_e32 v0, 2, v2
	v_and_b32_e32 v0, 60, v0
	v_bitop3_b32 v1, v20, 15, v20 bitop3:0xc
	v_add_u32_e32 v0, v5, v0
	v_lshl_add_u32 v1, v1, 2, v5
	ds_read_b32 v0, v0
	ds_read_b32 v1, v1 offset:64
	v_not_b32_e32 v2, v6
	s_waitcnt lgkmcnt(0)
	v_lshl_add_u32 v0, v0, 7, v1
	v_mul_f32_e32 v1, v37, v29
	ds_write_b64 v11, v[0:1] offset:88
	v_lshrrev_b32_e32 v0, 2, v2
	v_and_b32_e32 v0, 60, v0
	v_bitop3_b32 v1, v6, 15, v6 bitop3:0xc
	v_add_u32_e32 v0, v5, v0
	v_lshl_add_u32 v1, v1, 2, v5
	ds_read_b32 v0, v0
	ds_read_b32 v1, v1 offset:64
	v_not_b32_e32 v2, v18
	s_waitcnt lgkmcnt(0)
	v_lshl_add_u32 v0, v0, 7, v1
	v_mul_f32_e32 v1, v38, v29
	ds_write_b64 v11, v[0:1] offset:96
	v_lshrrev_b32_e32 v0, 2, v2
	v_and_b32_e32 v0, 60, v0
	v_bitop3_b32 v1, v18, 15, v18 bitop3:0xc
	v_add_u32_e32 v0, v5, v0
	v_lshl_add_u32 v1, v1, 2, v5
	ds_read_b32 v0, v0
	ds_read_b32 v1, v1 offset:64
	v_not_b32_e32 v2, v8
	s_waitcnt lgkmcnt(0)
	v_lshl_add_u32 v0, v0, 7, v1
	v_mul_f32_e32 v1, v39, v29
	ds_write_b64 v11, v[0:1] offset:104
	v_lshrrev_b32_e32 v0, 2, v2
	v_and_b32_e32 v0, 60, v0
	v_bitop3_b32 v1, v8, 15, v8 bitop3:0xc
	v_add_u32_e32 v0, v5, v0
	v_lshl_add_u32 v1, v1, 2, v5
	ds_read_b32 v0, v0
	ds_read_b32 v1, v1 offset:64
	v_not_b32_e32 v2, v10
	s_waitcnt lgkmcnt(0)
	v_lshl_add_u32 v0, v0, 7, v1
	v_mul_f32_e32 v1, v40, v29
	ds_write_b64 v11, v[0:1] offset:112
	v_lshrrev_b32_e32 v0, 2, v2
	v_and_b32_e32 v0, 60, v0
	v_bitop3_b32 v1, v10, 15, v10 bitop3:0xc
	v_add_u32_e32 v0, v5, v0
	v_lshl_add_u32 v1, v1, 2, v5
	ds_read_b32 v0, v0
	ds_read_b32 v1, v1 offset:64
	v_lshlrev_b32_e32 v5, 13, v7
	v_lshl_or_b32 v6, v9, 3, v5
	s_waitcnt lgkmcnt(0)
	v_lshl_add_u32 v0, v0, 7, v1
	v_mul_f32_e32 v1, v41, v29
	ds_write_b64 v11, v[0:1] offset:120
	s_waitcnt lgkmcnt(0)
	s_barrier
	s_mov_b64 exec, -1
	v_and_b32_e32 v240, 63, v214
	v_lshrrev_b32_e32 v242, 6, v214
	v_lshlrev_b32_e32 v240, 4, v240
	v_readfirstlane_b32 s16, v242
	v_lshlrev_b32_e32 v245, 1, v240
	v_lshlrev_b32_e32 v246, 2, v240
	v_lshrrev_b32_e32 v247, 4, v240
	v_and_b32_e32 v247, 48, v247
	v_mov_b32_e32 v244, 0
	v_mov_b32_e32 v243, 0x358637bd
	v_mov_b32_e32 v242, 0xbf3a00e3
	s_add_u32 s4, s50, 0x1000000
	s_addc_u32 s5, s51, 0
	s_add_u32 s6, s50, 0x2000000
	s_addc_u32 s7, s51, 0
	s_add_u32 s8, s50, 0x3000000
	s_addc_u32 s9, s51, 0
	s_add_u32 s52, s50, 0x3010000
	s_addc_u32 s53, s51, 0
	s_add_u32 s12, s50, 0xb000000
	s_addc_u32 s13, s51, 0
	s_add_u32 s14, s50, 0xd000000
	s_addc_u32 s15, s51, 0
	s_lshr_b32 s0, s2, 5
	s_mul_i32 s0, s0, 0x6000
	s_add_u32 s10, s50, s0
	s_addc_u32 s11, s51, 0
	s_add_u32 s80, s10, 0x4000
	s_addc_u32 s81, s11, 0
	s_add_u32 s82, s10, 0x6000
	s_addc_u32 s83, s11, 0
	s_mul_i32 s22, s16, 9920
	s_cmp_eq_u32 s16, 7
	s_cselect_b32 s22, 0x21000, s22
	s_mov_b32 s85, 0xffffffff
	s_mov_b32 s72, 0x3e6d3388
	s_mov_b32 s56, s4
	s_and_b32 s57, s5, 0xffff
	s_or_b32 s57, s57, 0x04000000
	s_mov_b32 s58, 16384
	s_mov_b32 s59, 0x00027000
	s_mov_b32 s60, s6
	s_and_b32 s61, s7, 0xffff
	s_or_b32 s61, s61, 0x04000000
	s_mov_b32 s62, 16384
	s_mov_b32 s63, 0x00027000
	s_lshl_b32 s76, s16, 3
	s_lshl_b32 s0, s2, 6
	s_add_i32 s77, s0, s76
	global_load_dwordx4 v[192:195], v246, s[80:81] offset:0
	global_load_dwordx4 v[196:199], v246, s[80:81] offset:16
	global_load_dwordx4 v[200:203], v246, s[80:81] offset:32
	global_load_dwordx4 v[204:207], v246, s[80:81] offset:48
	s_add_i32 s0, s77, 0
	s_lshl_b32 s1, s0, 11
	s_add_u32 s78, s12, s1
	s_addc_u32 s79, s13, 0
	global_load_dwordx4 v[128:131], v245, s[78:79]
	global_load_dwordx4 v[132:135], v245, s[78:79] offset:16
	global_load_dwordx4 v[136:139], v245, s[78:79] offset:2048
	global_load_dwordx4 v[140:143], v245, s[78:79] offset:2064
	s_lshl_b32 s1, s0, 6
	s_add_u32 s78, s14, s1
	s_addc_u32 s79, s15, 0
	global_load_dwordx4 v[144:147], v244, s[78:79] offset:0
	global_load_dwordx4 v[148:151], v244, s[78:79] offset:16
	global_load_dwordx4 v[152:155], v244, s[78:79] offset:32
	global_load_dwordx4 v[156:159], v244, s[78:79] offset:48
	global_load_dwordx4 v[160:163], v244, s[78:79] offset:64
	global_load_dwordx4 v[164:167], v244, s[78:79] offset:80
	global_load_dwordx4 v[168:171], v244, s[78:79] offset:96
	global_load_dwordx4 v[172:175], v244, s[78:79] offset:112
	s_add_i32 s0, s77, 2
	s_lshl_b32 s1, s0, 11
	s_add_u32 s78, s12, s1
	s_addc_u32 s79, s13, 0
	global_load_dwordx4 v[176:179], v245, s[78:79]
	global_load_dwordx4 v[180:183], v245, s[78:79] offset:16
	global_load_dwordx4 v[184:187], v245, s[78:79] offset:2048
	global_load_dwordx4 v[188:191], v245, s[78:79] offset:2064
	s_lshl_b32 s1, s0, 6
	s_add_u32 s78, s14, s1
	s_addc_u32 s79, s15, 0
	global_load_dwordx4 v[216:219], v244, s[78:79] offset:0
	global_load_dwordx4 v[220:223], v244, s[78:79] offset:16
	global_load_dwordx4 v[224:227], v244, s[78:79] offset:32
	global_load_dwordx4 v[228:231], v244, s[78:79] offset:48
	global_load_dwordx4 v[232:235], v244, s[78:79] offset:64
	global_load_dwordx4 v[236:239], v244, s[78:79] offset:80
	global_load_dwordx4 v[248:251], v244, s[78:79] offset:96
	global_load_dwordx4 v[252:255], v244, s[78:79] offset:112
	s_waitcnt vmcnt(12)
; __device__ __forceinline__ unsigned pk2(float lo, float hi) { const f32x2 v = {lo, hi}; const bf16x2_t b = __builtin_convertvector(v, bf16x2_t); return __builtin_bit_cast(unsigned, b); }
; __device__ __forceinline__ float bflo(unsigned u) { return __uint_as_float(u << 16); }
; __device__ __forceinline__ float bfhi(unsigned u) { return __uint_as_float(u & 0xffff0000u); }
; __device__ __forceinline__ void peer_tile(const Args& A, LAS unsigned char* lds, int tile) {
;     ...
;         for (int tk = 0; tk < 4; ++tk) { const size_t m = (size_t)tile * 64 + tb + tk;
;             { const u32x4 ra = *(const u32x4*)(A3 + m * 1024 + 16 * lane), rb = *(const u32x4*)(A3 + m * 1024 + 16 * lane + 8);
;               float xr_; { const f32x4 p0 = *(const f32x4*)(RSq + m * 16), p1 = *(const f32x4*)(RSq + m * 16 + 4), p2 = *(const f32x4*)(RSq + m * 16 + 8), p3 = *(const f32x4*)(RSq + m * 16 + 12);
;                 const f32x4 ps = (p0 + p1) + (p2 + p3); xr_ = rsqrtf(((ps[0] + ps[1]) + (ps[2] + ps[3])) * (1.f / 1024.f) + 1e-6f); }
;               const unsigned rr[8] = {ra.x, ra.y, ra.z, ra.w, rb.x, rb.y, rb.z, rb.w}; unsigned hh[8];
;               const float* sp = MOD + (int)(m >> 11) * 6144 + 3072 + 16 * lane;
; #pragma unroll
;               for (int q = 0; q < 8; ++q) { const f32x2 sh = *(const f32x2*)(sp + 2 * q); hh[q] = pk2(bflo(rr[q]) * xr_ + sh[0], bfhi(rr[q]) * xr_ + sh[1]); }
;               xpa[tk] = (u32x4){hh[0], hh[1], hh[2], hh[3]}; xpb[tk] = (u32x4){hh[4], hh[5], hh[6], hh[7]}; }
	v_pk_add_f32 v[144:145], v[144:145], v[148:149]
	v_pk_add_f32 v[146:147], v[146:147], v[150:151]
	v_pk_add_f32 v[152:153], v[152:153], v[156:157]
	v_pk_add_f32 v[154:155], v[154:155], v[158:159]
	v_pk_add_f32 v[144:145], v[144:145], v[152:153]
	v_pk_add_f32 v[146:147], v[146:147], v[154:155]
	v_add_f32_e32 v144, v144, v145
	v_add_f32_e32 v146, v146, v147
	v_add_f32_e32 v144, v144, v146
	v_fmamk_f32 v144, v144, 0x3a800000, v243
	v_rsq_f32_e32 v144, v144
	v_pk_add_f32 v[160:161], v[160:161], v[164:165]
	v_pk_add_f32 v[162:163], v[162:163], v[166:167]
	v_pk_add_f32 v[168:169], v[168:169], v[172:173]
	v_pk_add_f32 v[170:171], v[170:171], v[174:175]
	v_pk_add_f32 v[160:161], v[160:161], v[168:169]
	v_pk_add_f32 v[162:163], v[162:163], v[170:171]
	v_add_f32_e32 v160, v160, v161
	v_add_f32_e32 v162, v162, v163
	v_add_f32_e32 v160, v160, v162
	v_fmamk_f32 v160, v160, 0x3a800000, v243
	v_rsq_f32_e32 v160, v160
	v_lshlrev_b32_e32 v208, 16, v128
	v_and_b32_e32 v209, 0xffff0000, v128
	v_fma_f32 v208, v208, v144, v192
	v_fma_f32 v209, v209, v144, v193
	v_cvt_pk_bf16_f32 v210, v208, v209
	v_lshlrev_b32_e32 v0, 16, v210
	v_and_b32_e32 v1, 0xffff0000, v210
	v_lshlrev_b32_e32 v208, 16, v129
	v_and_b32_e32 v209, 0xffff0000, v129
	v_fma_f32 v208, v208, v144, v194
	v_fma_f32 v209, v209, v144, v195
	v_cvt_pk_bf16_f32 v210, v208, v209
	v_lshlrev_b32_e32 v2, 16, v210
	v_and_b32_e32 v3, 0xffff0000, v210
	v_lshlrev_b32_e32 v208, 16, v130
	v_and_b32_e32 v209, 0xffff0000, v130
	v_fma_f32 v208, v208, v144, v196
	v_fma_f32 v209, v209, v144, v197
	v_cvt_pk_bf16_f32 v210, v208, v209
	v_lshlrev_b32_e32 v4, 16, v210
	v_and_b32_e32 v5, 0xffff0000, v210
	v_lshlrev_b32_e32 v208, 16, v131
	v_and_b32_e32 v209, 0xffff0000, v131
	v_fma_f32 v208, v208, v144, v198
	v_fma_f32 v209, v209, v144, v199
	v_cvt_pk_bf16_f32 v210, v208, v209
	v_lshlrev_b32_e32 v6, 16, v210
	v_and_b32_e32 v7, 0xffff0000, v210
	v_lshlrev_b32_e32 v208, 16, v132
	v_and_b32_e32 v209, 0xffff0000, v132
	v_fma_f32 v208, v208, v144, v200
	v_fma_f32 v209, v209, v144, v201
	v_cvt_pk_bf16_f32 v210, v208, v209
	v_lshlrev_b32_e32 v8, 16, v210
	v_and_b32_e32 v9, 0xffff0000, v210
	v_lshlrev_b32_e32 v208, 16, v133
	v_and_b32_e32 v209, 0xffff0000, v133
	v_fma_f32 v208, v208, v144, v202
	v_fma_f32 v209, v209, v144, v203
	v_cvt_pk_bf16_f32 v210, v208, v209
	v_lshlrev_b32_e32 v10, 16, v210
	v_and_b32_e32 v11, 0xffff0000, v210
	v_lshlrev_b32_e32 v208, 16, v134
	v_and_b32_e32 v209, 0xffff0000, v134
	v_fma_f32 v208, v208, v144, v204
	v_fma_f32 v209, v209, v144, v205
	v_cvt_pk_bf16_f32 v210, v208, v209
	v_lshlrev_b32_e32 v12, 16, v210
	v_and_b32_e32 v13, 0xffff0000, v210
	v_lshlrev_b32_e32 v208, 16, v135
	v_and_b32_e32 v209, 0xffff0000, v135
	v_fma_f32 v208, v208, v144, v206
	v_fma_f32 v209, v209, v144, v207
	v_cvt_pk_bf16_f32 v210, v208, v209
	v_lshlrev_b32_e32 v14, 16, v210
	v_and_b32_e32 v15, 0xffff0000, v210
	v_lshlrev_b32_e32 v208, 16, v136
	v_and_b32_e32 v209, 0xffff0000, v136
	v_fma_f32 v208, v208, v160, v192
	v_fma_f32 v209, v209, v160, v193
	v_cvt_pk_bf16_f32 v210, v208, v209
	v_lshlrev_b32_e32 v16, 16, v210
	v_and_b32_e32 v17, 0xffff0000, v210
	v_lshlrev_b32_e32 v208, 16, v137
	v_and_b32_e32 v209, 0xffff0000, v137
	v_fma_f32 v208, v208, v160, v194
	v_fma_f32 v209, v209, v160, v195
	v_cvt_pk_bf16_f32 v210, v208, v209
	v_lshlrev_b32_e32 v18, 16, v210
	v_and_b32_e32 v19, 0xffff0000, v210
	v_lshlrev_b32_e32 v208, 16, v138
	v_and_b32_e32 v209, 0xffff0000, v138
	v_fma_f32 v208, v208, v160, v196
	v_fma_f32 v209, v209, v160, v197
	v_cvt_pk_bf16_f32 v210, v208, v209
	v_lshlrev_b32_e32 v20, 16, v210
	v_and_b32_e32 v21, 0xffff0000, v210
	v_lshlrev_b32_e32 v208, 16, v139
	v_and_b32_e32 v209, 0xffff0000, v139
	v_fma_f32 v208, v208, v160, v198
	v_fma_f32 v209, v209, v160, v199
	v_cvt_pk_bf16_f32 v210, v208, v209
	v_lshlrev_b32_e32 v22, 16, v210
	v_and_b32_e32 v23, 0xffff0000, v210
	v_lshlrev_b32_e32 v208, 16, v140
	v_and_b32_e32 v209, 0xffff0000, v140
	v_fma_f32 v208, v208, v160, v200
	v_fma_f32 v209, v209, v160, v201
	v_cvt_pk_bf16_f32 v210, v208, v209
	v_lshlrev_b32_e32 v24, 16, v210
	v_and_b32_e32 v25, 0xffff0000, v210
	v_lshlrev_b32_e32 v208, 16, v141
	v_and_b32_e32 v209, 0xffff0000, v141
	v_fma_f32 v208, v208, v160, v202
	v_fma_f32 v209, v209, v160, v203
	v_cvt_pk_bf16_f32 v210, v208, v209
	v_lshlrev_b32_e32 v26, 16, v210
	v_and_b32_e32 v27, 0xffff0000, v210
	v_lshlrev_b32_e32 v208, 16, v142
	v_and_b32_e32 v209, 0xffff0000, v142
	v_fma_f32 v208, v208, v160, v204
	v_fma_f32 v209, v209, v160, v205
	v_cvt_pk_bf16_f32 v210, v208, v209
	v_lshlrev_b32_e32 v28, 16, v210
	v_and_b32_e32 v29, 0xffff0000, v210
	v_lshlrev_b32_e32 v208, 16, v143
	v_and_b32_e32 v209, 0xffff0000, v143
	v_fma_f32 v208, v208, v160, v206
	v_fma_f32 v209, v209, v160, v207
	v_cvt_pk_bf16_f32 v210, v208, v209
	v_lshlrev_b32_e32 v30, 16, v210
	v_and_b32_e32 v31, 0xffff0000, v210
	s_nop 0
	s_add_i32 s0, s77, 4
	s_lshl_b32 s1, s0, 11
	s_add_u32 s78, s12, s1
	s_addc_u32 s79, s13, 0
	global_load_dwordx4 v[128:131], v245, s[78:79]
	global_load_dwordx4 v[132:135], v245, s[78:79] offset:16
	global_load_dwordx4 v[136:139], v245, s[78:79] offset:2048
	global_load_dwordx4 v[140:143], v245, s[78:79] offset:2064
	s_lshl_b32 s1, s0, 6
	s_add_u32 s78, s14, s1
	s_addc_u32 s79, s15, 0
	global_load_dwordx4 v[144:147], v244, s[78:79] offset:0
	global_load_dwordx4 v[148:151], v244, s[78:79] offset:16
	global_load_dwordx4 v[152:155], v244, s[78:79] offset:32
	global_load_dwordx4 v[156:159], v244, s[78:79] offset:48
	global_load_dwordx4 v[160:163], v244, s[78:79] offset:64
	global_load_dwordx4 v[164:167], v244, s[78:79] offset:80
	global_load_dwordx4 v[168:171], v244, s[78:79] offset:96
	global_load_dwordx4 v[172:175], v244, s[78:79] offset:112
	s_waitcnt vmcnt(12)
; __device__ __forceinline__ unsigned pk2(float lo, float hi) { const f32x2 v = {lo, hi}; const bf16x2_t b = __builtin_convertvector(v, bf16x2_t); return __builtin_bit_cast(unsigned, b); }
; __device__ __forceinline__ float bflo(unsigned u) { return __uint_as_float(u << 16); }
; __device__ __forceinline__ float bfhi(unsigned u) { return __uint_as_float(u & 0xffff0000u); }
; __device__ __forceinline__ void peer_tile(const Args& A, LAS unsigned char* lds, int tile) {
;     ...
;         for (int tk = 0; tk < 4; ++tk) { const size_t m = (size_t)tile * 64 + tb + tk;
;             { const u32x4 ra = *(const u32x4*)(A3 + m * 1024 + 16 * lane), rb = *(const u32x4*)(A3 + m * 1024 + 16 * lane + 8);
;               float xr_; { const f32x4 p0 = *(const f32x4*)(RSq + m * 16), p1 = *(const f32x4*)(RSq + m * 16 + 4), p2 = *(const f32x4*)(RSq + m * 16 + 8), p3 = *(const f32x4*)(RSq + m * 16 + 12);
;                 const f32x4 ps = (p0 + p1) + (p2 + p3); xr_ = rsqrtf(((ps[0] + ps[1]) + (ps[2] + ps[3])) * (1.f / 1024.f) + 1e-6f); }
;               const unsigned rr[8] = {ra.x, ra.y, ra.z, ra.w, rb.x, rb.y, rb.z, rb.w}; unsigned hh[8];
;               const float* sp = MOD + (int)(m >> 11) * 6144 + 3072 + 16 * lane;
; #pragma unroll
;               for (int q = 0; q < 8; ++q) { const f32x2 sh = *(const f32x2*)(sp + 2 * q); hh[q] = pk2(bflo(rr[q]) * xr_ + sh[0], bfhi(rr[q]) * xr_ + sh[1]); }
;               xpa[tk] = (u32x4){hh[0], hh[1], hh[2], hh[3]}; xpb[tk] = (u32x4){hh[4], hh[5], hh[6], hh[7]}; }
	v_pk_add_f32 v[216:217], v[216:217], v[220:221]
	v_pk_add_f32 v[218:219], v[218:219], v[222:223]
	v_pk_add_f32 v[224:225], v[224:225], v[228:229]
	v_pk_add_f32 v[226:227], v[226:227], v[230:231]
	v_pk_add_f32 v[216:217], v[216:217], v[224:225]
	v_pk_add_f32 v[218:219], v[218:219], v[226:227]
	v_add_f32_e32 v216, v216, v217
	v_add_f32_e32 v218, v218, v219
	v_add_f32_e32 v216, v216, v218
	v_fmamk_f32 v216, v216, 0x3a800000, v243
	v_rsq_f32_e32 v216, v216
	v_pk_add_f32 v[232:233], v[232:233], v[236:237]
	v_pk_add_f32 v[234:235], v[234:235], v[238:239]
	v_pk_add_f32 v[248:249], v[248:249], v[252:253]
	v_pk_add_f32 v[250:251], v[250:251], v[254:255]
	v_pk_add_f32 v[232:233], v[232:233], v[248:249]
	v_pk_add_f32 v[234:235], v[234:235], v[250:251]
	v_add_f32_e32 v232, v232, v233
	v_add_f32_e32 v234, v234, v235
	v_add_f32_e32 v232, v232, v234
	v_fmamk_f32 v232, v232, 0x3a800000, v243
	v_rsq_f32_e32 v232, v232
	v_lshlrev_b32_e32 v208, 16, v176
	v_and_b32_e32 v209, 0xffff0000, v176
	v_fma_f32 v208, v208, v216, v192
	v_fma_f32 v209, v209, v216, v193
	v_cvt_pk_bf16_f32 v210, v208, v209
	v_lshlrev_b32_e32 v32, 16, v210
	v_and_b32_e32 v33, 0xffff0000, v210
	v_lshlrev_b32_e32 v208, 16, v177
	v_and_b32_e32 v209, 0xffff0000, v177
	v_fma_f32 v208, v208, v216, v194
	v_fma_f32 v209, v209, v216, v195
	v_cvt_pk_bf16_f32 v210, v208, v209
	v_lshlrev_b32_e32 v34, 16, v210
	v_and_b32_e32 v35, 0xffff0000, v210
	v_lshlrev_b32_e32 v208, 16, v178
	v_and_b32_e32 v209, 0xffff0000, v178
	v_fma_f32 v208, v208, v216, v196
	v_fma_f32 v209, v209, v216, v197
	v_cvt_pk_bf16_f32 v210, v208, v209
	v_lshlrev_b32_e32 v36, 16, v210
	v_and_b32_e32 v37, 0xffff0000, v210
	v_lshlrev_b32_e32 v208, 16, v179
	v_and_b32_e32 v209, 0xffff0000, v179
	v_fma_f32 v208, v208, v216, v198
	v_fma_f32 v209, v209, v216, v199
	v_cvt_pk_bf16_f32 v210, v208, v209
	v_lshlrev_b32_e32 v38, 16, v210
	v_and_b32_e32 v39, 0xffff0000, v210
	v_lshlrev_b32_e32 v208, 16, v180
	v_and_b32_e32 v209, 0xffff0000, v180
	v_fma_f32 v208, v208, v216, v200
	v_fma_f32 v209, v209, v216, v201
	v_cvt_pk_bf16_f32 v210, v208, v209
	v_lshlrev_b32_e32 v40, 16, v210
	v_and_b32_e32 v41, 0xffff0000, v210
	v_lshlrev_b32_e32 v208, 16, v181
	v_and_b32_e32 v209, 0xffff0000, v181
	v_fma_f32 v208, v208, v216, v202
	v_fma_f32 v209, v209, v216, v203
	v_cvt_pk_bf16_f32 v210, v208, v209
	v_lshlrev_b32_e32 v42, 16, v210
	v_and_b32_e32 v43, 0xffff0000, v210
	v_lshlrev_b32_e32 v208, 16, v182
	v_and_b32_e32 v209, 0xffff0000, v182
	v_fma_f32 v208, v208, v216, v204
	v_fma_f32 v209, v209, v216, v205
	v_cvt_pk_bf16_f32 v210, v208, v209
	v_lshlrev_b32_e32 v44, 16, v210
	v_and_b32_e32 v45, 0xffff0000, v210
	v_lshlrev_b32_e32 v208, 16, v183
	v_and_b32_e32 v209, 0xffff0000, v183
	v_fma_f32 v208, v208, v216, v206
	v_fma_f32 v209, v209, v216, v207
	v_cvt_pk_bf16_f32 v210, v208, v209
	v_lshlrev_b32_e32 v46, 16, v210
	v_and_b32_e32 v47, 0xffff0000, v210
	v_lshlrev_b32_e32 v208, 16, v184
	v_and_b32_e32 v209, 0xffff0000, v184
	v_fma_f32 v208, v208, v232, v192
	v_fma_f32 v209, v209, v232, v193
	v_cvt_pk_bf16_f32 v210, v208, v209
	v_lshlrev_b32_e32 v48, 16, v210
	v_and_b32_e32 v49, 0xffff0000, v210
	v_lshlrev_b32_e32 v208, 16, v185
	v_and_b32_e32 v209, 0xffff0000, v185
	v_fma_f32 v208, v208, v232, v194
	v_fma_f32 v209, v209, v232, v195
	v_cvt_pk_bf16_f32 v210, v208, v209
	v_lshlrev_b32_e32 v50, 16, v210
	v_and_b32_e32 v51, 0xffff0000, v210
	v_lshlrev_b32_e32 v208, 16, v186
	v_and_b32_e32 v209, 0xffff0000, v186
	v_fma_f32 v208, v208, v232, v196
	v_fma_f32 v209, v209, v232, v197
	v_cvt_pk_bf16_f32 v210, v208, v209
	v_lshlrev_b32_e32 v52, 16, v210
	v_and_b32_e32 v53, 0xffff0000, v210
	v_lshlrev_b32_e32 v208, 16, v187
	v_and_b32_e32 v209, 0xffff0000, v187
	v_fma_f32 v208, v208, v232, v198
	v_fma_f32 v209, v209, v232, v199
	v_cvt_pk_bf16_f32 v210, v208, v209
	v_lshlrev_b32_e32 v54, 16, v210
	v_and_b32_e32 v55, 0xffff0000, v210
	v_lshlrev_b32_e32 v208, 16, v188
	v_and_b32_e32 v209, 0xffff0000, v188
	v_fma_f32 v208, v208, v232, v200
	v_fma_f32 v209, v209, v232, v201
	v_cvt_pk_bf16_f32 v210, v208, v209
	v_lshlrev_b32_e32 v56, 16, v210
	v_and_b32_e32 v57, 0xffff0000, v210
	v_lshlrev_b32_e32 v208, 16, v189
	v_and_b32_e32 v209, 0xffff0000, v189
	v_fma_f32 v208, v208, v232, v202
	v_fma_f32 v209, v209, v232, v203
	v_cvt_pk_bf16_f32 v210, v208, v209
	v_lshlrev_b32_e32 v58, 16, v210
	v_and_b32_e32 v59, 0xffff0000, v210
	v_lshlrev_b32_e32 v208, 16, v190
	v_and_b32_e32 v209, 0xffff0000, v190
	v_fma_f32 v208, v208, v232, v204
	v_fma_f32 v209, v209, v232, v205
	v_cvt_pk_bf16_f32 v210, v208, v209
	v_lshlrev_b32_e32 v60, 16, v210
	v_and_b32_e32 v61, 0xffff0000, v210
	v_lshlrev_b32_e32 v208, 16, v191
	v_and_b32_e32 v209, 0xffff0000, v191
	v_fma_f32 v208, v208, v232, v206
	v_fma_f32 v209, v209, v232, v207
	v_cvt_pk_bf16_f32 v210, v208, v209
	v_lshlrev_b32_e32 v62, 16, v210
	v_and_b32_e32 v63, 0xffff0000, v210
	s_nop 0
	s_add_i32 s0, s77, 6
	s_lshl_b32 s1, s0, 11
	s_add_u32 s78, s12, s1
	s_addc_u32 s79, s13, 0
	global_load_dwordx4 v[176:179], v245, s[78:79]
	global_load_dwordx4 v[180:183], v245, s[78:79] offset:16
	global_load_dwordx4 v[184:187], v245, s[78:79] offset:2048
	global_load_dwordx4 v[188:191], v245, s[78:79] offset:2064
	s_lshl_b32 s1, s0, 6
	s_add_u32 s78, s14, s1
	s_addc_u32 s79, s15, 0
	global_load_dwordx4 v[216:219], v244, s[78:79] offset:0
	global_load_dwordx4 v[220:223], v244, s[78:79] offset:16
	global_load_dwordx4 v[224:227], v244, s[78:79] offset:32
	global_load_dwordx4 v[228:231], v244, s[78:79] offset:48
	global_load_dwordx4 v[232:235], v244, s[78:79] offset:64
	global_load_dwordx4 v[236:239], v244, s[78:79] offset:80
	global_load_dwordx4 v[248:251], v244, s[78:79] offset:96
	global_load_dwordx4 v[252:255], v244, s[78:79] offset:112
	s_waitcnt vmcnt(12)
; __device__ __forceinline__ unsigned pk2(float lo, float hi) { const f32x2 v = {lo, hi}; const bf16x2_t b = __builtin_convertvector(v, bf16x2_t); return __builtin_bit_cast(unsigned, b); }
; __device__ __forceinline__ float bflo(unsigned u) { return __uint_as_float(u << 16); }
; __device__ __forceinline__ float bfhi(unsigned u) { return __uint_as_float(u & 0xffff0000u); }
; __device__ __forceinline__ void peer_tile(const Args& A, LAS unsigned char* lds, int tile) {
;     ...
;         for (int tk = 0; tk < 4; ++tk) { const size_t m = (size_t)tile * 64 + tb + tk;
;             { const u32x4 ra = *(const u32x4*)(A3 + m * 1024 + 16 * lane), rb = *(const u32x4*)(A3 + m * 1024 + 16 * lane + 8);
;               float xr_; { const f32x4 p0 = *(const f32x4*)(RSq + m * 16), p1 = *(const f32x4*)(RSq + m * 16 + 4), p2 = *(const f32x4*)(RSq + m * 16 + 8), p3 = *(const f32x4*)(RSq + m * 16 + 12);
;                 const f32x4 ps = (p0 + p1) + (p2 + p3); xr_ = rsqrtf(((ps[0] + ps[1]) + (ps[2] + ps[3])) * (1.f / 1024.f) + 1e-6f); }
;               const unsigned rr[8] = {ra.x, ra.y, ra.z, ra.w, rb.x, rb.y, rb.z, rb.w}; unsigned hh[8];
;               const float* sp = MOD + (int)(m >> 11) * 6144 + 3072 + 16 * lane;
; #pragma unroll
;               for (int q = 0; q < 8; ++q) { const f32x2 sh = *(const f32x2*)(sp + 2 * q); hh[q] = pk2(bflo(rr[q]) * xr_ + sh[0], bfhi(rr[q]) * xr_ + sh[1]); }
;               xpa[tk] = (u32x4){hh[0], hh[1], hh[2], hh[3]}; xpb[tk] = (u32x4){hh[4], hh[5], hh[6], hh[7]}; }
	v_pk_add_f32 v[144:145], v[144:145], v[148:149]
	v_pk_add_f32 v[146:147], v[146:147], v[150:151]
	v_pk_add_f32 v[152:153], v[152:153], v[156:157]
	v_pk_add_f32 v[154:155], v[154:155], v[158:159]
	v_pk_add_f32 v[144:145], v[144:145], v[152:153]
	v_pk_add_f32 v[146:147], v[146:147], v[154:155]
	v_add_f32_e32 v144, v144, v145
	v_add_f32_e32 v146, v146, v147
	v_add_f32_e32 v144, v144, v146
	v_fmamk_f32 v144, v144, 0x3a800000, v243
	v_rsq_f32_e32 v144, v144
	v_pk_add_f32 v[160:161], v[160:161], v[164:165]
	v_pk_add_f32 v[162:163], v[162:163], v[166:167]
	v_pk_add_f32 v[168:169], v[168:169], v[172:173]
	v_pk_add_f32 v[170:171], v[170:171], v[174:175]
	v_pk_add_f32 v[160:161], v[160:161], v[168:169]
	v_pk_add_f32 v[162:163], v[162:163], v[170:171]
	v_add_f32_e32 v160, v160, v161
	v_add_f32_e32 v162, v162, v163
	v_add_f32_e32 v160, v160, v162
	v_fmamk_f32 v160, v160, 0x3a800000, v243
	v_rsq_f32_e32 v160, v160
	v_lshlrev_b32_e32 v208, 16, v128
	v_and_b32_e32 v209, 0xffff0000, v128
	v_fma_f32 v208, v208, v144, v192
	v_fma_f32 v209, v209, v144, v193
	v_cvt_pk_bf16_f32 v210, v208, v209
	v_lshlrev_b32_e32 v64, 16, v210
	v_and_b32_e32 v65, 0xffff0000, v210
	v_lshlrev_b32_e32 v208, 16, v129
	v_and_b32_e32 v209, 0xffff0000, v129
	v_fma_f32 v208, v208, v144, v194
	v_fma_f32 v209, v209, v144, v195
	v_cvt_pk_bf16_f32 v210, v208, v209
	v_lshlrev_b32_e32 v66, 16, v210
	v_and_b32_e32 v67, 0xffff0000, v210
	v_lshlrev_b32_e32 v208, 16, v130
	v_and_b32_e32 v209, 0xffff0000, v130
	v_fma_f32 v208, v208, v144, v196
	v_fma_f32 v209, v209, v144, v197
	v_cvt_pk_bf16_f32 v210, v208, v209
	v_lshlrev_b32_e32 v68, 16, v210
	v_and_b32_e32 v69, 0xffff0000, v210
	v_lshlrev_b32_e32 v208, 16, v131
	v_and_b32_e32 v209, 0xffff0000, v131
	v_fma_f32 v208, v208, v144, v198
	v_fma_f32 v209, v209, v144, v199
	v_cvt_pk_bf16_f32 v210, v208, v209
	v_lshlrev_b32_e32 v70, 16, v210
	v_and_b32_e32 v71, 0xffff0000, v210
	v_lshlrev_b32_e32 v208, 16, v132
	v_and_b32_e32 v209, 0xffff0000, v132
	v_fma_f32 v208, v208, v144, v200
	v_fma_f32 v209, v209, v144, v201
	v_cvt_pk_bf16_f32 v210, v208, v209
	v_lshlrev_b32_e32 v72, 16, v210
	v_and_b32_e32 v73, 0xffff0000, v210
	v_lshlrev_b32_e32 v208, 16, v133
	v_and_b32_e32 v209, 0xffff0000, v133
	v_fma_f32 v208, v208, v144, v202
	v_fma_f32 v209, v209, v144, v203
	v_cvt_pk_bf16_f32 v210, v208, v209
	v_lshlrev_b32_e32 v74, 16, v210
	v_and_b32_e32 v75, 0xffff0000, v210
	v_lshlrev_b32_e32 v208, 16, v134
	v_and_b32_e32 v209, 0xffff0000, v134
	v_fma_f32 v208, v208, v144, v204
	v_fma_f32 v209, v209, v144, v205
	v_cvt_pk_bf16_f32 v210, v208, v209
	v_lshlrev_b32_e32 v76, 16, v210
	v_and_b32_e32 v77, 0xffff0000, v210
	v_lshlrev_b32_e32 v208, 16, v135
	v_and_b32_e32 v209, 0xffff0000, v135
	v_fma_f32 v208, v208, v144, v206
	v_fma_f32 v209, v209, v144, v207
	v_cvt_pk_bf16_f32 v210, v208, v209
	v_lshlrev_b32_e32 v78, 16, v210
	v_and_b32_e32 v79, 0xffff0000, v210
	v_lshlrev_b32_e32 v208, 16, v136
	v_and_b32_e32 v209, 0xffff0000, v136
	v_fma_f32 v208, v208, v160, v192
	v_fma_f32 v209, v209, v160, v193
	v_cvt_pk_bf16_f32 v210, v208, v209
	v_lshlrev_b32_e32 v80, 16, v210
	v_and_b32_e32 v81, 0xffff0000, v210
	v_lshlrev_b32_e32 v208, 16, v137
	v_and_b32_e32 v209, 0xffff0000, v137
	v_fma_f32 v208, v208, v160, v194
	v_fma_f32 v209, v209, v160, v195
	v_cvt_pk_bf16_f32 v210, v208, v209
	v_lshlrev_b32_e32 v82, 16, v210
	v_and_b32_e32 v83, 0xffff0000, v210
	v_lshlrev_b32_e32 v208, 16, v138
	v_and_b32_e32 v209, 0xffff0000, v138
	v_fma_f32 v208, v208, v160, v196
	v_fma_f32 v209, v209, v160, v197
	v_cvt_pk_bf16_f32 v210, v208, v209
	v_lshlrev_b32_e32 v84, 16, v210
	v_and_b32_e32 v85, 0xffff0000, v210
	v_lshlrev_b32_e32 v208, 16, v139
	v_and_b32_e32 v209, 0xffff0000, v139
	v_fma_f32 v208, v208, v160, v198
	v_fma_f32 v209, v209, v160, v199
	v_cvt_pk_bf16_f32 v210, v208, v209
	v_lshlrev_b32_e32 v86, 16, v210
	v_and_b32_e32 v87, 0xffff0000, v210
	v_lshlrev_b32_e32 v208, 16, v140
	v_and_b32_e32 v209, 0xffff0000, v140
	v_fma_f32 v208, v208, v160, v200
	v_fma_f32 v209, v209, v160, v201
	v_cvt_pk_bf16_f32 v210, v208, v209
	v_lshlrev_b32_e32 v88, 16, v210
	v_and_b32_e32 v89, 0xffff0000, v210
	v_lshlrev_b32_e32 v208, 16, v141
	v_and_b32_e32 v209, 0xffff0000, v141
	v_fma_f32 v208, v208, v160, v202
	v_fma_f32 v209, v209, v160, v203
	v_cvt_pk_bf16_f32 v210, v208, v209
	v_lshlrev_b32_e32 v90, 16, v210
	v_and_b32_e32 v91, 0xffff0000, v210
	v_lshlrev_b32_e32 v208, 16, v142
	v_and_b32_e32 v209, 0xffff0000, v142
	v_fma_f32 v208, v208, v160, v204
	v_fma_f32 v209, v209, v160, v205
	v_cvt_pk_bf16_f32 v210, v208, v209
	v_lshlrev_b32_e32 v92, 16, v210
	v_and_b32_e32 v93, 0xffff0000, v210
	v_lshlrev_b32_e32 v208, 16, v143
	v_and_b32_e32 v209, 0xffff0000, v143
	v_fma_f32 v208, v208, v160, v206
	v_fma_f32 v209, v209, v160, v207
	v_cvt_pk_bf16_f32 v210, v208, v209
	v_lshlrev_b32_e32 v94, 16, v210
	v_and_b32_e32 v95, 0xffff0000, v210
	s_nop 0
	s_waitcnt vmcnt(0)
; __device__ __forceinline__ unsigned pk2(float lo, float hi) { const f32x2 v = {lo, hi}; const bf16x2_t b = __builtin_convertvector(v, bf16x2_t); return __builtin_bit_cast(unsigned, b); }
; __device__ __forceinline__ float bflo(unsigned u) { return __uint_as_float(u << 16); }
; __device__ __forceinline__ float bfhi(unsigned u) { return __uint_as_float(u & 0xffff0000u); }
; __device__ __forceinline__ void peer_tile(const Args& A, LAS unsigned char* lds, int tile) {
;     ...
;     for (int ti = 0; ti < 8; ++ti) {
;         const int tl = 8 * w + ti;
;         const u32x2 e0 = SEL[tl * 128 + lane], e1 = SEL[tl * 128 + 64 + lane];
;         const int p0 = (int)(e0.x >> 10), p1 = (int)(e1.x >> 10);
;     ...
;         for (int tk = 0; tk < 4; ++tk) { const size_t m = (size_t)tile * 64 + tb + tk;
;             { const u32x4 ra = *(const u32x4*)(A3 + m * 1024 + 16 * lane), rb = *(const u32x4*)(A3 + m * 1024 + 16 * lane + 8);
;               float xr_; { const f32x4 p0 = *(const f32x4*)(RSq + m * 16), p1 = *(const f32x4*)(RSq + m * 16 + 4), p2 = *(const f32x4*)(RSq + m * 16 + 8), p3 = *(const f32x4*)(RSq + m * 16 + 12);
;                 const f32x4 ps = (p0 + p1) + (p2 + p3); xr_ = rsqrtf(((ps[0] + ps[1]) + (ps[2] + ps[3])) * (1.f / 1024.f) + 1e-6f); }
;               const unsigned rr[8] = {ra.x, ra.y, ra.z, ra.w, rb.x, rb.y, rb.z, rb.w}; unsigned hh[8];
;               const float* sp = MOD + (int)(m >> 11) * 6144 + 3072 + 16 * lane;
; #pragma unroll
;               for (int q = 0; q < 8; ++q) { const f32x2 sh = *(const f32x2*)(sp + 2 * q); hh[q] = pk2(bflo(rr[q]) * xr_ + sh[0], bfhi(rr[q]) * xr_ + sh[1]); }
;               xpa[tk] = (u32x4){hh[0], hh[1], hh[2], hh[3]}; xpb[tk] = (u32x4){hh[4], hh[5], hh[6], hh[7]}; }
; #pragma unroll
;             for (int q = 0; q < 8; ++q) oacc[tk][q] = (f32x2){0.f, 0.f}; }
	v_pk_add_f32 v[216:217], v[216:217], v[220:221]
	v_pk_add_f32 v[218:219], v[218:219], v[222:223]
	v_pk_add_f32 v[224:225], v[224:225], v[228:229]
	v_pk_add_f32 v[226:227], v[226:227], v[230:231]
	v_pk_add_f32 v[216:217], v[216:217], v[224:225]
	v_pk_add_f32 v[218:219], v[218:219], v[226:227]
	v_add_f32_e32 v216, v216, v217
	v_add_f32_e32 v218, v218, v219
	v_add_f32_e32 v216, v216, v218
	v_fmamk_f32 v216, v216, 0x3a800000, v243
	v_rsq_f32_e32 v216, v216
	v_pk_add_f32 v[232:233], v[232:233], v[236:237]
	v_pk_add_f32 v[234:235], v[234:235], v[238:239]
	v_pk_add_f32 v[248:249], v[248:249], v[252:253]
	v_pk_add_f32 v[250:251], v[250:251], v[254:255]
	v_pk_add_f32 v[232:233], v[232:233], v[248:249]
	v_pk_add_f32 v[234:235], v[234:235], v[250:251]
	v_add_f32_e32 v232, v232, v233
	v_add_f32_e32 v234, v234, v235
	v_add_f32_e32 v232, v232, v234
	v_fmamk_f32 v232, v232, 0x3a800000, v243
	v_rsq_f32_e32 v232, v232
	v_lshlrev_b32_e32 v208, 16, v176
	v_and_b32_e32 v209, 0xffff0000, v176
	v_fma_f32 v208, v208, v216, v192
	v_fma_f32 v209, v209, v216, v193
	v_cvt_pk_bf16_f32 v210, v208, v209
	v_lshlrev_b32_e32 v96, 16, v210
	v_and_b32_e32 v97, 0xffff0000, v210
	v_lshlrev_b32_e32 v208, 16, v177
	v_and_b32_e32 v209, 0xffff0000, v177
	v_fma_f32 v208, v208, v216, v194
	v_fma_f32 v209, v209, v216, v195
	v_cvt_pk_bf16_f32 v210, v208, v209
	v_lshlrev_b32_e32 v98, 16, v210
	v_and_b32_e32 v99, 0xffff0000, v210
	v_lshlrev_b32_e32 v208, 16, v178
	v_and_b32_e32 v209, 0xffff0000, v178
	v_fma_f32 v208, v208, v216, v196
	v_fma_f32 v209, v209, v216, v197
	v_cvt_pk_bf16_f32 v210, v208, v209
	v_lshlrev_b32_e32 v100, 16, v210
	v_and_b32_e32 v101, 0xffff0000, v210
	v_lshlrev_b32_e32 v208, 16, v179
	v_and_b32_e32 v209, 0xffff0000, v179
	v_fma_f32 v208, v208, v216, v198
	v_fma_f32 v209, v209, v216, v199
	v_cvt_pk_bf16_f32 v210, v208, v209
	v_lshlrev_b32_e32 v102, 16, v210
	v_and_b32_e32 v103, 0xffff0000, v210
	v_lshlrev_b32_e32 v208, 16, v180
	v_and_b32_e32 v209, 0xffff0000, v180
	v_fma_f32 v208, v208, v216, v200
	v_fma_f32 v209, v209, v216, v201
	v_cvt_pk_bf16_f32 v210, v208, v209
	v_lshlrev_b32_e32 v104, 16, v210
	v_and_b32_e32 v105, 0xffff0000, v210
	v_lshlrev_b32_e32 v208, 16, v181
	v_and_b32_e32 v209, 0xffff0000, v181
	v_fma_f32 v208, v208, v216, v202
	v_fma_f32 v209, v209, v216, v203
	v_cvt_pk_bf16_f32 v210, v208, v209
	v_lshlrev_b32_e32 v106, 16, v210
	v_and_b32_e32 v107, 0xffff0000, v210
	v_lshlrev_b32_e32 v208, 16, v182
	v_and_b32_e32 v209, 0xffff0000, v182
	v_fma_f32 v208, v208, v216, v204
	v_fma_f32 v209, v209, v216, v205
	v_cvt_pk_bf16_f32 v210, v208, v209
	v_lshlrev_b32_e32 v108, 16, v210
	v_and_b32_e32 v109, 0xffff0000, v210
	v_lshlrev_b32_e32 v208, 16, v183
	v_and_b32_e32 v209, 0xffff0000, v183
	v_fma_f32 v208, v208, v216, v206
	v_fma_f32 v209, v209, v216, v207
	v_cvt_pk_bf16_f32 v210, v208, v209
	v_lshlrev_b32_e32 v110, 16, v210
	v_and_b32_e32 v111, 0xffff0000, v210
	v_lshlrev_b32_e32 v208, 16, v184
	v_and_b32_e32 v209, 0xffff0000, v184
	v_fma_f32 v208, v208, v232, v192
	v_fma_f32 v209, v209, v232, v193
	v_cvt_pk_bf16_f32 v210, v208, v209
	v_lshlrev_b32_e32 v112, 16, v210
	v_and_b32_e32 v113, 0xffff0000, v210
	v_lshlrev_b32_e32 v208, 16, v185
	v_and_b32_e32 v209, 0xffff0000, v185
	v_fma_f32 v208, v208, v232, v194
	v_fma_f32 v209, v209, v232, v195
	v_cvt_pk_bf16_f32 v210, v208, v209
	v_lshlrev_b32_e32 v114, 16, v210
	v_and_b32_e32 v115, 0xffff0000, v210
	v_lshlrev_b32_e32 v208, 16, v186
	v_and_b32_e32 v209, 0xffff0000, v186
	v_fma_f32 v208, v208, v232, v196
	v_fma_f32 v209, v209, v232, v197
	v_cvt_pk_bf16_f32 v210, v208, v209
	v_lshlrev_b32_e32 v116, 16, v210
	v_and_b32_e32 v117, 0xffff0000, v210
	v_lshlrev_b32_e32 v208, 16, v187
	v_and_b32_e32 v209, 0xffff0000, v187
	v_fma_f32 v208, v208, v232, v198
	v_fma_f32 v209, v209, v232, v199
	v_cvt_pk_bf16_f32 v210, v208, v209
	v_lshlrev_b32_e32 v118, 16, v210
	v_and_b32_e32 v119, 0xffff0000, v210
	v_lshlrev_b32_e32 v208, 16, v188
	v_and_b32_e32 v209, 0xffff0000, v188
	v_fma_f32 v208, v208, v232, v200
	v_fma_f32 v209, v209, v232, v201
	v_cvt_pk_bf16_f32 v210, v208, v209
	v_lshlrev_b32_e32 v120, 16, v210
	v_and_b32_e32 v121, 0xffff0000, v210
	v_lshlrev_b32_e32 v208, 16, v189
	v_and_b32_e32 v209, 0xffff0000, v189
	v_fma_f32 v208, v208, v232, v202
	v_fma_f32 v209, v209, v232, v203
	v_cvt_pk_bf16_f32 v210, v208, v209
	v_lshlrev_b32_e32 v122, 16, v210
	v_and_b32_e32 v123, 0xffff0000, v210
	v_lshlrev_b32_e32 v208, 16, v190
	v_and_b32_e32 v209, 0xffff0000, v190
	v_fma_f32 v208, v208, v232, v204
	v_fma_f32 v209, v209, v232, v205
	v_cvt_pk_bf16_f32 v210, v208, v209
	v_lshlrev_b32_e32 v124, 16, v210
	v_and_b32_e32 v125, 0xffff0000, v210
	v_lshlrev_b32_e32 v208, 16, v191
	v_and_b32_e32 v209, 0xffff0000, v191
	v_fma_f32 v208, v208, v232, v206
	v_fma_f32 v209, v209, v232, v207
	v_cvt_pk_bf16_f32 v210, v208, v209
	v_lshlrev_b32_e32 v126, 16, v210
	v_and_b32_e32 v127, 0xffff0000, v210
	s_nop 0
	v_mov_b32_e32 v216, 0x7fffffff
	v_mov_b32_e32 v217, 0x7fffffff
	v_mov_b32_e32 v218, 0x7fffffff
	v_mov_b32_e32 v219, 0x7fffffff
	v_mov_b32_e32 v224, 0
	v_mov_b32_e32 v225, 0
	v_mov_b32_e32 v226, 0
	v_mov_b32_e32 v227, 0
	v_add_u32_e32 v220, s22, v240
	ds_write_b128 v220, v[216:219] offset:0
	ds_write_b128 v220, v[224:227] offset:4992
	ds_write_b128 v220, v[216:219] offset:1024
	ds_write_b128 v220, v[224:227] offset:6016
	ds_write_b128 v220, v[216:219] offset:2048
	ds_write_b128 v220, v[224:227] offset:7040
	ds_write_b128 v220, v[216:219] offset:3072
	ds_write_b128 v220, v[224:227] offset:8064
	s_mov_b32 exec_hi, 0x00ffffff
	ds_write_b128 v220, v[216:219] offset:4096
	s_mov_b32 exec_hi, 0x000fffff
	ds_write_b128 v220, v[224:227] offset:9088
	s_mov_b64 exec, -1
	v_lshrrev_b32_e32 v222, 1, v240
	s_lshl_b32 s0, s76, 10
	s_add_i32 s0, s0, 0x11000
	v_add_u32_e32 v221, s0, v222
	ds_read_b64 v[128:129], v221 offset:0
	ds_read_b64 v[130:131], v221 offset:512
	ds_read_b64 v[132:133], v221 offset:1024
	ds_read_b64 v[134:135], v221 offset:1536
	ds_read_b64 v[136:137], v221 offset:2048
	ds_read_b64 v[138:139], v221 offset:2560
	ds_read_b64 v[140:141], v221 offset:3072
	ds_read_b64 v[142:143], v221 offset:3584
	ds_read_b64 v[144:145], v221 offset:4096
	ds_read_b64 v[146:147], v221 offset:4608
	ds_read_b64 v[148:149], v221 offset:5120
	ds_read_b64 v[150:151], v221 offset:5632
	ds_read_b64 v[152:153], v221 offset:6144
	ds_read_b64 v[154:155], v221 offset:6656
	ds_read_b64 v[156:157], v221 offset:7168
	ds_read_b64 v[158:159], v221 offset:7680
	v_mov_b32_e32 v212, 0
	v_mov_b32_e32 v241, 0
	s_mov_b32 s38, 0
	s_mov_b32 s64, 0
	s_mov_b32 s39, 0
	s_mov_b32 s65, 0
	s_mov_b32 s40, 0
	s_mov_b32 s66, 0
	s_mov_b32 s41, 0
	s_mov_b32 s67, 0
	s_mov_b32 s42, 0
	s_mov_b32 s94, 0
	s_mov_b32 s43, 0
	s_mov_b32 s95, 0
	s_mov_b32 s44, 0
	s_mov_b32 s96, 0
	s_mov_b32 s45, 0
	s_mov_b32 s97, 0
	s_waitcnt lgkmcnt(0)
; __device__ __forceinline__ void peer_tile(const Args& A, LAS unsigned char* lds, int tile) {
;     ...
;     for (int ti = 0; ti < 8; ++ti) {
;         const int tl = 8 * w + ti;
;         const u32x2 e0 = SEL[tl * 128 + lane], e1 = SEL[tl * 128 + 64 + lane];
;         const int p0 = (int)(e0.x >> 10), p1 = (int)(e1.x >> 10);
;         int off = 0;
;         for (int p = 0; p < 16; ++p) {
;             const unsigned long long m0 = __ballot(p0 == p), m1 = __ballot(p1 == p);
;             const int c0 = __popcll(m0), c1 = __popcll(m1);
;             const int r0 = __builtin_amdgcn_mbcnt_hi((unsigned)(m0 >> 32), __builtin_amdgcn_mbcnt_lo((unsigned)m0, 0u));
;             const int r1 = __builtin_amdgcn_mbcnt_hi((unsigned)(m1 >> 32), __builtin_amdgcn_mbcnt_lo((unsigned)m1, 0u));
;             if (p0 == p) SORT[tl * 128 + off + r0] = e0;
;             if (p1 == p) SORT[tl * 128 + off + c0 + r1] = e1;
;             if (lane == 0) OFFS[tl * 17 + p] = off;
;             off += c0 + c1;
;         }
;         if (lane == 0) OFFS[tl * 17 + 16] = off;
	v_lshrrev_b32_e32 v160, 11, v128
	v_lshrrev_b32_e32 v161, 11, v130
	v_lshrrev_b32_e32 v162, 11, v132
	v_lshrrev_b32_e32 v163, 11, v134
	v_lshrrev_b32_e32 v164, 11, v136
	v_lshrrev_b32_e32 v165, 11, v138
	v_lshrrev_b32_e32 v166, 11, v140
	v_lshrrev_b32_e32 v167, 11, v142
	v_lshrrev_b32_e32 v168, 11, v144
	v_lshrrev_b32_e32 v169, 11, v146
	v_lshrrev_b32_e32 v170, 11, v148
	v_lshrrev_b32_e32 v171, 11, v150
	v_lshrrev_b32_e32 v172, 11, v152
	v_lshrrev_b32_e32 v173, 11, v154
	v_lshrrev_b32_e32 v174, 11, v156
	v_lshrrev_b32_e32 v175, 11, v158
	s_mov_b32 s74, 0
	s_mov_b32 s75, 0
	s_mov_b32 s37, 0
.Lbuild_c:
	v_cmp_eq_u32_e64 s[68:69], s74, v160
	v_cmp_eq_u32_e64 s[70:71], s74, v161
	s_add_i32 s3, s38, 3
	s_lshr_b32 s3, s3, 2
	s_bcnt1_i32_b64 s0, s[68:69]
	s_bcnt1_i32_b64 s1, s[70:71]
	v_mbcnt_lo_u32_b32 v222, s68, 0
	v_mbcnt_hi_u32_b32 v222, s69, v222
	v_mbcnt_lo_u32_b32 v223, s70, 0
	v_mbcnt_hi_u32_b32 v223, s71, v223
	v_add_u32_e32 v222, s38, v222
	s_add_i32 s38, s38, s0
	v_add_u32_e32 v223, s38, v223
	s_add_i32 s38, s38, s1
	v_lshrrev_b32_e32 v228, 2, v222
	v_and_b32_e32 v222, 3, v222
	v_subrev_u32_e32 v228, s3, v228
	v_lshrrev_b32_e32 v230, 2, v223
	v_and_b32_e32 v223, 3, v223
	v_subrev_u32_e32 v230, s3, v230
	v_cmp_gt_i32_e64 s[92:93], 0, v228
	v_cmp_gt_i32_e64 vcc, 0, v230
	v_add_u32_e32 v228, s75, v228
	v_add_u32_e32 v230, s75, v230
	v_mov_b32_e32 v229, s64
	v_cndmask_b32_e64 v228, v228, v229, s[92:93]
	v_cndmask_b32_e32 v230, v230, v229, vcc
	v_lshl_add_u32 v228, v228, 4, s22
	v_lshl_add_u32 v230, v230, 4, s22
	v_lshl_add_u32 v222, v222, 2, v228
	v_lshl_add_u32 v223, v223, 2, v230
	s_mov_b64 exec, s[68:69]
	ds_write_b32 v222, v128
	ds_write_b32 v222, v129 offset:4992
	s_mov_b64 exec, s[70:71]
	ds_write_b32 v223, v130
	ds_write_b32 v223, v131 offset:4992
	s_add_i32 s0, s38, 3
	s_lshr_b32 s0, s0, 2
	s_sub_i32 s0, s0, s3
	s_lshl_b64 s[92:93], 1, s37
	s_mov_b64 exec, s[92:93]
	v_mov_b32_e32 v212, s0
	s_mov_b64 exec, -1
	s_add_i32 s75, s75, s0
	s_sub_i32 s1, s75, 1
	s_cmp_lg_u32 s0, 0
	s_cselect_b32 s64, s1, s64
	s_add_i32 s37, s37, 1
	v_cmp_eq_u32_e64 s[68:69], s74, v162
	v_cmp_eq_u32_e64 s[70:71], s74, v163
	s_add_i32 s3, s39, 3
	s_lshr_b32 s3, s3, 2
	s_bcnt1_i32_b64 s0, s[68:69]
	s_bcnt1_i32_b64 s1, s[70:71]
	v_mbcnt_lo_u32_b32 v222, s68, 0
	v_mbcnt_hi_u32_b32 v222, s69, v222
	v_mbcnt_lo_u32_b32 v223, s70, 0
	v_mbcnt_hi_u32_b32 v223, s71, v223
	v_add_u32_e32 v222, s39, v222
	s_add_i32 s39, s39, s0
	v_add_u32_e32 v223, s39, v223
	s_add_i32 s39, s39, s1
	v_lshrrev_b32_e32 v228, 2, v222
	v_and_b32_e32 v222, 3, v222
	v_subrev_u32_e32 v228, s3, v228
	v_lshrrev_b32_e32 v230, 2, v223
	v_and_b32_e32 v223, 3, v223
	v_subrev_u32_e32 v230, s3, v230
	v_cmp_gt_i32_e64 s[92:93], 0, v228
	v_cmp_gt_i32_e64 vcc, 0, v230
	v_add_u32_e32 v228, s75, v228
	v_add_u32_e32 v230, s75, v230
	v_mov_b32_e32 v229, s65
	v_cndmask_b32_e64 v228, v228, v229, s[92:93]
	v_cndmask_b32_e32 v230, v230, v229, vcc
	v_lshl_add_u32 v228, v228, 4, s22
	v_lshl_add_u32 v230, v230, 4, s22
	v_lshl_add_u32 v222, v222, 2, v228
	v_lshl_add_u32 v223, v223, 2, v230
	s_mov_b64 exec, s[68:69]
	ds_write_b32 v222, v132
	ds_write_b32 v222, v133 offset:4992
	s_mov_b64 exec, s[70:71]
	ds_write_b32 v223, v134
	ds_write_b32 v223, v135 offset:4992
	s_add_i32 s0, s39, 3
	s_lshr_b32 s0, s0, 2
	s_sub_i32 s0, s0, s3
	s_lshl_b64 s[92:93], 1, s37
	s_mov_b64 exec, s[92:93]
	v_mov_b32_e32 v212, s0
	s_mov_b64 exec, -1
	s_add_i32 s75, s75, s0
	s_sub_i32 s1, s75, 1
	s_cmp_lg_u32 s0, 0
	s_cselect_b32 s65, s1, s65
	s_add_i32 s37, s37, 1
	v_cmp_eq_u32_e64 s[68:69], s74, v164
	v_cmp_eq_u32_e64 s[70:71], s74, v165
	s_add_i32 s3, s40, 3
	s_lshr_b32 s3, s3, 2
	s_bcnt1_i32_b64 s0, s[68:69]
	s_bcnt1_i32_b64 s1, s[70:71]
	v_mbcnt_lo_u32_b32 v222, s68, 0
	v_mbcnt_hi_u32_b32 v222, s69, v222
	v_mbcnt_lo_u32_b32 v223, s70, 0
	v_mbcnt_hi_u32_b32 v223, s71, v223
	v_add_u32_e32 v222, s40, v222
	s_add_i32 s40, s40, s0
	v_add_u32_e32 v223, s40, v223
	s_add_i32 s40, s40, s1
	v_lshrrev_b32_e32 v228, 2, v222
	v_and_b32_e32 v222, 3, v222
	v_subrev_u32_e32 v228, s3, v228
	v_lshrrev_b32_e32 v230, 2, v223
	v_and_b32_e32 v223, 3, v223
	v_subrev_u32_e32 v230, s3, v230
	v_cmp_gt_i32_e64 s[92:93], 0, v228
	v_cmp_gt_i32_e64 vcc, 0, v230
	v_add_u32_e32 v228, s75, v228
	v_add_u32_e32 v230, s75, v230
	v_mov_b32_e32 v229, s66
	v_cndmask_b32_e64 v228, v228, v229, s[92:93]
	v_cndmask_b32_e32 v230, v230, v229, vcc
	v_lshl_add_u32 v228, v228, 4, s22
	v_lshl_add_u32 v230, v230, 4, s22
	v_lshl_add_u32 v222, v222, 2, v228
	v_lshl_add_u32 v223, v223, 2, v230
	s_mov_b64 exec, s[68:69]
	ds_write_b32 v222, v136
	ds_write_b32 v222, v137 offset:4992
	s_mov_b64 exec, s[70:71]
	ds_write_b32 v223, v138
	ds_write_b32 v223, v139 offset:4992
	s_add_i32 s0, s40, 3
	s_lshr_b32 s0, s0, 2
	s_sub_i32 s0, s0, s3
	s_lshl_b64 s[92:93], 1, s37
	s_mov_b64 exec, s[92:93]
	v_mov_b32_e32 v212, s0
	s_mov_b64 exec, -1
	s_add_i32 s75, s75, s0
	s_sub_i32 s1, s75, 1
	s_cmp_lg_u32 s0, 0
	s_cselect_b32 s66, s1, s66
	s_add_i32 s37, s37, 1
	v_cmp_eq_u32_e64 s[68:69], s74, v166
	v_cmp_eq_u32_e64 s[70:71], s74, v167
	s_add_i32 s3, s41, 3
	s_lshr_b32 s3, s3, 2
	s_bcnt1_i32_b64 s0, s[68:69]
	s_bcnt1_i32_b64 s1, s[70:71]
	v_mbcnt_lo_u32_b32 v222, s68, 0
	v_mbcnt_hi_u32_b32 v222, s69, v222
	v_mbcnt_lo_u32_b32 v223, s70, 0
	v_mbcnt_hi_u32_b32 v223, s71, v223
	v_add_u32_e32 v222, s41, v222
	s_add_i32 s41, s41, s0
	v_add_u32_e32 v223, s41, v223
	s_add_i32 s41, s41, s1
	v_lshrrev_b32_e32 v228, 2, v222
	v_and_b32_e32 v222, 3, v222
	v_subrev_u32_e32 v228, s3, v228
	v_lshrrev_b32_e32 v230, 2, v223
	v_and_b32_e32 v223, 3, v223
	v_subrev_u32_e32 v230, s3, v230
	v_cmp_gt_i32_e64 s[92:93], 0, v228
; __device__ __forceinline__ void peer_tile(const Args& A, LAS unsigned char* lds, int tile) {
;     ...
;     for (int ti = 0; ti < 8; ++ti) {
;         const int tl = 8 * w + ti;
;         const u32x2 e0 = SEL[tl * 128 + lane], e1 = SEL[tl * 128 + 64 + lane];
;         const int p0 = (int)(e0.x >> 10), p1 = (int)(e1.x >> 10);
;         int off = 0;
;         for (int p = 0; p < 16; ++p) {
;             const unsigned long long m0 = __ballot(p0 == p), m1 = __ballot(p1 == p);
;             const int c0 = __popcll(m0), c1 = __popcll(m1);
;             const int r0 = __builtin_amdgcn_mbcnt_hi((unsigned)(m0 >> 32), __builtin_amdgcn_mbcnt_lo((unsigned)m0, 0u));
;             const int r1 = __builtin_amdgcn_mbcnt_hi((unsigned)(m1 >> 32), __builtin_amdgcn_mbcnt_lo((unsigned)m1, 0u));
;             if (p0 == p) SORT[tl * 128 + off + r0] = e0;
;             if (p1 == p) SORT[tl * 128 + off + c0 + r1] = e1;
;             if (lane == 0) OFFS[tl * 17 + p] = off;
;             off += c0 + c1;
;         }
;         if (lane == 0) OFFS[tl * 17 + 16] = off;
	v_cmp_gt_i32_e64 vcc, 0, v230
	v_add_u32_e32 v228, s75, v228
	v_add_u32_e32 v230, s75, v230
	v_mov_b32_e32 v229, s67
	v_cndmask_b32_e64 v228, v228, v229, s[92:93]
	v_cndmask_b32_e32 v230, v230, v229, vcc
	v_lshl_add_u32 v228, v228, 4, s22
	v_lshl_add_u32 v230, v230, 4, s22
	v_lshl_add_u32 v222, v222, 2, v228
	v_lshl_add_u32 v223, v223, 2, v230
	s_mov_b64 exec, s[68:69]
	ds_write_b32 v222, v140
	ds_write_b32 v222, v141 offset:4992
	s_mov_b64 exec, s[70:71]
	ds_write_b32 v223, v142
	ds_write_b32 v223, v143 offset:4992
	s_add_i32 s0, s41, 3
	s_lshr_b32 s0, s0, 2
	s_sub_i32 s0, s0, s3
	s_lshl_b64 s[92:93], 1, s37
	s_mov_b64 exec, s[92:93]
	v_mov_b32_e32 v212, s0
	s_mov_b64 exec, -1
	s_add_i32 s75, s75, s0
	s_sub_i32 s1, s75, 1
	s_cmp_lg_u32 s0, 0
	s_cselect_b32 s67, s1, s67
	s_add_i32 s37, s37, 1
	v_cmp_eq_u32_e64 s[68:69], s74, v168
	v_cmp_eq_u32_e64 s[70:71], s74, v169
	s_add_i32 s3, s42, 3
	s_lshr_b32 s3, s3, 2
	s_bcnt1_i32_b64 s0, s[68:69]
	s_bcnt1_i32_b64 s1, s[70:71]
	v_mbcnt_lo_u32_b32 v222, s68, 0
	v_mbcnt_hi_u32_b32 v222, s69, v222
	v_mbcnt_lo_u32_b32 v223, s70, 0
	v_mbcnt_hi_u32_b32 v223, s71, v223
	v_add_u32_e32 v222, s42, v222
	s_add_i32 s42, s42, s0
	v_add_u32_e32 v223, s42, v223
	s_add_i32 s42, s42, s1
	v_lshrrev_b32_e32 v228, 2, v222
	v_and_b32_e32 v222, 3, v222
	v_subrev_u32_e32 v228, s3, v228
	v_lshrrev_b32_e32 v230, 2, v223
	v_and_b32_e32 v223, 3, v223
	v_subrev_u32_e32 v230, s3, v230
	v_cmp_gt_i32_e64 s[92:93], 0, v228
	v_cmp_gt_i32_e64 vcc, 0, v230
	v_add_u32_e32 v228, s75, v228
	v_add_u32_e32 v230, s75, v230
	v_mov_b32_e32 v229, s94
	v_cndmask_b32_e64 v228, v228, v229, s[92:93]
	v_cndmask_b32_e32 v230, v230, v229, vcc
	v_lshl_add_u32 v228, v228, 4, s22
	v_lshl_add_u32 v230, v230, 4, s22
	v_lshl_add_u32 v222, v222, 2, v228
	v_lshl_add_u32 v223, v223, 2, v230
	s_mov_b64 exec, s[68:69]
	ds_write_b32 v222, v144
	ds_write_b32 v222, v145 offset:4992
	s_mov_b64 exec, s[70:71]
	ds_write_b32 v223, v146
	ds_write_b32 v223, v147 offset:4992
	s_add_i32 s0, s42, 3
	s_lshr_b32 s0, s0, 2
	s_sub_i32 s0, s0, s3
	s_lshl_b64 s[92:93], 1, s37
	s_mov_b64 exec, s[92:93]
	v_mov_b32_e32 v212, s0
	s_mov_b64 exec, -1
	s_add_i32 s75, s75, s0
	s_sub_i32 s1, s75, 1
	s_cmp_lg_u32 s0, 0
	s_cselect_b32 s94, s1, s94
	s_add_i32 s37, s37, 1
	v_cmp_eq_u32_e64 s[68:69], s74, v170
	v_cmp_eq_u32_e64 s[70:71], s74, v171
	s_add_i32 s3, s43, 3
	s_lshr_b32 s3, s3, 2
	s_bcnt1_i32_b64 s0, s[68:69]
	s_bcnt1_i32_b64 s1, s[70:71]
	v_mbcnt_lo_u32_b32 v222, s68, 0
	v_mbcnt_hi_u32_b32 v222, s69, v222
	v_mbcnt_lo_u32_b32 v223, s70, 0
	v_mbcnt_hi_u32_b32 v223, s71, v223
	v_add_u32_e32 v222, s43, v222
	s_add_i32 s43, s43, s0
	v_add_u32_e32 v223, s43, v223
	s_add_i32 s43, s43, s1
	v_lshrrev_b32_e32 v228, 2, v222
	v_and_b32_e32 v222, 3, v222
	v_subrev_u32_e32 v228, s3, v228
	v_lshrrev_b32_e32 v230, 2, v223
	v_and_b32_e32 v223, 3, v223
	v_subrev_u32_e32 v230, s3, v230
	v_cmp_gt_i32_e64 s[92:93], 0, v228
	v_cmp_gt_i32_e64 vcc, 0, v230
	v_add_u32_e32 v228, s75, v228
	v_add_u32_e32 v230, s75, v230
	v_mov_b32_e32 v229, s95
	v_cndmask_b32_e64 v228, v228, v229, s[92:93]
	v_cndmask_b32_e32 v230, v230, v229, vcc
	v_lshl_add_u32 v228, v228, 4, s22
	v_lshl_add_u32 v230, v230, 4, s22
	v_lshl_add_u32 v222, v222, 2, v228
	v_lshl_add_u32 v223, v223, 2, v230
	s_mov_b64 exec, s[68:69]
	ds_write_b32 v222, v148
	ds_write_b32 v222, v149 offset:4992
	s_mov_b64 exec, s[70:71]
	ds_write_b32 v223, v150
	ds_write_b32 v223, v151 offset:4992
	s_add_i32 s0, s43, 3
	s_lshr_b32 s0, s0, 2
	s_sub_i32 s0, s0, s3
	s_lshl_b64 s[92:93], 1, s37
	s_mov_b64 exec, s[92:93]
	v_mov_b32_e32 v212, s0
	s_mov_b64 exec, -1
	s_add_i32 s75, s75, s0
	s_sub_i32 s1, s75, 1
	s_cmp_lg_u32 s0, 0
	s_cselect_b32 s95, s1, s95
	s_add_i32 s37, s37, 1
	v_cmp_eq_u32_e64 s[68:69], s74, v172
	v_cmp_eq_u32_e64 s[70:71], s74, v173
	s_add_i32 s3, s44, 3
	s_lshr_b32 s3, s3, 2
	s_bcnt1_i32_b64 s0, s[68:69]
	s_bcnt1_i32_b64 s1, s[70:71]
	v_mbcnt_lo_u32_b32 v222, s68, 0
	v_mbcnt_hi_u32_b32 v222, s69, v222
	v_mbcnt_lo_u32_b32 v223, s70, 0
	v_mbcnt_hi_u32_b32 v223, s71, v223
	v_add_u32_e32 v222, s44, v222
	s_add_i32 s44, s44, s0
	v_add_u32_e32 v223, s44, v223
	s_add_i32 s44, s44, s1
	v_lshrrev_b32_e32 v228, 2, v222
	v_and_b32_e32 v222, 3, v222
	v_subrev_u32_e32 v228, s3, v228
	v_lshrrev_b32_e32 v230, 2, v223
	v_and_b32_e32 v223, 3, v223
	v_subrev_u32_e32 v230, s3, v230
	v_cmp_gt_i32_e64 s[92:93], 0, v228
	v_cmp_gt_i32_e64 vcc, 0, v230
	v_add_u32_e32 v228, s75, v228
	v_add_u32_e32 v230, s75, v230
	v_mov_b32_e32 v229, s96
	v_cndmask_b32_e64 v228, v228, v229, s[92:93]
	v_cndmask_b32_e32 v230, v230, v229, vcc
	v_lshl_add_u32 v228, v228, 4, s22
	v_lshl_add_u32 v230, v230, 4, s22
	v_lshl_add_u32 v222, v222, 2, v228
	v_lshl_add_u32 v223, v223, 2, v230
	s_mov_b64 exec, s[68:69]
	ds_write_b32 v222, v152
	ds_write_b32 v222, v153 offset:4992
	s_mov_b64 exec, s[70:71]
	ds_write_b32 v223, v154
	ds_write_b32 v223, v155 offset:4992
	s_add_i32 s0, s44, 3
	s_lshr_b32 s0, s0, 2
	s_sub_i32 s0, s0, s3
	s_lshl_b64 s[92:93], 1, s37
	s_mov_b64 exec, s[92:93]
	v_mov_b32_e32 v212, s0
	s_mov_b64 exec, -1
	s_add_i32 s75, s75, s0
	s_sub_i32 s1, s75, 1
	s_cmp_lg_u32 s0, 0
	s_cselect_b32 s96, s1, s96
	s_add_i32 s37, s37, 1
	v_cmp_eq_u32_e64 s[68:69], s74, v174
	v_cmp_eq_u32_e64 s[70:71], s74, v175
	s_add_i32 s3, s45, 3
	s_lshr_b32 s3, s3, 2
	s_bcnt1_i32_b64 s0, s[68:69]
	s_bcnt1_i32_b64 s1, s[70:71]
	v_mbcnt_lo_u32_b32 v222, s68, 0
	v_mbcnt_hi_u32_b32 v222, s69, v222
	v_mbcnt_lo_u32_b32 v223, s70, 0
	v_mbcnt_hi_u32_b32 v223, s71, v223
	v_add_u32_e32 v222, s45, v222
	s_add_i32 s45, s45, s0
	v_add_u32_e32 v223, s45, v223
	s_add_i32 s45, s45, s1
	v_lshrrev_b32_e32 v228, 2, v222
	v_and_b32_e32 v222, 3, v222
	v_subrev_u32_e32 v228, s3, v228
	v_lshrrev_b32_e32 v230, 2, v223
	v_and_b32_e32 v223, 3, v223
	v_subrev_u32_e32 v230, s3, v230
	v_cmp_gt_i32_e64 s[92:93], 0, v228
	v_cmp_gt_i32_e64 vcc, 0, v230
	v_add_u32_e32 v228, s75, v228
	v_add_u32_e32 v230, s75, v230
	v_mov_b32_e32 v229, s97
	v_cndmask_b32_e64 v228, v228, v229, s[92:93]
	v_cndmask_b32_e32 v230, v230, v229, vcc
	v_lshl_add_u32 v228, v228, 4, s22
	v_lshl_add_u32 v230, v230, 4, s22
	v_lshl_add_u32 v222, v222, 2, v228
	v_lshl_add_u32 v223, v223, 2, v230
	s_mov_b64 exec, s[68:69]
	ds_write_b32 v222, v156
	ds_write_b32 v222, v157 offset:4992
	s_mov_b64 exec, s[70:71]
	ds_write_b32 v223, v158
	ds_write_b32 v223, v159 offset:4992
	s_add_i32 s0, s45, 3
	s_lshr_b32 s0, s0, 2
	s_sub_i32 s0, s0, s3
	s_lshl_b64 s[92:93], 1, s37
	s_mov_b64 exec, s[92:93]
	v_mov_b32_e32 v212, s0
	s_mov_b64 exec, -1
	s_add_i32 s75, s75, s0
	s_sub_i32 s1, s75, 1
	s_cmp_lg_u32 s0, 0
	s_cselect_b32 s97, s1, s97
	s_add_i32 s37, s37, 1
	s_add_i32 s74, s74, 1
	s_cmp_lt_u32 s74, 8
	s_cbranch_scc1 .Lbuild_c
; #define IT_ADVANCE() do { it_j += 4; while (it_j >= it_end) { if (it_done) break; ++it_tk; if (it_tk == 4) { it_tk = 0; ++it_p; if (it_p == 16) { it_done = true; it_p = 15; it_j = 0; it_end = 1; break; } } \
;             it_j = __builtin_amdgcn_readfirstlane(OFFS[(tb + it_tk) * 17 + it_p]); it_end = __builtin_amdgcn_readfirstlane(OFFS[(tb + it_tk) * 17 + it_p + 1]); } } while (0)
; __device__ __forceinline__ void peer_tile(const Args& A, LAS unsigned char* lds, int tile) {
;     ...
;         int it_p = 0, it_tk = -1, it_j = 0, it_end = 0; bool it_done = false;
;     ...
;         u32x4 uA[4], vA[4], uB[4], vB[4]; float cgA = 0.f, suA = 0.f, svA = 0.f, cgB = 0.f, suB = 0.f, svB = 0.f;
; #pragma unroll
;         for (int k = 0; k < 4; ++k) { uA[k] = (u32x4){0u, 0u, 0u, 0u}; vA[k] = uA[k]; uB[k] = uA[k]; vB[k] = uA[k]; }
;         IT_ADVANCE();
;         LOAD_SET(uA, vA, cgA, suA, svA);
	s_mov_b32 s91, s75
	s_add_i32 s20, s91, 3
	s_and_b32 s20, s20, -4
	s_mov_b32 s24, s8
	s_and_b32 s25, s9, 0xffff
	s_mov_b32 s26, 0x10000
	s_mov_b32 s27, 0x00027000
	s_mov_b32 s28, s52
	s_and_b32 s29, s53, 0xffff
	s_mov_b32 s30, 0x10000
	s_mov_b32 s31, 0x00027000
	s_waitcnt vmcnt(0) lgkmcnt(0)
	v_mov_b32_e32 v213, s22
	v_mov_b32_e32 v233, v240
	v_mov_b32_e32 v235, v240
	v_mov_b32_e32 v237, v240
	v_mov_b32_e32 v239, v240
	ds_read_b32 v232, v213 offset:0
	ds_read_b32 v234, v213 offset:4
	ds_read_b32 v236, v213 offset:8
	ds_read_b32 v238, v213 offset:12
	s_waitcnt lgkmcnt(0)
	buffer_load_dwordx4 v[128:131], v[232:233], s[56:59], 0 idxen offen
	buffer_load_dwordx4 v[132:135], v[234:235], s[56:59], 0 idxen offen
	buffer_load_dwordx4 v[136:139], v[236:237], s[56:59], 0 idxen offen
	buffer_load_dwordx4 v[140:143], v[238:239], s[56:59], 0 idxen offen
	ds_read_b32 v232, v213 offset:16
	ds_read_b32 v234, v213 offset:20
	ds_read_b32 v236, v213 offset:24
	ds_read_b32 v238, v213 offset:28
	s_waitcnt lgkmcnt(0)
	buffer_load_dwordx4 v[144:147], v[232:233], s[56:59], 0 idxen offen
	buffer_load_dwordx4 v[148:151], v[234:235], s[56:59], 0 idxen offen
	buffer_load_dwordx4 v[152:155], v[236:237], s[56:59], 0 idxen offen
	buffer_load_dwordx4 v[156:159], v[238:239], s[56:59], 0 idxen offen
	ds_read_b32 v232, v213 offset:32
	ds_read_b32 v234, v213 offset:36
	ds_read_b32 v236, v213 offset:40
	ds_read_b32 v238, v213 offset:44
	s_waitcnt lgkmcnt(0)
	buffer_load_dwordx4 v[160:163], v[232:233], s[56:59], 0 idxen offen
	buffer_load_dwordx4 v[164:167], v[234:235], s[56:59], 0 idxen offen
	buffer_load_dwordx4 v[168:171], v[236:237], s[56:59], 0 idxen offen
	buffer_load_dwordx4 v[172:175], v[238:239], s[56:59], 0 idxen offen
	ds_read_b32 v232, v213 offset:48
	ds_read_b32 v234, v213 offset:52
	ds_read_b32 v236, v213 offset:56
	ds_read_b32 v238, v213 offset:60
	s_mov_b32 s21, 0
	s_mov_b32 s89, -1
	s_mov_b32 s86, 0
	v_lshrrev_b32_e32 v208, 6, v240
	v_and_b32_e32 v208, 3, v208
	v_lshrrev_b32_e32 v209, 1, v208
	v_lshlrev_b32_e32 v208, 1, v208
	v_and_b32_e32 v208, 2, v208
	v_or_b32_e32 v208, v208, v209
	v_lshlrev_b32_e32 v208, 2, v208
	v_add3_u32 v211, v208, v247, s22
	ds_read_b32 v248, v211
	ds_read_b32 v249, v211 offset:4992
	s_branch .LU_sw0

; #define IT_ADVANCE() do { it_j += 4; while (it_j >= it_end) { if (it_done) break; ++it_tk; if (it_tk == 4) { it_tk = 0; ++it_p; if (it_p == 16) { it_done = true; it_p = 15; it_j = 0; it_end = 1; break; } } \
;             it_j = __builtin_amdgcn_readfirstlane(OFFS[(tb + it_tk) * 17 + it_p]); it_end = __builtin_amdgcn_readfirstlane(OFFS[(tb + it_tk) * 17 + it_p + 1]); } } while (0)
; __device__ __forceinline__ void peer_tile(const Args& A, LAS unsigned char* lds, int tile) {
;     ...
;         int it_p = 0, it_tk = -1, it_j = 0, it_end = 0; bool it_done = false;
;     ...
;         u32x4 uA[4], vA[4], uB[4], vB[4]; float cgA = 0.f, suA = 0.f, svA = 0.f, cgB = 0.f, suB = 0.f, svB = 0.f;
; #pragma unroll
;         for (int k = 0; k < 4; ++k) { uA[k] = (u32x4){0u, 0u, 0u, 0u}; vA[k] = uA[k]; uB[k] = uA[k]; vB[k] = uA[k]; }
;         IT_ADVANCE();
;         LOAD_SET(uA, vA, cgA, suA, svA);
.LU_done:
	s_waitcnt vmcnt(0) lgkmcnt(0)
	v_mov_b64_e32 v[0:1], 0
	v_mov_b64_e32 v[2:3], 0
	v_mov_b64_e32 v[4:5], 0
	v_mov_b64_e32 v[6:7], 0
	v_mov_b64_e32 v[8:9], 0
	v_mov_b64_e32 v[10:11], 0
	v_mov_b64_e32 v[12:13], 0
	v_mov_b64_e32 v[14:15], 0
	v_mov_b64_e32 v[16:17], 0
	v_mov_b64_e32 v[18:19], 0
	v_mov_b64_e32 v[20:21], 0
	v_mov_b64_e32 v[22:23], 0
	v_mov_b64_e32 v[24:25], 0
	v_mov_b64_e32 v[26:27], 0
	v_mov_b64_e32 v[28:29], 0
	v_mov_b64_e32 v[30:31], 0
	v_mov_b64_e32 v[32:33], 0
	v_mov_b64_e32 v[34:35], 0
	v_mov_b64_e32 v[36:37], 0
	v_mov_b64_e32 v[38:39], 0
	v_mov_b64_e32 v[40:41], 0
	v_mov_b64_e32 v[42:43], 0
	v_mov_b64_e32 v[44:45], 0
	v_mov_b64_e32 v[46:47], 0
	v_mov_b64_e32 v[48:49], 0
	v_mov_b64_e32 v[50:51], 0
	v_mov_b64_e32 v[52:53], 0
	v_mov_b64_e32 v[54:55], 0
	v_mov_b64_e32 v[56:57], 0
	v_mov_b64_e32 v[58:59], 0
	v_mov_b64_e32 v[60:61], 0
	v_mov_b64_e32 v[62:63], 0
	v_mov_b64_e32 v[64:65], 0
	v_mov_b64_e32 v[66:67], 0
	v_mov_b64_e32 v[68:69], 0
	v_mov_b64_e32 v[70:71], 0
	v_mov_b64_e32 v[72:73], 0
	v_mov_b64_e32 v[74:75], 0
	v_mov_b64_e32 v[76:77], 0
	v_mov_b64_e32 v[78:79], 0
	v_mov_b64_e32 v[80:81], 0
	v_mov_b64_e32 v[82:83], 0
	v_mov_b64_e32 v[84:85], 0
	v_mov_b64_e32 v[86:87], 0
	v_mov_b64_e32 v[88:89], 0
	v_mov_b64_e32 v[90:91], 0
	v_mov_b64_e32 v[92:93], 0
	v_mov_b64_e32 v[94:95], 0
	v_mov_b64_e32 v[96:97], 0
	v_mov_b64_e32 v[98:99], 0
	v_mov_b64_e32 v[100:101], 0
	v_mov_b64_e32 v[102:103], 0
	v_mov_b64_e32 v[104:105], 0
	v_mov_b64_e32 v[106:107], 0
	v_mov_b64_e32 v[108:109], 0
	v_mov_b64_e32 v[110:111], 0
	v_mov_b64_e32 v[112:113], 0
	v_mov_b64_e32 v[114:115], 0
	v_mov_b64_e32 v[116:117], 0
	v_mov_b64_e32 v[118:119], 0
	v_mov_b64_e32 v[120:121], 0
	v_mov_b64_e32 v[122:123], 0
	v_mov_b64_e32 v[124:125], 0
	v_mov_b64_e32 v[126:127], 0
	s_add_i32 s20, s91, 3
	s_and_b32 s20, s20, -4
	s_waitcnt vmcnt(0) lgkmcnt(0)
	v_mov_b32_e32 v213, s22
	v_mov_b32_e32 v233, v240
	v_mov_b32_e32 v235, v240
	v_mov_b32_e32 v237, v240
	v_mov_b32_e32 v239, v240
	ds_read_b32 v232, v213 offset:0
	ds_read_b32 v234, v213 offset:4
	ds_read_b32 v236, v213 offset:8
	ds_read_b32 v238, v213 offset:12
	s_waitcnt lgkmcnt(0)
	buffer_load_dwordx4 v[128:131], v[232:233], s[60:63], 0 idxen offen
	buffer_load_dwordx4 v[132:135], v[234:235], s[60:63], 0 idxen offen
	buffer_load_dwordx4 v[136:139], v[236:237], s[60:63], 0 idxen offen
	buffer_load_dwordx4 v[140:143], v[238:239], s[60:63], 0 idxen offen
	ds_read_b32 v232, v213 offset:16
	ds_read_b32 v234, v213 offset:20
	ds_read_b32 v236, v213 offset:24
	ds_read_b32 v238, v213 offset:28
	s_waitcnt lgkmcnt(0)
	buffer_load_dwordx4 v[144:147], v[232:233], s[60:63], 0 idxen offen
	buffer_load_dwordx4 v[148:151], v[234:235], s[60:63], 0 idxen offen
	buffer_load_dwordx4 v[152:155], v[236:237], s[60:63], 0 idxen offen
	buffer_load_dwordx4 v[156:159], v[238:239], s[60:63], 0 idxen offen
	ds_read_b32 v232, v213 offset:32
	ds_read_b32 v234, v213 offset:36
	ds_read_b32 v236, v213 offset:40
	ds_read_b32 v238, v213 offset:44
	s_waitcnt lgkmcnt(0)
	buffer_load_dwordx4 v[160:163], v[232:233], s[60:63], 0 idxen offen
	buffer_load_dwordx4 v[164:167], v[234:235], s[60:63], 0 idxen offen
	buffer_load_dwordx4 v[168:171], v[236:237], s[60:63], 0 idxen offen
	buffer_load_dwordx4 v[172:175], v[238:239], s[60:63], 0 idxen offen
	ds_read_b128 v[248:251], v213 offset:4992
	ds_read_b32 v232, v213 offset:48
	ds_read_b32 v234, v213 offset:52
	ds_read_b32 v236, v213 offset:56
	ds_read_b32 v238, v213 offset:60
	s_mov_b32 s21, 0
	s_mov_b32 s89, -1
	s_mov_b32 s86, 0
	s_branch .LV_sw0
